# GEMM K-loops: redundant second s_waitcnt lgkmcnt(0) between s_setprio 1 and the MFMA block removed (66 sites)
# speedup vs baseline: 1.0066x; 1.0041x over previous
.LBB0_305:
	s_add_u32 s30, s4, 0xfffc0080
	s_addc_u32 s31, s5, -1
	s_add_i32 s52, 0, 0x10000
	ds_read_b128 v[150:153], v133
	ds_read_b128 v[156:159], v133 offset:1024
	ds_read_b128 v[160:163], v133 offset:2048
	ds_read_b128 v[164:167], v133 offset:3072
	s_cmp_eq_u32 s51, 12
	s_cselect_b32 s35, s27, s31
	s_cselect_b32 s34, s26, s30
	s_cselect_b32 s31, s29, s25
	s_cselect_b32 s30, s28, s23
	s_add_i32 m0, s42, 0xc000
	ds_read_b128 v[168:171], v155
	ds_read_b128 v[172:175], v155 offset:1024
	ds_read_b128 v[176:179], v155 offset:2048
	ds_read_b128 v[180:183], v155 offset:3072
	ds_read_b128 v[184:187], v155 offset:4096
	ds_read_b128 v[188:191], v155 offset:5120
	ds_read_b128 v[198:201], v155 offset:6144
	ds_read_b128 v[202:205], v155 offset:7168
	global_load_lds_dwordx4 v146, s[4:5]
	s_add_i32 m0, s42, 0xe000
	s_nop 0
	global_load_lds_dwordx4 v148, s[4:5]
	s_waitcnt lgkmcnt(8)
	s_barrier
	s_waitcnt lgkmcnt(0)
	s_setprio 1
	v_mfma_f32_16x16x32_bf16 v[126:129], v[150:153], v[168:171], v[126:129]
	v_mfma_f32_16x16x32_bf16 v[122:125], v[160:163], v[168:171], v[122:125]
	v_mfma_f32_16x16x32_bf16 v[110:113], v[150:153], v[176:179], v[110:113]
	v_mfma_f32_16x16x32_bf16 v[106:109], v[160:163], v[176:179], v[106:109]
	v_mfma_f32_16x16x32_bf16 v[94:97], v[150:153], v[184:187], v[94:97]
	v_mfma_f32_16x16x32_bf16 v[90:93], v[160:163], v[184:187], v[90:93]
	v_mfma_f32_16x16x32_bf16 v[78:81], v[150:153], v[198:201], v[78:81]
	v_mfma_f32_16x16x32_bf16 v[74:77], v[160:163], v[198:201], v[74:77]
	v_mfma_f32_16x16x32_bf16 v[126:129], v[156:159], v[172:175], v[126:129]
	v_mfma_f32_16x16x32_bf16 v[122:125], v[164:167], v[172:175], v[122:125]
	v_mfma_f32_16x16x32_bf16 v[110:113], v[156:159], v[180:183], v[110:113]
	v_mfma_f32_16x16x32_bf16 v[106:109], v[164:167], v[180:183], v[106:109]
	v_mfma_f32_16x16x32_bf16 v[94:97], v[156:159], v[188:191], v[94:97]
	v_mfma_f32_16x16x32_bf16 v[90:93], v[164:167], v[188:191], v[90:93]
	v_mfma_f32_16x16x32_bf16 v[78:81], v[156:159], v[202:205], v[78:81]
	v_mfma_f32_16x16x32_bf16 v[74:77], v[164:167], v[202:205], v[74:77]
	s_setprio 0
	s_barrier
	s_add_i32 s54, 0, 0x14000
	s_add_i32 s52, s52, s41
	s_mov_b32 m0, s52
	ds_read_b128 v[206:209], v133 offset:16384
	ds_read_b128 v[210:213], v133 offset:17408
	ds_read_b128 v[214:217], v133 offset:18432
	ds_read_b128 v[218:221], v133 offset:19456
	global_load_lds_dwordx4 v132, s[30:31]
	s_add_i32 m0, s52, 0x2000
	s_nop 0
	global_load_lds_dwordx4 v136, s[30:31]
	s_barrier
	s_waitcnt lgkmcnt(0)
	s_setprio 1
	v_mfma_f32_16x16x32_bf16 v[118:121], v[206:209], v[168:171], v[118:121]
	v_mfma_f32_16x16x32_bf16 v[114:117], v[214:217], v[168:171], v[114:117]
	v_mfma_f32_16x16x32_bf16 v[102:105], v[206:209], v[176:179], v[102:105]
	v_mfma_f32_16x16x32_bf16 v[98:101], v[214:217], v[176:179], v[98:101]
	v_mfma_f32_16x16x32_bf16 v[86:89], v[206:209], v[184:187], v[86:89]
	v_mfma_f32_16x16x32_bf16 v[82:85], v[214:217], v[184:187], v[82:85]
	v_mfma_f32_16x16x32_bf16 v[70:73], v[206:209], v[198:201], v[70:73]
	v_mfma_f32_16x16x32_bf16 v[66:69], v[214:217], v[198:201], v[66:69]
	v_mfma_f32_16x16x32_bf16 v[118:121], v[210:213], v[172:175], v[118:121]
	v_mfma_f32_16x16x32_bf16 v[114:117], v[218:221], v[172:175], v[114:117]
	v_mfma_f32_16x16x32_bf16 v[102:105], v[210:213], v[180:183], v[102:105]
	v_mfma_f32_16x16x32_bf16 v[98:101], v[218:221], v[180:183], v[98:101]
	v_mfma_f32_16x16x32_bf16 v[86:89], v[210:213], v[188:191], v[86:89]
	v_mfma_f32_16x16x32_bf16 v[82:85], v[218:221], v[188:191], v[82:85]
	v_mfma_f32_16x16x32_bf16 v[70:73], v[210:213], v[202:205], v[70:73]
	v_mfma_f32_16x16x32_bf16 v[66:69], v[218:221], v[202:205], v[66:69]
	s_setprio 0
	s_mov_b32 m0, s42
	v_lshl_add_u64 v[242:243], s[34:35], 0, v[130:131]
	s_barrier
	ds_read_b128 v[168:171], v155 offset:16384
	ds_read_b128 v[172:175], v155 offset:17408
	ds_read_b128 v[176:179], v155 offset:18432
	ds_read_b128 v[180:183], v155 offset:19456
	ds_read_b128 v[184:187], v155 offset:20480
	ds_read_b128 v[188:191], v155 offset:21504
	ds_read_b128 v[198:201], v155 offset:22528
	ds_read_b128 v[202:205], v155 offset:23552
	global_load_lds_dwordx4 v[242:243], off
	v_lshl_add_u64 v[244:245], s[34:35], 0, v[134:135]
	s_mov_b32 m0, s43
	s_nop 0
	global_load_lds_dwordx4 v[244:245], off
	s_barrier
	s_waitcnt lgkmcnt(0)
	s_setprio 1
	v_mfma_f32_16x16x32_bf16 v[62:65], v[150:153], v[168:171], v[62:65]
	v_mfma_f32_16x16x32_bf16 v[58:61], v[160:163], v[168:171], v[58:61]
	v_mfma_f32_16x16x32_bf16 v[44:47], v[150:153], v[176:179], v[44:47]
	v_mfma_f32_16x16x32_bf16 v[40:43], v[160:163], v[176:179], v[40:43]
	v_mfma_f32_16x16x32_bf16 v[28:31], v[150:153], v[184:187], v[28:31]
	v_mfma_f32_16x16x32_bf16 v[24:27], v[160:163], v[184:187], v[24:27]
	v_mfma_f32_16x16x32_bf16 v[12:15], v[150:153], v[198:201], v[12:15]
	v_mfma_f32_16x16x32_bf16 v[8:11], v[160:163], v[198:201], v[8:11]
	v_mfma_f32_16x16x32_bf16 v[62:65], v[156:159], v[172:175], v[62:65]
	v_mfma_f32_16x16x32_bf16 v[58:61], v[164:167], v[172:175], v[58:61]
	v_mfma_f32_16x16x32_bf16 v[44:47], v[156:159], v[180:183], v[44:47]
	v_mfma_f32_16x16x32_bf16 v[40:43], v[164:167], v[180:183], v[40:43]
	v_mfma_f32_16x16x32_bf16 v[28:31], v[156:159], v[188:191], v[28:31]
	v_mfma_f32_16x16x32_bf16 v[24:27], v[164:167], v[188:191], v[24:27]
	v_mfma_f32_16x16x32_bf16 v[12:15], v[156:159], v[202:205], v[12:15]
	v_mfma_f32_16x16x32_bf16 v[8:11], v[164:167], v[202:205], v[8:11]
	s_setprio 0
	s_barrier
	s_add_u32 s52, s30, 0x40000
	s_addc_u32 s53, s31, 0
	s_add_i32 s54, s54, s41
	s_mov_b32 m0, s54
	s_nop 0
	global_load_lds_dwordx4 v132, s[52:53]
	s_add_i32 m0, s54, 0x2000
	s_nop 0
	global_load_lds_dwordx4 v136, s[52:53]
	s_waitcnt vmcnt(6)
	s_barrier
	s_setprio 1
	v_mfma_f32_16x16x32_bf16 v[54:57], v[206:209], v[168:171], v[54:57]
	v_mfma_f32_16x16x32_bf16 v[50:53], v[214:217], v[168:171], v[50:53]
	v_mfma_f32_16x16x32_bf16 v[36:39], v[206:209], v[176:179], v[36:39]
	v_mfma_f32_16x16x32_bf16 v[32:35], v[214:217], v[176:179], v[32:35]
	v_mfma_f32_16x16x32_bf16 v[20:23], v[206:209], v[184:187], v[20:23]
	v_mfma_f32_16x16x32_bf16 v[16:19], v[214:217], v[184:187], v[16:19]
	v_mfma_f32_16x16x32_bf16 v[4:7], v[206:209], v[198:201], v[4:7]
	v_mfma_f32_16x16x32_bf16 v[0:3], v[214:217], v[198:201], v[0:3]
	v_mfma_f32_16x16x32_bf16 v[54:57], v[210:213], v[172:175], v[54:57]
	v_mfma_f32_16x16x32_bf16 v[50:53], v[218:221], v[172:175], v[50:53]
	v_mfma_f32_16x16x32_bf16 v[36:39], v[210:213], v[180:183], v[36:39]
	v_mfma_f32_16x16x32_bf16 v[32:35], v[218:221], v[180:183], v[32:35]
	v_mfma_f32_16x16x32_bf16 v[20:23], v[210:213], v[188:191], v[20:23]
	v_mfma_f32_16x16x32_bf16 v[16:19], v[218:221], v[188:191], v[16:19]
	v_mfma_f32_16x16x32_bf16 v[4:7], v[210:213], v[202:205], v[4:7]
	v_mfma_f32_16x16x32_bf16 v[0:3], v[218:221], v[202:205], v[0:3]
	s_setprio 0
	s_add_i32 s52, 0, 0x18000
	s_barrier
	ds_read_b128 v[150:153], v133 offset:32768
	ds_read_b128 v[156:159], v133 offset:33792
	ds_read_b128 v[160:163], v133 offset:34816
	ds_read_b128 v[164:167], v133 offset:35840
	s_add_u32 s34, s34, 0x40000
	s_addc_u32 s35, s35, 0
	s_mov_b32 m0, s44
	ds_read_b128 v[168:171], v155 offset:32768
	ds_read_b128 v[172:175], v155 offset:33792
	ds_read_b128 v[176:179], v155 offset:34816
	ds_read_b128 v[180:183], v155 offset:35840
	ds_read_b128 v[184:187], v155 offset:36864
	ds_read_b128 v[188:191], v155 offset:37888
	ds_read_b128 v[198:201], v155 offset:38912
	ds_read_b128 v[202:205], v155 offset:39936
	global_load_lds_dwordx4 v130, s[34:35]
	s_mov_b32 m0, s45
	s_nop 0
	global_load_lds_dwordx4 v134, s[34:35]
	s_waitcnt lgkmcnt(8)
	s_barrier
	s_waitcnt lgkmcnt(0)
	s_setprio 1
	v_mfma_f32_16x16x32_bf16 v[126:129], v[150:153], v[168:171], v[126:129]
	v_mfma_f32_16x16x32_bf16 v[122:125], v[160:163], v[168:171], v[122:125]
	v_mfma_f32_16x16x32_bf16 v[110:113], v[150:153], v[176:179], v[110:113]
	v_mfma_f32_16x16x32_bf16 v[106:109], v[160:163], v[176:179], v[106:109]
	v_mfma_f32_16x16x32_bf16 v[94:97], v[150:153], v[184:187], v[94:97]
	v_mfma_f32_16x16x32_bf16 v[90:93], v[160:163], v[184:187], v[90:93]
	v_mfma_f32_16x16x32_bf16 v[78:81], v[150:153], v[198:201], v[78:81]
	v_mfma_f32_16x16x32_bf16 v[74:77], v[160:163], v[198:201], v[74:77]
	v_mfma_f32_16x16x32_bf16 v[126:129], v[156:159], v[172:175], v[126:129]
	v_mfma_f32_16x16x32_bf16 v[122:125], v[164:167], v[172:175], v[122:125]
	v_mfma_f32_16x16x32_bf16 v[110:113], v[156:159], v[180:183], v[110:113]
	v_mfma_f32_16x16x32_bf16 v[106:109], v[164:167], v[180:183], v[106:109]
	v_mfma_f32_16x16x32_bf16 v[94:97], v[156:159], v[188:191], v[94:97]
	v_mfma_f32_16x16x32_bf16 v[90:93], v[164:167], v[188:191], v[90:93]
	v_mfma_f32_16x16x32_bf16 v[78:81], v[156:159], v[202:205], v[78:81]
	v_mfma_f32_16x16x32_bf16 v[74:77], v[164:167], v[202:205], v[74:77]
	s_setprio 0
	s_barrier
	s_add_i32 s34, 0, 0x1c000
	s_add_i32 s35, s52, s41
	s_add_u32 s52, s30, s66
	s_addc_u32 s53, s31, s67
	s_mov_b32 m0, s35
	ds_read_b128 v[206:209], v133 offset:49152
	ds_read_b128 v[210:213], v133 offset:50176
	ds_read_b128 v[214:217], v133 offset:51200
	ds_read_b128 v[218:221], v133 offset:52224
	global_load_lds_dwordx4 v132, s[52:53]
	s_add_i32 m0, s35, 0x2000
	s_nop 0
	global_load_lds_dwordx4 v136, s[52:53]
	s_barrier
	s_waitcnt lgkmcnt(0)
	s_setprio 1
	v_mfma_f32_16x16x32_bf16 v[118:121], v[206:209], v[168:171], v[118:121]
	v_mfma_f32_16x16x32_bf16 v[114:117], v[214:217], v[168:171], v[114:117]
	v_mfma_f32_16x16x32_bf16 v[102:105], v[206:209], v[176:179], v[102:105]
	v_mfma_f32_16x16x32_bf16 v[98:101], v[214:217], v[176:179], v[98:101]
	v_mfma_f32_16x16x32_bf16 v[86:89], v[206:209], v[184:187], v[86:89]
	v_mfma_f32_16x16x32_bf16 v[82:85], v[214:217], v[184:187], v[82:85]
	v_mfma_f32_16x16x32_bf16 v[70:73], v[206:209], v[198:201], v[70:73]
	v_mfma_f32_16x16x32_bf16 v[66:69], v[214:217], v[198:201], v[66:69]
	v_mfma_f32_16x16x32_bf16 v[118:121], v[210:213], v[172:175], v[118:121]
	v_mfma_f32_16x16x32_bf16 v[114:117], v[218:221], v[172:175], v[114:117]
	v_mfma_f32_16x16x32_bf16 v[102:105], v[210:213], v[180:183], v[102:105]
	v_mfma_f32_16x16x32_bf16 v[98:101], v[218:221], v[180:183], v[98:101]
	v_mfma_f32_16x16x32_bf16 v[86:89], v[210:213], v[188:191], v[86:89]
	v_mfma_f32_16x16x32_bf16 v[82:85], v[218:221], v[188:191], v[82:85]
	v_mfma_f32_16x16x32_bf16 v[70:73], v[210:213], v[202:205], v[70:73]
	v_mfma_f32_16x16x32_bf16 v[66:69], v[218:221], v[202:205], v[66:69]
	s_setprio 0
	s_mov_b32 m0, s46
	v_lshl_add_u64 v[192:193], v[242:243], 0, s[66:67]
	s_barrier
	ds_read_b128 v[168:171], v155 offset:49152
	ds_read_b128 v[172:175], v155 offset:50176
	ds_read_b128 v[176:179], v155 offset:51200
	ds_read_b128 v[180:183], v155 offset:52224
	ds_read_b128 v[184:187], v155 offset:53248
	ds_read_b128 v[188:191], v155 offset:54272
	ds_read_b128 v[198:201], v155 offset:55296
	ds_read_b128 v[202:205], v155 offset:56320
	global_load_lds_dwordx4 v[192:193], off
	v_lshl_add_u64 v[192:193], v[244:245], 0, s[66:67]
	s_mov_b32 m0, s47
	s_nop 0
	global_load_lds_dwordx4 v[192:193], off
	s_barrier
	s_waitcnt lgkmcnt(0)
	s_setprio 1
	v_mfma_f32_16x16x32_bf16 v[62:65], v[150:153], v[168:171], v[62:65]
	v_mfma_f32_16x16x32_bf16 v[58:61], v[160:163], v[168:171], v[58:61]
	v_mfma_f32_16x16x32_bf16 v[44:47], v[150:153], v[176:179], v[44:47]
	v_mfma_f32_16x16x32_bf16 v[40:43], v[160:163], v[176:179], v[40:43]
	v_mfma_f32_16x16x32_bf16 v[28:31], v[150:153], v[184:187], v[28:31]
	v_mfma_f32_16x16x32_bf16 v[24:27], v[160:163], v[184:187], v[24:27]
	v_mfma_f32_16x16x32_bf16 v[12:15], v[150:153], v[198:201], v[12:15]
	v_mfma_f32_16x16x32_bf16 v[8:11], v[160:163], v[198:201], v[8:11]
	v_mfma_f32_16x16x32_bf16 v[62:65], v[156:159], v[172:175], v[62:65]
	v_mfma_f32_16x16x32_bf16 v[58:61], v[164:167], v[172:175], v[58:61]
	v_mfma_f32_16x16x32_bf16 v[44:47], v[156:159], v[180:183], v[44:47]
	v_mfma_f32_16x16x32_bf16 v[40:43], v[164:167], v[180:183], v[40:43]
	v_mfma_f32_16x16x32_bf16 v[28:31], v[156:159], v[188:191], v[28:31]
	v_mfma_f32_16x16x32_bf16 v[24:27], v[164:167], v[188:191], v[24:27]
	v_mfma_f32_16x16x32_bf16 v[12:15], v[156:159], v[202:205], v[12:15]
	v_mfma_f32_16x16x32_bf16 v[8:11], v[164:167], v[202:205], v[8:11]
	s_setprio 0
	s_barrier
	s_add_u32 s30, s30, 0x40080
	s_addc_u32 s31, s31, 0
	s_add_i32 s34, s34, s41
	s_mov_b32 m0, s34
	s_nop 0
	global_load_lds_dwordx4 v132, s[30:31]
	s_add_i32 m0, s34, 0x2000
	s_nop 0
	global_load_lds_dwordx4 v136, s[30:31]
	s_waitcnt vmcnt(6)
	s_barrier
	s_setprio 1
	v_mfma_f32_16x16x32_bf16 v[54:57], v[206:209], v[168:171], v[54:57]
	v_mfma_f32_16x16x32_bf16 v[50:53], v[214:217], v[168:171], v[50:53]
	v_mfma_f32_16x16x32_bf16 v[36:39], v[206:209], v[176:179], v[36:39]
	v_mfma_f32_16x16x32_bf16 v[32:35], v[214:217], v[176:179], v[32:35]
	v_mfma_f32_16x16x32_bf16 v[20:23], v[206:209], v[184:187], v[20:23]
	v_mfma_f32_16x16x32_bf16 v[16:19], v[214:217], v[184:187], v[16:19]
	v_mfma_f32_16x16x32_bf16 v[4:7], v[206:209], v[198:201], v[4:7]
	v_mfma_f32_16x16x32_bf16 v[0:3], v[214:217], v[198:201], v[0:3]
	v_mfma_f32_16x16x32_bf16 v[54:57], v[210:213], v[172:175], v[54:57]
	v_mfma_f32_16x16x32_bf16 v[50:53], v[218:221], v[172:175], v[50:53]
	v_mfma_f32_16x16x32_bf16 v[36:39], v[210:213], v[180:183], v[36:39]
	v_mfma_f32_16x16x32_bf16 v[32:35], v[218:221], v[180:183], v[32:35]
	v_mfma_f32_16x16x32_bf16 v[20:23], v[210:213], v[188:191], v[20:23]
	v_mfma_f32_16x16x32_bf16 v[16:19], v[218:221], v[188:191], v[16:19]
	v_mfma_f32_16x16x32_bf16 v[4:7], v[210:213], v[202:205], v[4:7]
	v_mfma_f32_16x16x32_bf16 v[0:3], v[218:221], v[202:205], v[0:3]
	s_setprio 0
	s_add_i32 s51, s51, 2
	s_add_u32 s4, s4, 0x100
	s_addc_u32 s5, s5, 0
	s_add_u32 s23, s23, 0x100
	s_addc_u32 s25, s25, 0
	s_cmp_gt_u32 s51, 13
	s_barrier
	s_cbranch_scc0 .LBB0_305
	v_lshl_add_u32 v156, s50, 8, v139
	v_ashrrev_i32_e32 v48, 31, v156
	v_alignbit_b32 v150, v48, v156, 6
	v_mad_u64_u32 v[150:151], s[4:5], v150, s71, 0
	v_mad_i32_i24 v151, v48, s71, v151
	v_lshlrev_b32_e32 v48, 3, v156
	s_cmp_lg_u32 s49, 0
	v_and_b32_e32 v48, 0x78, v48
	s_cselect_b64 s[30:31], -1, 0
	s_and_b64 vcc, exec, s[30:31]
	v_lshl_add_u32 v157, s49, 8, v145
	v_lshlrev_b32_e32 v48, 1, v48
	s_cbranch_vccz .LBB0_314
	v_ashrrev_i32_e32 v152, 3, v157
	v_ashrrev_i32_e32 v153, 31, v152
	v_lshl_add_u64 v[152:153], v[150:151], 0, v[152:153]
	v_lshlrev_b64 v[152:153], 10, v[152:153]
	v_lshl_add_u64 v[152:153], s[18:19], 0, v[152:153]
	v_lshl_add_u64 v[152:153], v[152:153], 0, v[48:49]
	v_ashrrev_i32_e32 v159, 5, v156
	v_add_u32_e32 v158, v159, v140
	s_cbranch_execnz .LBB0_309

.LBB0_641:
	s_add_u32 s24, s22, 0x100
	s_addc_u32 s25, s23, 0
	s_add_i32 s50, 0, 0x10000
	ds_read_b128 v[146:149], v131
	ds_read_b128 v[150:153], v131 offset:1024
	ds_read_b128 v[154:157], v131 offset:2048
	ds_read_b128 v[158:161], v131 offset:3072
	s_cmp_eq_u32 s49, 4
	s_cselect_b32 s29, s19, s25
	s_cselect_b32 s28, s18, s24
	s_cselect_b32 s27, s21, s48
	s_cselect_b32 s26, s20, s5
	v_lshl_add_u64 v[198:199], s[22:23], 0, v[138:139]
	s_add_i32 m0, s38, 0xc000
	ds_read_b128 v[162:165], v144
	ds_read_b128 v[166:169], v144 offset:1024
	ds_read_b128 v[170:173], v144 offset:2048
	ds_read_b128 v[174:177], v144 offset:3072
	ds_read_b128 v[178:181], v144 offset:4096
	ds_read_b128 v[182:185], v144 offset:5120
	ds_read_b128 v[186:189], v144 offset:6144
	ds_read_b128 v[190:193], v144 offset:7168
	global_load_lds_dwordx4 v[198:199], off
	v_lshl_add_u64 v[198:199], s[22:23], 0, v[140:141]
	s_add_i32 m0, s38, 0xe000
	s_nop 0
	global_load_lds_dwordx4 v[198:199], off
	s_waitcnt lgkmcnt(8)
	s_barrier
	s_waitcnt lgkmcnt(0)
	s_setprio 1
	v_mfma_f32_16x16x32_bf16 v[126:129], v[146:149], v[162:165], v[126:129]
	v_mfma_f32_16x16x32_bf16 v[122:125], v[154:157], v[162:165], v[122:125]
	v_mfma_f32_16x16x32_bf16 v[118:121], v[146:149], v[170:173], v[118:121]
	v_mfma_f32_16x16x32_bf16 v[114:117], v[154:157], v[170:173], v[114:117]
	v_mfma_f32_16x16x32_bf16 v[106:109], v[146:149], v[178:181], v[106:109]
	v_mfma_f32_16x16x32_bf16 v[98:101], v[154:157], v[178:181], v[98:101]
	v_mfma_f32_16x16x32_bf16 v[90:93], v[146:149], v[186:189], v[90:93]
	v_mfma_f32_16x16x32_bf16 v[82:85], v[154:157], v[186:189], v[82:85]
	v_mfma_f32_16x16x32_bf16 v[126:129], v[150:153], v[166:169], v[126:129]
	v_mfma_f32_16x16x32_bf16 v[122:125], v[158:161], v[166:169], v[122:125]
	v_mfma_f32_16x16x32_bf16 v[118:121], v[150:153], v[174:177], v[118:121]
	v_mfma_f32_16x16x32_bf16 v[114:117], v[158:161], v[174:177], v[114:117]
	v_mfma_f32_16x16x32_bf16 v[106:109], v[150:153], v[182:185], v[106:109]
	v_mfma_f32_16x16x32_bf16 v[98:101], v[158:161], v[182:185], v[98:101]
	v_mfma_f32_16x16x32_bf16 v[90:93], v[150:153], v[190:193], v[90:93]
	v_mfma_f32_16x16x32_bf16 v[82:85], v[158:161], v[190:193], v[82:85]
	s_setprio 0
	s_barrier
	s_add_i32 s51, 0, 0x14000
	s_add_i32 s22, s50, s37
	s_mov_b32 m0, s22
	ds_read_b128 v[198:201], v131 offset:16384
	ds_read_b128 v[202:205], v131 offset:17408
	ds_read_b128 v[206:209], v131 offset:18432
	ds_read_b128 v[210:213], v131 offset:19456
	global_load_lds_dwordx4 v48, s[26:27]
	s_add_i32 m0, s22, 0x2000
	s_nop 0
	global_load_lds_dwordx4 v130, s[26:27]
	s_barrier
	s_waitcnt lgkmcnt(0)
	s_setprio 1
	v_mfma_f32_16x16x32_bf16 v[110:113], v[198:201], v[162:165], v[110:113]
	v_mfma_f32_16x16x32_bf16 v[102:105], v[206:209], v[162:165], v[102:105]
	v_mfma_f32_16x16x32_bf16 v[94:97], v[198:201], v[170:173], v[94:97]
	v_mfma_f32_16x16x32_bf16 v[86:89], v[206:209], v[170:173], v[86:89]
	v_mfma_f32_16x16x32_bf16 v[78:81], v[198:201], v[178:181], v[78:81]
	v_mfma_f32_16x16x32_bf16 v[74:77], v[206:209], v[178:181], v[74:77]
	v_mfma_f32_16x16x32_bf16 v[70:73], v[198:201], v[186:189], v[70:73]
	v_mfma_f32_16x16x32_bf16 v[66:69], v[206:209], v[186:189], v[66:69]
	v_mfma_f32_16x16x32_bf16 v[110:113], v[202:205], v[166:169], v[110:113]
	v_mfma_f32_16x16x32_bf16 v[102:105], v[210:213], v[166:169], v[102:105]
	v_mfma_f32_16x16x32_bf16 v[94:97], v[202:205], v[174:177], v[94:97]
	v_mfma_f32_16x16x32_bf16 v[86:89], v[210:213], v[174:177], v[86:89]
	v_mfma_f32_16x16x32_bf16 v[78:81], v[202:205], v[182:185], v[78:81]
	v_mfma_f32_16x16x32_bf16 v[74:77], v[210:213], v[182:185], v[74:77]
	v_mfma_f32_16x16x32_bf16 v[70:73], v[202:205], v[190:193], v[70:73]
	v_mfma_f32_16x16x32_bf16 v[66:69], v[210:213], v[190:193], v[66:69]
	s_setprio 0
	s_mov_b32 m0, s38
	v_lshl_add_u64 v[218:219], s[28:29], 0, v[134:135]
	s_barrier
	ds_read_b128 v[162:165], v144 offset:16384
	ds_read_b128 v[166:169], v144 offset:17408
	ds_read_b128 v[170:173], v144 offset:18432
	ds_read_b128 v[174:177], v144 offset:19456
	ds_read_b128 v[178:181], v144 offset:20480
	ds_read_b128 v[182:185], v144 offset:21504
	ds_read_b128 v[186:189], v144 offset:22528
	ds_read_b128 v[190:193], v144 offset:23552
	global_load_lds_dwordx4 v[218:219], off
	v_lshl_add_u64 v[220:221], s[28:29], 0, v[132:133]
	s_mov_b32 m0, s39
	s_nop 0
	global_load_lds_dwordx4 v[220:221], off
	s_barrier
	s_waitcnt lgkmcnt(0)
	s_setprio 1
	v_mfma_f32_16x16x32_bf16 v[62:65], v[146:149], v[162:165], v[62:65]
	v_mfma_f32_16x16x32_bf16 v[58:61], v[154:157], v[162:165], v[58:61]
	v_mfma_f32_16x16x32_bf16 v[54:57], v[146:149], v[170:173], v[54:57]
	v_mfma_f32_16x16x32_bf16 v[50:53], v[154:157], v[170:173], v[50:53]
	v_mfma_f32_16x16x32_bf16 v[36:39], v[146:149], v[178:181], v[36:39]
	v_mfma_f32_16x16x32_bf16 v[32:35], v[154:157], v[178:181], v[32:35]
	v_mfma_f32_16x16x32_bf16 v[20:23], v[146:149], v[186:189], v[20:23]
	v_mfma_f32_16x16x32_bf16 v[16:19], v[154:157], v[186:189], v[16:19]
	v_mfma_f32_16x16x32_bf16 v[62:65], v[150:153], v[166:169], v[62:65]
	v_mfma_f32_16x16x32_bf16 v[58:61], v[158:161], v[166:169], v[58:61]
	v_mfma_f32_16x16x32_bf16 v[54:57], v[150:153], v[174:177], v[54:57]
	v_mfma_f32_16x16x32_bf16 v[50:53], v[158:161], v[174:177], v[50:53]
	v_mfma_f32_16x16x32_bf16 v[36:39], v[150:153], v[182:185], v[36:39]
	v_mfma_f32_16x16x32_bf16 v[32:35], v[158:161], v[182:185], v[32:35]
	v_mfma_f32_16x16x32_bf16 v[20:23], v[150:153], v[190:193], v[20:23]
	v_mfma_f32_16x16x32_bf16 v[16:19], v[158:161], v[190:193], v[16:19]
	s_setprio 0
	s_barrier
	s_add_u32 s22, s26, 0x20000
	s_addc_u32 s23, s27, 0
	s_add_i32 s50, s51, s37
	s_mov_b32 m0, s50
	s_nop 0
	global_load_lds_dwordx4 v48, s[22:23]
	s_add_i32 m0, s50, 0x2000
	s_nop 0
	global_load_lds_dwordx4 v130, s[22:23]
	s_waitcnt vmcnt(6)
	s_barrier
	s_setprio 1
	v_mfma_f32_16x16x32_bf16 v[44:47], v[198:201], v[162:165], v[44:47]
	v_mfma_f32_16x16x32_bf16 v[40:43], v[206:209], v[162:165], v[40:43]
	v_mfma_f32_16x16x32_bf16 v[28:31], v[198:201], v[170:173], v[28:31]
	v_mfma_f32_16x16x32_bf16 v[24:27], v[206:209], v[170:173], v[24:27]
	v_mfma_f32_16x16x32_bf16 v[12:15], v[198:201], v[178:181], v[12:15]
	v_mfma_f32_16x16x32_bf16 v[8:11], v[206:209], v[178:181], v[8:11]
	v_mfma_f32_16x16x32_bf16 v[4:7], v[198:201], v[186:189], v[4:7]
	v_mfma_f32_16x16x32_bf16 v[0:3], v[206:209], v[186:189], v[0:3]
	v_mfma_f32_16x16x32_bf16 v[44:47], v[202:205], v[166:169], v[44:47]
	v_mfma_f32_16x16x32_bf16 v[40:43], v[210:213], v[166:169], v[40:43]
	v_mfma_f32_16x16x32_bf16 v[28:31], v[202:205], v[174:177], v[28:31]
	v_mfma_f32_16x16x32_bf16 v[24:27], v[210:213], v[174:177], v[24:27]
	v_mfma_f32_16x16x32_bf16 v[12:15], v[202:205], v[182:185], v[12:15]
	v_mfma_f32_16x16x32_bf16 v[8:11], v[210:213], v[182:185], v[8:11]
	v_mfma_f32_16x16x32_bf16 v[4:7], v[202:205], v[190:193], v[4:7]
	v_mfma_f32_16x16x32_bf16 v[0:3], v[210:213], v[190:193], v[0:3]
	s_setprio 0
	s_add_i32 s50, 0, 0x18000
	s_barrier
	ds_read_b128 v[146:149], v131 offset:32768
	ds_read_b128 v[150:153], v131 offset:33792
	ds_read_b128 v[154:157], v131 offset:34816
	ds_read_b128 v[158:161], v131 offset:35840
	s_add_u32 s22, s28, 0x30000
	s_addc_u32 s23, s29, 0
	s_mov_b32 m0, s40
	ds_read_b128 v[162:165], v144 offset:32768
	ds_read_b128 v[166:169], v144 offset:33792
	ds_read_b128 v[170:173], v144 offset:34816
	ds_read_b128 v[174:177], v144 offset:35840
	ds_read_b128 v[178:181], v144 offset:36864
	ds_read_b128 v[182:185], v144 offset:37888
	ds_read_b128 v[186:189], v144 offset:38912
	ds_read_b128 v[190:193], v144 offset:39936
	global_load_lds_dwordx4 v134, s[22:23]
	s_mov_b32 m0, s41
	s_nop 0
	global_load_lds_dwordx4 v132, s[22:23]
	s_waitcnt lgkmcnt(8)
	s_barrier
	s_waitcnt lgkmcnt(0)
	s_setprio 1
	v_mfma_f32_16x16x32_bf16 v[126:129], v[146:149], v[162:165], v[126:129]
	v_mfma_f32_16x16x32_bf16 v[122:125], v[154:157], v[162:165], v[122:125]
	v_mfma_f32_16x16x32_bf16 v[118:121], v[146:149], v[170:173], v[118:121]
	v_mfma_f32_16x16x32_bf16 v[114:117], v[154:157], v[170:173], v[114:117]
	v_mfma_f32_16x16x32_bf16 v[106:109], v[146:149], v[178:181], v[106:109]
	v_mfma_f32_16x16x32_bf16 v[98:101], v[154:157], v[178:181], v[98:101]
	v_mfma_f32_16x16x32_bf16 v[90:93], v[146:149], v[186:189], v[90:93]
	v_mfma_f32_16x16x32_bf16 v[82:85], v[154:157], v[186:189], v[82:85]
	v_mfma_f32_16x16x32_bf16 v[126:129], v[150:153], v[166:169], v[126:129]
	v_mfma_f32_16x16x32_bf16 v[122:125], v[158:161], v[166:169], v[122:125]
	v_mfma_f32_16x16x32_bf16 v[118:121], v[150:153], v[174:177], v[118:121]
	v_mfma_f32_16x16x32_bf16 v[114:117], v[158:161], v[174:177], v[114:117]
	v_mfma_f32_16x16x32_bf16 v[106:109], v[150:153], v[182:185], v[106:109]
	v_mfma_f32_16x16x32_bf16 v[98:101], v[158:161], v[182:185], v[98:101]
	v_mfma_f32_16x16x32_bf16 v[90:93], v[150:153], v[190:193], v[90:93]
	v_mfma_f32_16x16x32_bf16 v[82:85], v[158:161], v[190:193], v[82:85]
	s_setprio 0
	s_barrier
	s_add_i32 s28, 0, 0x1c000
	s_add_i32 s22, s50, s37
	s_add_u32 s52, s26, s66
	s_addc_u32 s53, s27, s67
	s_mov_b32 m0, s22
	ds_read_b128 v[198:201], v131 offset:49152
	ds_read_b128 v[202:205], v131 offset:50176
	ds_read_b128 v[206:209], v131 offset:51200
	ds_read_b128 v[210:213], v131 offset:52224
	global_load_lds_dwordx4 v48, s[52:53]
	s_add_i32 m0, s22, 0x2000
	s_nop 0
	global_load_lds_dwordx4 v130, s[52:53]
	s_barrier
	s_waitcnt lgkmcnt(0)
	s_setprio 1
	v_mfma_f32_16x16x32_bf16 v[110:113], v[198:201], v[162:165], v[110:113]
	v_mfma_f32_16x16x32_bf16 v[102:105], v[206:209], v[162:165], v[102:105]
	v_mfma_f32_16x16x32_bf16 v[94:97], v[198:201], v[170:173], v[94:97]
	v_mfma_f32_16x16x32_bf16 v[86:89], v[206:209], v[170:173], v[86:89]
	v_mfma_f32_16x16x32_bf16 v[78:81], v[198:201], v[178:181], v[78:81]
	v_mfma_f32_16x16x32_bf16 v[74:77], v[206:209], v[178:181], v[74:77]
	v_mfma_f32_16x16x32_bf16 v[70:73], v[198:201], v[186:189], v[70:73]
	v_mfma_f32_16x16x32_bf16 v[66:69], v[206:209], v[186:189], v[66:69]
	v_mfma_f32_16x16x32_bf16 v[110:113], v[202:205], v[166:169], v[110:113]
	v_mfma_f32_16x16x32_bf16 v[102:105], v[210:213], v[166:169], v[102:105]
	v_mfma_f32_16x16x32_bf16 v[94:97], v[202:205], v[174:177], v[94:97]
	v_mfma_f32_16x16x32_bf16 v[86:89], v[210:213], v[174:177], v[86:89]
	v_mfma_f32_16x16x32_bf16 v[78:81], v[202:205], v[182:185], v[78:81]
	v_mfma_f32_16x16x32_bf16 v[74:77], v[210:213], v[182:185], v[74:77]
	v_mfma_f32_16x16x32_bf16 v[70:73], v[202:205], v[190:193], v[70:73]
	v_mfma_f32_16x16x32_bf16 v[66:69], v[210:213], v[190:193], v[66:69]
	s_setprio 0
	s_mov_b32 m0, s42
	v_lshl_add_u64 v[214:215], v[218:219], 0, s[66:67]
	s_barrier
	ds_read_b128 v[162:165], v144 offset:49152
	ds_read_b128 v[166:169], v144 offset:50176
	ds_read_b128 v[170:173], v144 offset:51200
	ds_read_b128 v[174:177], v144 offset:52224
	ds_read_b128 v[178:181], v144 offset:53248
	ds_read_b128 v[182:185], v144 offset:54272
	ds_read_b128 v[186:189], v144 offset:55296
	ds_read_b128 v[190:193], v144 offset:56320
	global_load_lds_dwordx4 v[214:215], off
	v_lshl_add_u64 v[214:215], v[220:221], 0, s[66:67]
	s_mov_b32 m0, s43
	s_nop 0
	global_load_lds_dwordx4 v[214:215], off
	s_barrier
	s_waitcnt lgkmcnt(0)
	s_setprio 1
	v_mfma_f32_16x16x32_bf16 v[62:65], v[146:149], v[162:165], v[62:65]
	v_mfma_f32_16x16x32_bf16 v[58:61], v[154:157], v[162:165], v[58:61]
	v_mfma_f32_16x16x32_bf16 v[54:57], v[146:149], v[170:173], v[54:57]
	v_mfma_f32_16x16x32_bf16 v[50:53], v[154:157], v[170:173], v[50:53]
	v_mfma_f32_16x16x32_bf16 v[36:39], v[146:149], v[178:181], v[36:39]
	v_mfma_f32_16x16x32_bf16 v[32:35], v[154:157], v[178:181], v[32:35]
	v_mfma_f32_16x16x32_bf16 v[20:23], v[146:149], v[186:189], v[20:23]
	v_mfma_f32_16x16x32_bf16 v[16:19], v[154:157], v[186:189], v[16:19]
	v_mfma_f32_16x16x32_bf16 v[62:65], v[150:153], v[166:169], v[62:65]
	v_mfma_f32_16x16x32_bf16 v[58:61], v[158:161], v[166:169], v[58:61]
	v_mfma_f32_16x16x32_bf16 v[54:57], v[150:153], v[174:177], v[54:57]
	v_mfma_f32_16x16x32_bf16 v[50:53], v[158:161], v[174:177], v[50:53]
	v_mfma_f32_16x16x32_bf16 v[36:39], v[150:153], v[182:185], v[36:39]
	v_mfma_f32_16x16x32_bf16 v[32:35], v[158:161], v[182:185], v[32:35]
	v_mfma_f32_16x16x32_bf16 v[20:23], v[150:153], v[190:193], v[20:23]
	v_mfma_f32_16x16x32_bf16 v[16:19], v[158:161], v[190:193], v[16:19]
	s_setprio 0
	s_barrier
	s_add_u32 s22, s26, 0x20080
	s_addc_u32 s23, s27, 0
	s_add_i32 s26, s28, s37
	s_mov_b32 m0, s26
	s_nop 0
	global_load_lds_dwordx4 v48, s[22:23]
	s_add_i32 m0, s26, 0x2000
	s_nop 0
	global_load_lds_dwordx4 v130, s[22:23]
	s_waitcnt vmcnt(6)
	s_barrier
	s_setprio 1
	v_mfma_f32_16x16x32_bf16 v[44:47], v[198:201], v[162:165], v[44:47]
	v_mfma_f32_16x16x32_bf16 v[40:43], v[206:209], v[162:165], v[40:43]
	v_mfma_f32_16x16x32_bf16 v[28:31], v[198:201], v[170:173], v[28:31]
	v_mfma_f32_16x16x32_bf16 v[24:27], v[206:209], v[170:173], v[24:27]
	v_mfma_f32_16x16x32_bf16 v[12:15], v[198:201], v[178:181], v[12:15]
	v_mfma_f32_16x16x32_bf16 v[8:11], v[206:209], v[178:181], v[8:11]
	v_mfma_f32_16x16x32_bf16 v[4:7], v[198:201], v[186:189], v[4:7]
	v_mfma_f32_16x16x32_bf16 v[0:3], v[206:209], v[186:189], v[0:3]
	v_mfma_f32_16x16x32_bf16 v[44:47], v[202:205], v[166:169], v[44:47]
	v_mfma_f32_16x16x32_bf16 v[40:43], v[210:213], v[166:169], v[40:43]
	v_mfma_f32_16x16x32_bf16 v[28:31], v[202:205], v[174:177], v[28:31]
	v_mfma_f32_16x16x32_bf16 v[24:27], v[210:213], v[174:177], v[24:27]
	v_mfma_f32_16x16x32_bf16 v[12:15], v[202:205], v[182:185], v[12:15]
	v_mfma_f32_16x16x32_bf16 v[8:11], v[210:213], v[182:185], v[8:11]
	v_mfma_f32_16x16x32_bf16 v[4:7], v[202:205], v[190:193], v[4:7]
	v_mfma_f32_16x16x32_bf16 v[0:3], v[210:213], v[190:193], v[0:3]
	s_setprio 0
	s_add_i32 s49, s49, 2
	s_add_u32 s5, s5, 0x100
	s_addc_u32 s48, s48, 0
	s_cmp_gt_u32 s49, 5
	s_mov_b64 s[22:23], s[24:25]
	s_barrier
	s_cbranch_scc0 .LBB0_641
	v_lshl_add_u32 v146, s47, 8, v142
	v_mov_b32_e32 v145, 0x240000
	v_ashrrev_i32_e32 v147, 31, v146
	v_mad_i64_i32 v[148:149], s[22:23], s46, v145, v[136:137]
	v_lshlrev_b64 v[150:151], 10, v[146:147]
	v_lshl_add_u64 v[150:151], v[148:149], 0, v[150:151]
	global_store_dwordx4 v[150:151], v[126:129], off
	global_store_dwordx4 v[150:151], v[122:125], off offset:64
	global_store_dwordx4 v[150:151], v[110:113], off offset:512
	global_store_dwordx4 v[150:151], v[102:105], off offset:576
	s_mov_b32 s5, 0x20000
	s_mov_b64 s[22:23], 0x20000
	v_or_b32_e32 v102, 16, v146
	v_ashrrev_i32_e32 v103, 31, v102
	v_lshlrev_b64 v[102:103], 10, v[102:103]
	v_lshl_add_u64 v[102:103], v[148:149], 0, v[102:103]
	global_store_dwordx4 v[102:103], v[118:121], off
	global_store_dwordx4 v[102:103], v[114:117], off offset:64
	global_store_dwordx4 v[102:103], v[94:97], off offset:512
	global_store_dwordx4 v[102:103], v[86:89], off offset:576
	s_mov_b32 s46, s4
	s_mov_b32 s47, s45
	v_or_b32_e32 v86, 32, v146
	v_ashrrev_i32_e32 v87, 31, v86
	v_lshlrev_b64 v[86:87], 10, v[86:87]
	v_lshl_add_u64 v[86:87], v[148:149], 0, v[86:87]
	global_store_dwordx4 v[86:87], v[106:109], off
	global_store_dwordx4 v[86:87], v[98:101], off offset:64
	global_store_dwordx4 v[86:87], v[78:81], off offset:512
	global_store_dwordx4 v[86:87], v[74:77], off offset:576
	s_mov_b64 s[24:25], s[20:21]
	s_nop 0
	v_or_b32_e32 v74, 48, v146
	v_ashrrev_i32_e32 v75, 31, v74
	v_lshlrev_b64 v[74:75], 10, v[74:75]
	v_lshl_add_u64 v[74:75], v[148:149], 0, v[74:75]
	global_store_dwordx4 v[74:75], v[90:93], off
	global_store_dwordx4 v[74:75], v[82:85], off offset:64
	global_store_dwordx4 v[74:75], v[70:73], off offset:512
	global_store_dwordx4 v[74:75], v[66:69], off offset:576
	s_nop 1
	v_add_co_u32_e32 v68, vcc, s5, v150
	s_mov_b32 s5, 0x24000
	s_nop 0
	v_addc_co_u32_e32 v69, vcc, 0, v151, vcc
	v_lshl_add_u64 v[66:67], v[150:151], 0, s[22:23]
	global_store_dwordx4 v[68:69], v[62:65], off
	global_store_dwordx4 v[66:67], v[58:61], off offset:64
	global_store_dwordx4 v[66:67], v[44:47], off offset:512
	global_store_dwordx4 v[66:67], v[40:43], off offset:576
	s_mov_b64 s[22:23], 0x24000
	s_nop 0
	v_add_co_u32_e32 v42, vcc, s5, v150
	s_mov_b32 s5, 0x28000
	s_nop 0
	v_addc_co_u32_e32 v43, vcc, 0, v151, vcc
	v_lshl_add_u64 v[40:41], v[150:151], 0, s[22:23]
	global_store_dwordx4 v[42:43], v[54:57], off
	global_store_dwordx4 v[40:41], v[50:53], off offset:64
	global_store_dwordx4 v[40:41], v[28:31], off offset:512
	global_store_dwordx4 v[40:41], v[24:27], off offset:576
	s_mov_b64 s[22:23], 0x28000
	s_nop 0
	v_add_co_u32_e32 v26, vcc, s5, v150
	v_lshl_add_u64 v[24:25], v[150:151], 0, s[22:23]
	s_nop 0
	v_addc_co_u32_e32 v27, vcc, 0, v151, vcc
	global_store_dwordx4 v[26:27], v[36:39], off
	global_store_dwordx4 v[24:25], v[32:35], off offset:64
	global_store_dwordx4 v[24:25], v[12:15], off offset:512
	global_store_dwordx4 v[24:25], v[8:11], off offset:576
	s_mov_b64 s[22:23], 0x2c000
	s_nop 0
	v_add_co_u32_e32 v10, vcc, 0x2c000, v150
	v_lshl_add_u64 v[8:9], v[150:151], 0, s[22:23]
	s_nop 0
	v_addc_co_u32_e32 v11, vcc, 0, v151, vcc
	s_and_b64 vcc, exec, s[0:1]
	s_mov_b64 s[22:23], s[18:19]
	global_store_dwordx4 v[10:11], v[20:23], off
	global_store_dwordx4 v[8:9], v[16:19], off offset:64
	global_store_dwordx4 v[8:9], v[4:7], off offset:512
	global_store_dwordx4 v[8:9], v[0:3], off offset:576
	s_cbranch_vccz .LBB0_638
	s_waitcnt vmcnt(0)
	s_cmpk_gt_u32 s30, 0xff
	s_cbranch_scc1 .LBB0_645
	s_barrier

.LBB0_822:
	s_add_u32 s12, s10, 0x100
	s_addc_u32 s13, s11, 0
	s_add_i32 s42, 0, 0x10000
	ds_read_b128 v[142:145], v131
	ds_read_b128 v[150:153], v131 offset:1024
	ds_read_b128 v[154:157], v131 offset:2048
	ds_read_b128 v[158:161], v131 offset:3072
	s_cmp_eq_u32 s41, 8
	s_cselect_b32 s17, s5, s13
	s_cselect_b32 s16, s4, s12
	s_cselect_b32 s15, s7, s40
	s_cselect_b32 s14, s6, s39
	v_lshl_add_u64 v[198:199], s[10:11], 0, v[138:139]
	s_add_i32 m0, s24, 0xc000
	ds_read_b128 v[162:165], v149
	ds_read_b128 v[166:169], v149 offset:1024
	ds_read_b128 v[170:173], v149 offset:2048
	ds_read_b128 v[174:177], v149 offset:3072
	ds_read_b128 v[178:181], v149 offset:4096
	ds_read_b128 v[182:185], v149 offset:5120
	ds_read_b128 v[186:189], v149 offset:6144
	ds_read_b128 v[190:193], v149 offset:7168
	global_load_lds_dwordx4 v[198:199], off
	v_lshl_add_u64 v[198:199], s[10:11], 0, v[140:141]
	s_add_i32 m0, s24, 0xe000
	s_nop 0
	global_load_lds_dwordx4 v[198:199], off
	s_waitcnt lgkmcnt(8)
	s_barrier
	s_waitcnt lgkmcnt(0)
	s_setprio 1
	v_mfma_f32_16x16x32_bf16 v[126:129], v[142:145], v[162:165], v[126:129]
	v_mfma_f32_16x16x32_bf16 v[122:125], v[154:157], v[162:165], v[122:125]
	v_mfma_f32_16x16x32_bf16 v[110:113], v[142:145], v[170:173], v[110:113]
	v_mfma_f32_16x16x32_bf16 v[106:109], v[154:157], v[170:173], v[106:109]
	v_mfma_f32_16x16x32_bf16 v[94:97], v[142:145], v[178:181], v[94:97]
	v_mfma_f32_16x16x32_bf16 v[90:93], v[154:157], v[178:181], v[90:93]
	v_mfma_f32_16x16x32_bf16 v[78:81], v[142:145], v[186:189], v[78:81]
	v_mfma_f32_16x16x32_bf16 v[74:77], v[154:157], v[186:189], v[74:77]
	v_mfma_f32_16x16x32_bf16 v[126:129], v[150:153], v[166:169], v[126:129]
	v_mfma_f32_16x16x32_bf16 v[122:125], v[158:161], v[166:169], v[122:125]
	v_mfma_f32_16x16x32_bf16 v[110:113], v[150:153], v[174:177], v[110:113]
	v_mfma_f32_16x16x32_bf16 v[106:109], v[158:161], v[174:177], v[106:109]
	v_mfma_f32_16x16x32_bf16 v[94:97], v[150:153], v[182:185], v[94:97]
	v_mfma_f32_16x16x32_bf16 v[90:93], v[158:161], v[182:185], v[90:93]
	v_mfma_f32_16x16x32_bf16 v[78:81], v[150:153], v[190:193], v[78:81]
	v_mfma_f32_16x16x32_bf16 v[74:77], v[158:161], v[190:193], v[74:77]
	s_setprio 0
	s_barrier
	s_add_i32 s43, 0, 0x14000
	s_add_i32 s10, s42, s23
	s_mov_b32 m0, s10
	ds_read_b128 v[198:201], v131 offset:16384
	ds_read_b128 v[202:205], v131 offset:17408
	ds_read_b128 v[206:209], v131 offset:18432
	ds_read_b128 v[210:213], v131 offset:19456
	global_load_lds_dwordx4 v134, s[14:15]
	s_add_i32 m0, s10, 0x2000
	s_nop 0
	global_load_lds_dwordx4 v130, s[14:15]
	s_barrier
	s_waitcnt lgkmcnt(0)
	s_setprio 1
	v_mfma_f32_16x16x32_bf16 v[118:121], v[198:201], v[162:165], v[118:121]
	v_mfma_f32_16x16x32_bf16 v[114:117], v[206:209], v[162:165], v[114:117]
	v_mfma_f32_16x16x32_bf16 v[102:105], v[198:201], v[170:173], v[102:105]
	v_mfma_f32_16x16x32_bf16 v[98:101], v[206:209], v[170:173], v[98:101]
	v_mfma_f32_16x16x32_bf16 v[86:89], v[198:201], v[178:181], v[86:89]
	v_mfma_f32_16x16x32_bf16 v[82:85], v[206:209], v[178:181], v[82:85]
	v_mfma_f32_16x16x32_bf16 v[70:73], v[198:201], v[186:189], v[70:73]
	v_mfma_f32_16x16x32_bf16 v[66:69], v[206:209], v[186:189], v[66:69]
	v_mfma_f32_16x16x32_bf16 v[118:121], v[202:205], v[166:169], v[118:121]
	v_mfma_f32_16x16x32_bf16 v[114:117], v[210:213], v[166:169], v[114:117]
	v_mfma_f32_16x16x32_bf16 v[102:105], v[202:205], v[174:177], v[102:105]
	v_mfma_f32_16x16x32_bf16 v[98:101], v[210:213], v[174:177], v[98:101]
	v_mfma_f32_16x16x32_bf16 v[86:89], v[202:205], v[182:185], v[86:89]
	v_mfma_f32_16x16x32_bf16 v[82:85], v[210:213], v[182:185], v[82:85]
	v_mfma_f32_16x16x32_bf16 v[70:73], v[202:205], v[190:193], v[70:73]
	v_mfma_f32_16x16x32_bf16 v[66:69], v[210:213], v[190:193], v[66:69]
	s_setprio 0
	s_mov_b32 m0, s24
	v_lshl_add_u64 v[218:219], s[16:17], 0, v[136:137]
	s_barrier
	ds_read_b128 v[162:165], v149 offset:16384
	ds_read_b128 v[166:169], v149 offset:17408
	ds_read_b128 v[170:173], v149 offset:18432
	ds_read_b128 v[174:177], v149 offset:19456
	ds_read_b128 v[178:181], v149 offset:20480
	ds_read_b128 v[182:185], v149 offset:21504
	ds_read_b128 v[186:189], v149 offset:22528
	ds_read_b128 v[190:193], v149 offset:23552
	global_load_lds_dwordx4 v[218:219], off
	v_lshl_add_u64 v[220:221], s[16:17], 0, v[132:133]
	s_mov_b32 m0, s25
	s_nop 0
	global_load_lds_dwordx4 v[220:221], off
	s_barrier
	s_waitcnt lgkmcnt(0)
	s_setprio 1
	v_mfma_f32_16x16x32_bf16 v[62:65], v[142:145], v[162:165], v[62:65]
	v_mfma_f32_16x16x32_bf16 v[58:61], v[154:157], v[162:165], v[58:61]
	v_mfma_f32_16x16x32_bf16 v[44:47], v[142:145], v[170:173], v[44:47]
	v_mfma_f32_16x16x32_bf16 v[40:43], v[154:157], v[170:173], v[40:43]
	v_mfma_f32_16x16x32_bf16 v[28:31], v[142:145], v[178:181], v[28:31]
	v_mfma_f32_16x16x32_bf16 v[24:27], v[154:157], v[178:181], v[24:27]
	v_mfma_f32_16x16x32_bf16 v[12:15], v[142:145], v[186:189], v[12:15]
	v_mfma_f32_16x16x32_bf16 v[8:11], v[154:157], v[186:189], v[8:11]
	v_mfma_f32_16x16x32_bf16 v[62:65], v[150:153], v[166:169], v[62:65]
	v_mfma_f32_16x16x32_bf16 v[58:61], v[158:161], v[166:169], v[58:61]
	v_mfma_f32_16x16x32_bf16 v[44:47], v[150:153], v[174:177], v[44:47]
	v_mfma_f32_16x16x32_bf16 v[40:43], v[158:161], v[174:177], v[40:43]
	v_mfma_f32_16x16x32_bf16 v[28:31], v[150:153], v[182:185], v[28:31]
	v_mfma_f32_16x16x32_bf16 v[24:27], v[158:161], v[182:185], v[24:27]
	v_mfma_f32_16x16x32_bf16 v[12:15], v[150:153], v[190:193], v[12:15]
	v_mfma_f32_16x16x32_bf16 v[8:11], v[158:161], v[190:193], v[8:11]
	s_setprio 0
	s_barrier
	s_add_u32 s10, s14, 0x30000
	s_addc_u32 s11, s15, 0
	s_add_i32 s42, s43, s23
	s_mov_b32 m0, s42
	s_nop 0
	global_load_lds_dwordx4 v134, s[10:11]
	s_add_i32 m0, s42, 0x2000
	s_nop 0
	global_load_lds_dwordx4 v130, s[10:11]
	s_waitcnt vmcnt(6)
	s_barrier
	s_setprio 1
	v_mfma_f32_16x16x32_bf16 v[54:57], v[198:201], v[162:165], v[54:57]
	v_mfma_f32_16x16x32_bf16 v[50:53], v[206:209], v[162:165], v[50:53]
	v_mfma_f32_16x16x32_bf16 v[36:39], v[198:201], v[170:173], v[36:39]
	v_mfma_f32_16x16x32_bf16 v[32:35], v[206:209], v[170:173], v[32:35]
	v_mfma_f32_16x16x32_bf16 v[20:23], v[198:201], v[178:181], v[20:23]
	v_mfma_f32_16x16x32_bf16 v[16:19], v[206:209], v[178:181], v[16:19]
	v_mfma_f32_16x16x32_bf16 v[4:7], v[198:201], v[186:189], v[4:7]
	v_mfma_f32_16x16x32_bf16 v[0:3], v[206:209], v[186:189], v[0:3]
	v_mfma_f32_16x16x32_bf16 v[54:57], v[202:205], v[166:169], v[54:57]
	v_mfma_f32_16x16x32_bf16 v[50:53], v[210:213], v[166:169], v[50:53]
	v_mfma_f32_16x16x32_bf16 v[36:39], v[202:205], v[174:177], v[36:39]
	v_mfma_f32_16x16x32_bf16 v[32:35], v[210:213], v[174:177], v[32:35]
	v_mfma_f32_16x16x32_bf16 v[20:23], v[202:205], v[182:185], v[20:23]
	v_mfma_f32_16x16x32_bf16 v[16:19], v[210:213], v[182:185], v[16:19]
	v_mfma_f32_16x16x32_bf16 v[4:7], v[202:205], v[190:193], v[4:7]
	v_mfma_f32_16x16x32_bf16 v[0:3], v[210:213], v[190:193], v[0:3]
	s_setprio 0
	s_add_i32 s42, 0, 0x18000
	s_barrier
	ds_read_b128 v[142:145], v131 offset:32768
	ds_read_b128 v[150:153], v131 offset:33792
	ds_read_b128 v[154:157], v131 offset:34816
	ds_read_b128 v[158:161], v131 offset:35840
	s_add_u32 s10, s16, 0x30000
	s_addc_u32 s11, s17, 0
	s_mov_b32 m0, s26
	ds_read_b128 v[162:165], v149 offset:32768
	ds_read_b128 v[166:169], v149 offset:33792
	ds_read_b128 v[170:173], v149 offset:34816
	ds_read_b128 v[174:177], v149 offset:35840
	ds_read_b128 v[178:181], v149 offset:36864
	ds_read_b128 v[182:185], v149 offset:37888
	ds_read_b128 v[186:189], v149 offset:38912
	ds_read_b128 v[190:193], v149 offset:39936
	global_load_lds_dwordx4 v136, s[10:11]
	s_mov_b32 m0, s27
	s_nop 0
	global_load_lds_dwordx4 v132, s[10:11]
	s_waitcnt lgkmcnt(8)
	s_barrier
	s_waitcnt lgkmcnt(0)
	s_setprio 1
	v_mfma_f32_16x16x32_bf16 v[126:129], v[142:145], v[162:165], v[126:129]
	v_mfma_f32_16x16x32_bf16 v[122:125], v[154:157], v[162:165], v[122:125]
	v_mfma_f32_16x16x32_bf16 v[110:113], v[142:145], v[170:173], v[110:113]
	v_mfma_f32_16x16x32_bf16 v[106:109], v[154:157], v[170:173], v[106:109]
	v_mfma_f32_16x16x32_bf16 v[94:97], v[142:145], v[178:181], v[94:97]
	v_mfma_f32_16x16x32_bf16 v[90:93], v[154:157], v[178:181], v[90:93]
	v_mfma_f32_16x16x32_bf16 v[78:81], v[142:145], v[186:189], v[78:81]
	v_mfma_f32_16x16x32_bf16 v[74:77], v[154:157], v[186:189], v[74:77]
	v_mfma_f32_16x16x32_bf16 v[126:129], v[150:153], v[166:169], v[126:129]
	v_mfma_f32_16x16x32_bf16 v[122:125], v[158:161], v[166:169], v[122:125]
	v_mfma_f32_16x16x32_bf16 v[110:113], v[150:153], v[174:177], v[110:113]
	v_mfma_f32_16x16x32_bf16 v[106:109], v[158:161], v[174:177], v[106:109]
	v_mfma_f32_16x16x32_bf16 v[94:97], v[150:153], v[182:185], v[94:97]
	v_mfma_f32_16x16x32_bf16 v[90:93], v[158:161], v[182:185], v[90:93]
	v_mfma_f32_16x16x32_bf16 v[78:81], v[150:153], v[190:193], v[78:81]
	v_mfma_f32_16x16x32_bf16 v[74:77], v[158:161], v[190:193], v[74:77]
	s_setprio 0
	s_barrier
	s_add_i32 s16, 0, 0x1c000
	s_add_i32 s10, s42, s23
	s_add_u32 s72, s14, s66
	s_addc_u32 s73, s15, s67
	s_mov_b32 m0, s10
	ds_read_b128 v[198:201], v131 offset:49152
	ds_read_b128 v[202:205], v131 offset:50176
	ds_read_b128 v[206:209], v131 offset:51200
	ds_read_b128 v[210:213], v131 offset:52224
	global_load_lds_dwordx4 v134, s[72:73]
	s_add_i32 m0, s10, 0x2000
	s_nop 0
	global_load_lds_dwordx4 v130, s[72:73]
	s_barrier
	s_waitcnt lgkmcnt(0)
	s_setprio 1
	v_mfma_f32_16x16x32_bf16 v[118:121], v[198:201], v[162:165], v[118:121]
	v_mfma_f32_16x16x32_bf16 v[114:117], v[206:209], v[162:165], v[114:117]
	v_mfma_f32_16x16x32_bf16 v[102:105], v[198:201], v[170:173], v[102:105]
	v_mfma_f32_16x16x32_bf16 v[98:101], v[206:209], v[170:173], v[98:101]
	v_mfma_f32_16x16x32_bf16 v[86:89], v[198:201], v[178:181], v[86:89]
	v_mfma_f32_16x16x32_bf16 v[82:85], v[206:209], v[178:181], v[82:85]
	v_mfma_f32_16x16x32_bf16 v[70:73], v[198:201], v[186:189], v[70:73]
	v_mfma_f32_16x16x32_bf16 v[66:69], v[206:209], v[186:189], v[66:69]
	v_mfma_f32_16x16x32_bf16 v[118:121], v[202:205], v[166:169], v[118:121]
	v_mfma_f32_16x16x32_bf16 v[114:117], v[210:213], v[166:169], v[114:117]
	v_mfma_f32_16x16x32_bf16 v[102:105], v[202:205], v[174:177], v[102:105]
	v_mfma_f32_16x16x32_bf16 v[98:101], v[210:213], v[174:177], v[98:101]
	v_mfma_f32_16x16x32_bf16 v[86:89], v[202:205], v[182:185], v[86:89]
	v_mfma_f32_16x16x32_bf16 v[82:85], v[210:213], v[182:185], v[82:85]
	v_mfma_f32_16x16x32_bf16 v[70:73], v[202:205], v[190:193], v[70:73]
	v_mfma_f32_16x16x32_bf16 v[66:69], v[210:213], v[190:193], v[66:69]
	s_setprio 0
	s_mov_b32 m0, s28
	v_lshl_add_u64 v[214:215], v[218:219], 0, s[66:67]
	s_barrier
	ds_read_b128 v[162:165], v149 offset:49152
	ds_read_b128 v[166:169], v149 offset:50176
	ds_read_b128 v[170:173], v149 offset:51200
	ds_read_b128 v[174:177], v149 offset:52224
	ds_read_b128 v[178:181], v149 offset:53248
	ds_read_b128 v[182:185], v149 offset:54272
	ds_read_b128 v[186:189], v149 offset:55296
	ds_read_b128 v[190:193], v149 offset:56320
	global_load_lds_dwordx4 v[214:215], off
	v_lshl_add_u64 v[214:215], v[220:221], 0, s[66:67]
	s_mov_b32 m0, s29
	s_nop 0
	global_load_lds_dwordx4 v[214:215], off
	s_barrier
	s_waitcnt lgkmcnt(0)
	s_setprio 1
	v_mfma_f32_16x16x32_bf16 v[62:65], v[142:145], v[162:165], v[62:65]
	v_mfma_f32_16x16x32_bf16 v[58:61], v[154:157], v[162:165], v[58:61]
	v_mfma_f32_16x16x32_bf16 v[44:47], v[142:145], v[170:173], v[44:47]
	v_mfma_f32_16x16x32_bf16 v[40:43], v[154:157], v[170:173], v[40:43]
	v_mfma_f32_16x16x32_bf16 v[28:31], v[142:145], v[178:181], v[28:31]
	v_mfma_f32_16x16x32_bf16 v[24:27], v[154:157], v[178:181], v[24:27]
	v_mfma_f32_16x16x32_bf16 v[12:15], v[142:145], v[186:189], v[12:15]
	v_mfma_f32_16x16x32_bf16 v[8:11], v[154:157], v[186:189], v[8:11]
	v_mfma_f32_16x16x32_bf16 v[62:65], v[150:153], v[166:169], v[62:65]
	v_mfma_f32_16x16x32_bf16 v[58:61], v[158:161], v[166:169], v[58:61]
	v_mfma_f32_16x16x32_bf16 v[44:47], v[150:153], v[174:177], v[44:47]
	v_mfma_f32_16x16x32_bf16 v[40:43], v[158:161], v[174:177], v[40:43]
	v_mfma_f32_16x16x32_bf16 v[28:31], v[150:153], v[182:185], v[28:31]
	v_mfma_f32_16x16x32_bf16 v[24:27], v[158:161], v[182:185], v[24:27]
	v_mfma_f32_16x16x32_bf16 v[12:15], v[150:153], v[190:193], v[12:15]
	v_mfma_f32_16x16x32_bf16 v[8:11], v[158:161], v[190:193], v[8:11]
	s_setprio 0
	s_barrier
	s_add_u32 s10, s14, 0x30080
	s_addc_u32 s11, s15, 0
	s_add_i32 s14, s16, s23
	s_mov_b32 m0, s14
	s_nop 0
	global_load_lds_dwordx4 v134, s[10:11]
	s_add_i32 m0, s14, 0x2000
	s_nop 0
	global_load_lds_dwordx4 v130, s[10:11]
	s_waitcnt vmcnt(6)
	s_barrier
	s_setprio 1
	v_mfma_f32_16x16x32_bf16 v[54:57], v[198:201], v[162:165], v[54:57]
	v_mfma_f32_16x16x32_bf16 v[50:53], v[206:209], v[162:165], v[50:53]
	v_mfma_f32_16x16x32_bf16 v[36:39], v[198:201], v[170:173], v[36:39]
	v_mfma_f32_16x16x32_bf16 v[32:35], v[206:209], v[170:173], v[32:35]
	v_mfma_f32_16x16x32_bf16 v[20:23], v[198:201], v[178:181], v[20:23]
	v_mfma_f32_16x16x32_bf16 v[16:19], v[206:209], v[178:181], v[16:19]
	v_mfma_f32_16x16x32_bf16 v[4:7], v[198:201], v[186:189], v[4:7]
	v_mfma_f32_16x16x32_bf16 v[0:3], v[206:209], v[186:189], v[0:3]
	v_mfma_f32_16x16x32_bf16 v[54:57], v[202:205], v[166:169], v[54:57]
	v_mfma_f32_16x16x32_bf16 v[50:53], v[210:213], v[166:169], v[50:53]
	v_mfma_f32_16x16x32_bf16 v[36:39], v[202:205], v[174:177], v[36:39]
	v_mfma_f32_16x16x32_bf16 v[32:35], v[210:213], v[174:177], v[32:35]
	v_mfma_f32_16x16x32_bf16 v[20:23], v[202:205], v[182:185], v[20:23]
	v_mfma_f32_16x16x32_bf16 v[16:19], v[210:213], v[182:185], v[16:19]
	v_mfma_f32_16x16x32_bf16 v[4:7], v[202:205], v[190:193], v[4:7]
	v_mfma_f32_16x16x32_bf16 v[0:3], v[210:213], v[190:193], v[0:3]
	s_setprio 0
	s_add_i32 s41, s41, 2
	s_add_u32 s39, s39, 0x100
	s_addc_u32 s40, s40, 0
	s_cmp_gt_u32 s41, 9
	s_mov_b64 s[10:11], s[12:13]
	s_barrier
	s_cbranch_scc0 .LBB0_822
	v_lshl_add_u32 v142, s38, 8, v146
	v_ashrrev_i32_e32 v143, 31, v142
	v_lshlrev_b64 v[144:145], 14, v[142:143]
	v_mul_f32_e32 v143, 0x3d372713, v126
	v_mul_f32_e32 v143, v126, v143
	v_fma_f32 v143, v126, v143, v126
	v_mul_f32_e32 v143, 0xbfcc422a, v143
	v_mul_f32_e32 v143, 0x3fb8aa3b, v143
	v_exp_f32_e32 v150, v143
	v_mul_f32_e32 v143, 0x3d372713, v122
	v_mul_f32_e32 v143, v122, v143
	v_fma_f32 v143, v122, v143, v122
	v_mul_f32_e32 v143, 0xbfcc422a, v143
	v_mul_f32_e32 v143, 0x3fb8aa3b, v143
	v_exp_f32_e32 v152, v143
	v_mul_f32_e32 v143, 0x3d372713, v127
	v_mul_f32_e32 v143, v127, v143
	v_fma_f32 v143, v127, v143, v127
	v_mul_f32_e32 v143, 0xbfcc422a, v143
	v_mul_f32_e32 v143, 0x3fb8aa3b, v143
	v_exp_f32_e32 v151, v143
	v_lshl_or_b32 v154, s37, 8, v148
	s_lshl_b32 s10, s36, 4
	s_ashr_i32 s11, s10, 31
	v_pk_add_f32 v[150:151], v[150:151], 1.0 op_sel_hi:[1,0]
	s_lshl_b64 s[10:11], s[10:11], 1
	s_mov_b32 s36, s31
	s_mov_b32 s37, s35
	s_mov_b32 s38, s34
	v_rcp_f32_e32 v143, v151
	s_nop 0
	v_mul_f32_e32 v143, v127, v143
	s_nop 0
	v_rcp_f32_e32 v127, v150
	s_nop 0
	v_mul_f32_e32 v150, v126, v127
	v_mul_f32_e32 v126, 0x3d372713, v123
	v_mul_f32_e32 v126, v123, v126
	v_fma_f32 v126, v123, v126, v123
	v_mul_f32_e32 v126, 0xbfcc422a, v126
	v_mul_f32_e32 v126, 0x3fb8aa3b, v126
	v_exp_f32_e32 v153, v126
	v_cvt_pk_bf16_f32 v150, v150, v143
	v_pk_add_f32 v[126:127], v[152:153], 1.0 op_sel_hi:[1,0]
	s_nop 0
	s_nop 0
	v_rcp_f32_e32 v151, v127
	s_nop 0
	v_mul_f32_e32 v152, v123, v151
	s_nop 0
	v_rcp_f32_e32 v123, v126
	s_nop 0
	v_mul_f32_e32 v153, v122, v123
	v_mul_f32_e32 v123, 0x3d372713, v124
	v_mul_f32_e32 v123, v124, v123
	v_fma_f32 v123, v124, v123, v124
	v_mul_f32_e32 v123, 0xbfcc422a, v123
	v_mul_f32_e32 v123, 0x3fb8aa3b, v123
	v_mul_f32_e32 v122, 0x3d372713, v128
	v_exp_f32_e32 v126, v123
	v_mul_f32_e32 v123, 0x3d372713, v129
	v_mul_f32_e32 v122, v128, v122
	v_mul_f32_e32 v123, v129, v123
	v_fma_f32 v122, v128, v122, v128
	v_fma_f32 v123, v129, v123, v129
	v_mul_f32_e32 v122, 0xbfcc422a, v122
	v_mul_f32_e32 v123, 0xbfcc422a, v123
	v_mul_f32_e32 v122, 0x3fb8aa3b, v122
	v_mul_f32_e32 v123, 0x3fb8aa3b, v123
	v_exp_f32_e32 v122, v122
	v_exp_f32_e32 v123, v123
	v_cvt_pk_bf16_f32 v152, v153, v152
	v_pk_add_f32 v[122:123], v[122:123], 1.0 op_sel_hi:[1,0]
	s_nop 0
	s_nop 0
	v_rcp_f32_e32 v127, v123
	s_nop 0
	v_mul_f32_e32 v129, v129, v127
	s_nop 0
	v_rcp_f32_e32 v123, v122
	s_nop 0
	v_mul_f32_e32 v128, v128, v123
	v_mul_f32_e32 v122, 0x3d372713, v125
	v_mul_f32_e32 v122, v125, v122
	v_fma_f32 v122, v125, v122, v125
	v_mul_f32_e32 v122, 0xbfcc422a, v122
	v_mul_f32_e32 v122, 0x3fb8aa3b, v122
	v_exp_f32_e32 v127, v122
	s_nop 0
	v_pk_add_f32 v[122:123], v[126:127], 1.0 op_sel_hi:[1,0]
	s_nop 0
	s_nop 0
	v_rcp_f32_e32 v126, v123
	s_nop 0
	v_mul_f32_e32 v123, v125, v126
	s_nop 0
	v_ashrrev_i32_e32 v126, 4, v154
	v_ashrrev_i32_e32 v127, 31, v126
	v_rcp_f32_e32 v125, v122
	s_nop 0
	v_mul_f32_e32 v122, v124, v125
	v_lshlrev_b64 v[124:125], 9, v[126:127]
	v_mul_f32_e32 v127, 0x3d372713, v118
	v_cvt_pk_bf16_f32 v153, v122, v123
	v_lshl_add_u64 v[122:123], s[0:1], 0, v[144:145]
	v_mul_f32_e32 v127, v118, v127
	v_cvt_pk_bf16_f32 v151, v128, v129
	v_lshl_add_u64 v[128:129], v[122:123], 0, v[124:125]
	v_fma_f32 v127, v118, v127, v118
	v_lshl_add_u64 v[128:129], v[128:129], 0, s[10:11]
	v_mul_f32_e32 v127, 0xbfcc422a, v127
	v_lshl_add_u64 v[128:129], v[128:129], 0, v[48:49]
	v_mul_f32_e32 v127, 0x3fb8aa3b, v127
	global_store_dwordx4 v[128:129], v[150:153], off
	v_exp_f32_e32 v128, v127
	v_mul_f32_e32 v127, 0x3d372713, v114
	v_mul_f32_e32 v127, v114, v127
	v_fma_f32 v127, v114, v127, v114
	v_mul_f32_e32 v127, 0xbfcc422a, v127
	v_mul_f32_e32 v127, 0x3fb8aa3b, v127
	v_exp_f32_e32 v144, v127
	v_mul_f32_e32 v127, 0x3d372713, v119
	v_mul_f32_e32 v127, v119, v127
	v_fma_f32 v127, v119, v127, v119
	v_mul_f32_e32 v127, 0xbfcc422a, v127
	v_mul_f32_e32 v127, 0x3fb8aa3b, v127
	v_exp_f32_e32 v129, v127
	s_nop 0
	v_pk_add_f32 v[128:129], v[128:129], 1.0 op_sel_hi:[1,0]
	s_nop 0
	s_nop 0
	v_rcp_f32_e32 v127, v129
	s_nop 0
	v_mul_f32_e32 v127, v119, v127
	s_nop 0
	v_rcp_f32_e32 v119, v128
	s_nop 0
	v_mul_f32_e32 v128, v118, v119
	v_mul_f32_e32 v118, 0x3d372713, v115
	v_mul_f32_e32 v118, v115, v118
	v_fma_f32 v118, v115, v118, v115
	v_mul_f32_e32 v118, 0xbfcc422a, v118
	v_mul_f32_e32 v118, 0x3fb8aa3b, v118
	v_exp_f32_e32 v145, v118
	s_nop 0
	v_pk_add_f32 v[118:119], v[144:145], 1.0 op_sel_hi:[1,0]
	s_nop 0
	s_nop 0
	v_rcp_f32_e32 v129, v119
	s_nop 0
	v_mul_f32_e32 v129, v115, v129
	s_nop 0
	v_rcp_f32_e32 v115, v118
	s_nop 0
	v_mul_f32_e32 v143, v114, v115
	v_mul_f32_e32 v115, 0x3d372713, v116
	v_mul_f32_e32 v115, v116, v115
	v_fma_f32 v115, v116, v115, v116
	v_mul_f32_e32 v115, 0xbfcc422a, v115
	v_mul_f32_e32 v115, 0x3fb8aa3b, v115
	v_mul_f32_e32 v114, 0x3d372713, v120
	v_exp_f32_e32 v118, v115
	v_mul_f32_e32 v115, 0x3d372713, v121
	v_mul_f32_e32 v114, v120, v114
	v_mul_f32_e32 v115, v121, v115
	v_fma_f32 v114, v120, v114, v120
	v_fma_f32 v115, v121, v115, v121
	v_mul_f32_e32 v114, 0xbfcc422a, v114
	v_mul_f32_e32 v115, 0xbfcc422a, v115
	v_mul_f32_e32 v114, 0x3fb8aa3b, v114
	v_mul_f32_e32 v115, 0x3fb8aa3b, v115
	v_exp_f32_e32 v114, v114
	v_exp_f32_e32 v115, v115
	s_nop 0
	v_pk_add_f32 v[114:115], v[114:115], 1.0 op_sel_hi:[1,0]
	s_nop 0
	s_nop 0
	v_rcp_f32_e32 v119, v115
	s_nop 0
	v_mul_f32_e32 v121, v121, v119
	s_nop 0
	v_rcp_f32_e32 v115, v114
	s_nop 0
	v_mul_f32_e32 v120, v120, v115
	v_mul_f32_e32 v114, 0x3d372713, v117
	v_mul_f32_e32 v114, v117, v114
	v_fma_f32 v114, v117, v114, v117
	v_mul_f32_e32 v114, 0xbfcc422a, v114
	v_mul_f32_e32 v114, 0x3fb8aa3b, v114
	v_exp_f32_e32 v119, v114
	s_nop 0
	v_pk_add_f32 v[114:115], v[118:119], 1.0 op_sel_hi:[1,0]
	s_nop 0
	s_nop 0
	v_rcp_f32_e32 v118, v115
	s_nop 0
	v_mul_f32_e32 v115, v117, v118
	s_nop 0
	v_rcp_f32_e32 v117, v114
	s_nop 0
	v_mul_f32_e32 v119, v116, v117
	v_or_b32_e32 v114, 8, v126
	v_cvt_pk_bf16_f32 v119, v119, v115
	v_ashrrev_i32_e32 v115, 31, v114
	v_lshlrev_b64 v[114:115], 9, v[114:115]
	v_cvt_pk_bf16_f32 v117, v120, v121
	v_lshl_add_u64 v[120:121], v[122:123], 0, v[114:115]
	v_lshl_add_u64 v[120:121], v[120:121], 0, s[10:11]
	v_cvt_pk_bf16_f32 v116, v128, v127
	v_cvt_pk_bf16_f32 v118, v143, v129
	v_lshl_add_u64 v[120:121], v[120:121], 0, v[48:49]
	global_store_dwordx4 v[120:121], v[116:119], off
	s_nop 1
	v_mul_f32_e32 v119, 0x3d372713, v106
	v_mul_f32_e32 v119, v106, v119
	v_fma_f32 v119, v106, v119, v106
	v_mul_f32_e32 v119, 0xbfcc422a, v119
	v_mul_f32_e32 v119, 0x3fb8aa3b, v119
	v_mul_f32_e32 v118, 0x3d372713, v110
	v_exp_f32_e32 v120, v119
	v_mul_f32_e32 v119, 0x3d372713, v111
	v_mul_f32_e32 v118, v110, v118
	v_mul_f32_e32 v119, v111, v119
	v_fma_f32 v118, v110, v118, v110
	v_fma_f32 v119, v111, v119, v111
	v_mul_f32_e32 v118, 0xbfcc422a, v118
	v_mul_f32_e32 v119, 0xbfcc422a, v119
	v_mul_f32_e32 v118, 0x3fb8aa3b, v118
	v_mul_f32_e32 v119, 0x3fb8aa3b, v119
	v_exp_f32_e32 v118, v118
	v_exp_f32_e32 v119, v119
	v_or_b32_e32 v116, 16, v142
	v_ashrrev_i32_e32 v117, 31, v116
	v_lshlrev_b64 v[116:117], 14, v[116:117]
	v_pk_add_f32 v[118:119], v[118:119], 1.0 op_sel_hi:[1,0]
	s_nop 0
	s_nop 0
	v_rcp_f32_e32 v121, v119
	s_nop 0
	v_mul_f32_e32 v119, v111, v121
	s_nop 0
	v_rcp_f32_e32 v111, v118
	s_nop 0
	v_mul_f32_e32 v118, v110, v111
	v_mul_f32_e32 v110, 0x3d372713, v107
	v_mul_f32_e32 v110, v107, v110
	v_fma_f32 v110, v107, v110, v107
	v_mul_f32_e32 v110, 0xbfcc422a, v110
	v_mul_f32_e32 v110, 0x3fb8aa3b, v110
	v_exp_f32_e32 v121, v110
	s_nop 0
	v_pk_add_f32 v[110:111], v[120:121], 1.0 op_sel_hi:[1,0]
	s_nop 0
	s_nop 0
	v_rcp_f32_e32 v120, v111
	s_nop 0
	v_mul_f32_e32 v120, v107, v120
	s_nop 0
	v_rcp_f32_e32 v107, v110
	s_nop 0
	v_mul_f32_e32 v121, v106, v107
	v_mul_f32_e32 v107, 0x3d372713, v108
	v_mul_f32_e32 v107, v108, v107
	v_fma_f32 v107, v108, v107, v108
	v_mul_f32_e32 v107, 0xbfcc422a, v107
	v_mul_f32_e32 v107, 0x3fb8aa3b, v107
	v_mul_f32_e32 v106, 0x3d372713, v112
	v_exp_f32_e32 v110, v107
	v_mul_f32_e32 v107, 0x3d372713, v113
	v_mul_f32_e32 v106, v112, v106
	v_mul_f32_e32 v107, v113, v107
	v_fma_f32 v106, v112, v106, v112
	v_fma_f32 v107, v113, v107, v113
	v_mul_f32_e32 v106, 0xbfcc422a, v106
	v_mul_f32_e32 v107, 0xbfcc422a, v107
	v_mul_f32_e32 v106, 0x3fb8aa3b, v106
	v_mul_f32_e32 v107, 0x3fb8aa3b, v107
	v_exp_f32_e32 v106, v106
	v_exp_f32_e32 v107, v107
	s_nop 0
	v_pk_add_f32 v[106:107], v[106:107], 1.0 op_sel_hi:[1,0]
	s_nop 0
	s_nop 0
	v_rcp_f32_e32 v111, v107
	s_nop 0
	v_mul_f32_e32 v113, v113, v111
	s_nop 0
	v_rcp_f32_e32 v107, v106
	s_nop 0
	v_mul_f32_e32 v112, v112, v107
	v_mul_f32_e32 v106, 0x3d372713, v109
	v_mul_f32_e32 v106, v109, v106
	v_fma_f32 v106, v109, v106, v109
	v_mul_f32_e32 v106, 0xbfcc422a, v106
	v_mul_f32_e32 v106, 0x3fb8aa3b, v106
	v_exp_f32_e32 v111, v106
	s_nop 0
	v_pk_add_f32 v[106:107], v[110:111], 1.0 op_sel_hi:[1,0]
	s_nop 0
	s_nop 0
	v_rcp_f32_e32 v110, v107
	s_nop 0
	v_mul_f32_e32 v107, v109, v110
	s_nop 0
	v_rcp_f32_e32 v109, v106
	s_nop 0
	v_mul_f32_e32 v106, v108, v109
	v_cvt_pk_bf16_f32 v111, v106, v107
	v_lshl_add_u64 v[106:107], s[0:1], 0, v[116:117]
	v_cvt_pk_bf16_f32 v109, v112, v113
	v_lshl_add_u64 v[112:113], v[106:107], 0, v[124:125]
	v_lshl_add_u64 v[112:113], v[112:113], 0, s[10:11]
	v_cvt_pk_bf16_f32 v108, v118, v119
	v_cvt_pk_bf16_f32 v110, v121, v120
	v_lshl_add_u64 v[112:113], v[112:113], 0, v[48:49]
	global_store_dwordx4 v[112:113], v[108:111], off
	s_nop 1
	v_mul_f32_e32 v109, 0x3d372713, v98
	v_mul_f32_e32 v109, v98, v109
	v_fma_f32 v109, v98, v109, v98
	v_mul_f32_e32 v109, 0xbfcc422a, v109
	v_mul_f32_e32 v109, 0x3fb8aa3b, v109
	v_mul_f32_e32 v108, 0x3d372713, v102
	v_exp_f32_e32 v110, v109
	v_mul_f32_e32 v109, 0x3d372713, v103
	v_mul_f32_e32 v108, v102, v108
	v_mul_f32_e32 v109, v103, v109
	v_fma_f32 v108, v102, v108, v102
	v_fma_f32 v109, v103, v109, v103
	v_mul_f32_e32 v108, 0xbfcc422a, v108
	v_mul_f32_e32 v109, 0xbfcc422a, v109
	v_mul_f32_e32 v108, 0x3fb8aa3b, v108
	v_mul_f32_e32 v109, 0x3fb8aa3b, v109
	v_exp_f32_e32 v108, v108
	v_exp_f32_e32 v109, v109
	s_nop 0
	v_pk_add_f32 v[108:109], v[108:109], 1.0 op_sel_hi:[1,0]
	s_nop 0
	s_nop 0
	v_rcp_f32_e32 v111, v109
	s_nop 0
	v_mul_f32_e32 v109, v103, v111
	s_nop 0
	v_rcp_f32_e32 v103, v108
	s_nop 0
	v_mul_f32_e32 v108, v102, v103
	v_mul_f32_e32 v102, 0x3d372713, v99
	v_mul_f32_e32 v102, v99, v102
	v_fma_f32 v102, v99, v102, v99
	v_mul_f32_e32 v102, 0xbfcc422a, v102
	v_mul_f32_e32 v102, 0x3fb8aa3b, v102
	v_exp_f32_e32 v111, v102
	s_nop 0
	v_pk_add_f32 v[102:103], v[110:111], 1.0 op_sel_hi:[1,0]
	s_nop 0
	s_nop 0
	v_rcp_f32_e32 v110, v103
	s_nop 0
	v_mul_f32_e32 v110, v99, v110
	s_nop 0
	v_rcp_f32_e32 v99, v102
	s_nop 0
	v_mul_f32_e32 v111, v98, v99
	v_mul_f32_e32 v99, 0x3d372713, v100
	v_mul_f32_e32 v99, v100, v99
	v_fma_f32 v99, v100, v99, v100
	v_mul_f32_e32 v99, 0xbfcc422a, v99
	v_mul_f32_e32 v99, 0x3fb8aa3b, v99
	v_mul_f32_e32 v98, 0x3d372713, v104
	v_exp_f32_e32 v102, v99
	v_mul_f32_e32 v99, 0x3d372713, v105
	v_mul_f32_e32 v98, v104, v98
	v_mul_f32_e32 v99, v105, v99
	v_fma_f32 v98, v104, v98, v104
	v_fma_f32 v99, v105, v99, v105
	v_mul_f32_e32 v98, 0xbfcc422a, v98
	v_mul_f32_e32 v99, 0xbfcc422a, v99
	v_mul_f32_e32 v98, 0x3fb8aa3b, v98
	v_mul_f32_e32 v99, 0x3fb8aa3b, v99
	v_exp_f32_e32 v98, v98
	v_exp_f32_e32 v99, v99
	s_nop 0
	v_pk_add_f32 v[98:99], v[98:99], 1.0 op_sel_hi:[1,0]
	s_nop 0
	s_nop 0
	v_rcp_f32_e32 v103, v99
	s_nop 0
	v_mul_f32_e32 v105, v105, v103
	s_nop 0
	v_rcp_f32_e32 v99, v98
	s_nop 0
	v_mul_f32_e32 v104, v104, v99
	v_mul_f32_e32 v98, 0x3d372713, v101
	v_mul_f32_e32 v98, v101, v98
	v_fma_f32 v98, v101, v98, v101
	v_mul_f32_e32 v98, 0xbfcc422a, v98
	v_mul_f32_e32 v98, 0x3fb8aa3b, v98
	v_exp_f32_e32 v103, v98
	s_nop 0
	v_pk_add_f32 v[98:99], v[102:103], 1.0 op_sel_hi:[1,0]
	s_nop 0
	s_nop 0
	v_rcp_f32_e32 v102, v99
	s_nop 0
	v_mul_f32_e32 v101, v101, v102
	s_nop 0
	v_rcp_f32_e32 v99, v98
	s_nop 0
	v_mul_f32_e32 v102, v100, v99
	v_cvt_pk_bf16_f32 v101, v102, v101
	v_lshl_add_u64 v[102:103], v[106:107], 0, v[114:115]
	v_lshl_add_u64 v[102:103], v[102:103], 0, s[10:11]
	v_cvt_pk_bf16_f32 v98, v108, v109
	v_cvt_pk_bf16_f32 v99, v104, v105
	v_cvt_pk_bf16_f32 v100, v111, v110
	v_lshl_add_u64 v[102:103], v[102:103], 0, v[48:49]
	global_store_dwordx4 v[102:103], v[98:101], off
	s_nop 1
	v_mul_f32_e32 v101, 0x3d372713, v90
	v_mul_f32_e32 v101, v90, v101
	v_fma_f32 v101, v90, v101, v90
	v_mul_f32_e32 v101, 0xbfcc422a, v101
	v_mul_f32_e32 v101, 0x3fb8aa3b, v101
	v_mul_f32_e32 v100, 0x3d372713, v94
	v_exp_f32_e32 v102, v101
	v_mul_f32_e32 v101, 0x3d372713, v95
	v_mul_f32_e32 v100, v94, v100
	v_mul_f32_e32 v101, v95, v101
	v_fma_f32 v100, v94, v100, v94
	v_fma_f32 v101, v95, v101, v95
	v_mul_f32_e32 v100, 0xbfcc422a, v100
	v_mul_f32_e32 v101, 0xbfcc422a, v101
	v_mul_f32_e32 v100, 0x3fb8aa3b, v100
	v_mul_f32_e32 v101, 0x3fb8aa3b, v101
	v_exp_f32_e32 v100, v100
	v_exp_f32_e32 v101, v101
	v_or_b32_e32 v98, 32, v142
	v_ashrrev_i32_e32 v99, 31, v98
	v_lshlrev_b64 v[98:99], 14, v[98:99]
	v_pk_add_f32 v[100:101], v[100:101], 1.0 op_sel_hi:[1,0]
	s_nop 0
	s_nop 0
	v_rcp_f32_e32 v103, v101
	s_nop 0
	v_mul_f32_e32 v101, v95, v103
	s_nop 0
	v_rcp_f32_e32 v95, v100
	s_nop 0
	v_mul_f32_e32 v100, v94, v95
	v_mul_f32_e32 v94, 0x3d372713, v91
	v_mul_f32_e32 v94, v91, v94
	v_fma_f32 v94, v91, v94, v91
	v_mul_f32_e32 v94, 0xbfcc422a, v94
	v_mul_f32_e32 v94, 0x3fb8aa3b, v94
	v_exp_f32_e32 v103, v94
	s_nop 0
	v_pk_add_f32 v[94:95], v[102:103], 1.0 op_sel_hi:[1,0]
	s_nop 0
	s_nop 0
	v_rcp_f32_e32 v102, v95
	s_nop 0
	v_mul_f32_e32 v102, v91, v102
	s_nop 0
	v_rcp_f32_e32 v91, v94
	s_nop 0
	v_mul_f32_e32 v103, v90, v91
	v_mul_f32_e32 v91, 0x3d372713, v92
	v_mul_f32_e32 v91, v92, v91
	v_fma_f32 v91, v92, v91, v92
	v_mul_f32_e32 v91, 0xbfcc422a, v91
	v_mul_f32_e32 v91, 0x3fb8aa3b, v91
	v_mul_f32_e32 v90, 0x3d372713, v96
	v_exp_f32_e32 v94, v91
	v_mul_f32_e32 v91, 0x3d372713, v97
	v_mul_f32_e32 v90, v96, v90
	v_mul_f32_e32 v91, v97, v91
	v_fma_f32 v90, v96, v90, v96
	v_fma_f32 v91, v97, v91, v97
	v_mul_f32_e32 v90, 0xbfcc422a, v90
	v_mul_f32_e32 v91, 0xbfcc422a, v91
	v_mul_f32_e32 v90, 0x3fb8aa3b, v90
	v_mul_f32_e32 v91, 0x3fb8aa3b, v91
	v_exp_f32_e32 v90, v90
	v_exp_f32_e32 v91, v91
	s_nop 0
	v_pk_add_f32 v[90:91], v[90:91], 1.0 op_sel_hi:[1,0]
	s_nop 0
	s_nop 0
	v_rcp_f32_e32 v95, v91
	s_nop 0
	v_mul_f32_e32 v97, v97, v95
	s_nop 0
	v_rcp_f32_e32 v91, v90
	s_nop 0
	v_mul_f32_e32 v96, v96, v91
	v_mul_f32_e32 v90, 0x3d372713, v93
	v_mul_f32_e32 v90, v93, v90
	v_fma_f32 v90, v93, v90, v93
	v_mul_f32_e32 v90, 0xbfcc422a, v90
	v_mul_f32_e32 v90, 0x3fb8aa3b, v90
	v_exp_f32_e32 v95, v90
	s_nop 0
	v_pk_add_f32 v[90:91], v[94:95], 1.0 op_sel_hi:[1,0]
	s_nop 0
	s_nop 0
	v_rcp_f32_e32 v94, v91
	s_nop 0
	v_mul_f32_e32 v91, v93, v94
	s_nop 0
	v_rcp_f32_e32 v93, v90
	s_nop 0
	v_mul_f32_e32 v90, v92, v93
	v_cvt_pk_bf16_f32 v95, v90, v91
	v_lshl_add_u64 v[90:91], s[0:1], 0, v[98:99]
	v_cvt_pk_bf16_f32 v93, v96, v97
	v_lshl_add_u64 v[96:97], v[90:91], 0, v[124:125]
	v_lshl_add_u64 v[96:97], v[96:97], 0, s[10:11]
	v_cvt_pk_bf16_f32 v92, v100, v101
	v_cvt_pk_bf16_f32 v94, v103, v102
	v_lshl_add_u64 v[96:97], v[96:97], 0, v[48:49]
	global_store_dwordx4 v[96:97], v[92:95], off
	s_nop 1
	v_mul_f32_e32 v93, 0x3d372713, v82
	v_mul_f32_e32 v93, v82, v93
	v_fma_f32 v93, v82, v93, v82
	v_mul_f32_e32 v93, 0xbfcc422a, v93
	v_mul_f32_e32 v93, 0x3fb8aa3b, v93
	v_mul_f32_e32 v92, 0x3d372713, v86
	v_exp_f32_e32 v94, v93
	v_mul_f32_e32 v93, 0x3d372713, v87
	v_mul_f32_e32 v92, v86, v92
	v_mul_f32_e32 v93, v87, v93
	v_fma_f32 v92, v86, v92, v86
	v_fma_f32 v93, v87, v93, v87
	v_mul_f32_e32 v92, 0xbfcc422a, v92
	v_mul_f32_e32 v93, 0xbfcc422a, v93
	v_mul_f32_e32 v92, 0x3fb8aa3b, v92
	v_mul_f32_e32 v93, 0x3fb8aa3b, v93
	v_exp_f32_e32 v92, v92
	v_exp_f32_e32 v93, v93
	s_nop 0
	v_pk_add_f32 v[92:93], v[92:93], 1.0 op_sel_hi:[1,0]
	s_nop 0
	s_nop 0
	v_rcp_f32_e32 v95, v93
	s_nop 0
	v_mul_f32_e32 v93, v87, v95
	s_nop 0
	v_rcp_f32_e32 v87, v92
	s_nop 0
	v_mul_f32_e32 v92, v86, v87
	v_mul_f32_e32 v86, 0x3d372713, v83
	v_mul_f32_e32 v86, v83, v86
	v_fma_f32 v86, v83, v86, v83
	v_mul_f32_e32 v86, 0xbfcc422a, v86
	v_mul_f32_e32 v86, 0x3fb8aa3b, v86
	v_exp_f32_e32 v95, v86
	s_nop 0
	v_pk_add_f32 v[86:87], v[94:95], 1.0 op_sel_hi:[1,0]
	s_nop 0
	s_nop 0
	v_rcp_f32_e32 v94, v87
	s_nop 0
	v_mul_f32_e32 v94, v83, v94
	s_nop 0
	v_rcp_f32_e32 v83, v86
	s_nop 0
	v_mul_f32_e32 v95, v82, v83
	v_mul_f32_e32 v83, 0x3d372713, v84
	v_mul_f32_e32 v83, v84, v83
	v_fma_f32 v83, v84, v83, v84
	v_mul_f32_e32 v83, 0xbfcc422a, v83
	v_mul_f32_e32 v83, 0x3fb8aa3b, v83
	v_mul_f32_e32 v82, 0x3d372713, v88
	v_exp_f32_e32 v86, v83
	v_mul_f32_e32 v83, 0x3d372713, v89
	v_mul_f32_e32 v82, v88, v82
	v_mul_f32_e32 v83, v89, v83
	v_fma_f32 v82, v88, v82, v88
	v_fma_f32 v83, v89, v83, v89
	v_mul_f32_e32 v82, 0xbfcc422a, v82
	v_mul_f32_e32 v83, 0xbfcc422a, v83
	v_mul_f32_e32 v82, 0x3fb8aa3b, v82
	v_mul_f32_e32 v83, 0x3fb8aa3b, v83
	v_exp_f32_e32 v82, v82
	v_exp_f32_e32 v83, v83
	s_nop 0
	v_pk_add_f32 v[82:83], v[82:83], 1.0 op_sel_hi:[1,0]
	s_nop 0
	s_nop 0
	v_rcp_f32_e32 v87, v83
	s_nop 0
	v_mul_f32_e32 v89, v89, v87
	s_nop 0
	v_rcp_f32_e32 v83, v82
	s_nop 0
	v_mul_f32_e32 v88, v88, v83
	v_mul_f32_e32 v82, 0x3d372713, v85
	v_mul_f32_e32 v82, v85, v82
	v_fma_f32 v82, v85, v82, v85
	v_mul_f32_e32 v82, 0xbfcc422a, v82
	v_mul_f32_e32 v82, 0x3fb8aa3b, v82
	v_exp_f32_e32 v87, v82
	s_nop 0
	v_pk_add_f32 v[82:83], v[86:87], 1.0 op_sel_hi:[1,0]
	s_nop 0
	s_nop 0
	v_rcp_f32_e32 v86, v83
	s_nop 0
	v_mul_f32_e32 v85, v85, v86
	s_nop 0
	v_rcp_f32_e32 v83, v82
	s_nop 0
	v_mul_f32_e32 v86, v84, v83
	v_cvt_pk_bf16_f32 v85, v86, v85
	v_lshl_add_u64 v[86:87], v[90:91], 0, v[114:115]
	v_lshl_add_u64 v[86:87], v[86:87], 0, s[10:11]
	v_cvt_pk_bf16_f32 v82, v92, v93
	v_cvt_pk_bf16_f32 v83, v88, v89
	v_cvt_pk_bf16_f32 v84, v95, v94
	v_lshl_add_u64 v[86:87], v[86:87], 0, v[48:49]
	global_store_dwordx4 v[86:87], v[82:85], off
	s_nop 1
	v_mul_f32_e32 v85, 0x3d372713, v74
	v_mul_f32_e32 v85, v74, v85
	v_fma_f32 v85, v74, v85, v74
	v_mul_f32_e32 v85, 0xbfcc422a, v85
	v_mul_f32_e32 v85, 0x3fb8aa3b, v85
	v_mul_f32_e32 v84, 0x3d372713, v78
	v_exp_f32_e32 v86, v85
	v_mul_f32_e32 v85, 0x3d372713, v79
	v_mul_f32_e32 v84, v78, v84
	v_mul_f32_e32 v85, v79, v85
	v_fma_f32 v84, v78, v84, v78
	v_fma_f32 v85, v79, v85, v79
	v_mul_f32_e32 v84, 0xbfcc422a, v84
	v_mul_f32_e32 v85, 0xbfcc422a, v85
	v_mul_f32_e32 v84, 0x3fb8aa3b, v84
	v_mul_f32_e32 v85, 0x3fb8aa3b, v85
	v_exp_f32_e32 v84, v84
	v_exp_f32_e32 v85, v85
	v_or_b32_e32 v82, 48, v142
	v_ashrrev_i32_e32 v83, 31, v82
	v_lshlrev_b64 v[82:83], 14, v[82:83]
	v_pk_add_f32 v[84:85], v[84:85], 1.0 op_sel_hi:[1,0]
	s_nop 0
	s_nop 0
	v_rcp_f32_e32 v87, v85
	s_nop 0
	v_mul_f32_e32 v85, v79, v87
	s_nop 0
	v_rcp_f32_e32 v79, v84
	s_nop 0
	v_mul_f32_e32 v84, v78, v79
	v_mul_f32_e32 v78, 0x3d372713, v75
	v_mul_f32_e32 v78, v75, v78
	v_fma_f32 v78, v75, v78, v75
	v_mul_f32_e32 v78, 0xbfcc422a, v78
	v_mul_f32_e32 v78, 0x3fb8aa3b, v78
	v_exp_f32_e32 v87, v78
	s_nop 0
	v_pk_add_f32 v[78:79], v[86:87], 1.0 op_sel_hi:[1,0]
	s_nop 0
	s_nop 0
	v_rcp_f32_e32 v86, v79
	s_nop 0
	v_mul_f32_e32 v86, v75, v86
	s_nop 0
	v_rcp_f32_e32 v75, v78
	s_nop 0
	v_mul_f32_e32 v87, v74, v75
	v_mul_f32_e32 v75, 0x3d372713, v76
	v_mul_f32_e32 v75, v76, v75
	v_fma_f32 v75, v76, v75, v76
	v_mul_f32_e32 v75, 0xbfcc422a, v75
	v_mul_f32_e32 v75, 0x3fb8aa3b, v75
	v_mul_f32_e32 v74, 0x3d372713, v80
	v_exp_f32_e32 v78, v75
	v_mul_f32_e32 v75, 0x3d372713, v81
	v_mul_f32_e32 v74, v80, v74
	v_mul_f32_e32 v75, v81, v75
	v_fma_f32 v74, v80, v74, v80
	v_fma_f32 v75, v81, v75, v81
	v_mul_f32_e32 v74, 0xbfcc422a, v74
	v_mul_f32_e32 v75, 0xbfcc422a, v75
	v_mul_f32_e32 v74, 0x3fb8aa3b, v74
	v_mul_f32_e32 v75, 0x3fb8aa3b, v75
	v_exp_f32_e32 v74, v74
	v_exp_f32_e32 v75, v75
	s_nop 0
	v_pk_add_f32 v[74:75], v[74:75], 1.0 op_sel_hi:[1,0]
	s_nop 0
	s_nop 0
	v_rcp_f32_e32 v79, v75
	s_nop 0
	v_mul_f32_e32 v81, v81, v79
	s_nop 0
	v_rcp_f32_e32 v75, v74
	s_nop 0
	v_mul_f32_e32 v80, v80, v75
	v_mul_f32_e32 v74, 0x3d372713, v77
	v_mul_f32_e32 v74, v77, v74
	v_fma_f32 v74, v77, v74, v77
	v_mul_f32_e32 v74, 0xbfcc422a, v74
	v_mul_f32_e32 v74, 0x3fb8aa3b, v74
	v_exp_f32_e32 v79, v74
	s_nop 0
	v_pk_add_f32 v[74:75], v[78:79], 1.0 op_sel_hi:[1,0]
	s_nop 0
	s_nop 0
	v_rcp_f32_e32 v78, v75
	s_nop 0
	v_mul_f32_e32 v75, v77, v78
	s_nop 0
	v_rcp_f32_e32 v77, v74
	s_nop 0
	v_mul_f32_e32 v74, v76, v77
	v_cvt_pk_bf16_f32 v79, v74, v75
	v_lshl_add_u64 v[74:75], s[0:1], 0, v[82:83]
	v_cvt_pk_bf16_f32 v77, v80, v81
	v_lshl_add_u64 v[80:81], v[74:75], 0, v[124:125]
	v_lshl_add_u64 v[80:81], v[80:81], 0, s[10:11]
	v_cvt_pk_bf16_f32 v76, v84, v85
	v_cvt_pk_bf16_f32 v78, v87, v86
	v_lshl_add_u64 v[80:81], v[80:81], 0, v[48:49]
	global_store_dwordx4 v[80:81], v[76:79], off
	s_nop 1
	v_mul_f32_e32 v77, 0x3d372713, v66
	v_mul_f32_e32 v77, v66, v77
	v_fma_f32 v77, v66, v77, v66
	v_mul_f32_e32 v77, 0xbfcc422a, v77
	v_mul_f32_e32 v77, 0x3fb8aa3b, v77
	v_mul_f32_e32 v76, 0x3d372713, v70
	v_exp_f32_e32 v78, v77
	v_mul_f32_e32 v77, 0x3d372713, v71
	v_mul_f32_e32 v76, v70, v76
	v_mul_f32_e32 v77, v71, v77
	v_fma_f32 v76, v70, v76, v70
	v_fma_f32 v77, v71, v77, v71
	v_mul_f32_e32 v76, 0xbfcc422a, v76
	v_mul_f32_e32 v77, 0xbfcc422a, v77
	v_mul_f32_e32 v76, 0x3fb8aa3b, v76
	v_mul_f32_e32 v77, 0x3fb8aa3b, v77
	v_exp_f32_e32 v76, v76
	v_exp_f32_e32 v77, v77
	s_nop 0
	v_pk_add_f32 v[76:77], v[76:77], 1.0 op_sel_hi:[1,0]
	s_nop 0
	s_nop 0
	v_rcp_f32_e32 v79, v77
	s_nop 0
	v_mul_f32_e32 v77, v71, v79
	s_nop 0
	v_rcp_f32_e32 v71, v76
	s_nop 0
	v_mul_f32_e32 v76, v70, v71
	v_mul_f32_e32 v70, 0x3d372713, v67
	v_mul_f32_e32 v70, v67, v70
	v_fma_f32 v70, v67, v70, v67
	v_mul_f32_e32 v70, 0xbfcc422a, v70
	v_mul_f32_e32 v70, 0x3fb8aa3b, v70
	v_exp_f32_e32 v79, v70
	s_nop 0
	v_pk_add_f32 v[70:71], v[78:79], 1.0 op_sel_hi:[1,0]
	s_nop 0
	s_nop 0
	v_rcp_f32_e32 v78, v71
	s_nop 0
	v_mul_f32_e32 v78, v67, v78
	s_nop 0
	v_rcp_f32_e32 v67, v70
	s_nop 0
	v_mul_f32_e32 v79, v66, v67
	v_mul_f32_e32 v67, 0x3d372713, v68
	v_mul_f32_e32 v67, v68, v67
	v_fma_f32 v67, v68, v67, v68
	v_mul_f32_e32 v67, 0xbfcc422a, v67
	v_mul_f32_e32 v67, 0x3fb8aa3b, v67
	v_mul_f32_e32 v66, 0x3d372713, v72
	v_exp_f32_e32 v70, v67
	v_mul_f32_e32 v67, 0x3d372713, v73
	v_mul_f32_e32 v66, v72, v66
	v_mul_f32_e32 v67, v73, v67
	v_fma_f32 v66, v72, v66, v72
	v_fma_f32 v67, v73, v67, v73
	v_mul_f32_e32 v66, 0xbfcc422a, v66
	v_mul_f32_e32 v67, 0xbfcc422a, v67
	v_mul_f32_e32 v66, 0x3fb8aa3b, v66
	v_mul_f32_e32 v67, 0x3fb8aa3b, v67
	v_exp_f32_e32 v66, v66
	v_exp_f32_e32 v67, v67
	s_nop 0
	v_pk_add_f32 v[66:67], v[66:67], 1.0 op_sel_hi:[1,0]
	s_nop 0
	s_nop 0
	v_rcp_f32_e32 v71, v67
	s_nop 0
	v_mul_f32_e32 v73, v73, v71
	s_nop 0
	v_rcp_f32_e32 v67, v66
	s_nop 0
	v_mul_f32_e32 v72, v72, v67
	v_mul_f32_e32 v66, 0x3d372713, v69
	v_mul_f32_e32 v66, v69, v66
	v_fma_f32 v66, v69, v66, v69
	v_mul_f32_e32 v66, 0xbfcc422a, v66
	v_mul_f32_e32 v66, 0x3fb8aa3b, v66
	v_exp_f32_e32 v71, v66
	s_nop 0
	v_pk_add_f32 v[66:67], v[70:71], 1.0 op_sel_hi:[1,0]
	s_nop 0
	s_nop 0
	v_rcp_f32_e32 v70, v67
	s_nop 0
	v_mul_f32_e32 v69, v69, v70
	s_nop 0
	v_rcp_f32_e32 v67, v66
	s_nop 0
	v_mul_f32_e32 v70, v68, v67
	v_cvt_pk_bf16_f32 v69, v70, v69
	v_lshl_add_u64 v[70:71], v[74:75], 0, v[114:115]
	v_lshl_add_u64 v[70:71], v[70:71], 0, s[10:11]
	v_cvt_pk_bf16_f32 v66, v76, v77
	v_cvt_pk_bf16_f32 v67, v72, v73
	v_cvt_pk_bf16_f32 v68, v79, v78
	v_lshl_add_u64 v[70:71], v[70:71], 0, v[48:49]
	global_store_dwordx4 v[70:71], v[66:69], off
	s_nop 1
	v_mul_f32_e32 v67, 0x3d372713, v58
	v_mul_f32_e32 v67, v58, v67
	v_fma_f32 v67, v58, v67, v58
	v_mul_f32_e32 v67, 0xbfcc422a, v67
	v_mul_f32_e32 v67, 0x3fb8aa3b, v67
	v_mul_f32_e32 v66, 0x3d372713, v62
	v_exp_f32_e32 v68, v67
	v_mul_f32_e32 v67, 0x3d372713, v63
	v_mul_f32_e32 v66, v62, v66
	v_mul_f32_e32 v67, v63, v67
	v_fma_f32 v66, v62, v66, v62
	v_fma_f32 v67, v63, v67, v63
	v_mul_f32_e32 v66, 0xbfcc422a, v66
	v_mul_f32_e32 v67, 0xbfcc422a, v67
	v_mul_f32_e32 v66, 0x3fb8aa3b, v66
	v_mul_f32_e32 v67, 0x3fb8aa3b, v67
	v_exp_f32_e32 v66, v66
	v_exp_f32_e32 v67, v67
	s_nop 0
	v_pk_add_f32 v[66:67], v[66:67], 1.0 op_sel_hi:[1,0]
	s_nop 0
	s_nop 0
	v_rcp_f32_e32 v69, v67
	s_nop 0
	v_mul_f32_e32 v67, v63, v69
	s_nop 0
	v_rcp_f32_e32 v63, v66
	s_nop 0
	v_mul_f32_e32 v66, v62, v63
	v_mul_f32_e32 v62, 0x3d372713, v59
	v_mul_f32_e32 v62, v59, v62
	v_fma_f32 v62, v59, v62, v59
	v_mul_f32_e32 v62, 0xbfcc422a, v62
	v_mul_f32_e32 v62, 0x3fb8aa3b, v62
	v_exp_f32_e32 v69, v62
	s_nop 0
	v_pk_add_f32 v[62:63], v[68:69], 1.0 op_sel_hi:[1,0]
	s_nop 0
	s_nop 0
	v_rcp_f32_e32 v68, v63
	s_nop 0
	v_mul_f32_e32 v68, v59, v68
	s_nop 0
	v_rcp_f32_e32 v59, v62
	s_nop 0
	v_mul_f32_e32 v69, v58, v59
	v_mul_f32_e32 v59, 0x3d372713, v60
	v_mul_f32_e32 v59, v60, v59
	v_fma_f32 v59, v60, v59, v60
	v_mul_f32_e32 v59, 0xbfcc422a, v59
	v_mul_f32_e32 v59, 0x3fb8aa3b, v59
	v_mul_f32_e32 v58, 0x3d372713, v64
	v_exp_f32_e32 v62, v59
	v_mul_f32_e32 v59, 0x3d372713, v65
	v_mul_f32_e32 v58, v64, v58
	v_mul_f32_e32 v59, v65, v59
	v_fma_f32 v58, v64, v58, v64
	v_fma_f32 v59, v65, v59, v65
	v_mul_f32_e32 v58, 0xbfcc422a, v58
	v_mul_f32_e32 v59, 0xbfcc422a, v59
	v_mul_f32_e32 v58, 0x3fb8aa3b, v58
	v_mul_f32_e32 v59, 0x3fb8aa3b, v59
	v_exp_f32_e32 v58, v58
	v_exp_f32_e32 v59, v59
	s_nop 0
	v_pk_add_f32 v[58:59], v[58:59], 1.0 op_sel_hi:[1,0]
	s_nop 0
	s_nop 0
	v_rcp_f32_e32 v63, v59
	s_nop 0
	v_mul_f32_e32 v65, v65, v63
	s_nop 0
	v_rcp_f32_e32 v59, v58
	s_nop 0
	v_mul_f32_e32 v64, v64, v59
	v_mul_f32_e32 v58, 0x3d372713, v61
	v_mul_f32_e32 v58, v61, v58
	v_fma_f32 v58, v61, v58, v61
	v_mul_f32_e32 v58, 0xbfcc422a, v58
	v_mul_f32_e32 v58, 0x3fb8aa3b, v58
	v_exp_f32_e32 v63, v58
	s_nop 0
	v_pk_add_f32 v[58:59], v[62:63], 1.0 op_sel_hi:[1,0]
	s_nop 0
	s_nop 0
	v_rcp_f32_e32 v62, v59
	s_nop 0
	v_mul_f32_e32 v59, v61, v62
	s_mov_b64 s[12:13], 0x200000
	v_rcp_f32_e32 v61, v58
	s_nop 0
	v_mul_f32_e32 v58, v60, v61
	v_cvt_pk_bf16_f32 v63, v58, v59
	v_lshl_add_u64 v[58:59], v[122:123], 0, s[12:13]
	v_cvt_pk_bf16_f32 v61, v64, v65
	v_lshl_add_u64 v[64:65], v[58:59], 0, v[124:125]
	v_lshl_add_u64 v[64:65], v[64:65], 0, s[10:11]
	v_cvt_pk_bf16_f32 v60, v66, v67
	v_cvt_pk_bf16_f32 v62, v69, v68
	v_lshl_add_u64 v[64:65], v[64:65], 0, v[48:49]
	global_store_dwordx4 v[64:65], v[60:63], off
	s_nop 1
	v_mul_f32_e32 v61, 0x3d372713, v50
	v_mul_f32_e32 v61, v50, v61
	v_fma_f32 v61, v50, v61, v50
	v_mul_f32_e32 v61, 0xbfcc422a, v61
	v_mul_f32_e32 v61, 0x3fb8aa3b, v61
	v_mul_f32_e32 v60, 0x3d372713, v54
	v_exp_f32_e32 v62, v61
	v_mul_f32_e32 v61, 0x3d372713, v55
	v_mul_f32_e32 v60, v54, v60
	v_mul_f32_e32 v61, v55, v61
	v_fma_f32 v60, v54, v60, v54
	v_fma_f32 v61, v55, v61, v55
	v_mul_f32_e32 v60, 0xbfcc422a, v60
	v_mul_f32_e32 v61, 0xbfcc422a, v61
	v_mul_f32_e32 v60, 0x3fb8aa3b, v60
	v_mul_f32_e32 v61, 0x3fb8aa3b, v61
	v_exp_f32_e32 v60, v60
	v_exp_f32_e32 v61, v61
	s_nop 0
	v_pk_add_f32 v[60:61], v[60:61], 1.0 op_sel_hi:[1,0]
	s_nop 0
	s_nop 0
	v_rcp_f32_e32 v63, v61
	s_nop 0
	v_mul_f32_e32 v61, v55, v63
	s_nop 0
	v_rcp_f32_e32 v55, v60
	s_nop 0
	v_mul_f32_e32 v60, v54, v55
	v_mul_f32_e32 v54, 0x3d372713, v51
	v_mul_f32_e32 v54, v51, v54
	v_fma_f32 v54, v51, v54, v51
	v_mul_f32_e32 v54, 0xbfcc422a, v54
	v_mul_f32_e32 v54, 0x3fb8aa3b, v54
	v_exp_f32_e32 v63, v54
	s_nop 0
	v_pk_add_f32 v[54:55], v[62:63], 1.0 op_sel_hi:[1,0]
	s_nop 0
	s_nop 0
	v_rcp_f32_e32 v62, v55
	s_nop 0
	v_mul_f32_e32 v62, v51, v62
	s_nop 0
	v_rcp_f32_e32 v51, v54
	s_nop 0
	v_mul_f32_e32 v63, v50, v51
	v_mul_f32_e32 v51, 0x3d372713, v52
	v_mul_f32_e32 v51, v52, v51
	v_fma_f32 v51, v52, v51, v52
	v_mul_f32_e32 v51, 0xbfcc422a, v51
	v_mul_f32_e32 v51, 0x3fb8aa3b, v51
	v_mul_f32_e32 v50, 0x3d372713, v56
	v_exp_f32_e32 v54, v51
	v_mul_f32_e32 v51, 0x3d372713, v57
	v_mul_f32_e32 v50, v56, v50
	v_mul_f32_e32 v51, v57, v51
	v_fma_f32 v50, v56, v50, v56
	v_fma_f32 v51, v57, v51, v57
	v_mul_f32_e32 v50, 0xbfcc422a, v50
	v_mul_f32_e32 v51, 0xbfcc422a, v51
	v_mul_f32_e32 v50, 0x3fb8aa3b, v50
	v_mul_f32_e32 v51, 0x3fb8aa3b, v51
	v_exp_f32_e32 v50, v50
	v_exp_f32_e32 v51, v51
	s_nop 0
	v_pk_add_f32 v[50:51], v[50:51], 1.0 op_sel_hi:[1,0]
	s_nop 0
	s_nop 0
	v_rcp_f32_e32 v55, v51
	s_nop 0
	v_mul_f32_e32 v57, v57, v55
	s_nop 0
	v_rcp_f32_e32 v51, v50
	s_nop 0
	v_mul_f32_e32 v56, v56, v51
	v_mul_f32_e32 v50, 0x3d372713, v53
	v_mul_f32_e32 v50, v53, v50
	v_fma_f32 v50, v53, v50, v53
	v_mul_f32_e32 v50, 0xbfcc422a, v50
	v_mul_f32_e32 v50, 0x3fb8aa3b, v50
	v_exp_f32_e32 v55, v50
	s_nop 0
	v_pk_add_f32 v[50:51], v[54:55], 1.0 op_sel_hi:[1,0]
	s_nop 0
	s_nop 0
	v_rcp_f32_e32 v54, v51
	s_nop 0
	v_mul_f32_e32 v53, v53, v54
	s_nop 0
	v_rcp_f32_e32 v51, v50
	s_nop 0
	v_mul_f32_e32 v54, v52, v51
	v_cvt_pk_bf16_f32 v53, v54, v53
	v_lshl_add_u64 v[54:55], v[58:59], 0, v[114:115]
	v_lshl_add_u64 v[54:55], v[54:55], 0, s[10:11]
	v_cvt_pk_bf16_f32 v50, v60, v61
	v_cvt_pk_bf16_f32 v51, v56, v57
	v_cvt_pk_bf16_f32 v52, v63, v62
	v_lshl_add_u64 v[54:55], v[54:55], 0, v[48:49]
	global_store_dwordx4 v[54:55], v[50:53], off
	s_nop 1
	v_mul_f32_e32 v51, 0x3d372713, v40
	v_mul_f32_e32 v51, v40, v51
	v_fma_f32 v51, v40, v51, v40
	v_mul_f32_e32 v51, 0xbfcc422a, v51
	v_mul_f32_e32 v51, 0x3fb8aa3b, v51
	v_mul_f32_e32 v50, 0x3d372713, v44
	v_exp_f32_e32 v52, v51
	v_mul_f32_e32 v51, 0x3d372713, v45
	v_mul_f32_e32 v50, v44, v50
	v_mul_f32_e32 v51, v45, v51
	v_fma_f32 v50, v44, v50, v44
	v_fma_f32 v51, v45, v51, v45
	v_mul_f32_e32 v50, 0xbfcc422a, v50
	v_mul_f32_e32 v51, 0xbfcc422a, v51
	v_mul_f32_e32 v50, 0x3fb8aa3b, v50
	v_mul_f32_e32 v51, 0x3fb8aa3b, v51
	v_exp_f32_e32 v50, v50
	v_exp_f32_e32 v51, v51
	s_nop 0
	v_pk_add_f32 v[50:51], v[50:51], 1.0 op_sel_hi:[1,0]
	s_nop 0
	s_nop 0
	v_rcp_f32_e32 v53, v51
	s_nop 0
	v_mul_f32_e32 v51, v45, v53
	s_nop 0
	v_rcp_f32_e32 v45, v50
	s_nop 0
	v_mul_f32_e32 v50, v44, v45
	v_mul_f32_e32 v44, 0x3d372713, v41
	v_mul_f32_e32 v44, v41, v44
	v_fma_f32 v44, v41, v44, v41
	v_mul_f32_e32 v44, 0xbfcc422a, v44
	v_mul_f32_e32 v44, 0x3fb8aa3b, v44
	v_exp_f32_e32 v53, v44
	s_nop 0
	v_pk_add_f32 v[44:45], v[52:53], 1.0 op_sel_hi:[1,0]
	s_nop 0
	s_nop 0
	v_rcp_f32_e32 v52, v45
	s_nop 0
	v_mul_f32_e32 v52, v41, v52
	s_nop 0
	v_rcp_f32_e32 v41, v44
	s_nop 0
	v_mul_f32_e32 v53, v40, v41
	v_mul_f32_e32 v41, 0x3d372713, v42
	v_mul_f32_e32 v41, v42, v41
	v_fma_f32 v41, v42, v41, v42
	v_mul_f32_e32 v41, 0xbfcc422a, v41
	v_mul_f32_e32 v41, 0x3fb8aa3b, v41
	v_mul_f32_e32 v40, 0x3d372713, v46
	v_exp_f32_e32 v44, v41
	v_mul_f32_e32 v41, 0x3d372713, v47
	v_mul_f32_e32 v40, v46, v40
	v_mul_f32_e32 v41, v47, v41
	v_fma_f32 v40, v46, v40, v46
	v_fma_f32 v41, v47, v41, v47
	v_mul_f32_e32 v40, 0xbfcc422a, v40
	v_mul_f32_e32 v41, 0xbfcc422a, v41
	v_mul_f32_e32 v40, 0x3fb8aa3b, v40
	v_mul_f32_e32 v41, 0x3fb8aa3b, v41
	v_exp_f32_e32 v40, v40
	v_exp_f32_e32 v41, v41
	s_nop 0
	v_pk_add_f32 v[40:41], v[40:41], 1.0 op_sel_hi:[1,0]
	s_nop 0
	s_nop 0
	v_rcp_f32_e32 v45, v41
	s_nop 0
	v_mul_f32_e32 v47, v47, v45
	s_nop 0
	v_rcp_f32_e32 v41, v40
	s_nop 0
	v_mul_f32_e32 v46, v46, v41
	v_mul_f32_e32 v40, 0x3d372713, v43
	v_mul_f32_e32 v40, v43, v40
	v_fma_f32 v40, v43, v40, v43
	v_mul_f32_e32 v40, 0xbfcc422a, v40
	v_mul_f32_e32 v40, 0x3fb8aa3b, v40
	v_exp_f32_e32 v45, v40
	s_nop 0
	v_pk_add_f32 v[40:41], v[44:45], 1.0 op_sel_hi:[1,0]
	s_nop 0
	s_nop 0
	v_rcp_f32_e32 v44, v41
	s_nop 0
	v_mul_f32_e32 v41, v43, v44
	s_mov_b64 s[12:13], 0x240000
	v_rcp_f32_e32 v43, v40
	s_nop 0
	v_mul_f32_e32 v40, v42, v43
	v_cvt_pk_bf16_f32 v45, v40, v41
	v_lshl_add_u64 v[40:41], v[122:123], 0, s[12:13]
	v_cvt_pk_bf16_f32 v43, v46, v47
	v_lshl_add_u64 v[46:47], v[40:41], 0, v[124:125]
	v_lshl_add_u64 v[46:47], v[46:47], 0, s[10:11]
	v_cvt_pk_bf16_f32 v42, v50, v51
	v_cvt_pk_bf16_f32 v44, v53, v52
	v_lshl_add_u64 v[46:47], v[46:47], 0, v[48:49]
	global_store_dwordx4 v[46:47], v[42:45], off
	s_nop 1
	v_mul_f32_e32 v43, 0x3d372713, v32
	v_mul_f32_e32 v43, v32, v43
	v_fma_f32 v43, v32, v43, v32
	v_mul_f32_e32 v43, 0xbfcc422a, v43
	v_mul_f32_e32 v43, 0x3fb8aa3b, v43
	v_mul_f32_e32 v42, 0x3d372713, v36
	v_exp_f32_e32 v44, v43
	v_mul_f32_e32 v43, 0x3d372713, v37
	v_mul_f32_e32 v42, v36, v42
	v_mul_f32_e32 v43, v37, v43
	v_fma_f32 v42, v36, v42, v36
	v_fma_f32 v43, v37, v43, v37
	v_mul_f32_e32 v42, 0xbfcc422a, v42
	v_mul_f32_e32 v43, 0xbfcc422a, v43
	v_mul_f32_e32 v42, 0x3fb8aa3b, v42
	v_mul_f32_e32 v43, 0x3fb8aa3b, v43
	v_exp_f32_e32 v42, v42
	v_exp_f32_e32 v43, v43
	s_nop 0
	v_pk_add_f32 v[42:43], v[42:43], 1.0 op_sel_hi:[1,0]
	s_nop 0
	s_nop 0
	v_rcp_f32_e32 v45, v43
	s_nop 0
	v_mul_f32_e32 v43, v37, v45
	s_nop 0
	v_rcp_f32_e32 v37, v42
	s_nop 0
	v_mul_f32_e32 v42, v36, v37
	v_mul_f32_e32 v36, 0x3d372713, v33
	v_mul_f32_e32 v36, v33, v36
	v_fma_f32 v36, v33, v36, v33
	v_mul_f32_e32 v36, 0xbfcc422a, v36
	v_mul_f32_e32 v36, 0x3fb8aa3b, v36
	v_exp_f32_e32 v45, v36
	s_nop 0
	v_pk_add_f32 v[36:37], v[44:45], 1.0 op_sel_hi:[1,0]
	s_nop 0
	s_nop 0
	v_rcp_f32_e32 v44, v37
	s_nop 0
	v_mul_f32_e32 v44, v33, v44
	s_nop 0
	v_rcp_f32_e32 v33, v36
	s_nop 0
	v_mul_f32_e32 v45, v32, v33
	v_mul_f32_e32 v33, 0x3d372713, v34
	v_mul_f32_e32 v33, v34, v33
	v_fma_f32 v33, v34, v33, v34
	v_mul_f32_e32 v33, 0xbfcc422a, v33
	v_mul_f32_e32 v33, 0x3fb8aa3b, v33
	v_mul_f32_e32 v32, 0x3d372713, v38
	v_exp_f32_e32 v36, v33
	v_mul_f32_e32 v33, 0x3d372713, v39
	v_mul_f32_e32 v32, v38, v32
	v_mul_f32_e32 v33, v39, v33
	v_fma_f32 v32, v38, v32, v38
	v_fma_f32 v33, v39, v33, v39
	v_mul_f32_e32 v32, 0xbfcc422a, v32
	v_mul_f32_e32 v33, 0xbfcc422a, v33
	v_mul_f32_e32 v32, 0x3fb8aa3b, v32
	v_mul_f32_e32 v33, 0x3fb8aa3b, v33
	v_exp_f32_e32 v32, v32
	v_exp_f32_e32 v33, v33
	s_nop 0
	v_pk_add_f32 v[32:33], v[32:33], 1.0 op_sel_hi:[1,0]
	s_nop 0
	s_nop 0
	v_rcp_f32_e32 v37, v33
	s_nop 0
	v_mul_f32_e32 v39, v39, v37
	s_nop 0
	v_rcp_f32_e32 v33, v32
	s_nop 0
	v_mul_f32_e32 v38, v38, v33
	v_mul_f32_e32 v32, 0x3d372713, v35
	v_mul_f32_e32 v32, v35, v32
	v_fma_f32 v32, v35, v32, v35
	v_mul_f32_e32 v32, 0xbfcc422a, v32
	v_mul_f32_e32 v32, 0x3fb8aa3b, v32
	v_exp_f32_e32 v37, v32
	s_nop 0
	v_pk_add_f32 v[32:33], v[36:37], 1.0 op_sel_hi:[1,0]
	s_nop 0
	s_nop 0
	v_rcp_f32_e32 v36, v33
	s_nop 0
	v_mul_f32_e32 v35, v35, v36
	s_nop 0
	v_rcp_f32_e32 v33, v32
	s_nop 0
	v_mul_f32_e32 v36, v34, v33
	v_cvt_pk_bf16_f32 v35, v36, v35
	v_lshl_add_u64 v[36:37], v[40:41], 0, v[114:115]
	v_lshl_add_u64 v[36:37], v[36:37], 0, s[10:11]
	v_cvt_pk_bf16_f32 v32, v42, v43
	v_cvt_pk_bf16_f32 v33, v38, v39
	v_cvt_pk_bf16_f32 v34, v45, v44
	v_lshl_add_u64 v[36:37], v[36:37], 0, v[48:49]
	global_store_dwordx4 v[36:37], v[32:35], off
	s_nop 1
	v_mul_f32_e32 v33, 0x3d372713, v24
	v_mul_f32_e32 v33, v24, v33
	v_fma_f32 v33, v24, v33, v24
	v_mul_f32_e32 v33, 0xbfcc422a, v33
	v_mul_f32_e32 v33, 0x3fb8aa3b, v33
	v_mul_f32_e32 v32, 0x3d372713, v28
	v_exp_f32_e32 v34, v33
	v_mul_f32_e32 v33, 0x3d372713, v29
	v_mul_f32_e32 v32, v28, v32
	v_mul_f32_e32 v33, v29, v33
	v_fma_f32 v32, v28, v32, v28
	v_fma_f32 v33, v29, v33, v29
	v_mul_f32_e32 v32, 0xbfcc422a, v32
	v_mul_f32_e32 v33, 0xbfcc422a, v33
	v_mul_f32_e32 v32, 0x3fb8aa3b, v32
	v_mul_f32_e32 v33, 0x3fb8aa3b, v33
	v_exp_f32_e32 v32, v32
	v_exp_f32_e32 v33, v33
	s_nop 0
	v_pk_add_f32 v[32:33], v[32:33], 1.0 op_sel_hi:[1,0]
	s_nop 0
	s_nop 0
	v_rcp_f32_e32 v35, v33
	s_nop 0
	v_mul_f32_e32 v33, v29, v35
	s_nop 0
	v_rcp_f32_e32 v29, v32
	s_nop 0
	v_mul_f32_e32 v32, v28, v29
	v_mul_f32_e32 v28, 0x3d372713, v25
	v_mul_f32_e32 v28, v25, v28
	v_fma_f32 v28, v25, v28, v25
	v_mul_f32_e32 v28, 0xbfcc422a, v28
	v_mul_f32_e32 v28, 0x3fb8aa3b, v28
	v_exp_f32_e32 v35, v28
	s_nop 0
	v_pk_add_f32 v[28:29], v[34:35], 1.0 op_sel_hi:[1,0]
	s_nop 0
	s_nop 0
	v_rcp_f32_e32 v34, v29
	s_nop 0
	v_mul_f32_e32 v34, v25, v34
	s_nop 0
	v_rcp_f32_e32 v25, v28
	s_nop 0
	v_mul_f32_e32 v35, v24, v25
	v_mul_f32_e32 v25, 0x3d372713, v26
	v_mul_f32_e32 v25, v26, v25
	v_fma_f32 v25, v26, v25, v26
	v_mul_f32_e32 v25, 0xbfcc422a, v25
	v_mul_f32_e32 v25, 0x3fb8aa3b, v25
	v_mul_f32_e32 v24, 0x3d372713, v30
	v_exp_f32_e32 v28, v25
	v_mul_f32_e32 v25, 0x3d372713, v31
	v_mul_f32_e32 v24, v30, v24
	v_mul_f32_e32 v25, v31, v25
	v_fma_f32 v24, v30, v24, v30
	v_fma_f32 v25, v31, v25, v31
	v_mul_f32_e32 v24, 0xbfcc422a, v24
	v_mul_f32_e32 v25, 0xbfcc422a, v25
	v_mul_f32_e32 v24, 0x3fb8aa3b, v24
	v_mul_f32_e32 v25, 0x3fb8aa3b, v25
	v_exp_f32_e32 v24, v24
	v_exp_f32_e32 v25, v25
	s_nop 0
	v_pk_add_f32 v[24:25], v[24:25], 1.0 op_sel_hi:[1,0]
	s_nop 0
	s_nop 0
	v_rcp_f32_e32 v29, v25
	s_nop 0
	v_mul_f32_e32 v31, v31, v29
	s_nop 0
	v_rcp_f32_e32 v25, v24
	s_nop 0
	v_mul_f32_e32 v30, v30, v25
	v_mul_f32_e32 v24, 0x3d372713, v27
	v_mul_f32_e32 v24, v27, v24
	v_fma_f32 v24, v27, v24, v27
	v_mul_f32_e32 v24, 0xbfcc422a, v24
	v_mul_f32_e32 v24, 0x3fb8aa3b, v24
	v_exp_f32_e32 v29, v24
	s_nop 0
	v_pk_add_f32 v[24:25], v[28:29], 1.0 op_sel_hi:[1,0]
	s_nop 0
	s_nop 0
	v_rcp_f32_e32 v28, v25
	s_nop 0
	v_mul_f32_e32 v25, v27, v28
	s_mov_b64 s[12:13], 0x280000
	v_rcp_f32_e32 v27, v24
	s_nop 0
	v_mul_f32_e32 v24, v26, v27
	v_cvt_pk_bf16_f32 v29, v24, v25
	v_lshl_add_u64 v[24:25], v[122:123], 0, s[12:13]
	v_cvt_pk_bf16_f32 v27, v30, v31
	v_lshl_add_u64 v[30:31], v[24:25], 0, v[124:125]
	v_lshl_add_u64 v[30:31], v[30:31], 0, s[10:11]
	v_cvt_pk_bf16_f32 v26, v32, v33
	v_cvt_pk_bf16_f32 v28, v35, v34
	v_lshl_add_u64 v[30:31], v[30:31], 0, v[48:49]
	global_store_dwordx4 v[30:31], v[26:29], off
	s_nop 1
	v_mul_f32_e32 v27, 0x3d372713, v16
	v_mul_f32_e32 v27, v16, v27
	v_fma_f32 v27, v16, v27, v16
	v_mul_f32_e32 v27, 0xbfcc422a, v27
	v_mul_f32_e32 v27, 0x3fb8aa3b, v27
	v_mul_f32_e32 v26, 0x3d372713, v20
	v_exp_f32_e32 v28, v27
	v_mul_f32_e32 v27, 0x3d372713, v21
	v_mul_f32_e32 v26, v20, v26
	v_mul_f32_e32 v27, v21, v27
	v_fma_f32 v26, v20, v26, v20
	v_fma_f32 v27, v21, v27, v21
	v_mul_f32_e32 v26, 0xbfcc422a, v26
	v_mul_f32_e32 v27, 0xbfcc422a, v27
	v_mul_f32_e32 v26, 0x3fb8aa3b, v26
	v_mul_f32_e32 v27, 0x3fb8aa3b, v27
	v_exp_f32_e32 v26, v26
	v_exp_f32_e32 v27, v27
	s_nop 0
	v_pk_add_f32 v[26:27], v[26:27], 1.0 op_sel_hi:[1,0]
	s_nop 0
	s_nop 0
	v_rcp_f32_e32 v29, v27
	s_nop 0
	v_mul_f32_e32 v27, v21, v29
	s_nop 0
	v_rcp_f32_e32 v21, v26
	s_nop 0
	v_mul_f32_e32 v26, v20, v21
	v_mul_f32_e32 v20, 0x3d372713, v17
	v_mul_f32_e32 v20, v17, v20
	v_fma_f32 v20, v17, v20, v17
	v_mul_f32_e32 v20, 0xbfcc422a, v20
	v_mul_f32_e32 v20, 0x3fb8aa3b, v20
	v_exp_f32_e32 v29, v20
	s_nop 0
	v_pk_add_f32 v[20:21], v[28:29], 1.0 op_sel_hi:[1,0]
	s_nop 0
	s_nop 0
	v_rcp_f32_e32 v28, v21
	s_nop 0
	v_mul_f32_e32 v28, v17, v28
	s_nop 0
	v_rcp_f32_e32 v17, v20
	s_nop 0
	v_mul_f32_e32 v29, v16, v17
	v_mul_f32_e32 v17, 0x3d372713, v18
	v_mul_f32_e32 v17, v18, v17
	v_fma_f32 v17, v18, v17, v18
	v_mul_f32_e32 v17, 0xbfcc422a, v17
	v_mul_f32_e32 v17, 0x3fb8aa3b, v17
	v_mul_f32_e32 v16, 0x3d372713, v22
	v_exp_f32_e32 v20, v17
	v_mul_f32_e32 v17, 0x3d372713, v23
	v_mul_f32_e32 v16, v22, v16
	v_mul_f32_e32 v17, v23, v17
	v_fma_f32 v16, v22, v16, v22
	v_fma_f32 v17, v23, v17, v23
	v_mul_f32_e32 v16, 0xbfcc422a, v16
	v_mul_f32_e32 v17, 0xbfcc422a, v17
	v_mul_f32_e32 v16, 0x3fb8aa3b, v16
	v_mul_f32_e32 v17, 0x3fb8aa3b, v17
	v_exp_f32_e32 v16, v16
	v_exp_f32_e32 v17, v17
	s_nop 0
	v_pk_add_f32 v[16:17], v[16:17], 1.0 op_sel_hi:[1,0]
	s_nop 0
	s_nop 0
	v_rcp_f32_e32 v21, v17
	s_nop 0
	v_mul_f32_e32 v23, v23, v21
	s_nop 0
	v_rcp_f32_e32 v17, v16
	s_nop 0
	v_mul_f32_e32 v22, v22, v17
	v_mul_f32_e32 v16, 0x3d372713, v19
	v_mul_f32_e32 v16, v19, v16
	v_fma_f32 v16, v19, v16, v19
	v_mul_f32_e32 v16, 0xbfcc422a, v16
	v_mul_f32_e32 v16, 0x3fb8aa3b, v16
	v_exp_f32_e32 v21, v16
	s_nop 0
	v_pk_add_f32 v[16:17], v[20:21], 1.0 op_sel_hi:[1,0]
	s_nop 0
	s_nop 0
	v_rcp_f32_e32 v20, v17
	s_nop 0
	v_mul_f32_e32 v19, v19, v20
	s_nop 0
	v_rcp_f32_e32 v17, v16
	s_nop 0
	v_mul_f32_e32 v20, v18, v17
	v_cvt_pk_bf16_f32 v19, v20, v19
	v_lshl_add_u64 v[20:21], v[24:25], 0, v[114:115]
	v_lshl_add_u64 v[20:21], v[20:21], 0, s[10:11]
	v_cvt_pk_bf16_f32 v16, v26, v27
	v_cvt_pk_bf16_f32 v17, v22, v23
	v_cvt_pk_bf16_f32 v18, v29, v28
	v_lshl_add_u64 v[20:21], v[20:21], 0, v[48:49]
	global_store_dwordx4 v[20:21], v[16:19], off
	s_nop 1
	v_mul_f32_e32 v17, 0x3d372713, v8
	v_mul_f32_e32 v17, v8, v17
	v_fma_f32 v17, v8, v17, v8
	v_mul_f32_e32 v17, 0xbfcc422a, v17
	v_mul_f32_e32 v17, 0x3fb8aa3b, v17
	v_mul_f32_e32 v16, 0x3d372713, v12
	v_exp_f32_e32 v18, v17
	v_mul_f32_e32 v17, 0x3d372713, v13
	v_mul_f32_e32 v16, v12, v16
	v_mul_f32_e32 v17, v13, v17
	v_fma_f32 v16, v12, v16, v12
	v_fma_f32 v17, v13, v17, v13
	v_mul_f32_e32 v16, 0xbfcc422a, v16
	v_mul_f32_e32 v17, 0xbfcc422a, v17
	v_mul_f32_e32 v16, 0x3fb8aa3b, v16
	v_mul_f32_e32 v17, 0x3fb8aa3b, v17
	v_exp_f32_e32 v16, v16
	v_exp_f32_e32 v17, v17
	s_nop 0
	v_pk_add_f32 v[16:17], v[16:17], 1.0 op_sel_hi:[1,0]
	s_nop 0
	s_nop 0
	v_rcp_f32_e32 v19, v17
	s_nop 0
	v_mul_f32_e32 v17, v13, v19
	s_nop 0
	v_rcp_f32_e32 v13, v16
	s_nop 0
	v_mul_f32_e32 v16, v12, v13
	v_mul_f32_e32 v12, 0x3d372713, v9
	v_mul_f32_e32 v12, v9, v12
	v_fma_f32 v12, v9, v12, v9
	v_mul_f32_e32 v12, 0xbfcc422a, v12
	v_mul_f32_e32 v12, 0x3fb8aa3b, v12
	v_exp_f32_e32 v19, v12
	s_nop 0
	v_pk_add_f32 v[12:13], v[18:19], 1.0 op_sel_hi:[1,0]
	s_nop 0
	s_nop 0
	v_rcp_f32_e32 v18, v13
	s_nop 0
	v_mul_f32_e32 v18, v9, v18
	s_nop 0
	v_rcp_f32_e32 v9, v12
	s_nop 0
	v_mul_f32_e32 v19, v8, v9
	v_mul_f32_e32 v9, 0x3d372713, v10
	v_mul_f32_e32 v9, v10, v9
	v_fma_f32 v9, v10, v9, v10
	v_mul_f32_e32 v9, 0xbfcc422a, v9
	v_mul_f32_e32 v9, 0x3fb8aa3b, v9
	v_mul_f32_e32 v8, 0x3d372713, v14
	v_exp_f32_e32 v12, v9
	v_mul_f32_e32 v9, 0x3d372713, v15
	v_mul_f32_e32 v8, v14, v8
	v_mul_f32_e32 v9, v15, v9
	v_fma_f32 v8, v14, v8, v14
	v_fma_f32 v9, v15, v9, v15
	v_mul_f32_e32 v8, 0xbfcc422a, v8
	v_mul_f32_e32 v9, 0xbfcc422a, v9
	v_mul_f32_e32 v8, 0x3fb8aa3b, v8
	v_mul_f32_e32 v9, 0x3fb8aa3b, v9
	v_exp_f32_e32 v8, v8
	v_exp_f32_e32 v9, v9
	s_nop 0
	v_pk_add_f32 v[8:9], v[8:9], 1.0 op_sel_hi:[1,0]
	s_nop 0
	s_nop 0
	v_rcp_f32_e32 v13, v9
	s_nop 0
	v_mul_f32_e32 v15, v15, v13
	s_nop 0
	v_rcp_f32_e32 v9, v8
	s_nop 0
	v_mul_f32_e32 v14, v14, v9
	v_mul_f32_e32 v8, 0x3d372713, v11
	v_mul_f32_e32 v8, v11, v8
	v_fma_f32 v8, v11, v8, v11
	v_mul_f32_e32 v8, 0xbfcc422a, v8
	v_mul_f32_e32 v8, 0x3fb8aa3b, v8
	v_exp_f32_e32 v13, v8
	s_nop 0
	v_pk_add_f32 v[8:9], v[12:13], 1.0 op_sel_hi:[1,0]
	s_nop 0
	s_nop 0
	v_rcp_f32_e32 v12, v9
	s_nop 0
	v_mul_f32_e32 v9, v11, v12
	s_mov_b64 s[12:13], 0x2c0000
	v_rcp_f32_e32 v11, v8
	s_nop 0
	v_mul_f32_e32 v8, v10, v11
	v_cvt_pk_bf16_f32 v13, v8, v9
	v_lshl_add_u64 v[8:9], v[122:123], 0, s[12:13]
	v_cvt_pk_bf16_f32 v11, v14, v15
	v_lshl_add_u64 v[14:15], v[8:9], 0, v[124:125]
	v_lshl_add_u64 v[14:15], v[14:15], 0, s[10:11]
	v_cvt_pk_bf16_f32 v10, v16, v17
	v_cvt_pk_bf16_f32 v12, v19, v18
	v_lshl_add_u64 v[14:15], v[14:15], 0, v[48:49]
	global_store_dwordx4 v[14:15], v[10:13], off
	s_nop 1
	v_mul_f32_e32 v11, 0x3d372713, v0
	v_mul_f32_e32 v11, v0, v11
	v_fma_f32 v11, v0, v11, v0
	v_mul_f32_e32 v11, 0xbfcc422a, v11
	v_mul_f32_e32 v11, 0x3fb8aa3b, v11
	v_mul_f32_e32 v10, 0x3d372713, v4
	v_exp_f32_e32 v12, v11
	v_mul_f32_e32 v11, 0x3d372713, v5
	v_mul_f32_e32 v10, v4, v10
	v_mul_f32_e32 v11, v5, v11
	v_fma_f32 v10, v4, v10, v4
	v_fma_f32 v11, v5, v11, v5
	v_mul_f32_e32 v10, 0xbfcc422a, v10
	v_mul_f32_e32 v11, 0xbfcc422a, v11
	v_mul_f32_e32 v10, 0x3fb8aa3b, v10
	v_mul_f32_e32 v11, 0x3fb8aa3b, v11
	v_exp_f32_e32 v10, v10
	v_exp_f32_e32 v11, v11
	s_nop 0
	v_pk_add_f32 v[10:11], v[10:11], 1.0 op_sel_hi:[1,0]
	s_nop 0
	s_nop 0
	v_rcp_f32_e32 v13, v11
	s_nop 0
	v_mul_f32_e32 v11, v5, v13
	s_nop 0
	v_rcp_f32_e32 v5, v10
	s_nop 0
	v_mul_f32_e32 v10, v4, v5
	v_mul_f32_e32 v4, 0x3d372713, v1
	v_mul_f32_e32 v4, v1, v4
	v_fma_f32 v4, v1, v4, v1
	v_mul_f32_e32 v4, 0xbfcc422a, v4
	v_mul_f32_e32 v4, 0x3fb8aa3b, v4
	v_exp_f32_e32 v13, v4
	s_nop 0
	v_pk_add_f32 v[4:5], v[12:13], 1.0 op_sel_hi:[1,0]
	s_nop 0
	s_nop 0
	v_rcp_f32_e32 v12, v5
	s_nop 0
	v_mul_f32_e32 v12, v1, v12
	s_nop 0
	v_rcp_f32_e32 v1, v4
	s_nop 0
	v_mul_f32_e32 v13, v0, v1
	v_mul_f32_e32 v1, 0x3d372713, v2
	v_mul_f32_e32 v1, v2, v1
	v_fma_f32 v1, v2, v1, v2
	v_mul_f32_e32 v1, 0xbfcc422a, v1
	v_mul_f32_e32 v1, 0x3fb8aa3b, v1
	v_mul_f32_e32 v0, 0x3d372713, v6
	v_exp_f32_e32 v4, v1
	v_mul_f32_e32 v1, 0x3d372713, v7
	v_mul_f32_e32 v0, v6, v0
	v_mul_f32_e32 v1, v7, v1
	v_fma_f32 v0, v6, v0, v6
	v_fma_f32 v1, v7, v1, v7
	v_mul_f32_e32 v0, 0xbfcc422a, v0
	v_mul_f32_e32 v1, 0xbfcc422a, v1
	v_mul_f32_e32 v0, 0x3fb8aa3b, v0
	v_mul_f32_e32 v1, 0x3fb8aa3b, v1
	v_exp_f32_e32 v0, v0
	v_exp_f32_e32 v1, v1
	s_nop 0
	v_pk_add_f32 v[0:1], v[0:1], 1.0 op_sel_hi:[1,0]
	s_nop 0
	s_nop 0
	v_rcp_f32_e32 v5, v1
	s_nop 0
	v_mul_f32_e32 v7, v7, v5
	s_nop 0
	v_rcp_f32_e32 v1, v0
	s_nop 0
	v_mul_f32_e32 v6, v6, v1
	v_mul_f32_e32 v0, 0x3d372713, v3
	v_mul_f32_e32 v0, v3, v0
	v_fma_f32 v0, v3, v0, v3
	v_mul_f32_e32 v0, 0xbfcc422a, v0
	v_mul_f32_e32 v0, 0x3fb8aa3b, v0
	v_exp_f32_e32 v5, v0
	s_nop 0
	v_pk_add_f32 v[0:1], v[4:5], 1.0 op_sel_hi:[1,0]
	s_nop 0
	s_nop 0
	v_rcp_f32_e32 v4, v1
	s_nop 0
	v_mul_f32_e32 v3, v3, v4
	s_mov_b64 s[12:13], s[6:7]
	v_rcp_f32_e32 v1, v0
	s_nop 0
	v_mul_f32_e32 v4, v2, v1
	v_cvt_pk_bf16_f32 v3, v4, v3
	v_lshl_add_u64 v[4:5], v[8:9], 0, v[114:115]
	v_lshl_add_u64 v[4:5], v[4:5], 0, s[10:11]
	v_cvt_pk_bf16_f32 v0, v10, v11
	v_cvt_pk_bf16_f32 v1, v6, v7
	v_cvt_pk_bf16_f32 v2, v13, v12
	v_lshl_add_u64 v[4:5], v[4:5], 0, v[48:49]
	s_and_b64 vcc, exec, s[8:9]
	s_mov_b64 s[10:11], s[4:5]
	global_store_dwordx4 v[4:5], v[0:3], off
	s_cbranch_vccz .LBB0_819
	s_waitcnt vmcnt(0)
	s_cmpk_gt_u32 s18, 0xff
	s_cbranch_scc1 .LBB0_826
	s_barrier

.LBB0_982:
	s_add_i32 s22, s7, 0x100
	s_add_u32 s7, s14, s7
	s_addc_u32 s23, s15, 0
	s_add_u32 s24, s7, 0x100
	s_addc_u32 s25, s23, 0
	s_and_b64 s[20:21], s[18:19], exec
	s_cselect_b32 s25, s11, s25
	s_cselect_b32 s24, s10, s24
	s_add_i32 s49, 0, 0x10000
	s_and_b64 s[18:19], s[18:19], exec
	s_cselect_b32 s19, 0, s22
	s_cselect_b32 s18, 0, 0
	s_add_u32 s26, s0, s19
	s_addc_u32 s27, s1, s18
	s_add_u32 s28, s7, 0x10080
	s_addc_u32 s29, s23, 0
	s_add_i32 s53, s49, s35
	s_add_i32 m0, s13, 0xc000
	s_add_i32 s54, s13, 0xe000
	s_add_i32 s52, 0, 0x14000
	s_add_i32 s51, s53, 0x2000
	s_add_u32 s22, s26, 0x10000
	v_add_u32_e32 v36, s49, v205
	s_addc_u32 s23, s27, 0
	s_add_i32 s48, s52, s35
	ds_read_b128 v[16:19], v36
	ds_read_b128 v[20:23], v36 offset:1024
	ds_read_b128 v[32:35], v36 offset:2048
	ds_read_b128 v[36:39], v36 offset:3072
	s_add_i32 s47, s48, 0x2000
	s_add_i32 s46, 0, 0x18000
	s_add_u32 s20, s24, 0x10000
	s_addc_u32 s21, s25, 0
	s_add_i32 s45, s46, s35
	s_add_i32 s44, 0, 0x1c000
	s_add_i32 s7, s45, 0x2000
	s_add_u32 s18, s26, 0x10080
	s_addc_u32 s19, s27, 0
	s_add_i32 s50, s44, s35
	s_add_i32 s49, s50, 0x2000
	v_lshl_add_u64 v[190:191], s[28:29], 0, v[48:49]
	ds_read_b128 v[98:101], v206
	ds_read_b128 v[110:113], v206 offset:1024
	ds_read_b128 v[114:117], v206 offset:2048
	ds_read_b128 v[130:133], v206 offset:3072
	ds_read_b128 v[138:141], v206 offset:4096
	ds_read_b128 v[150:153], v206 offset:5120
	ds_read_b128 v[162:165], v206 offset:6144
	ds_read_b128 v[174:177], v206 offset:7168
	global_load_lds_dwordx4 v[190:191], off
	v_lshl_add_u64 v[190:191], s[28:29], 0, v[180:181]
	s_mov_b32 m0, s54
	s_nop 0
	global_load_lds_dwordx4 v[190:191], off
	s_waitcnt lgkmcnt(8)
	s_barrier
	s_waitcnt lgkmcnt(0)
	s_setprio 1
	v_mfma_f32_16x16x32_bf16 v[170:173], v[16:19], v[98:101], v[170:173]
	v_mfma_f32_16x16x32_bf16 v[166:169], v[32:35], v[98:101], v[166:169]
	v_mfma_f32_16x16x32_bf16 v[146:149], v[16:19], v[114:117], v[146:149]
	v_mfma_f32_16x16x32_bf16 v[142:145], v[32:35], v[114:117], v[142:145]
	v_mfma_f32_16x16x32_bf16 v[122:125], v[16:19], v[138:141], v[122:125]
	v_mfma_f32_16x16x32_bf16 v[118:121], v[32:35], v[138:141], v[118:121]
	v_mfma_f32_16x16x32_bf16 v[94:97], v[16:19], v[162:165], v[94:97]
	v_mfma_f32_16x16x32_bf16 v[90:93], v[32:35], v[162:165], v[90:93]
	v_mfma_f32_16x16x32_bf16 v[170:173], v[20:23], v[110:113], v[170:173]
	v_mfma_f32_16x16x32_bf16 v[166:169], v[36:39], v[110:113], v[166:169]
	v_mfma_f32_16x16x32_bf16 v[146:149], v[20:23], v[130:133], v[146:149]
	v_mfma_f32_16x16x32_bf16 v[142:145], v[36:39], v[130:133], v[142:145]
	v_mfma_f32_16x16x32_bf16 v[122:125], v[20:23], v[150:153], v[122:125]
	v_mfma_f32_16x16x32_bf16 v[118:121], v[36:39], v[150:153], v[118:121]
	v_mfma_f32_16x16x32_bf16 v[94:97], v[20:23], v[174:177], v[94:97]
	v_mfma_f32_16x16x32_bf16 v[90:93], v[36:39], v[174:177], v[90:93]
	s_setprio 0
	s_barrier
	v_add_u32_e32 v202, s52, v205
	s_mov_b32 m0, s53
	ds_read_b128 v[190:193], v202
	ds_read_b128 v[198:201], v202 offset:1024
	ds_read_b128 v[208:211], v202 offset:2048
	ds_read_b128 v[212:215], v202 offset:3072
	v_lshl_add_u64 v[202:203], s[26:27], 0, v[182:183]
	global_load_lds_dwordx4 v[202:203], off
	v_lshl_add_u64 v[242:243], s[26:27], 0, v[178:179]
	s_mov_b32 m0, s51
	s_nop 0
	global_load_lds_dwordx4 v[242:243], off
	s_barrier
	s_waitcnt lgkmcnt(0)
	s_setprio 1
	v_mfma_f32_16x16x32_bf16 v[158:161], v[190:193], v[98:101], v[158:161]
	v_mfma_f32_16x16x32_bf16 v[98:101], v[208:211], v[98:101], v[154:157]
	v_mfma_f32_16x16x32_bf16 v[106:109], v[190:193], v[138:141], v[106:109]
	v_mfma_f32_16x16x32_bf16 v[102:105], v[208:211], v[138:141], v[102:105]
	v_mfma_f32_16x16x32_bf16 v[86:89], v[190:193], v[162:165], v[86:89]
	v_mfma_f32_16x16x32_bf16 v[82:85], v[208:211], v[162:165], v[82:85]
	v_mfma_f32_16x16x32_bf16 v[158:161], v[198:201], v[110:113], v[158:161]
	v_mfma_f32_16x16x32_bf16 v[98:101], v[212:215], v[110:113], v[98:101]
	v_mfma_f32_16x16x32_bf16 v[110:113], v[190:193], v[114:117], v[134:137]
	v_mfma_f32_16x16x32_bf16 v[114:117], v[208:211], v[114:117], v[126:129]
	v_mfma_f32_16x16x32_bf16 v[106:109], v[198:201], v[150:153], v[106:109]
	v_mfma_f32_16x16x32_bf16 v[102:105], v[212:215], v[150:153], v[102:105]
	v_mfma_f32_16x16x32_bf16 v[86:89], v[198:201], v[174:177], v[86:89]
	v_mfma_f32_16x16x32_bf16 v[82:85], v[212:215], v[174:177], v[82:85]
	v_mfma_f32_16x16x32_bf16 v[110:113], v[198:201], v[130:133], v[110:113]
	v_mfma_f32_16x16x32_bf16 v[114:117], v[212:215], v[130:133], v[114:117]
	s_setprio 0
	s_mov_b32 m0, s13
	v_lshl_add_u64 v[244:245], s[24:25], 0, v[48:49]
	s_barrier
	ds_read_b128 v[126:129], v206 offset:16384
	ds_read_b128 v[130:133], v206 offset:17408
	ds_read_b128 v[134:137], v206 offset:18432
	ds_read_b128 v[138:141], v206 offset:19456
	ds_read_b128 v[150:153], v206 offset:20480
	ds_read_b128 v[154:157], v206 offset:21504
	ds_read_b128 v[162:165], v206 offset:22528
	ds_read_b128 v[174:177], v206 offset:23552
	global_load_lds_dwordx4 v[244:245], off
	v_lshl_add_u64 v[246:247], s[24:25], 0, v[180:181]
	s_mov_b32 m0, s38
	s_nop 0
	global_load_lds_dwordx4 v[246:247], off
	s_barrier
	s_waitcnt lgkmcnt(0)
	s_setprio 1
	v_mfma_f32_16x16x32_bf16 v[78:81], v[16:19], v[126:129], v[78:81]
	v_mfma_f32_16x16x32_bf16 v[74:77], v[32:35], v[126:129], v[74:77]
	v_mfma_f32_16x16x32_bf16 v[62:65], v[16:19], v[134:137], v[62:65]
	v_mfma_f32_16x16x32_bf16 v[58:61], v[32:35], v[134:137], v[58:61]
	v_mfma_f32_16x16x32_bf16 v[44:47], v[16:19], v[150:153], v[44:47]
	v_mfma_f32_16x16x32_bf16 v[40:43], v[32:35], v[150:153], v[40:43]
	v_mfma_f32_16x16x32_bf16 v[12:15], v[16:19], v[162:165], v[12:15]
	v_mfma_f32_16x16x32_bf16 v[8:11], v[32:35], v[162:165], v[8:11]
	v_mfma_f32_16x16x32_bf16 v[78:81], v[20:23], v[130:133], v[78:81]
	v_mfma_f32_16x16x32_bf16 v[74:77], v[36:39], v[130:133], v[74:77]
	v_mfma_f32_16x16x32_bf16 v[62:65], v[20:23], v[138:141], v[62:65]
	v_mfma_f32_16x16x32_bf16 v[58:61], v[36:39], v[138:141], v[58:61]
	v_mfma_f32_16x16x32_bf16 v[44:47], v[20:23], v[154:157], v[44:47]
	v_mfma_f32_16x16x32_bf16 v[40:43], v[36:39], v[154:157], v[40:43]
	v_mfma_f32_16x16x32_bf16 v[12:15], v[20:23], v[174:177], v[12:15]
	v_mfma_f32_16x16x32_bf16 v[8:11], v[36:39], v[174:177], v[8:11]
	s_setprio 0
	s_barrier
	s_mov_b32 m0, s48
	v_lshl_add_u64 v[16:17], s[22:23], 0, v[182:183]
	global_load_lds_dwordx4 v[16:17], off
	v_lshl_add_u64 v[16:17], s[22:23], 0, v[178:179]
	s_mov_b32 m0, s47
	s_nop 0
	global_load_lds_dwordx4 v[16:17], off
	s_waitcnt vmcnt(6)
	s_barrier
	s_setprio 1
	v_mfma_f32_16x16x32_bf16 v[28:31], v[190:193], v[150:153], v[28:31]
	v_mfma_f32_16x16x32_bf16 v[24:27], v[208:211], v[150:153], v[24:27]
	v_mfma_f32_16x16x32_bf16 v[4:7], v[190:193], v[162:165], v[4:7]
	v_mfma_f32_16x16x32_bf16 v[0:3], v[208:211], v[162:165], v[0:3]
	v_mfma_f32_16x16x32_bf16 v[16:19], v[190:193], v[126:129], v[70:73]
	v_mfma_f32_16x16x32_bf16 v[20:23], v[208:211], v[126:129], v[66:69]
	v_mfma_f32_16x16x32_bf16 v[32:35], v[190:193], v[134:137], v[54:57]
	v_mfma_f32_16x16x32_bf16 v[36:39], v[208:211], v[134:137], v[50:53]
	v_mfma_f32_16x16x32_bf16 v[28:31], v[198:201], v[154:157], v[28:31]
	v_mfma_f32_16x16x32_bf16 v[24:27], v[212:215], v[154:157], v[24:27]
	v_mfma_f32_16x16x32_bf16 v[4:7], v[198:201], v[174:177], v[4:7]
	v_mfma_f32_16x16x32_bf16 v[0:3], v[212:215], v[174:177], v[0:3]
	v_mfma_f32_16x16x32_bf16 v[16:19], v[198:201], v[130:133], v[16:19]
	v_mfma_f32_16x16x32_bf16 v[20:23], v[212:215], v[130:133], v[20:23]
	v_mfma_f32_16x16x32_bf16 v[32:35], v[198:201], v[138:141], v[32:35]
	v_mfma_f32_16x16x32_bf16 v[36:39], v[212:215], v[138:141], v[36:39]
	s_setprio 0
	v_add_u32_e32 v70, s46, v205
	s_barrier
	ds_read_b128 v[50:53], v70
	ds_read_b128 v[54:57], v70 offset:1024
	ds_read_b128 v[66:69], v70 offset:2048
	ds_read_b128 v[70:73], v70 offset:3072
	s_mov_b32 m0, s39
	v_lshl_add_u64 v[134:135], s[20:21], 0, v[48:49]
	ds_read_b128 v[126:129], v206 offset:32768
	ds_read_b128 v[130:133], v206 offset:33792
	ds_read_b128 v[138:141], v206 offset:34816
	ds_read_b128 v[150:153], v206 offset:35840
	ds_read_b128 v[162:165], v206 offset:36864
	ds_read_b128 v[174:177], v206 offset:37888
	ds_read_b128 v[190:193], v206 offset:38912
	ds_read_b128 v[198:201], v206 offset:39936
	global_load_lds_dwordx4 v[134:135], off
	v_lshl_add_u64 v[134:135], s[20:21], 0, v[180:181]
	s_mov_b32 m0, s40
	s_nop 0
	global_load_lds_dwordx4 v[134:135], off
	s_waitcnt lgkmcnt(8)
	s_barrier
	s_waitcnt lgkmcnt(0)
	s_setprio 1
	v_mfma_f32_16x16x32_bf16 v[134:137], v[50:53], v[126:129], v[170:173]
	v_mfma_f32_16x16x32_bf16 v[170:173], v[54:57], v[130:133], v[134:137]
	v_mfma_f32_16x16x32_bf16 v[134:137], v[66:69], v[126:129], v[166:169]
	v_mfma_f32_16x16x32_bf16 v[166:169], v[70:73], v[130:133], v[134:137]
	v_mfma_f32_16x16x32_bf16 v[134:137], v[50:53], v[138:141], v[146:149]
	v_mfma_f32_16x16x32_bf16 v[146:149], v[54:57], v[150:153], v[134:137]
	v_mfma_f32_16x16x32_bf16 v[134:137], v[66:69], v[138:141], v[142:145]
	v_mfma_f32_16x16x32_bf16 v[122:125], v[50:53], v[162:165], v[122:125]
	v_mfma_f32_16x16x32_bf16 v[118:121], v[66:69], v[162:165], v[118:121]
	v_mfma_f32_16x16x32_bf16 v[94:97], v[50:53], v[190:193], v[94:97]
	v_mfma_f32_16x16x32_bf16 v[90:93], v[66:69], v[190:193], v[90:93]
	v_mfma_f32_16x16x32_bf16 v[142:145], v[70:73], v[150:153], v[134:137]
	v_mfma_f32_16x16x32_bf16 v[122:125], v[54:57], v[174:177], v[122:125]
	v_mfma_f32_16x16x32_bf16 v[118:121], v[70:73], v[174:177], v[118:121]
	v_mfma_f32_16x16x32_bf16 v[94:97], v[54:57], v[198:201], v[94:97]
	v_mfma_f32_16x16x32_bf16 v[90:93], v[70:73], v[198:201], v[90:93]
	s_setprio 0
	s_barrier
	v_add_u32_e32 v134, s44, v205
	s_mov_b32 m0, s45
	ds_read_b128 v[208:211], v134
	ds_read_b128 v[212:215], v134 offset:1024
	ds_read_b128 v[216:219], v134 offset:2048
	ds_read_b128 v[220:223], v134 offset:3072
	v_lshl_add_u64 v[134:135], v[202:203], 0, s[66:67]
	global_load_lds_dwordx4 v[134:135], off
	v_lshl_add_u64 v[134:135], v[242:243], 0, s[66:67]
	s_mov_b32 m0, s7
	s_nop 0
	global_load_lds_dwordx4 v[134:135], off
	s_barrier
	s_waitcnt lgkmcnt(0)
	s_setprio 1
	v_mfma_f32_16x16x32_bf16 v[98:101], v[216:219], v[126:129], v[98:101]
	v_mfma_f32_16x16x32_bf16 v[134:137], v[208:211], v[126:129], v[158:161]
	v_mfma_f32_16x16x32_bf16 v[154:157], v[220:223], v[130:133], v[98:101]
	v_mfma_f32_16x16x32_bf16 v[98:101], v[208:211], v[138:141], v[110:113]
	v_mfma_f32_16x16x32_bf16 v[158:161], v[212:215], v[130:133], v[134:137]
	v_mfma_f32_16x16x32_bf16 v[134:137], v[212:215], v[150:153], v[98:101]
	v_mfma_f32_16x16x32_bf16 v[98:101], v[216:219], v[138:141], v[114:117]
	v_mfma_f32_16x16x32_bf16 v[126:129], v[220:223], v[150:153], v[98:101]
	v_mfma_f32_16x16x32_bf16 v[98:101], v[208:211], v[162:165], v[106:109]
	v_mfma_f32_16x16x32_bf16 v[106:109], v[212:215], v[174:177], v[98:101]
	v_mfma_f32_16x16x32_bf16 v[98:101], v[216:219], v[162:165], v[102:105]
	v_mfma_f32_16x16x32_bf16 v[86:89], v[208:211], v[190:193], v[86:89]
	v_mfma_f32_16x16x32_bf16 v[82:85], v[216:219], v[190:193], v[82:85]
	v_mfma_f32_16x16x32_bf16 v[102:105], v[220:223], v[174:177], v[98:101]
	v_mfma_f32_16x16x32_bf16 v[86:89], v[212:215], v[198:201], v[86:89]
	v_mfma_f32_16x16x32_bf16 v[82:85], v[220:223], v[198:201], v[82:85]
	s_setprio 0
	s_mov_b32 m0, s41
	v_lshl_add_u64 v[190:191], v[244:245], 0, s[66:67]
	s_barrier
	ds_read_b128 v[98:101], v206 offset:49152
	ds_read_b128 v[110:113], v206 offset:50176
	ds_read_b128 v[114:117], v206 offset:51200
	ds_read_b128 v[130:133], v206 offset:52224
	ds_read_b128 v[138:141], v206 offset:53248
	ds_read_b128 v[150:153], v206 offset:54272
	ds_read_b128 v[162:165], v206 offset:55296
	ds_read_b128 v[174:177], v206 offset:56320
	global_load_lds_dwordx4 v[190:191], off
	v_lshl_add_u64 v[190:191], v[246:247], 0, s[66:67]
	s_mov_b32 m0, s42
	s_nop 0
	global_load_lds_dwordx4 v[190:191], off
	s_barrier
	s_waitcnt lgkmcnt(0)
	s_setprio 1
	v_mfma_f32_16x16x32_bf16 v[78:81], v[50:53], v[98:101], v[78:81]
	v_mfma_f32_16x16x32_bf16 v[74:77], v[66:69], v[98:101], v[74:77]
	v_mfma_f32_16x16x32_bf16 v[62:65], v[50:53], v[114:117], v[62:65]
	v_mfma_f32_16x16x32_bf16 v[58:61], v[66:69], v[114:117], v[58:61]
	v_mfma_f32_16x16x32_bf16 v[44:47], v[50:53], v[138:141], v[44:47]
	v_mfma_f32_16x16x32_bf16 v[40:43], v[66:69], v[138:141], v[40:43]
	v_mfma_f32_16x16x32_bf16 v[12:15], v[50:53], v[162:165], v[12:15]
	v_mfma_f32_16x16x32_bf16 v[8:11], v[66:69], v[162:165], v[8:11]
	v_mfma_f32_16x16x32_bf16 v[78:81], v[54:57], v[110:113], v[78:81]
	v_mfma_f32_16x16x32_bf16 v[74:77], v[70:73], v[110:113], v[74:77]
	v_mfma_f32_16x16x32_bf16 v[62:65], v[54:57], v[130:133], v[62:65]
	v_mfma_f32_16x16x32_bf16 v[58:61], v[70:73], v[130:133], v[58:61]
	v_mfma_f32_16x16x32_bf16 v[44:47], v[54:57], v[150:153], v[44:47]
	v_mfma_f32_16x16x32_bf16 v[40:43], v[70:73], v[150:153], v[40:43]
	v_mfma_f32_16x16x32_bf16 v[12:15], v[54:57], v[174:177], v[12:15]
	v_mfma_f32_16x16x32_bf16 v[8:11], v[70:73], v[174:177], v[8:11]
	s_setprio 0
	s_barrier
	s_mov_b32 m0, s50
	v_lshl_add_u64 v[50:51], s[18:19], 0, v[182:183]
	global_load_lds_dwordx4 v[50:51], off
	v_lshl_add_u64 v[50:51], s[18:19], 0, v[178:179]
	s_mov_b32 m0, s49
	s_nop 0
	global_load_lds_dwordx4 v[50:51], off
	s_waitcnt vmcnt(6)
	s_barrier
	s_setprio 1
	v_mfma_f32_16x16x32_bf16 v[16:19], v[208:211], v[98:101], v[16:19]
	v_mfma_f32_16x16x32_bf16 v[70:73], v[212:215], v[110:113], v[16:19]
	v_mfma_f32_16x16x32_bf16 v[16:19], v[216:219], v[98:101], v[20:23]
	v_mfma_f32_16x16x32_bf16 v[66:69], v[220:223], v[110:113], v[16:19]
	v_mfma_f32_16x16x32_bf16 v[16:19], v[208:211], v[114:117], v[32:35]
	v_mfma_f32_16x16x32_bf16 v[54:57], v[212:215], v[130:133], v[16:19]
	v_mfma_f32_16x16x32_bf16 v[16:19], v[216:219], v[114:117], v[36:39]
	v_mfma_f32_16x16x32_bf16 v[50:53], v[220:223], v[130:133], v[16:19]
	v_mfma_f32_16x16x32_bf16 v[16:19], v[208:211], v[138:141], v[28:31]
	v_mfma_f32_16x16x32_bf16 v[28:31], v[212:215], v[150:153], v[16:19]
	v_mfma_f32_16x16x32_bf16 v[16:19], v[216:219], v[138:141], v[24:27]
	v_mfma_f32_16x16x32_bf16 v[4:7], v[208:211], v[162:165], v[4:7]
	v_mfma_f32_16x16x32_bf16 v[0:3], v[216:219], v[162:165], v[0:3]
	v_mfma_f32_16x16x32_bf16 v[24:27], v[220:223], v[150:153], v[16:19]
	v_mfma_f32_16x16x32_bf16 v[4:7], v[212:215], v[174:177], v[4:7]
	v_mfma_f32_16x16x32_bf16 v[0:3], v[220:223], v[174:177], v[0:3]
	s_setprio 0
	s_andn2_b64 vcc, exec, s[16:17]
	s_mov_b64 s[18:19], -1
	s_mov_b64 s[16:17], 0
	s_movk_i32 s7, 0x100
	s_barrier
	s_cbranch_vccz .LBB0_982
	global_load_dwordx4 v[32:35], v[184:185], off offset:16
	global_load_dwordx4 v[36:39], v[184:185], off
	global_load_dwordx4 v[16:19], v[184:185], off offset:528
	global_load_dwordx4 v[20:23], v[184:185], off offset:512
	v_lshl_add_u32 v190, s12, 8, v204
	v_ashrrev_i32_e32 v191, 31, v190
	v_lshlrev_b64 v[98:99], 9, v[190:191]
	v_lshl_add_u64 v[98:99], v[186:187], 0, v[98:99]
	global_load_dwordx4 v[174:177], v[98:99], off
	global_load_dwordx4 v[162:165], v[98:99], off offset:256
	v_lshlrev_b64 v[202:203], 11, v[190:191]
	v_or_b32_e32 v200, 16, v190
	v_ashrrev_i32_e32 v201, 31, v200
	v_lshlrev_b64 v[98:99], 9, v[200:201]
	v_or_b32_e32 v198, 32, v190
	v_lshl_add_u64 v[98:99], v[186:187], 0, v[98:99]
	v_ashrrev_i32_e32 v199, 31, v198
	global_load_dwordx4 v[150:153], v[98:99], off
	global_load_dwordx4 v[138:141], v[98:99], off offset:256
	v_lshlrev_b64 v[98:99], 9, v[198:199]
	v_or_b32_e32 v192, 48, v190
	v_lshl_add_u64 v[98:99], v[186:187], 0, v[98:99]
	v_ashrrev_i32_e32 v193, 31, v192
	global_load_dwordx4 v[130:133], v[98:99], off
	global_load_dwordx4 v[114:117], v[98:99], off offset:256
	v_lshlrev_b64 v[98:99], 9, v[192:193]
	v_lshl_add_u64 v[98:99], v[186:187], 0, v[98:99]
	global_load_dwordx4 v[110:113], v[98:99], off
	s_nop 0
	global_load_dwordx4 v[98:101], v[98:99], off offset:256
	s_mov_b32 s12, s6
	s_waitcnt vmcnt(0)
	v_pk_add_f32 v[168:169], v[168:169], v[34:35]
	v_pk_add_f32 v[170:171], v[170:171], v[36:37]
	v_pk_add_f32 v[208:209], v[172:173], v[38:39]
	v_pk_add_f32 v[172:173], v[166:167], v[32:33]
	v_mul_f32_e32 v166, 0xbfb8aa3b, v170
	v_mul_f32_e32 v167, 0xbfb8aa3b, v171
	v_exp_f32_e32 v166, v166
	v_exp_f32_e32 v167, v167
	v_lshlrev_b32_e32 v170, 16, v174
	v_and_b32_e32 v171, 0xffff0000, v174
	v_mul_f32_e32 v172, 0xbfb8aa3b, v172
	v_pk_add_f32 v[166:167], v[166:167], 1.0 op_sel_hi:[1,0]
	v_mul_f32_e32 v173, 0xbfb8aa3b, v173
	v_exp_f32_e32 v172, v172
	v_exp_f32_e32 v173, v173
	v_mul_f32_e32 v168, 0xbfb8aa3b, v168
	v_rcp_f32_e32 v167, v167
	s_nop 0
	v_pk_add_f32 v[172:173], v[172:173], 1.0 op_sel_hi:[1,0]
	v_mul_f32_e32 v169, 0xbfb8aa3b, v169
	v_exp_f32_e32 v168, v168
	v_rcp_f32_e32 v166, v166
	s_nop 0
	v_pk_mul_f32 v[166:167], v[166:167], v[170:171]
	v_mul_f32_e32 v170, 0xbfb8aa3b, v208
	v_mul_f32_e32 v171, 0xbfb8aa3b, v209
	v_exp_f32_e32 v170, v170
	v_exp_f32_e32 v171, v171
	v_lshlrev_b32_e32 v174, 16, v175
	v_and_b32_e32 v175, 0xffff0000, v175
	v_exp_f32_e32 v169, v169
	v_pk_add_f32 v[170:171], v[170:171], 1.0 op_sel_hi:[1,0]
	v_pk_add_f32 v[158:159], v[158:159], v[20:21]
	v_pk_add_f32 v[168:169], v[168:169], 1.0 op_sel_hi:[1,0]
	v_pk_add_f32 v[160:161], v[160:161], v[22:23]
	v_pk_add_f32 v[156:157], v[156:157], v[18:19]
	v_rcp_f32_e32 v171, v171
	s_nop 0
	v_mul_f32_e32 v156, 0xbfb8aa3b, v156
	v_mul_f32_e32 v157, 0xbfb8aa3b, v157
	v_exp_f32_e32 v156, v156
	v_rcp_f32_e32 v170, v170
	s_nop 0
	v_pk_mul_f32 v[170:171], v[170:171], v[174:175]
	v_lshlrev_b32_e32 v174, 16, v176
	v_and_b32_e32 v175, 0xffff0000, v176
	v_exp_f32_e32 v157, v157
	v_pk_add_f32 v[146:147], v[146:147], v[36:37]
	v_pk_add_f32 v[148:149], v[148:149], v[38:39]
	v_rcp_f32_e32 v173, v173
	s_nop 0
	v_pk_add_f32 v[156:157], v[156:157], 1.0 op_sel_hi:[1,0]
	v_pk_add_f32 v[144:145], v[144:145], v[34:35]
	v_pk_add_f32 v[134:135], v[134:135], v[20:21]
	v_rcp_f32_e32 v172, v172
	s_nop 0
	v_pk_mul_f32 v[172:173], v[172:173], v[174:175]
	v_lshlrev_b32_e32 v174, 16, v177
	v_and_b32_e32 v175, 0xffff0000, v177
	v_mul_f32_e32 v144, 0xbfb8aa3b, v144
	v_mul_f32_e32 v145, 0xbfb8aa3b, v145
	v_exp_f32_e32 v144, v144
	v_rcp_f32_e32 v169, v169
	s_nop 0
	v_exp_f32_e32 v145, v145
	v_pk_add_f32 v[136:137], v[136:137], v[22:23]
	v_pk_add_f32 v[128:129], v[128:129], v[18:19]
	v_rcp_f32_e32 v168, v168
	s_nop 0
	v_pk_mul_f32 v[174:175], v[168:169], v[174:175]
	v_cvt_pk_bf16_f32 v168, v166, v167
	v_cvt_pk_bf16_f32 v169, v170, v171
	v_cvt_pk_bf16_f32 v170, v172, v173
	v_cvt_pk_bf16_f32 v171, v174, v175
	v_lshl_add_u64 v[166:167], v[188:189], 0, v[202:203]
	global_store_dwordx4 v[166:167], v[168:171], off
	v_pk_add_f32 v[144:145], v[144:145], 1.0 op_sel_hi:[1,0]
	v_mul_f32_e32 v128, 0xbfb8aa3b, v128
	v_pk_add_f32 v[168:169], v[154:155], v[16:17]
	v_mul_f32_e32 v154, 0xbfb8aa3b, v158
	v_mul_f32_e32 v155, 0xbfb8aa3b, v159
	v_exp_f32_e32 v154, v154
	v_exp_f32_e32 v155, v155
	v_lshlrev_b32_e32 v158, 16, v162
	v_and_b32_e32 v159, 0xffff0000, v162
	v_mul_f32_e32 v129, 0xbfb8aa3b, v129
	v_pk_add_f32 v[154:155], v[154:155], 1.0 op_sel_hi:[1,0]
	v_exp_f32_e32 v128, v128
	v_exp_f32_e32 v129, v129
	v_pk_add_f32 v[122:123], v[122:123], v[36:37]
	v_pk_add_f32 v[124:125], v[124:125], v[38:39]
	v_rcp_f32_e32 v155, v155
	s_nop 0
	v_pk_add_f32 v[128:129], v[128:129], 1.0 op_sel_hi:[1,0]
	v_pk_add_f32 v[120:121], v[120:121], v[34:35]
	v_pk_add_f32 v[106:107], v[106:107], v[20:21]
	v_rcp_f32_e32 v154, v154
	s_nop 0
	v_pk_mul_f32 v[154:155], v[154:155], v[158:159]
	v_mul_f32_e32 v158, 0xbfb8aa3b, v160
	v_mul_f32_e32 v159, 0xbfb8aa3b, v161
	v_exp_f32_e32 v158, v158
	v_exp_f32_e32 v159, v159
	v_lshlrev_b32_e32 v160, 16, v163
	v_and_b32_e32 v161, 0xffff0000, v163
	v_cvt_pk_bf16_f32 v154, v154, v155
	v_pk_add_f32 v[158:159], v[158:159], 1.0 op_sel_hi:[1,0]
	v_mul_f32_e32 v120, 0xbfb8aa3b, v120
	v_mul_f32_e32 v121, 0xbfb8aa3b, v121
	v_exp_f32_e32 v120, v120
	v_exp_f32_e32 v121, v121
	v_rcp_f32_e32 v159, v159
	s_nop 0
	v_pk_add_f32 v[120:121], v[120:121], 1.0 op_sel_hi:[1,0]
	v_pk_add_f32 v[108:109], v[108:109], v[22:23]
	v_pk_add_f32 v[104:105], v[104:105], v[18:19]
	v_rcp_f32_e32 v158, v158
	s_nop 0
	v_pk_mul_f32 v[158:159], v[158:159], v[160:161]
	v_mul_f32_e32 v160, 0xbfb8aa3b, v168
	v_mul_f32_e32 v161, 0xbfb8aa3b, v169
	v_exp_f32_e32 v160, v160
	v_exp_f32_e32 v161, v161
	v_lshlrev_b32_e32 v162, 16, v164
	v_and_b32_e32 v163, 0xffff0000, v164
	v_cvt_pk_bf16_f32 v155, v158, v159
	v_pk_add_f32 v[160:161], v[160:161], 1.0 op_sel_hi:[1,0]
	v_mul_f32_e32 v104, 0xbfb8aa3b, v104
	v_mul_f32_e32 v105, 0xbfb8aa3b, v105
	v_exp_f32_e32 v104, v104
	v_exp_f32_e32 v105, v105
	v_rcp_f32_e32 v161, v161
	s_nop 0
	v_pk_add_f32 v[104:105], v[104:105], 1.0 op_sel_hi:[1,0]
	v_pk_add_f32 v[94:95], v[94:95], v[36:37]
	v_pk_add_f32 v[96:97], v[96:97], v[38:39]
	v_rcp_f32_e32 v160, v160
	s_nop 0
	v_pk_mul_f32 v[160:161], v[160:161], v[162:163]
	v_lshlrev_b32_e32 v162, 16, v165
	v_and_b32_e32 v163, 0xffff0000, v165
	v_pk_add_f32 v[92:93], v[92:93], v[34:35]
	v_pk_add_f32 v[86:87], v[86:87], v[20:21]
	v_mul_f32_e32 v92, 0xbfb8aa3b, v92
	v_rcp_f32_e32 v157, v157
	s_nop 0
	v_mul_f32_e32 v93, 0xbfb8aa3b, v93
	v_exp_f32_e32 v92, v92
	v_exp_f32_e32 v93, v93
	v_rcp_f32_e32 v156, v156
	s_nop 0
	v_pk_mul_f32 v[162:163], v[156:157], v[162:163]
	v_cvt_pk_bf16_f32 v156, v160, v161
	v_cvt_pk_bf16_f32 v157, v162, v163
	global_store_dwordx4 v[166:167], v[154:157], off offset:256
	v_pk_add_f32 v[92:93], v[92:93], 1.0 op_sel_hi:[1,0]
	v_pk_add_f32 v[88:89], v[88:89], v[22:23]
	v_pk_add_f32 v[156:157], v[142:143], v[32:33]
	v_mul_f32_e32 v142, 0xbfb8aa3b, v146
	v_mul_f32_e32 v143, 0xbfb8aa3b, v147
	v_exp_f32_e32 v142, v142
	v_exp_f32_e32 v143, v143
	v_lshlrev_b32_e32 v146, 16, v150
	v_and_b32_e32 v147, 0xffff0000, v150
	v_lshlrev_b64 v[154:155], 11, v[200:201]
	v_pk_add_f32 v[142:143], v[142:143], 1.0 op_sel_hi:[1,0]
	v_pk_add_f32 v[84:85], v[84:85], v[18:19]
	v_mul_f32_e32 v84, 0xbfb8aa3b, v84
	v_mul_f32_e32 v85, 0xbfb8aa3b, v85
	v_exp_f32_e32 v84, v84
	v_rcp_f32_e32 v143, v143
	s_nop 0
	v_exp_f32_e32 v85, v85
	v_pk_add_f32 v[78:79], v[78:79], v[36:37]
	v_pk_add_f32 v[80:81], v[80:81], v[38:39]
	v_rcp_f32_e32 v142, v142
	s_nop 0
	v_pk_mul_f32 v[142:143], v[142:143], v[146:147]
	v_mul_f32_e32 v146, 0xbfb8aa3b, v148
	v_mul_f32_e32 v147, 0xbfb8aa3b, v149
	v_exp_f32_e32 v146, v146
	v_exp_f32_e32 v147, v147
	v_lshlrev_b32_e32 v148, 16, v151
	v_and_b32_e32 v149, 0xffff0000, v151
	v_pk_add_f32 v[84:85], v[84:85], 1.0 op_sel_hi:[1,0]
	v_pk_add_f32 v[146:147], v[146:147], 1.0 op_sel_hi:[1,0]
	v_pk_add_f32 v[76:77], v[76:77], v[34:35]
	v_mul_f32_e32 v76, 0xbfb8aa3b, v76
	v_mul_f32_e32 v77, 0xbfb8aa3b, v77
	v_exp_f32_e32 v76, v76
	v_rcp_f32_e32 v147, v147
	s_nop 0
	v_exp_f32_e32 v77, v77
	v_pk_add_f32 v[70:71], v[70:71], v[20:21]
	v_pk_add_f32 v[72:73], v[72:73], v[22:23]
	v_rcp_f32_e32 v146, v146
	s_nop 0
	v_pk_mul_f32 v[146:147], v[146:147], v[148:149]
	v_mul_f32_e32 v148, 0xbfb8aa3b, v156
	v_mul_f32_e32 v149, 0xbfb8aa3b, v157
	v_exp_f32_e32 v148, v148
	v_exp_f32_e32 v149, v149
	v_lshlrev_b32_e32 v150, 16, v152
	v_and_b32_e32 v151, 0xffff0000, v152
	v_pk_add_f32 v[76:77], v[76:77], 1.0 op_sel_hi:[1,0]
	v_pk_add_f32 v[148:149], v[148:149], 1.0 op_sel_hi:[1,0]
	v_pk_add_f32 v[68:69], v[68:69], v[18:19]
	v_mul_f32_e32 v68, 0xbfb8aa3b, v68
	v_mul_f32_e32 v69, 0xbfb8aa3b, v69
	v_exp_f32_e32 v68, v68
	v_rcp_f32_e32 v149, v149
	s_nop 0
	v_exp_f32_e32 v69, v69
	v_pk_add_f32 v[62:63], v[62:63], v[36:37]
	v_pk_add_f32 v[64:65], v[64:65], v[38:39]
	v_rcp_f32_e32 v148, v148
	s_nop 0
	v_pk_mul_f32 v[148:149], v[148:149], v[150:151]
	v_lshlrev_b32_e32 v150, 16, v153
	v_and_b32_e32 v151, 0xffff0000, v153
	v_pk_add_f32 v[68:69], v[68:69], 1.0 op_sel_hi:[1,0]
	v_pk_add_f32 v[60:61], v[60:61], v[34:35]
	v_pk_add_f32 v[54:55], v[54:55], v[20:21]
	v_rcp_f32_e32 v145, v145
	s_nop 0
	v_mul_f32_e32 v60, 0xbfb8aa3b, v60
	v_mul_f32_e32 v61, 0xbfb8aa3b, v61
	v_exp_f32_e32 v60, v60
	v_rcp_f32_e32 v144, v144
	s_nop 0
	v_pk_mul_f32 v[150:151], v[144:145], v[150:151]
	v_cvt_pk_bf16_f32 v144, v142, v143
	v_cvt_pk_bf16_f32 v145, v146, v147
	v_cvt_pk_bf16_f32 v146, v148, v149
	v_cvt_pk_bf16_f32 v147, v150, v151
	v_lshl_add_u64 v[142:143], v[188:189], 0, v[154:155]
	global_store_dwordx4 v[142:143], v[144:147], off
	v_exp_f32_e32 v61, v61
	v_pk_add_f32 v[56:57], v[56:57], v[22:23]
	v_pk_add_f32 v[144:145], v[126:127], v[16:17]
	v_mul_f32_e32 v126, 0xbfb8aa3b, v134
	v_mul_f32_e32 v127, 0xbfb8aa3b, v135
	v_exp_f32_e32 v126, v126
	v_exp_f32_e32 v127, v127
	v_lshlrev_b32_e32 v134, 16, v138
	v_and_b32_e32 v135, 0xffff0000, v138
	v_pk_add_f32 v[60:61], v[60:61], 1.0 op_sel_hi:[1,0]
	v_pk_add_f32 v[126:127], v[126:127], 1.0 op_sel_hi:[1,0]
	v_pk_add_f32 v[52:53], v[52:53], v[18:19]
	v_mul_f32_e32 v52, 0xbfb8aa3b, v52
	v_mul_f32_e32 v53, 0xbfb8aa3b, v53
	v_exp_f32_e32 v52, v52
	v_rcp_f32_e32 v127, v127
	s_nop 0
	v_exp_f32_e32 v53, v53
	v_pk_add_f32 v[44:45], v[44:45], v[36:37]
	v_pk_add_f32 v[46:47], v[46:47], v[38:39]
	v_rcp_f32_e32 v126, v126
	s_nop 0
	v_pk_mul_f32 v[126:127], v[126:127], v[134:135]
	v_mul_f32_e32 v134, 0xbfb8aa3b, v136
	v_mul_f32_e32 v135, 0xbfb8aa3b, v137
	v_exp_f32_e32 v134, v134
	v_exp_f32_e32 v135, v135
	v_lshlrev_b32_e32 v136, 16, v139
	v_and_b32_e32 v137, 0xffff0000, v139
	v_cvt_pk_bf16_f32 v126, v126, v127
	v_pk_add_f32 v[134:135], v[134:135], 1.0 op_sel_hi:[1,0]
	v_pk_add_f32 v[52:53], v[52:53], 1.0 op_sel_hi:[1,0]
	v_pk_add_f32 v[42:43], v[42:43], v[34:35]
	v_pk_add_f32 v[28:29], v[28:29], v[20:21]
	v_mul_f32_e32 v42, 0xbfb8aa3b, v42
	v_rcp_f32_e32 v135, v135
	s_nop 0
	v_mul_f32_e32 v43, 0xbfb8aa3b, v43
	v_exp_f32_e32 v42, v42
	v_exp_f32_e32 v43, v43
	v_rcp_f32_e32 v134, v134
	s_nop 0
	v_pk_mul_f32 v[134:135], v[134:135], v[136:137]
	v_mul_f32_e32 v136, 0xbfb8aa3b, v144
	v_mul_f32_e32 v137, 0xbfb8aa3b, v145
	v_exp_f32_e32 v136, v136
	v_exp_f32_e32 v137, v137
	v_lshlrev_b32_e32 v138, 16, v140
	v_and_b32_e32 v139, 0xffff0000, v140
	v_cvt_pk_bf16_f32 v127, v134, v135
	v_pk_add_f32 v[136:137], v[136:137], 1.0 op_sel_hi:[1,0]
	v_pk_add_f32 v[42:43], v[42:43], 1.0 op_sel_hi:[1,0]
	v_pk_add_f32 v[30:31], v[30:31], v[22:23]
	v_pk_add_f32 v[26:27], v[26:27], v[18:19]
	v_pk_add_f32 v[12:13], v[12:13], v[36:37]
	v_rcp_f32_e32 v137, v137
	s_nop 0
	v_mul_f32_e32 v26, 0xbfb8aa3b, v26
	v_mul_f32_e32 v27, 0xbfb8aa3b, v27
	v_exp_f32_e32 v26, v26
	v_rcp_f32_e32 v136, v136
	s_nop 0
	v_pk_mul_f32 v[136:137], v[136:137], v[138:139]
	v_lshlrev_b32_e32 v138, 16, v141
	v_and_b32_e32 v139, 0xffff0000, v141
	v_exp_f32_e32 v27, v27
	v_pk_add_f32 v[14:15], v[14:15], v[38:39]
	v_pk_add_f32 v[10:11], v[10:11], v[34:35]
	v_rcp_f32_e32 v129, v129
	s_nop 0
	v_pk_add_f32 v[26:27], v[26:27], 1.0 op_sel_hi:[1,0]
	v_mul_f32_e32 v10, 0xbfb8aa3b, v10
	v_mul_f32_e32 v11, 0xbfb8aa3b, v11
	v_rcp_f32_e32 v128, v128
	s_nop 0
	v_pk_mul_f32 v[138:139], v[128:129], v[138:139]
	v_cvt_pk_bf16_f32 v128, v136, v137
	v_cvt_pk_bf16_f32 v129, v138, v139
	global_store_dwordx4 v[142:143], v[126:129], off offset:256
	v_exp_f32_e32 v10, v10
	v_exp_f32_e32 v11, v11
	v_pk_add_f32 v[128:129], v[118:119], v[32:33]
	v_mul_f32_e32 v118, 0xbfb8aa3b, v122
	v_mul_f32_e32 v119, 0xbfb8aa3b, v123
	v_exp_f32_e32 v118, v118
	v_exp_f32_e32 v119, v119
	v_lshlrev_b32_e32 v122, 16, v130
	v_and_b32_e32 v123, 0xffff0000, v130
	v_lshlrev_b64 v[126:127], 11, v[198:199]
	v_pk_add_f32 v[118:119], v[118:119], 1.0 op_sel_hi:[1,0]
	v_pk_add_f32 v[10:11], v[10:11], 1.0 op_sel_hi:[1,0]
	v_pk_add_f32 v[4:5], v[4:5], v[20:21]
	v_pk_add_f32 v[6:7], v[6:7], v[22:23]
	v_pk_add_f32 v[2:3], v[2:3], v[18:19]
	v_rcp_f32_e32 v119, v119
	s_nop 0
	v_mul_f32_e32 v2, 0xbfb8aa3b, v2
	v_mul_f32_e32 v3, 0xbfb8aa3b, v3
	v_exp_f32_e32 v2, v2
	v_rcp_f32_e32 v118, v118
	s_nop 0
	v_pk_mul_f32 v[118:119], v[118:119], v[122:123]
	v_mul_f32_e32 v122, 0xbfb8aa3b, v124
	v_mul_f32_e32 v123, 0xbfb8aa3b, v125
	v_exp_f32_e32 v122, v122
	v_exp_f32_e32 v123, v123
	v_lshlrev_b32_e32 v124, 16, v131
	v_and_b32_e32 v125, 0xffff0000, v131
	v_exp_f32_e32 v3, v3
	v_pk_add_f32 v[122:123], v[122:123], 1.0 op_sel_hi:[1,0]
	v_pk_add_f32 v[2:3], v[2:3], 1.0 op_sel_hi:[1,0]
	s_nop 0
	v_rcp_f32_e32 v123, v123
	s_nop 0
	s_nop 0
	v_rcp_f32_e32 v122, v122
	s_nop 0
	v_pk_mul_f32 v[122:123], v[122:123], v[124:125]
	v_mul_f32_e32 v124, 0xbfb8aa3b, v128
	v_mul_f32_e32 v125, 0xbfb8aa3b, v129
	v_exp_f32_e32 v124, v124
	v_exp_f32_e32 v125, v125
	v_lshlrev_b32_e32 v128, 16, v132
	v_and_b32_e32 v129, 0xffff0000, v132
	v_pk_add_f32 v[124:125], v[124:125], 1.0 op_sel_hi:[1,0]
	s_nop 0
	s_nop 0
	v_rcp_f32_e32 v125, v125
	s_nop 0
	s_nop 0
	v_rcp_f32_e32 v124, v124
	s_nop 0
	v_pk_mul_f32 v[124:125], v[124:125], v[128:129]
	v_lshlrev_b32_e32 v128, 16, v133
	v_and_b32_e32 v129, 0xffff0000, v133
	v_rcp_f32_e32 v121, v121
	s_nop 0
	s_nop 0
	v_rcp_f32_e32 v120, v120
	s_nop 0
	v_pk_mul_f32 v[128:129], v[120:121], v[128:129]
	v_cvt_pk_bf16_f32 v120, v118, v119
	v_cvt_pk_bf16_f32 v121, v122, v123
	v_cvt_pk_bf16_f32 v122, v124, v125
	v_cvt_pk_bf16_f32 v123, v128, v129
	v_lshl_add_u64 v[118:119], v[188:189], 0, v[126:127]
	global_store_dwordx4 v[118:119], v[120:123], off
	s_nop 1
	v_pk_add_f32 v[120:121], v[102:103], v[16:17]
	v_mul_f32_e32 v102, 0xbfb8aa3b, v106
	v_mul_f32_e32 v103, 0xbfb8aa3b, v107
	v_exp_f32_e32 v102, v102
	v_exp_f32_e32 v103, v103
	v_lshlrev_b32_e32 v106, 16, v114
	v_and_b32_e32 v107, 0xffff0000, v114
	v_pk_add_f32 v[102:103], v[102:103], 1.0 op_sel_hi:[1,0]
	s_nop 0
	s_nop 0
	v_rcp_f32_e32 v103, v103
	s_nop 0
	s_nop 0
	v_rcp_f32_e32 v102, v102
	s_nop 0
	v_pk_mul_f32 v[102:103], v[102:103], v[106:107]
	v_mul_f32_e32 v106, 0xbfb8aa3b, v108
	v_mul_f32_e32 v107, 0xbfb8aa3b, v109
	v_exp_f32_e32 v106, v106
	v_exp_f32_e32 v107, v107
	v_lshlrev_b32_e32 v108, 16, v115
	v_and_b32_e32 v109, 0xffff0000, v115
	v_cvt_pk_bf16_f32 v102, v102, v103
	v_pk_add_f32 v[106:107], v[106:107], 1.0 op_sel_hi:[1,0]
	s_nop 0
	s_nop 0
	v_rcp_f32_e32 v107, v107
	s_nop 0
	s_nop 0
	v_rcp_f32_e32 v106, v106
	s_nop 0
	v_pk_mul_f32 v[106:107], v[106:107], v[108:109]
	v_mul_f32_e32 v108, 0xbfb8aa3b, v120
	v_mul_f32_e32 v109, 0xbfb8aa3b, v121
	v_exp_f32_e32 v108, v108
	v_exp_f32_e32 v109, v109
	v_lshlrev_b32_e32 v114, 16, v116
	v_and_b32_e32 v115, 0xffff0000, v116
	v_cvt_pk_bf16_f32 v103, v106, v107
	v_pk_add_f32 v[108:109], v[108:109], 1.0 op_sel_hi:[1,0]
	s_nop 0
	s_nop 0
	v_rcp_f32_e32 v109, v109
	s_nop 0
	s_nop 0
	v_rcp_f32_e32 v108, v108
	s_nop 0
	v_pk_mul_f32 v[108:109], v[108:109], v[114:115]
	v_lshlrev_b32_e32 v114, 16, v117
	v_and_b32_e32 v115, 0xffff0000, v117
	s_nop 0
	v_rcp_f32_e32 v105, v105
	s_nop 0
	s_nop 0
	v_rcp_f32_e32 v104, v104
	s_nop 0
	v_pk_mul_f32 v[114:115], v[104:105], v[114:115]
	v_cvt_pk_bf16_f32 v104, v108, v109
	v_cvt_pk_bf16_f32 v105, v114, v115
	global_store_dwordx4 v[118:119], v[102:105], off offset:256
	v_add_u32_e32 v120, 0x80, v190
	v_ashrrev_i32_e32 v121, 31, v120
	v_pk_add_f32 v[104:105], v[90:91], v[32:33]
	v_mul_f32_e32 v90, 0xbfb8aa3b, v94
	v_mul_f32_e32 v91, 0xbfb8aa3b, v95
	v_exp_f32_e32 v90, v90
	v_exp_f32_e32 v91, v91
	v_lshlrev_b32_e32 v94, 16, v110
	v_and_b32_e32 v95, 0xffff0000, v110
	v_lshlrev_b64 v[102:103], 11, v[192:193]
	v_pk_add_f32 v[90:91], v[90:91], 1.0 op_sel_hi:[1,0]
	v_pk_add_f32 v[122:123], v[74:75], v[32:33]
	v_mul_f32_e32 v74, 0xbfb8aa3b, v78
	v_mul_f32_e32 v75, 0xbfb8aa3b, v79
	v_exp_f32_e32 v74, v74
	v_rcp_f32_e32 v91, v91
	s_nop 0
	v_exp_f32_e32 v75, v75
	v_add_u32_e32 v118, 0x90, v190
	v_ashrrev_i32_e32 v119, 31, v118
	v_rcp_f32_e32 v90, v90
	s_nop 0
	v_pk_mul_f32 v[90:91], v[90:91], v[94:95]
	v_mul_f32_e32 v94, 0xbfb8aa3b, v96
	v_mul_f32_e32 v95, 0xbfb8aa3b, v97
	v_exp_f32_e32 v94, v94
	v_exp_f32_e32 v95, v95
	v_lshlrev_b32_e32 v96, 16, v111
	v_and_b32_e32 v97, 0xffff0000, v111
	v_pk_add_f32 v[74:75], v[74:75], 1.0 op_sel_hi:[1,0]
	v_pk_add_f32 v[94:95], v[94:95], 1.0 op_sel_hi:[1,0]
	v_add_u32_e32 v116, 0xa0, v190
	v_ashrrev_i32_e32 v117, 31, v116
	v_add_u32_e32 v114, 0xb0, v190
	v_ashrrev_i32_e32 v115, 31, v114
	v_rcp_f32_e32 v95, v95
	s_nop 0
	s_nop 0
	v_rcp_f32_e32 v94, v94
	s_nop 0
	v_pk_mul_f32 v[94:95], v[94:95], v[96:97]
	v_mul_f32_e32 v96, 0xbfb8aa3b, v104
	v_mul_f32_e32 v97, 0xbfb8aa3b, v105
	v_exp_f32_e32 v96, v96
	v_exp_f32_e32 v97, v97
	v_lshlrev_b32_e32 v104, 16, v112
	v_and_b32_e32 v105, 0xffff0000, v112
	v_pk_add_f32 v[96:97], v[96:97], 1.0 op_sel_hi:[1,0]
	s_nop 0
	s_nop 0
	v_rcp_f32_e32 v97, v97
	s_nop 0
	s_nop 0
	v_rcp_f32_e32 v96, v96
	s_nop 0
	v_pk_mul_f32 v[96:97], v[96:97], v[104:105]
	v_lshlrev_b32_e32 v104, 16, v113
	v_and_b32_e32 v105, 0xffff0000, v113
	v_rcp_f32_e32 v93, v93
	s_nop 0
	s_nop 0
	v_rcp_f32_e32 v92, v92
	s_nop 0
	v_pk_mul_f32 v[104:105], v[92:93], v[104:105]
	v_cvt_pk_bf16_f32 v92, v90, v91
	v_cvt_pk_bf16_f32 v93, v94, v95
	v_cvt_pk_bf16_f32 v94, v96, v97
	v_cvt_pk_bf16_f32 v95, v104, v105
	v_lshl_add_u64 v[90:91], v[188:189], 0, v[102:103]
	global_store_dwordx4 v[90:91], v[92:95], off
	s_nop 1
	v_pk_add_f32 v[92:93], v[82:83], v[16:17]
	v_mul_f32_e32 v82, 0xbfb8aa3b, v86
	v_mul_f32_e32 v83, 0xbfb8aa3b, v87
	v_exp_f32_e32 v82, v82
	v_exp_f32_e32 v83, v83
	v_lshlrev_b32_e32 v86, 16, v98
	v_and_b32_e32 v87, 0xffff0000, v98
	v_pk_add_f32 v[82:83], v[82:83], 1.0 op_sel_hi:[1,0]
	s_nop 0
	s_nop 0
	v_rcp_f32_e32 v83, v83
	s_nop 0
	s_nop 0
	v_rcp_f32_e32 v82, v82
	s_nop 0
	v_pk_mul_f32 v[82:83], v[82:83], v[86:87]
	v_mul_f32_e32 v86, 0xbfb8aa3b, v88
	v_mul_f32_e32 v87, 0xbfb8aa3b, v89
	v_exp_f32_e32 v86, v86
	v_exp_f32_e32 v87, v87
	v_lshlrev_b32_e32 v88, 16, v99
	v_and_b32_e32 v89, 0xffff0000, v99
	v_cvt_pk_bf16_f32 v82, v82, v83
	v_pk_add_f32 v[86:87], v[86:87], 1.0 op_sel_hi:[1,0]
	s_nop 0
	s_nop 0
	v_rcp_f32_e32 v87, v87
	s_nop 0
	s_nop 0
	v_rcp_f32_e32 v86, v86
	s_nop 0
	v_pk_mul_f32 v[86:87], v[86:87], v[88:89]
	v_mul_f32_e32 v88, 0xbfb8aa3b, v92
	v_mul_f32_e32 v89, 0xbfb8aa3b, v93
	v_exp_f32_e32 v88, v88
	v_exp_f32_e32 v89, v89
	v_lshlrev_b32_e32 v92, 16, v100
	v_and_b32_e32 v93, 0xffff0000, v100
	v_cvt_pk_bf16_f32 v83, v86, v87
	v_pk_add_f32 v[88:89], v[88:89], 1.0 op_sel_hi:[1,0]
	s_nop 0
	s_nop 0
	v_rcp_f32_e32 v89, v89
	s_nop 0
	s_nop 0
	v_rcp_f32_e32 v88, v88
	s_nop 0
	v_pk_mul_f32 v[88:89], v[88:89], v[92:93]
	v_lshlrev_b32_e32 v92, 16, v101
	v_and_b32_e32 v93, 0xffff0000, v101
	v_rcp_f32_e32 v85, v85
	s_nop 0
	s_nop 0
	v_rcp_f32_e32 v84, v84
	s_nop 0
	v_pk_mul_f32 v[92:93], v[84:85], v[92:93]
	v_cvt_pk_bf16_f32 v84, v88, v89
	v_cvt_pk_bf16_f32 v85, v92, v93
	global_store_dwordx4 v[90:91], v[82:85], off offset:256
	s_nop 1
	v_lshlrev_b64 v[82:83], 9, v[120:121]
	v_lshl_add_u64 v[82:83], v[186:187], 0, v[82:83]
	global_load_dwordx4 v[110:113], v[82:83], off
	global_load_dwordx4 v[106:109], v[82:83], off offset:256
	v_lshlrev_b64 v[82:83], 9, v[118:119]
	v_lshl_add_u64 v[82:83], v[186:187], 0, v[82:83]
	global_load_dwordx4 v[102:105], v[82:83], off
	global_load_dwordx4 v[98:101], v[82:83], off offset:256
	v_lshlrev_b64 v[82:83], 9, v[116:117]
	v_lshl_add_u64 v[82:83], v[186:187], 0, v[82:83]
	global_load_dwordx4 v[94:97], v[82:83], off
	global_load_dwordx4 v[90:93], v[82:83], off offset:256
	v_lshlrev_b64 v[82:83], 9, v[114:115]
	v_lshlrev_b64 v[120:121], 11, v[120:121]
	v_lshl_add_u64 v[82:83], v[186:187], 0, v[82:83]
	global_load_dwordx4 v[86:89], v[82:83], off
	s_nop 0
	global_load_dwordx4 v[82:85], v[82:83], off offset:256
	s_waitcnt vmcnt(0)
	v_lshlrev_b32_e32 v78, 16, v110
	v_and_b32_e32 v79, 0xffff0000, v110
	s_nop 0
	v_rcp_f32_e32 v75, v75
	s_nop 0
	s_nop 0
	v_rcp_f32_e32 v74, v74
	s_nop 0
	v_pk_mul_f32 v[74:75], v[74:75], v[78:79]
	v_mul_f32_e32 v78, 0xbfb8aa3b, v80
	v_mul_f32_e32 v79, 0xbfb8aa3b, v81
	v_exp_f32_e32 v78, v78
	v_exp_f32_e32 v79, v79
	v_lshlrev_b32_e32 v80, 16, v111
	v_and_b32_e32 v81, 0xffff0000, v111
	v_pk_add_f32 v[78:79], v[78:79], 1.0 op_sel_hi:[1,0]
	s_nop 0
	s_nop 0
	v_rcp_f32_e32 v79, v79
	s_nop 0
	s_nop 0
	v_rcp_f32_e32 v78, v78
	s_nop 0
	v_pk_mul_f32 v[78:79], v[78:79], v[80:81]
	v_mul_f32_e32 v80, 0xbfb8aa3b, v122
	v_mul_f32_e32 v81, 0xbfb8aa3b, v123
	v_exp_f32_e32 v80, v80
	v_exp_f32_e32 v81, v81
	v_lshlrev_b32_e32 v110, 16, v112
	v_and_b32_e32 v111, 0xffff0000, v112
	v_pk_add_f32 v[80:81], v[80:81], 1.0 op_sel_hi:[1,0]
	s_nop 0
	s_nop 0
	v_rcp_f32_e32 v81, v81
	s_nop 0
	s_nop 0
	v_rcp_f32_e32 v80, v80
	s_nop 0
	v_pk_mul_f32 v[80:81], v[80:81], v[110:111]
	v_lshlrev_b32_e32 v110, 16, v113
	v_and_b32_e32 v111, 0xffff0000, v113
	s_nop 0
	v_rcp_f32_e32 v77, v77
	s_nop 0
	s_nop 0
	v_rcp_f32_e32 v76, v76
	s_nop 0
	v_pk_mul_f32 v[110:111], v[76:77], v[110:111]
	v_cvt_pk_bf16_f32 v76, v74, v75
	v_cvt_pk_bf16_f32 v77, v78, v79
	v_cvt_pk_bf16_f32 v78, v80, v81
	v_cvt_pk_bf16_f32 v79, v110, v111
	v_lshl_add_u64 v[74:75], v[188:189], 0, v[120:121]
	global_store_dwordx4 v[74:75], v[76:79], off
	s_nop 1
	v_pk_add_f32 v[76:77], v[66:67], v[16:17]
	v_mul_f32_e32 v66, 0xbfb8aa3b, v70
	v_mul_f32_e32 v67, 0xbfb8aa3b, v71
	v_exp_f32_e32 v66, v66
	v_exp_f32_e32 v67, v67
	v_lshlrev_b32_e32 v70, 16, v106
	v_and_b32_e32 v71, 0xffff0000, v106
	v_pk_add_f32 v[66:67], v[66:67], 1.0 op_sel_hi:[1,0]
	s_nop 0
	s_nop 0
	v_rcp_f32_e32 v67, v67
	s_nop 0
	s_nop 0
	v_rcp_f32_e32 v66, v66
	s_nop 0
	v_pk_mul_f32 v[66:67], v[66:67], v[70:71]
	v_mul_f32_e32 v70, 0xbfb8aa3b, v72
	v_mul_f32_e32 v71, 0xbfb8aa3b, v73
	v_exp_f32_e32 v70, v70
	v_exp_f32_e32 v71, v71
	v_lshlrev_b32_e32 v72, 16, v107
	v_and_b32_e32 v73, 0xffff0000, v107
	v_cvt_pk_bf16_f32 v66, v66, v67
	v_pk_add_f32 v[70:71], v[70:71], 1.0 op_sel_hi:[1,0]
	s_nop 0
	s_nop 0
	v_rcp_f32_e32 v71, v71
	s_nop 0
	s_nop 0
	v_rcp_f32_e32 v70, v70
	s_nop 0
	v_pk_mul_f32 v[70:71], v[70:71], v[72:73]
	v_mul_f32_e32 v72, 0xbfb8aa3b, v76
	v_mul_f32_e32 v73, 0xbfb8aa3b, v77
	v_exp_f32_e32 v72, v72
	v_exp_f32_e32 v73, v73
	v_lshlrev_b32_e32 v76, 16, v108
	v_and_b32_e32 v77, 0xffff0000, v108
	v_cvt_pk_bf16_f32 v67, v70, v71
	v_pk_add_f32 v[72:73], v[72:73], 1.0 op_sel_hi:[1,0]
	s_nop 0
	s_nop 0
	v_rcp_f32_e32 v73, v73
	s_nop 0
	s_nop 0
	v_rcp_f32_e32 v72, v72
	s_nop 0
	v_pk_mul_f32 v[72:73], v[72:73], v[76:77]
	v_lshlrev_b32_e32 v76, 16, v109
	v_and_b32_e32 v77, 0xffff0000, v109
	v_rcp_f32_e32 v69, v69
	s_nop 0
	s_nop 0
	v_rcp_f32_e32 v68, v68
	s_nop 0
	v_pk_mul_f32 v[76:77], v[68:69], v[76:77]
	v_cvt_pk_bf16_f32 v68, v72, v73
	v_cvt_pk_bf16_f32 v69, v76, v77
	global_store_dwordx4 v[74:75], v[66:69], off offset:256
	s_nop 1
	v_pk_add_f32 v[68:69], v[58:59], v[32:33]
	v_mul_f32_e32 v58, 0xbfb8aa3b, v62
	v_mul_f32_e32 v59, 0xbfb8aa3b, v63
	v_exp_f32_e32 v58, v58
	v_exp_f32_e32 v59, v59
	v_lshlrev_b32_e32 v62, 16, v102
	v_and_b32_e32 v63, 0xffff0000, v102
	v_lshlrev_b64 v[66:67], 11, v[118:119]
	v_pk_add_f32 v[58:59], v[58:59], 1.0 op_sel_hi:[1,0]
	s_nop 0
	s_nop 0
	v_rcp_f32_e32 v59, v59
	s_nop 0
	s_nop 0
	v_rcp_f32_e32 v58, v58
	s_nop 0
	v_pk_mul_f32 v[58:59], v[58:59], v[62:63]
	v_mul_f32_e32 v62, 0xbfb8aa3b, v64
	v_mul_f32_e32 v63, 0xbfb8aa3b, v65
	v_exp_f32_e32 v62, v62
	v_exp_f32_e32 v63, v63
	v_lshlrev_b32_e32 v64, 16, v103
	v_and_b32_e32 v65, 0xffff0000, v103
	v_pk_add_f32 v[62:63], v[62:63], 1.0 op_sel_hi:[1,0]
	s_nop 0
	s_nop 0
	v_rcp_f32_e32 v63, v63
	s_nop 0
	s_nop 0
	v_rcp_f32_e32 v62, v62
	s_nop 0
	v_pk_mul_f32 v[62:63], v[62:63], v[64:65]
	v_mul_f32_e32 v64, 0xbfb8aa3b, v68
	v_mul_f32_e32 v65, 0xbfb8aa3b, v69
	v_exp_f32_e32 v64, v64
	v_exp_f32_e32 v65, v65
	v_lshlrev_b32_e32 v68, 16, v104
	v_and_b32_e32 v69, 0xffff0000, v104
	v_pk_add_f32 v[64:65], v[64:65], 1.0 op_sel_hi:[1,0]
	s_nop 0
	s_nop 0
	v_rcp_f32_e32 v65, v65
	s_nop 0
	s_nop 0
	v_rcp_f32_e32 v64, v64
	s_nop 0
	v_pk_mul_f32 v[64:65], v[64:65], v[68:69]
	v_lshlrev_b32_e32 v68, 16, v105
	v_and_b32_e32 v69, 0xffff0000, v105
	v_rcp_f32_e32 v61, v61
	s_nop 0
	s_nop 0
	v_rcp_f32_e32 v60, v60
	s_nop 0
	v_pk_mul_f32 v[68:69], v[60:61], v[68:69]
	v_cvt_pk_bf16_f32 v60, v58, v59
	v_cvt_pk_bf16_f32 v61, v62, v63
	v_cvt_pk_bf16_f32 v62, v64, v65
	v_cvt_pk_bf16_f32 v63, v68, v69
	v_lshl_add_u64 v[58:59], v[188:189], 0, v[66:67]
	global_store_dwordx4 v[58:59], v[60:63], off
	s_nop 1
	v_pk_add_f32 v[60:61], v[50:51], v[16:17]
	v_mul_f32_e32 v50, 0xbfb8aa3b, v54
	v_mul_f32_e32 v51, 0xbfb8aa3b, v55
	v_exp_f32_e32 v50, v50
	v_exp_f32_e32 v51, v51
	v_lshlrev_b32_e32 v54, 16, v98
	v_and_b32_e32 v55, 0xffff0000, v98
	v_pk_add_f32 v[50:51], v[50:51], 1.0 op_sel_hi:[1,0]
	s_nop 0
	s_nop 0
	v_rcp_f32_e32 v51, v51
	s_nop 0
	s_nop 0
	v_rcp_f32_e32 v50, v50
	s_nop 0
	v_pk_mul_f32 v[50:51], v[50:51], v[54:55]
	v_mul_f32_e32 v54, 0xbfb8aa3b, v56
	v_mul_f32_e32 v55, 0xbfb8aa3b, v57
	v_exp_f32_e32 v54, v54
	v_exp_f32_e32 v55, v55
	v_lshlrev_b32_e32 v56, 16, v99
	v_and_b32_e32 v57, 0xffff0000, v99
	v_cvt_pk_bf16_f32 v50, v50, v51
	v_pk_add_f32 v[54:55], v[54:55], 1.0 op_sel_hi:[1,0]
	s_nop 0
	s_nop 0
	v_rcp_f32_e32 v55, v55
	s_nop 0
	s_nop 0
	v_rcp_f32_e32 v54, v54
	s_nop 0
	v_pk_mul_f32 v[54:55], v[54:55], v[56:57]
	v_mul_f32_e32 v56, 0xbfb8aa3b, v60
	v_mul_f32_e32 v57, 0xbfb8aa3b, v61
	v_exp_f32_e32 v56, v56
	v_exp_f32_e32 v57, v57
	v_lshlrev_b32_e32 v60, 16, v100
	v_and_b32_e32 v61, 0xffff0000, v100
	v_cvt_pk_bf16_f32 v51, v54, v55
	v_pk_add_f32 v[56:57], v[56:57], 1.0 op_sel_hi:[1,0]
	s_nop 0
	s_nop 0
	v_rcp_f32_e32 v57, v57
	s_nop 0
	s_nop 0
	v_rcp_f32_e32 v56, v56
	s_nop 0
	v_pk_mul_f32 v[56:57], v[56:57], v[60:61]
	v_lshlrev_b32_e32 v60, 16, v101
	v_and_b32_e32 v61, 0xffff0000, v101
	v_rcp_f32_e32 v53, v53
	s_nop 0
	s_nop 0
	v_rcp_f32_e32 v52, v52
	s_nop 0
	v_pk_mul_f32 v[60:61], v[52:53], v[60:61]
	v_cvt_pk_bf16_f32 v52, v56, v57
	v_cvt_pk_bf16_f32 v53, v60, v61
	global_store_dwordx4 v[58:59], v[50:53], off offset:256
	s_nop 1
	v_pk_add_f32 v[52:53], v[40:41], v[32:33]
	v_mul_f32_e32 v40, 0xbfb8aa3b, v44
	v_mul_f32_e32 v41, 0xbfb8aa3b, v45
	v_exp_f32_e32 v40, v40
	v_exp_f32_e32 v41, v41
	v_lshlrev_b32_e32 v44, 16, v94
	v_and_b32_e32 v45, 0xffff0000, v94
	v_lshlrev_b64 v[50:51], 11, v[116:117]
	v_pk_add_f32 v[40:41], v[40:41], 1.0 op_sel_hi:[1,0]
	s_nop 0
	s_nop 0
	v_rcp_f32_e32 v41, v41
	s_nop 0
	s_nop 0
	v_rcp_f32_e32 v40, v40
	s_nop 0
	v_pk_mul_f32 v[40:41], v[40:41], v[44:45]
	v_mul_f32_e32 v44, 0xbfb8aa3b, v46
	v_mul_f32_e32 v45, 0xbfb8aa3b, v47
	v_exp_f32_e32 v44, v44
	v_exp_f32_e32 v45, v45
	v_lshlrev_b32_e32 v46, 16, v95
	v_and_b32_e32 v47, 0xffff0000, v95
	v_pk_add_f32 v[44:45], v[44:45], 1.0 op_sel_hi:[1,0]
	s_nop 0
	s_nop 0
	v_rcp_f32_e32 v45, v45
	s_nop 0
	s_nop 0
	v_rcp_f32_e32 v44, v44
	s_nop 0
	v_pk_mul_f32 v[44:45], v[44:45], v[46:47]
	v_mul_f32_e32 v46, 0xbfb8aa3b, v52
	v_mul_f32_e32 v47, 0xbfb8aa3b, v53
	v_exp_f32_e32 v46, v46
	v_exp_f32_e32 v47, v47
	v_lshlrev_b32_e32 v52, 16, v96
	v_and_b32_e32 v53, 0xffff0000, v96
	v_pk_add_f32 v[46:47], v[46:47], 1.0 op_sel_hi:[1,0]
	s_nop 0
	s_nop 0
	v_rcp_f32_e32 v47, v47
	s_nop 0
	s_nop 0
	v_rcp_f32_e32 v46, v46
	s_nop 0
	v_pk_mul_f32 v[46:47], v[46:47], v[52:53]
	v_lshlrev_b32_e32 v52, 16, v97
	v_and_b32_e32 v53, 0xffff0000, v97
	v_rcp_f32_e32 v43, v43
	s_nop 0
	s_nop 0
	v_rcp_f32_e32 v42, v42
	s_nop 0
	v_pk_mul_f32 v[52:53], v[42:43], v[52:53]
	v_cvt_pk_bf16_f32 v42, v40, v41
	v_cvt_pk_bf16_f32 v43, v44, v45
	v_cvt_pk_bf16_f32 v44, v46, v47
	v_cvt_pk_bf16_f32 v45, v52, v53
	v_lshl_add_u64 v[40:41], v[188:189], 0, v[50:51]
	global_store_dwordx4 v[40:41], v[42:45], off
	s_nop 1
	v_pk_add_f32 v[42:43], v[24:25], v[16:17]
	v_mul_f32_e32 v24, 0xbfb8aa3b, v28
	v_mul_f32_e32 v25, 0xbfb8aa3b, v29
	v_exp_f32_e32 v24, v24
	v_exp_f32_e32 v25, v25
	v_lshlrev_b32_e32 v28, 16, v90
	v_and_b32_e32 v29, 0xffff0000, v90
	v_pk_add_f32 v[24:25], v[24:25], 1.0 op_sel_hi:[1,0]
	s_nop 0
	s_nop 0
	v_rcp_f32_e32 v25, v25
	s_nop 0
	s_nop 0
	v_rcp_f32_e32 v24, v24
	s_nop 0
	v_pk_mul_f32 v[24:25], v[24:25], v[28:29]
	v_mul_f32_e32 v28, 0xbfb8aa3b, v30
	v_mul_f32_e32 v29, 0xbfb8aa3b, v31
	v_exp_f32_e32 v28, v28
	v_exp_f32_e32 v29, v29
	v_lshlrev_b32_e32 v30, 16, v91
	v_and_b32_e32 v31, 0xffff0000, v91
	v_cvt_pk_bf16_f32 v24, v24, v25
	v_pk_add_f32 v[28:29], v[28:29], 1.0 op_sel_hi:[1,0]
	s_nop 0
	s_nop 0
	v_rcp_f32_e32 v29, v29
	s_nop 0
	s_nop 0
	v_rcp_f32_e32 v28, v28
	s_nop 0
	v_pk_mul_f32 v[28:29], v[28:29], v[30:31]
	v_mul_f32_e32 v30, 0xbfb8aa3b, v42
	v_mul_f32_e32 v31, 0xbfb8aa3b, v43
	v_exp_f32_e32 v30, v30
	v_exp_f32_e32 v31, v31
	v_lshlrev_b32_e32 v42, 16, v92
	v_and_b32_e32 v43, 0xffff0000, v92
	v_cvt_pk_bf16_f32 v25, v28, v29
	v_pk_add_f32 v[30:31], v[30:31], 1.0 op_sel_hi:[1,0]
	s_nop 0
	s_nop 0
	v_rcp_f32_e32 v31, v31
	s_nop 0
	s_nop 0
	v_rcp_f32_e32 v30, v30
	s_nop 0
	v_pk_mul_f32 v[30:31], v[30:31], v[42:43]
	v_lshlrev_b32_e32 v42, 16, v93
	v_and_b32_e32 v43, 0xffff0000, v93
	v_rcp_f32_e32 v27, v27
	s_nop 0
	s_nop 0
	v_rcp_f32_e32 v26, v26
	s_nop 0
	v_pk_mul_f32 v[42:43], v[26:27], v[42:43]
	v_cvt_pk_bf16_f32 v26, v30, v31
	v_cvt_pk_bf16_f32 v27, v42, v43
	global_store_dwordx4 v[40:41], v[24:27], off offset:256
	s_nop 1
	v_pk_add_f32 v[26:27], v[8:9], v[32:33]
	v_mul_f32_e32 v8, 0xbfb8aa3b, v12
	v_mul_f32_e32 v9, 0xbfb8aa3b, v13
	v_exp_f32_e32 v8, v8
	v_exp_f32_e32 v9, v9
	v_lshlrev_b32_e32 v12, 16, v86
	v_and_b32_e32 v13, 0xffff0000, v86
	v_lshlrev_b64 v[24:25], 11, v[114:115]
	v_pk_add_f32 v[8:9], v[8:9], 1.0 op_sel_hi:[1,0]
	s_nop 0
	s_nop 0
	v_rcp_f32_e32 v9, v9
	s_nop 0
	s_nop 0
	v_rcp_f32_e32 v8, v8
	s_nop 0
	v_pk_mul_f32 v[8:9], v[8:9], v[12:13]
	v_mul_f32_e32 v12, 0xbfb8aa3b, v14
	v_mul_f32_e32 v13, 0xbfb8aa3b, v15
	v_exp_f32_e32 v12, v12
	v_exp_f32_e32 v13, v13
	v_lshlrev_b32_e32 v14, 16, v87
	v_and_b32_e32 v15, 0xffff0000, v87
	v_pk_add_f32 v[12:13], v[12:13], 1.0 op_sel_hi:[1,0]
	s_nop 0
	s_nop 0
	v_rcp_f32_e32 v13, v13
	s_nop 0
	s_nop 0
	v_rcp_f32_e32 v12, v12
	s_nop 0
	v_pk_mul_f32 v[12:13], v[12:13], v[14:15]
	v_mul_f32_e32 v14, 0xbfb8aa3b, v26
	v_mul_f32_e32 v15, 0xbfb8aa3b, v27
	v_exp_f32_e32 v14, v14
	v_exp_f32_e32 v15, v15
	v_lshlrev_b32_e32 v26, 16, v88
	v_and_b32_e32 v27, 0xffff0000, v88
	v_pk_add_f32 v[14:15], v[14:15], 1.0 op_sel_hi:[1,0]
	s_nop 0
	s_nop 0
	v_rcp_f32_e32 v15, v15
	s_nop 0
	s_nop 0
	v_rcp_f32_e32 v14, v14
	s_nop 0
	v_pk_mul_f32 v[14:15], v[14:15], v[26:27]
	v_lshlrev_b32_e32 v26, 16, v89
	v_and_b32_e32 v27, 0xffff0000, v89
	v_rcp_f32_e32 v11, v11
	s_nop 0
	s_nop 0
	v_rcp_f32_e32 v10, v10
	s_nop 0
	v_pk_mul_f32 v[26:27], v[10:11], v[26:27]
	v_cvt_pk_bf16_f32 v10, v8, v9
	v_cvt_pk_bf16_f32 v11, v12, v13
	v_cvt_pk_bf16_f32 v12, v14, v15
	v_cvt_pk_bf16_f32 v13, v26, v27
	v_lshl_add_u64 v[8:9], v[188:189], 0, v[24:25]
	global_store_dwordx4 v[8:9], v[10:13], off
	s_nop 1
	v_pk_add_f32 v[10:11], v[0:1], v[16:17]
	v_mul_f32_e32 v0, 0xbfb8aa3b, v4
	v_mul_f32_e32 v1, 0xbfb8aa3b, v5
	v_exp_f32_e32 v0, v0
	v_exp_f32_e32 v1, v1
	v_lshlrev_b32_e32 v4, 16, v82
	v_and_b32_e32 v5, 0xffff0000, v82
	v_pk_add_f32 v[0:1], v[0:1], 1.0 op_sel_hi:[1,0]
	s_nop 0
	s_nop 0
	v_rcp_f32_e32 v1, v1
	s_nop 0
	s_nop 0
	v_rcp_f32_e32 v0, v0
	s_nop 0
	v_pk_mul_f32 v[0:1], v[0:1], v[4:5]
	v_mul_f32_e32 v4, 0xbfb8aa3b, v6
	v_mul_f32_e32 v5, 0xbfb8aa3b, v7
	v_exp_f32_e32 v4, v4
	v_exp_f32_e32 v5, v5
	v_lshlrev_b32_e32 v6, 16, v83
	v_and_b32_e32 v7, 0xffff0000, v83
	v_cvt_pk_bf16_f32 v0, v0, v1
	v_pk_add_f32 v[4:5], v[4:5], 1.0 op_sel_hi:[1,0]
	s_nop 0
	s_nop 0
	v_rcp_f32_e32 v5, v5
	s_nop 0
	s_nop 0
	v_rcp_f32_e32 v4, v4
	s_nop 0
	v_pk_mul_f32 v[4:5], v[4:5], v[6:7]
	v_mul_f32_e32 v6, 0xbfb8aa3b, v10
	v_mul_f32_e32 v7, 0xbfb8aa3b, v11
	v_exp_f32_e32 v6, v6
	v_exp_f32_e32 v7, v7
	v_lshlrev_b32_e32 v10, 16, v84
	v_and_b32_e32 v11, 0xffff0000, v84
	v_cvt_pk_bf16_f32 v1, v4, v5
	v_pk_add_f32 v[6:7], v[6:7], 1.0 op_sel_hi:[1,0]
	s_nop 0
	s_nop 0
	v_rcp_f32_e32 v7, v7
	s_nop 0
	s_nop 0
	v_rcp_f32_e32 v6, v6
	s_nop 0
	v_pk_mul_f32 v[6:7], v[6:7], v[10:11]
	v_lshlrev_b32_e32 v10, 16, v85
	v_and_b32_e32 v11, 0xffff0000, v85
	v_rcp_f32_e32 v3, v3
	s_nop 0
	s_mov_b64 s[14:15], s[10:11]
	v_rcp_f32_e32 v2, v2
	s_nop 0
	v_pk_mul_f32 v[10:11], v[2:3], v[10:11]
	v_cvt_pk_bf16_f32 v2, v6, v7
	v_cvt_pk_bf16_f32 v3, v10, v11
	s_and_b64 vcc, exec, s[8:9]
	global_store_dwordx4 v[8:9], v[0:3], off offset:256
	s_cbranch_vccz .LBB0_979
	s_waitcnt vmcnt(0)
	s_cmpk_gt_u32 s30, 0xff
	s_cbranch_scc1 .LBB0_986
	s_barrier

.LBB0_1056:
	s_add_i32 s56, s28, 2
	s_add_u32 s29, s24, 0xfffc0080
	s_addc_u32 s30, s25, -1
	s_add_i32 s57, 0, 0x10000
	ds_read_b128 v[130:133], v203
	ds_read_b128 v[134:137], v203 offset:1024
	ds_read_b128 v[138:141], v203 offset:2048
	ds_read_b128 v[142:145], v203 offset:3072
	s_cmp_eq_u32 s17, s28
	s_cselect_b32 s28, s22, s19
	s_cselect_b32 s31, s21, s30
	s_cselect_b32 s30, s20, s29
	s_cselect_b32 s29, s23, s27
	s_add_i32 m0, s39, 0xc000
	ds_read_b128 v[146:149], v217
	ds_read_b128 v[150:153], v217 offset:1024
	ds_read_b128 v[154:157], v217 offset:2048
	ds_read_b128 v[158:161], v217 offset:3072
	ds_read_b128 v[162:165], v217 offset:4096
	ds_read_b128 v[166:169], v217 offset:5120
	ds_read_b128 v[170:173], v217 offset:6144
	ds_read_b128 v[174:177], v217 offset:7168
	global_load_lds_dwordx4 v204, s[24:25]
	s_add_i32 m0, s39, 0xe000
	s_nop 0
	global_load_lds_dwordx4 v206, s[24:25]
	s_waitcnt lgkmcnt(8)
	s_barrier
	s_waitcnt lgkmcnt(0)
	s_setprio 1
	v_mfma_f32_16x16x32_bf16 v[126:129], v[130:133], v[146:149], v[126:129]
	v_mfma_f32_16x16x32_bf16 v[122:125], v[138:141], v[146:149], v[122:125]
	v_mfma_f32_16x16x32_bf16 v[118:121], v[130:133], v[154:157], v[118:121]
	v_mfma_f32_16x16x32_bf16 v[114:117], v[138:141], v[154:157], v[114:117]
	v_mfma_f32_16x16x32_bf16 v[102:105], v[130:133], v[162:165], v[102:105]
	v_mfma_f32_16x16x32_bf16 v[98:101], v[138:141], v[162:165], v[98:101]
	v_mfma_f32_16x16x32_bf16 v[86:89], v[130:133], v[170:173], v[86:89]
	v_mfma_f32_16x16x32_bf16 v[82:85], v[138:141], v[170:173], v[82:85]
	v_mfma_f32_16x16x32_bf16 v[126:129], v[134:137], v[150:153], v[126:129]
	v_mfma_f32_16x16x32_bf16 v[122:125], v[142:145], v[150:153], v[122:125]
	v_mfma_f32_16x16x32_bf16 v[118:121], v[134:137], v[158:161], v[118:121]
	v_mfma_f32_16x16x32_bf16 v[114:117], v[142:145], v[158:161], v[114:117]
	v_mfma_f32_16x16x32_bf16 v[102:105], v[134:137], v[166:169], v[102:105]
	v_mfma_f32_16x16x32_bf16 v[98:101], v[142:145], v[166:169], v[98:101]
	v_mfma_f32_16x16x32_bf16 v[86:89], v[134:137], v[174:177], v[86:89]
	v_mfma_f32_16x16x32_bf16 v[82:85], v[142:145], v[174:177], v[82:85]
	s_setprio 0
	s_barrier
	s_add_i32 s60, 0, 0x14000
	s_add_i32 s57, s57, s38
	s_mov_b32 m0, s57
	ds_read_b128 v[178:181], v203 offset:16384
	ds_read_b128 v[182:185], v203 offset:17408
	ds_read_b128 v[186:189], v203 offset:18432
	ds_read_b128 v[190:193], v203 offset:19456
	global_load_lds_dwordx4 v48, s[28:29]
	s_add_i32 m0, s57, 0x2000
	s_nop 0
	global_load_lds_dwordx4 v202, s[28:29]
	s_barrier
	s_waitcnt lgkmcnt(0)
	s_setprio 1
	v_mfma_f32_16x16x32_bf16 v[110:113], v[178:181], v[146:149], v[110:113]
	v_mfma_f32_16x16x32_bf16 v[106:109], v[186:189], v[146:149], v[106:109]
	v_mfma_f32_16x16x32_bf16 v[94:97], v[178:181], v[154:157], v[94:97]
	v_mfma_f32_16x16x32_bf16 v[90:93], v[186:189], v[154:157], v[90:93]
	v_mfma_f32_16x16x32_bf16 v[78:81], v[178:181], v[162:165], v[78:81]
	v_mfma_f32_16x16x32_bf16 v[74:77], v[186:189], v[162:165], v[74:77]
	v_mfma_f32_16x16x32_bf16 v[70:73], v[178:181], v[170:173], v[70:73]
	v_mfma_f32_16x16x32_bf16 v[66:69], v[186:189], v[170:173], v[66:69]
	v_mfma_f32_16x16x32_bf16 v[110:113], v[182:185], v[150:153], v[110:113]
	v_mfma_f32_16x16x32_bf16 v[106:109], v[190:193], v[150:153], v[106:109]
	v_mfma_f32_16x16x32_bf16 v[94:97], v[182:185], v[158:161], v[94:97]
	v_mfma_f32_16x16x32_bf16 v[90:93], v[190:193], v[158:161], v[90:93]
	v_mfma_f32_16x16x32_bf16 v[78:81], v[182:185], v[166:169], v[78:81]
	v_mfma_f32_16x16x32_bf16 v[74:77], v[190:193], v[166:169], v[74:77]
	v_mfma_f32_16x16x32_bf16 v[70:73], v[182:185], v[174:177], v[70:73]
	v_mfma_f32_16x16x32_bf16 v[66:69], v[190:193], v[174:177], v[66:69]
	s_setprio 0
	s_mov_b32 m0, s39
	v_lshl_add_u64 v[212:213], s[30:31], 0, v[198:199]
	s_barrier
	ds_read_b128 v[146:149], v217 offset:16384
	ds_read_b128 v[150:153], v217 offset:17408
	ds_read_b128 v[154:157], v217 offset:18432
	ds_read_b128 v[158:161], v217 offset:19456
	ds_read_b128 v[162:165], v217 offset:20480
	ds_read_b128 v[166:169], v217 offset:21504
	ds_read_b128 v[170:173], v217 offset:22528
	ds_read_b128 v[174:177], v217 offset:23552
	global_load_lds_dwordx4 v[212:213], off
	v_lshl_add_u64 v[218:219], s[30:31], 0, v[200:201]
	s_mov_b32 m0, s40
	s_nop 0
	global_load_lds_dwordx4 v[218:219], off
	s_barrier
	s_waitcnt lgkmcnt(0)
	s_setprio 1
	v_mfma_f32_16x16x32_bf16 v[62:65], v[130:133], v[146:149], v[62:65]
	v_mfma_f32_16x16x32_bf16 v[58:61], v[138:141], v[146:149], v[58:61]
	v_mfma_f32_16x16x32_bf16 v[54:57], v[130:133], v[154:157], v[54:57]
	v_mfma_f32_16x16x32_bf16 v[50:53], v[138:141], v[154:157], v[50:53]
	v_mfma_f32_16x16x32_bf16 v[36:39], v[130:133], v[162:165], v[36:39]
	v_mfma_f32_16x16x32_bf16 v[32:35], v[138:141], v[162:165], v[32:35]
	v_mfma_f32_16x16x32_bf16 v[20:23], v[130:133], v[170:173], v[20:23]
	v_mfma_f32_16x16x32_bf16 v[16:19], v[138:141], v[170:173], v[16:19]
	v_mfma_f32_16x16x32_bf16 v[62:65], v[134:137], v[150:153], v[62:65]
	v_mfma_f32_16x16x32_bf16 v[58:61], v[142:145], v[150:153], v[58:61]
	v_mfma_f32_16x16x32_bf16 v[54:57], v[134:137], v[158:161], v[54:57]
	v_mfma_f32_16x16x32_bf16 v[50:53], v[142:145], v[158:161], v[50:53]
	v_mfma_f32_16x16x32_bf16 v[36:39], v[134:137], v[166:169], v[36:39]
	v_mfma_f32_16x16x32_bf16 v[32:35], v[142:145], v[166:169], v[32:35]
	v_mfma_f32_16x16x32_bf16 v[20:23], v[134:137], v[174:177], v[20:23]
	v_mfma_f32_16x16x32_bf16 v[16:19], v[142:145], v[174:177], v[16:19]
	s_setprio 0
	s_barrier
	s_add_u32 s58, s28, 0x40000
	s_addc_u32 s59, s29, 0
	s_add_i32 s57, s60, s38
	s_mov_b32 m0, s57
	s_nop 0
	global_load_lds_dwordx4 v48, s[58:59]
	s_add_i32 m0, s57, 0x2000
	s_nop 0
	global_load_lds_dwordx4 v202, s[58:59]
	s_waitcnt vmcnt(6)
	s_barrier
	s_setprio 1
	v_mfma_f32_16x16x32_bf16 v[44:47], v[178:181], v[146:149], v[44:47]
	v_mfma_f32_16x16x32_bf16 v[40:43], v[186:189], v[146:149], v[40:43]
	v_mfma_f32_16x16x32_bf16 v[28:31], v[178:181], v[154:157], v[28:31]
	v_mfma_f32_16x16x32_bf16 v[24:27], v[186:189], v[154:157], v[24:27]
	v_mfma_f32_16x16x32_bf16 v[12:15], v[178:181], v[162:165], v[12:15]
	v_mfma_f32_16x16x32_bf16 v[8:11], v[186:189], v[162:165], v[8:11]
	v_mfma_f32_16x16x32_bf16 v[4:7], v[178:181], v[170:173], v[4:7]
	v_mfma_f32_16x16x32_bf16 v[0:3], v[186:189], v[170:173], v[0:3]
	v_mfma_f32_16x16x32_bf16 v[44:47], v[182:185], v[150:153], v[44:47]
	v_mfma_f32_16x16x32_bf16 v[40:43], v[190:193], v[150:153], v[40:43]
	v_mfma_f32_16x16x32_bf16 v[28:31], v[182:185], v[158:161], v[28:31]
	v_mfma_f32_16x16x32_bf16 v[24:27], v[190:193], v[158:161], v[24:27]
	v_mfma_f32_16x16x32_bf16 v[12:15], v[182:185], v[166:169], v[12:15]
	v_mfma_f32_16x16x32_bf16 v[8:11], v[190:193], v[166:169], v[8:11]
	v_mfma_f32_16x16x32_bf16 v[4:7], v[182:185], v[174:177], v[4:7]
	v_mfma_f32_16x16x32_bf16 v[0:3], v[190:193], v[174:177], v[0:3]
	s_setprio 0
	s_add_i32 s57, 0, 0x18000
	s_barrier
	ds_read_b128 v[130:133], v203 offset:32768
	ds_read_b128 v[134:137], v203 offset:33792
	ds_read_b128 v[138:141], v203 offset:34816
	ds_read_b128 v[142:145], v203 offset:35840
	s_add_u32 s30, s30, 0x40000
	s_addc_u32 s31, s31, 0
	s_mov_b32 m0, s41
	ds_read_b128 v[146:149], v217 offset:32768
	ds_read_b128 v[150:153], v217 offset:33792
	ds_read_b128 v[154:157], v217 offset:34816
	ds_read_b128 v[158:161], v217 offset:35840
	ds_read_b128 v[162:165], v217 offset:36864
	ds_read_b128 v[166:169], v217 offset:37888
	ds_read_b128 v[170:173], v217 offset:38912
	ds_read_b128 v[174:177], v217 offset:39936
	global_load_lds_dwordx4 v198, s[30:31]
	s_mov_b32 m0, s42
	s_nop 0
	global_load_lds_dwordx4 v200, s[30:31]
	s_waitcnt lgkmcnt(8)
	s_barrier
	s_waitcnt lgkmcnt(0)
	s_setprio 1
	v_mfma_f32_16x16x32_bf16 v[126:129], v[130:133], v[146:149], v[126:129]
	v_mfma_f32_16x16x32_bf16 v[122:125], v[138:141], v[146:149], v[122:125]
	v_mfma_f32_16x16x32_bf16 v[118:121], v[130:133], v[154:157], v[118:121]
	v_mfma_f32_16x16x32_bf16 v[114:117], v[138:141], v[154:157], v[114:117]
	v_mfma_f32_16x16x32_bf16 v[102:105], v[130:133], v[162:165], v[102:105]
	v_mfma_f32_16x16x32_bf16 v[98:101], v[138:141], v[162:165], v[98:101]
	v_mfma_f32_16x16x32_bf16 v[86:89], v[130:133], v[170:173], v[86:89]
	v_mfma_f32_16x16x32_bf16 v[82:85], v[138:141], v[170:173], v[82:85]
	v_mfma_f32_16x16x32_bf16 v[126:129], v[134:137], v[150:153], v[126:129]
	v_mfma_f32_16x16x32_bf16 v[122:125], v[142:145], v[150:153], v[122:125]
	v_mfma_f32_16x16x32_bf16 v[118:121], v[134:137], v[158:161], v[118:121]
	v_mfma_f32_16x16x32_bf16 v[114:117], v[142:145], v[158:161], v[114:117]
	v_mfma_f32_16x16x32_bf16 v[102:105], v[134:137], v[166:169], v[102:105]
	v_mfma_f32_16x16x32_bf16 v[98:101], v[142:145], v[166:169], v[98:101]
	v_mfma_f32_16x16x32_bf16 v[86:89], v[134:137], v[174:177], v[86:89]
	v_mfma_f32_16x16x32_bf16 v[82:85], v[142:145], v[174:177], v[82:85]
	s_setprio 0
	s_barrier
	s_add_i32 s30, 0, 0x1c000
	s_add_i32 s31, s57, s38
	s_add_u32 s58, s28, s66
	s_addc_u32 s59, s29, s67
	s_mov_b32 m0, s31
	ds_read_b128 v[178:181], v203 offset:49152
	ds_read_b128 v[182:185], v203 offset:50176
	ds_read_b128 v[186:189], v203 offset:51200
	ds_read_b128 v[190:193], v203 offset:52224
	global_load_lds_dwordx4 v48, s[58:59]
	s_add_i32 m0, s31, 0x2000
	s_nop 0
	global_load_lds_dwordx4 v202, s[58:59]
	s_barrier
	s_waitcnt lgkmcnt(0)
	s_setprio 1
	v_mfma_f32_16x16x32_bf16 v[110:113], v[178:181], v[146:149], v[110:113]
	v_mfma_f32_16x16x32_bf16 v[106:109], v[186:189], v[146:149], v[106:109]
	v_mfma_f32_16x16x32_bf16 v[94:97], v[178:181], v[154:157], v[94:97]
	v_mfma_f32_16x16x32_bf16 v[90:93], v[186:189], v[154:157], v[90:93]
	v_mfma_f32_16x16x32_bf16 v[78:81], v[178:181], v[162:165], v[78:81]
	v_mfma_f32_16x16x32_bf16 v[74:77], v[186:189], v[162:165], v[74:77]
	v_mfma_f32_16x16x32_bf16 v[70:73], v[178:181], v[170:173], v[70:73]
	v_mfma_f32_16x16x32_bf16 v[66:69], v[186:189], v[170:173], v[66:69]
	v_mfma_f32_16x16x32_bf16 v[110:113], v[182:185], v[150:153], v[110:113]
	v_mfma_f32_16x16x32_bf16 v[106:109], v[190:193], v[150:153], v[106:109]
	v_mfma_f32_16x16x32_bf16 v[94:97], v[182:185], v[158:161], v[94:97]
	v_mfma_f32_16x16x32_bf16 v[90:93], v[190:193], v[158:161], v[90:93]
	v_mfma_f32_16x16x32_bf16 v[78:81], v[182:185], v[166:169], v[78:81]
	v_mfma_f32_16x16x32_bf16 v[74:77], v[190:193], v[166:169], v[74:77]
	v_mfma_f32_16x16x32_bf16 v[70:73], v[182:185], v[174:177], v[70:73]
	v_mfma_f32_16x16x32_bf16 v[66:69], v[190:193], v[174:177], v[66:69]
	s_setprio 0
	s_mov_b32 m0, s49
	v_lshl_add_u64 v[208:209], v[212:213], 0, s[66:67]
	s_barrier
	ds_read_b128 v[146:149], v217 offset:49152
	ds_read_b128 v[150:153], v217 offset:50176
	ds_read_b128 v[154:157], v217 offset:51200
	ds_read_b128 v[158:161], v217 offset:52224
	ds_read_b128 v[162:165], v217 offset:53248
	ds_read_b128 v[166:169], v217 offset:54272
	ds_read_b128 v[170:173], v217 offset:55296
	ds_read_b128 v[174:177], v217 offset:56320
	global_load_lds_dwordx4 v[208:209], off
	v_lshl_add_u64 v[208:209], v[218:219], 0, s[66:67]
	s_mov_b32 m0, s50
	s_nop 0
	global_load_lds_dwordx4 v[208:209], off
	s_barrier
	s_waitcnt lgkmcnt(0)
	s_setprio 1
	v_mfma_f32_16x16x32_bf16 v[62:65], v[130:133], v[146:149], v[62:65]
	v_mfma_f32_16x16x32_bf16 v[58:61], v[138:141], v[146:149], v[58:61]
	v_mfma_f32_16x16x32_bf16 v[54:57], v[130:133], v[154:157], v[54:57]
	v_mfma_f32_16x16x32_bf16 v[50:53], v[138:141], v[154:157], v[50:53]
	v_mfma_f32_16x16x32_bf16 v[36:39], v[130:133], v[162:165], v[36:39]
	v_mfma_f32_16x16x32_bf16 v[32:35], v[138:141], v[162:165], v[32:35]
	v_mfma_f32_16x16x32_bf16 v[20:23], v[130:133], v[170:173], v[20:23]
	v_mfma_f32_16x16x32_bf16 v[16:19], v[138:141], v[170:173], v[16:19]
	v_mfma_f32_16x16x32_bf16 v[62:65], v[134:137], v[150:153], v[62:65]
	v_mfma_f32_16x16x32_bf16 v[58:61], v[142:145], v[150:153], v[58:61]
	v_mfma_f32_16x16x32_bf16 v[54:57], v[134:137], v[158:161], v[54:57]
	v_mfma_f32_16x16x32_bf16 v[50:53], v[142:145], v[158:161], v[50:53]
	v_mfma_f32_16x16x32_bf16 v[36:39], v[134:137], v[166:169], v[36:39]
	v_mfma_f32_16x16x32_bf16 v[32:35], v[142:145], v[166:169], v[32:35]
	v_mfma_f32_16x16x32_bf16 v[20:23], v[134:137], v[174:177], v[20:23]
	v_mfma_f32_16x16x32_bf16 v[16:19], v[142:145], v[174:177], v[16:19]
	s_setprio 0
	s_barrier
	s_add_u32 s28, s28, 0x40080
	s_addc_u32 s29, s29, 0
	s_add_i32 s30, s30, s38
	s_mov_b32 m0, s30
	s_nop 0
	global_load_lds_dwordx4 v48, s[28:29]
	s_add_i32 m0, s30, 0x2000
	s_nop 0
	global_load_lds_dwordx4 v202, s[28:29]
	s_waitcnt vmcnt(6)
	s_barrier
	s_setprio 1
	v_mfma_f32_16x16x32_bf16 v[44:47], v[178:181], v[146:149], v[44:47]
	v_mfma_f32_16x16x32_bf16 v[40:43], v[186:189], v[146:149], v[40:43]
	v_mfma_f32_16x16x32_bf16 v[28:31], v[178:181], v[154:157], v[28:31]
	v_mfma_f32_16x16x32_bf16 v[24:27], v[186:189], v[154:157], v[24:27]
	v_mfma_f32_16x16x32_bf16 v[12:15], v[178:181], v[162:165], v[12:15]
	v_mfma_f32_16x16x32_bf16 v[8:11], v[186:189], v[162:165], v[8:11]
	v_mfma_f32_16x16x32_bf16 v[4:7], v[178:181], v[170:173], v[4:7]
	v_mfma_f32_16x16x32_bf16 v[0:3], v[186:189], v[170:173], v[0:3]
	v_mfma_f32_16x16x32_bf16 v[44:47], v[182:185], v[150:153], v[44:47]
	v_mfma_f32_16x16x32_bf16 v[40:43], v[190:193], v[150:153], v[40:43]
	v_mfma_f32_16x16x32_bf16 v[28:31], v[182:185], v[158:161], v[28:31]
	v_mfma_f32_16x16x32_bf16 v[24:27], v[190:193], v[158:161], v[24:27]
	v_mfma_f32_16x16x32_bf16 v[12:15], v[182:185], v[166:169], v[12:15]
	v_mfma_f32_16x16x32_bf16 v[8:11], v[190:193], v[166:169], v[8:11]
	v_mfma_f32_16x16x32_bf16 v[4:7], v[182:185], v[174:177], v[4:7]
	v_mfma_f32_16x16x32_bf16 v[0:3], v[190:193], v[174:177], v[0:3]
	s_setprio 0
	s_add_u32 s24, s24, 0x100
	s_addc_u32 s25, s25, 0
	s_add_u32 s19, s19, 0x100
	s_addc_u32 s27, s27, 0
	s_cmp_ge_i32 s56, s1
	s_mov_b32 s28, s56
	s_barrier
	s_cbranch_scc0 .LBB0_1056
	v_mov_b32_e32 v130, v214
	v_mov_b32_e32 v131, v215
	s_bitcmp1_b32 s55, 0
	v_add_u32_e32 v134, s47, v130
	v_lshlrev_b32_e32 v130, 8, v134
	v_lshl_add_u32 v132, v131, 3, s48
	v_ashrrev_i32_e32 v131, 31, v130
	v_lshl_add_u64 v[130:131], v[130:131], 1, s[12:13]
	v_ashrrev_i32_e32 v133, 31, v132
	s_cselect_b64 s[28:29], -1, 0
	v_lshlrev_b32_e32 v208, 9, v215
	v_lshl_add_u32 v208, v214, 4, v208
	v_lshl_add_u32 v208, s47, 9, v208
	v_lshl_add_u32 v208, s48, 6, v208
	v_mov_b32_e32 v209, 0
	v_lshl_add_u64 v[208:209], v[208:209], 0, s[12:13]
	s_mov_b64 s[24:25], -1
	s_and_b64 vcc, exec, s[28:29]
	s_mov_b32 s57, s81
	s_cbranch_vccz .LBB0_1093
	s_mov_b64 s[24:25], 0x20000
	v_lshl_add_u64 v[130:131], v[208:209], 0, s[24:25]
	s_and_b32 s1, s55, -2
	s_mov_b64 s[24:25], 0x100
	s_cmp_lg_u32 s1, 4
	v_mov_b64_e32 v[210:211], v[130:131]
	s_cbranch_scc1 .LBB0_1060
	v_lshl_add_u32 v134, s26, 8, v134
	v_ashrrev_i32_e32 v135, 31, v134
	v_lshlrev_b64 v[134:135], 11, v[134:135]
	s_lshl_b32 s0, s0, 8
	v_lshl_add_u64 v[134:135], s[14:15], 0, v[134:135]
	s_ashr_i32 s1, s0, 31
	v_lshl_add_u64 v[134:135], s[0:1], 1, v[134:135]
	v_lshl_add_u64 v[210:211], v[132:133], 1, v[134:135]
	s_mov_b64 s[24:25], 0x400

.LBB0_1202:
	s_add_u32 s28, s26, 0xfffc0080
	s_addc_u32 s29, s27, -1
	s_add_i32 s49, 0, 0x10000
	ds_read_b128 v[130:133], v218
	ds_read_b128 v[134:137], v218 offset:1024
	ds_read_b128 v[138:141], v218 offset:2048
	ds_read_b128 v[142:145], v218 offset:3072
	s_cmp_eq_u32 s25, 12
	s_cselect_b32 s31, s19, s29
	s_cselect_b32 s30, s18, s28
	s_cselect_b32 s29, s21, s17
	s_cselect_b32 s28, s20, s15
	v_lshl_add_u64 v[190:191], s[26:27], 0, v[150:151]
	s_add_i32 m0, s23, 0xc000
	ds_read_b128 v[154:157], v172
	ds_read_b128 v[158:161], v172 offset:1024
	ds_read_b128 v[162:165], v172 offset:2048
	ds_read_b128 v[166:169], v172 offset:3072
	ds_read_b128 v[174:177], v172 offset:4096
	ds_read_b128 v[178:181], v172 offset:5120
	ds_read_b128 v[182:185], v172 offset:6144
	ds_read_b128 v[186:189], v172 offset:7168
	global_load_lds_dwordx4 v[190:191], off
	v_lshl_add_u64 v[190:191], s[26:27], 0, v[152:153]
	s_add_i32 m0, s23, 0xe000
	s_nop 0
	global_load_lds_dwordx4 v[190:191], off
	s_waitcnt lgkmcnt(8)
	s_barrier
	s_waitcnt lgkmcnt(0)
	s_setprio 1
	v_mfma_f32_16x16x32_bf16 v[126:129], v[130:133], v[154:157], v[126:129]
	v_mfma_f32_16x16x32_bf16 v[122:125], v[138:141], v[154:157], v[122:125]
	v_mfma_f32_16x16x32_bf16 v[114:117], v[130:133], v[162:165], v[114:117]
	v_mfma_f32_16x16x32_bf16 v[106:109], v[138:141], v[162:165], v[106:109]
	v_mfma_f32_16x16x32_bf16 v[94:97], v[130:133], v[174:177], v[94:97]
	v_mfma_f32_16x16x32_bf16 v[90:93], v[138:141], v[174:177], v[90:93]
	v_mfma_f32_16x16x32_bf16 v[82:85], v[130:133], v[182:185], v[82:85]
	v_mfma_f32_16x16x32_bf16 v[74:77], v[138:141], v[182:185], v[74:77]
	v_mfma_f32_16x16x32_bf16 v[126:129], v[134:137], v[158:161], v[126:129]
	v_mfma_f32_16x16x32_bf16 v[122:125], v[142:145], v[158:161], v[122:125]
	v_mfma_f32_16x16x32_bf16 v[114:117], v[134:137], v[166:169], v[114:117]
	v_mfma_f32_16x16x32_bf16 v[106:109], v[142:145], v[166:169], v[106:109]
	v_mfma_f32_16x16x32_bf16 v[94:97], v[134:137], v[178:181], v[94:97]
	v_mfma_f32_16x16x32_bf16 v[90:93], v[142:145], v[178:181], v[90:93]
	v_mfma_f32_16x16x32_bf16 v[82:85], v[134:137], v[186:189], v[82:85]
	v_mfma_f32_16x16x32_bf16 v[74:77], v[142:145], v[186:189], v[74:77]
	s_setprio 0
	s_barrier
	s_add_i32 s52, 0, 0x14000
	s_add_i32 s49, s49, s35
	s_mov_b32 m0, s49
	ds_read_b128 v[190:193], v218 offset:16384
	ds_read_b128 v[198:201], v218 offset:17408
	ds_read_b128 v[202:205], v218 offset:18432
	ds_read_b128 v[206:209], v218 offset:19456
	global_load_lds_dwordx4 v48, s[28:29]
	v_lshl_add_u64 v[212:213], s[28:29], 0, v[146:147]
	s_add_i32 m0, s49, 0x2000
	s_nop 0
	global_load_lds_dwordx4 v[212:213], off
	s_barrier
	s_waitcnt lgkmcnt(0)
	s_setprio 1
	v_mfma_f32_16x16x32_bf16 v[118:121], v[190:193], v[154:157], v[118:121]
	v_mfma_f32_16x16x32_bf16 v[110:113], v[202:205], v[154:157], v[110:113]
	v_mfma_f32_16x16x32_bf16 v[102:105], v[190:193], v[162:165], v[102:105]
	v_mfma_f32_16x16x32_bf16 v[98:101], v[202:205], v[162:165], v[98:101]
	v_mfma_f32_16x16x32_bf16 v[86:89], v[190:193], v[174:177], v[86:89]
	v_mfma_f32_16x16x32_bf16 v[78:81], v[202:205], v[174:177], v[78:81]
	v_mfma_f32_16x16x32_bf16 v[70:73], v[190:193], v[182:185], v[70:73]
	v_mfma_f32_16x16x32_bf16 v[66:69], v[202:205], v[182:185], v[66:69]
	v_mfma_f32_16x16x32_bf16 v[118:121], v[198:201], v[158:161], v[118:121]
	v_mfma_f32_16x16x32_bf16 v[110:113], v[206:209], v[158:161], v[110:113]
	v_mfma_f32_16x16x32_bf16 v[102:105], v[198:201], v[166:169], v[102:105]
	v_mfma_f32_16x16x32_bf16 v[98:101], v[206:209], v[166:169], v[98:101]
	v_mfma_f32_16x16x32_bf16 v[86:89], v[198:201], v[178:181], v[86:89]
	v_mfma_f32_16x16x32_bf16 v[78:81], v[206:209], v[178:181], v[78:81]
	v_mfma_f32_16x16x32_bf16 v[70:73], v[198:201], v[186:189], v[70:73]
	v_mfma_f32_16x16x32_bf16 v[66:69], v[206:209], v[186:189], v[66:69]
	s_setprio 0
	s_mov_b32 m0, s23
	v_lshl_add_u64 v[214:215], s[30:31], 0, v[48:49]
	s_barrier
	ds_read_b128 v[154:157], v172 offset:16384
	ds_read_b128 v[158:161], v172 offset:17408
	ds_read_b128 v[162:165], v172 offset:18432
	ds_read_b128 v[166:169], v172 offset:19456
	ds_read_b128 v[174:177], v172 offset:20480
	ds_read_b128 v[178:181], v172 offset:21504
	ds_read_b128 v[182:185], v172 offset:22528
	ds_read_b128 v[186:189], v172 offset:23552
	global_load_lds_dwordx4 v[214:215], off
	v_lshl_add_u64 v[216:217], s[30:31], 0, v[146:147]
	s_mov_b32 m0, s41
	s_nop 0
	global_load_lds_dwordx4 v[216:217], off
	s_barrier
	s_waitcnt lgkmcnt(0)
	s_setprio 1
	v_mfma_f32_16x16x32_bf16 v[62:65], v[130:133], v[154:157], v[62:65]
	v_mfma_f32_16x16x32_bf16 v[58:61], v[138:141], v[154:157], v[58:61]
	v_mfma_f32_16x16x32_bf16 v[50:53], v[130:133], v[162:165], v[50:53]
	v_mfma_f32_16x16x32_bf16 v[40:43], v[138:141], v[162:165], v[40:43]
	v_mfma_f32_16x16x32_bf16 v[32:35], v[130:133], v[174:177], v[32:35]
	v_mfma_f32_16x16x32_bf16 v[24:27], v[138:141], v[174:177], v[24:27]
	v_mfma_f32_16x16x32_bf16 v[16:19], v[130:133], v[182:185], v[16:19]
	v_mfma_f32_16x16x32_bf16 v[8:11], v[138:141], v[182:185], v[8:11]
	v_mfma_f32_16x16x32_bf16 v[62:65], v[134:137], v[158:161], v[62:65]
	v_mfma_f32_16x16x32_bf16 v[58:61], v[142:145], v[158:161], v[58:61]
	v_mfma_f32_16x16x32_bf16 v[50:53], v[134:137], v[166:169], v[50:53]
	v_mfma_f32_16x16x32_bf16 v[40:43], v[142:145], v[166:169], v[40:43]
	v_mfma_f32_16x16x32_bf16 v[32:35], v[134:137], v[178:181], v[32:35]
	v_mfma_f32_16x16x32_bf16 v[24:27], v[142:145], v[178:181], v[24:27]
	v_mfma_f32_16x16x32_bf16 v[16:19], v[134:137], v[186:189], v[16:19]
	v_mfma_f32_16x16x32_bf16 v[8:11], v[142:145], v[186:189], v[8:11]
	s_setprio 0
	s_barrier
	s_add_u32 s50, s28, 0x40000
	s_addc_u32 s51, s29, 0
	s_add_i32 s49, s52, s35
	s_mov_b32 m0, s49
	s_nop 0
	global_load_lds_dwordx4 v48, s[50:51]
	v_lshl_add_u64 v[130:131], s[50:51], 0, v[146:147]
	s_add_i32 m0, s49, 0x2000
	s_nop 0
	global_load_lds_dwordx4 v[130:131], off
	s_waitcnt vmcnt(6)
	s_barrier
	s_setprio 1
	v_mfma_f32_16x16x32_bf16 v[54:57], v[190:193], v[154:157], v[54:57]
	v_mfma_f32_16x16x32_bf16 v[44:47], v[202:205], v[154:157], v[44:47]
	v_mfma_f32_16x16x32_bf16 v[36:39], v[190:193], v[162:165], v[36:39]
	v_mfma_f32_16x16x32_bf16 v[28:31], v[202:205], v[162:165], v[28:31]
	v_mfma_f32_16x16x32_bf16 v[20:23], v[190:193], v[174:177], v[20:23]
	v_mfma_f32_16x16x32_bf16 v[12:15], v[202:205], v[174:177], v[12:15]
	v_mfma_f32_16x16x32_bf16 v[4:7], v[190:193], v[182:185], v[4:7]
	v_mfma_f32_16x16x32_bf16 v[0:3], v[202:205], v[182:185], v[0:3]
	v_mfma_f32_16x16x32_bf16 v[54:57], v[198:201], v[158:161], v[54:57]
	v_mfma_f32_16x16x32_bf16 v[44:47], v[206:209], v[158:161], v[44:47]
	v_mfma_f32_16x16x32_bf16 v[36:39], v[198:201], v[166:169], v[36:39]
	v_mfma_f32_16x16x32_bf16 v[28:31], v[206:209], v[166:169], v[28:31]
	v_mfma_f32_16x16x32_bf16 v[20:23], v[198:201], v[178:181], v[20:23]
	v_mfma_f32_16x16x32_bf16 v[12:15], v[206:209], v[178:181], v[12:15]
	v_mfma_f32_16x16x32_bf16 v[4:7], v[198:201], v[186:189], v[4:7]
	v_mfma_f32_16x16x32_bf16 v[0:3], v[206:209], v[186:189], v[0:3]
	s_setprio 0
	s_add_i32 s49, 0, 0x18000
	s_barrier
	ds_read_b128 v[130:133], v218 offset:32768
	ds_read_b128 v[134:137], v218 offset:33792
	ds_read_b128 v[138:141], v218 offset:34816
	ds_read_b128 v[142:145], v218 offset:35840
	s_add_u32 s30, s30, 0x40000
	s_addc_u32 s31, s31, 0
	s_mov_b32 m0, s42
	ds_read_b128 v[154:157], v172 offset:32768
	ds_read_b128 v[158:161], v172 offset:33792
	ds_read_b128 v[162:165], v172 offset:34816
	ds_read_b128 v[166:169], v172 offset:35840
	ds_read_b128 v[174:177], v172 offset:36864
	ds_read_b128 v[178:181], v172 offset:37888
	ds_read_b128 v[182:185], v172 offset:38912
	ds_read_b128 v[186:189], v172 offset:39936
	global_load_lds_dwordx4 v48, s[30:31]
	v_lshl_add_u64 v[190:191], s[30:31], 0, v[146:147]
	s_mov_b32 m0, s43
	s_nop 0
	global_load_lds_dwordx4 v[190:191], off
	s_waitcnt lgkmcnt(8)
	s_barrier
	s_waitcnt lgkmcnt(0)
	s_setprio 1
	v_mfma_f32_16x16x32_bf16 v[126:129], v[130:133], v[154:157], v[126:129]
	v_mfma_f32_16x16x32_bf16 v[122:125], v[138:141], v[154:157], v[122:125]
	v_mfma_f32_16x16x32_bf16 v[114:117], v[130:133], v[162:165], v[114:117]
	v_mfma_f32_16x16x32_bf16 v[106:109], v[138:141], v[162:165], v[106:109]
	v_mfma_f32_16x16x32_bf16 v[94:97], v[130:133], v[174:177], v[94:97]
	v_mfma_f32_16x16x32_bf16 v[90:93], v[138:141], v[174:177], v[90:93]
	v_mfma_f32_16x16x32_bf16 v[82:85], v[130:133], v[182:185], v[82:85]
	v_mfma_f32_16x16x32_bf16 v[74:77], v[138:141], v[182:185], v[74:77]
	v_mfma_f32_16x16x32_bf16 v[126:129], v[134:137], v[158:161], v[126:129]
	v_mfma_f32_16x16x32_bf16 v[122:125], v[142:145], v[158:161], v[122:125]
	v_mfma_f32_16x16x32_bf16 v[114:117], v[134:137], v[166:169], v[114:117]
	v_mfma_f32_16x16x32_bf16 v[106:109], v[142:145], v[166:169], v[106:109]
	v_mfma_f32_16x16x32_bf16 v[94:97], v[134:137], v[178:181], v[94:97]
	v_mfma_f32_16x16x32_bf16 v[90:93], v[142:145], v[178:181], v[90:93]
	v_mfma_f32_16x16x32_bf16 v[82:85], v[134:137], v[186:189], v[82:85]
	v_mfma_f32_16x16x32_bf16 v[74:77], v[142:145], v[186:189], v[74:77]
	s_setprio 0
	s_barrier
	s_add_i32 s30, 0, 0x1c000
	s_add_i32 s31, s49, s35
	s_add_u32 s52, s28, s66
	s_addc_u32 s53, s29, s67
	s_mov_b32 m0, s31
	ds_read_b128 v[190:193], v218 offset:49152
	ds_read_b128 v[198:201], v218 offset:50176
	ds_read_b128 v[202:205], v218 offset:51200
	ds_read_b128 v[206:209], v218 offset:52224
	global_load_lds_dwordx4 v48, s[52:53]
	v_lshl_add_u64 v[210:211], v[212:213], 0, s[66:67]
	s_add_i32 m0, s31, 0x2000
	s_nop 0
	global_load_lds_dwordx4 v[210:211], off
	s_barrier
	s_waitcnt lgkmcnt(0)
	s_setprio 1
	v_mfma_f32_16x16x32_bf16 v[118:121], v[190:193], v[154:157], v[118:121]
	v_mfma_f32_16x16x32_bf16 v[110:113], v[202:205], v[154:157], v[110:113]
	v_mfma_f32_16x16x32_bf16 v[102:105], v[190:193], v[162:165], v[102:105]
	v_mfma_f32_16x16x32_bf16 v[98:101], v[202:205], v[162:165], v[98:101]
	v_mfma_f32_16x16x32_bf16 v[86:89], v[190:193], v[174:177], v[86:89]
	v_mfma_f32_16x16x32_bf16 v[78:81], v[202:205], v[174:177], v[78:81]
	v_mfma_f32_16x16x32_bf16 v[70:73], v[190:193], v[182:185], v[70:73]
	v_mfma_f32_16x16x32_bf16 v[66:69], v[202:205], v[182:185], v[66:69]
	v_mfma_f32_16x16x32_bf16 v[118:121], v[198:201], v[158:161], v[118:121]
	v_mfma_f32_16x16x32_bf16 v[110:113], v[206:209], v[158:161], v[110:113]
	v_mfma_f32_16x16x32_bf16 v[102:105], v[198:201], v[166:169], v[102:105]
	v_mfma_f32_16x16x32_bf16 v[98:101], v[206:209], v[166:169], v[98:101]
	v_mfma_f32_16x16x32_bf16 v[86:89], v[198:201], v[178:181], v[86:89]
	v_mfma_f32_16x16x32_bf16 v[78:81], v[206:209], v[178:181], v[78:81]
	v_mfma_f32_16x16x32_bf16 v[70:73], v[198:201], v[186:189], v[70:73]
	v_mfma_f32_16x16x32_bf16 v[66:69], v[206:209], v[186:189], v[66:69]
	s_setprio 0
	s_mov_b32 m0, s46
	v_lshl_add_u64 v[210:211], v[214:215], 0, s[66:67]
	s_barrier
	ds_read_b128 v[154:157], v172 offset:49152
	ds_read_b128 v[158:161], v172 offset:50176
	ds_read_b128 v[162:165], v172 offset:51200
	ds_read_b128 v[166:169], v172 offset:52224
	ds_read_b128 v[174:177], v172 offset:53248
	ds_read_b128 v[178:181], v172 offset:54272
	ds_read_b128 v[182:185], v172 offset:55296
	ds_read_b128 v[186:189], v172 offset:56320
	global_load_lds_dwordx4 v[210:211], off
	v_lshl_add_u64 v[210:211], v[216:217], 0, s[66:67]
	s_mov_b32 m0, s47
	s_nop 0
	global_load_lds_dwordx4 v[210:211], off
	s_barrier
	s_waitcnt lgkmcnt(0)
	s_setprio 1
	v_mfma_f32_16x16x32_bf16 v[62:65], v[130:133], v[154:157], v[62:65]
	v_mfma_f32_16x16x32_bf16 v[58:61], v[138:141], v[154:157], v[58:61]
	v_mfma_f32_16x16x32_bf16 v[50:53], v[130:133], v[162:165], v[50:53]
	v_mfma_f32_16x16x32_bf16 v[40:43], v[138:141], v[162:165], v[40:43]
	v_mfma_f32_16x16x32_bf16 v[32:35], v[130:133], v[174:177], v[32:35]
	v_mfma_f32_16x16x32_bf16 v[24:27], v[138:141], v[174:177], v[24:27]
	v_mfma_f32_16x16x32_bf16 v[16:19], v[130:133], v[182:185], v[16:19]
	v_mfma_f32_16x16x32_bf16 v[8:11], v[138:141], v[182:185], v[8:11]
	v_mfma_f32_16x16x32_bf16 v[62:65], v[134:137], v[158:161], v[62:65]
	v_mfma_f32_16x16x32_bf16 v[58:61], v[142:145], v[158:161], v[58:61]
	v_mfma_f32_16x16x32_bf16 v[50:53], v[134:137], v[166:169], v[50:53]
	v_mfma_f32_16x16x32_bf16 v[40:43], v[142:145], v[166:169], v[40:43]
	v_mfma_f32_16x16x32_bf16 v[32:35], v[134:137], v[178:181], v[32:35]
	v_mfma_f32_16x16x32_bf16 v[24:27], v[142:145], v[178:181], v[24:27]
	v_mfma_f32_16x16x32_bf16 v[16:19], v[134:137], v[186:189], v[16:19]
	v_mfma_f32_16x16x32_bf16 v[8:11], v[142:145], v[186:189], v[8:11]
	s_setprio 0
	s_barrier
	s_add_u32 s28, s28, 0x40080
	s_addc_u32 s29, s29, 0
	s_add_i32 s30, s30, s35
	s_mov_b32 m0, s30
	s_nop 0
	global_load_lds_dwordx4 v48, s[28:29]
	v_lshl_add_u64 v[130:131], s[28:29], 0, v[146:147]
	s_add_i32 m0, s30, 0x2000
	s_nop 0
	global_load_lds_dwordx4 v[130:131], off
	s_waitcnt vmcnt(6)
	s_barrier
	s_setprio 1
	v_mfma_f32_16x16x32_bf16 v[54:57], v[190:193], v[154:157], v[54:57]
	v_mfma_f32_16x16x32_bf16 v[44:47], v[202:205], v[154:157], v[44:47]
	v_mfma_f32_16x16x32_bf16 v[36:39], v[190:193], v[162:165], v[36:39]
	v_mfma_f32_16x16x32_bf16 v[28:31], v[202:205], v[162:165], v[28:31]
	v_mfma_f32_16x16x32_bf16 v[20:23], v[190:193], v[174:177], v[20:23]
	v_mfma_f32_16x16x32_bf16 v[12:15], v[202:205], v[174:177], v[12:15]
	v_mfma_f32_16x16x32_bf16 v[4:7], v[190:193], v[182:185], v[4:7]
	v_mfma_f32_16x16x32_bf16 v[0:3], v[202:205], v[182:185], v[0:3]
	v_mfma_f32_16x16x32_bf16 v[54:57], v[198:201], v[158:161], v[54:57]
	v_mfma_f32_16x16x32_bf16 v[44:47], v[206:209], v[158:161], v[44:47]
	v_mfma_f32_16x16x32_bf16 v[36:39], v[198:201], v[166:169], v[36:39]
	v_mfma_f32_16x16x32_bf16 v[28:31], v[206:209], v[166:169], v[28:31]
	v_mfma_f32_16x16x32_bf16 v[20:23], v[198:201], v[178:181], v[20:23]
	v_mfma_f32_16x16x32_bf16 v[12:15], v[206:209], v[178:181], v[12:15]
	v_mfma_f32_16x16x32_bf16 v[4:7], v[198:201], v[186:189], v[4:7]
	v_mfma_f32_16x16x32_bf16 v[0:3], v[206:209], v[186:189], v[0:3]
	s_setprio 0
	s_add_i32 s25, s25, 2
	s_add_u32 s26, s26, 0x100
	s_addc_u32 s27, s27, 0
	s_add_u32 s15, s15, 0x100
	s_addc_u32 s17, s17, 0
	s_cmp_gt_u32 s25, 13
	s_barrier
	s_cbranch_scc0 .LBB0_1202
	s_mul_hi_i32 s15, s24, 0x38e38e39
	s_lshr_b32 s17, s15, 31
	s_ashr_i32 s15, s15, 1
	s_add_i32 s15, s15, s17
	s_mul_i32 s17, s15, -9
	s_sub_i32 s25, 0, s24
	s_cmp_eq_u32 s17, s25
	s_mov_b64 s[26:27], 0x30000
	s_cbranch_scc1 .LBB0_1198
	s_mul_hi_i32 s27, s15, 0x1800
	s_mul_i32 s26, s15, 0x1800
	s_branch .LBB0_1198

.LBB0_1219:
	s_add_u32 s26, s24, 0xfffc0080
	s_addc_u32 s27, s25, -1
	s_add_i32 s31, 0, 0x10000
	ds_read_b128 v[130:133], v201
	ds_read_b128 v[134:137], v201 offset:1024
	ds_read_b128 v[138:141], v201 offset:2048
	ds_read_b128 v[142:145], v201 offset:3072
	s_cmp_eq_u32 s30, 12
	s_cselect_b32 s29, s19, s27
	s_cselect_b32 s28, s18, s26
	s_cselect_b32 s27, s21, s17
	s_cselect_b32 s26, s20, s15
	s_add_i32 m0, s41, 0xc000
	ds_read_b128 v[146:149], v210
	ds_read_b128 v[150:153], v210 offset:1024
	ds_read_b128 v[154:157], v210 offset:2048
	ds_read_b128 v[158:161], v210 offset:3072
	ds_read_b128 v[162:165], v210 offset:4096
	ds_read_b128 v[166:169], v210 offset:5120
	ds_read_b128 v[170:173], v210 offset:6144
	ds_read_b128 v[174:177], v210 offset:7168
	global_load_lds_dwordx4 v200, s[24:25]
	s_add_i32 m0, s41, 0xe000
	s_nop 0
	global_load_lds_dwordx4 v202, s[24:25]
	s_waitcnt lgkmcnt(8)
	s_barrier
	s_waitcnt lgkmcnt(0)
	s_setprio 1
	v_mfma_f32_16x16x32_bf16 v[126:129], v[130:133], v[146:149], v[126:129]
	v_mfma_f32_16x16x32_bf16 v[122:125], v[138:141], v[146:149], v[122:125]
	v_mfma_f32_16x16x32_bf16 v[118:121], v[130:133], v[154:157], v[118:121]
	v_mfma_f32_16x16x32_bf16 v[106:109], v[138:141], v[154:157], v[106:109]
	v_mfma_f32_16x16x32_bf16 v[94:97], v[130:133], v[162:165], v[94:97]
	v_mfma_f32_16x16x32_bf16 v[90:93], v[138:141], v[162:165], v[90:93]
	v_mfma_f32_16x16x32_bf16 v[86:89], v[130:133], v[170:173], v[86:89]
	v_mfma_f32_16x16x32_bf16 v[74:77], v[138:141], v[170:173], v[74:77]
	v_mfma_f32_16x16x32_bf16 v[126:129], v[134:137], v[150:153], v[126:129]
	v_mfma_f32_16x16x32_bf16 v[122:125], v[142:145], v[150:153], v[122:125]
	v_mfma_f32_16x16x32_bf16 v[118:121], v[134:137], v[158:161], v[118:121]
	v_mfma_f32_16x16x32_bf16 v[106:109], v[142:145], v[158:161], v[106:109]
	v_mfma_f32_16x16x32_bf16 v[94:97], v[134:137], v[166:169], v[94:97]
	v_mfma_f32_16x16x32_bf16 v[90:93], v[142:145], v[166:169], v[90:93]
	v_mfma_f32_16x16x32_bf16 v[86:89], v[134:137], v[174:177], v[86:89]
	v_mfma_f32_16x16x32_bf16 v[74:77], v[142:145], v[174:177], v[74:77]
	s_setprio 0
	s_barrier
	s_add_i32 s50, 0, 0x14000
	s_add_i32 s31, s31, s40
	s_mov_b32 m0, s31
	ds_read_b128 v[178:181], v201 offset:16384
	ds_read_b128 v[182:185], v201 offset:17408
	ds_read_b128 v[186:189], v201 offset:18432
	ds_read_b128 v[204:207], v201 offset:19456
	global_load_lds_dwordx4 v48, s[26:27]
	s_add_i32 m0, s31, 0x2000
	s_nop 0
	global_load_lds_dwordx4 v190, s[26:27]
	s_barrier
	s_waitcnt lgkmcnt(0)
	s_setprio 1
	v_mfma_f32_16x16x32_bf16 v[114:117], v[178:181], v[146:149], v[114:117]
	v_mfma_f32_16x16x32_bf16 v[110:113], v[186:189], v[146:149], v[110:113]
	v_mfma_f32_16x16x32_bf16 v[102:105], v[178:181], v[154:157], v[102:105]
	v_mfma_f32_16x16x32_bf16 v[98:101], v[186:189], v[154:157], v[98:101]
	v_mfma_f32_16x16x32_bf16 v[82:85], v[178:181], v[162:165], v[82:85]
	v_mfma_f32_16x16x32_bf16 v[78:81], v[186:189], v[162:165], v[78:81]
	v_mfma_f32_16x16x32_bf16 v[70:73], v[178:181], v[170:173], v[70:73]
	v_mfma_f32_16x16x32_bf16 v[66:69], v[186:189], v[170:173], v[66:69]
	v_mfma_f32_16x16x32_bf16 v[114:117], v[182:185], v[150:153], v[114:117]
	v_mfma_f32_16x16x32_bf16 v[110:113], v[204:207], v[150:153], v[110:113]
	v_mfma_f32_16x16x32_bf16 v[102:105], v[182:185], v[158:161], v[102:105]
	v_mfma_f32_16x16x32_bf16 v[98:101], v[204:207], v[158:161], v[98:101]
	v_mfma_f32_16x16x32_bf16 v[82:85], v[182:185], v[166:169], v[82:85]
	v_mfma_f32_16x16x32_bf16 v[78:81], v[204:207], v[166:169], v[78:81]
	v_mfma_f32_16x16x32_bf16 v[70:73], v[182:185], v[174:177], v[70:73]
	v_mfma_f32_16x16x32_bf16 v[66:69], v[204:207], v[174:177], v[66:69]
	s_setprio 0
	s_mov_b32 m0, s41
	v_lshl_add_u64 v[216:217], s[28:29], 0, v[48:49]
	s_barrier
	ds_read_b128 v[146:149], v210 offset:16384
	ds_read_b128 v[150:153], v210 offset:17408
	ds_read_b128 v[154:157], v210 offset:18432
	ds_read_b128 v[158:161], v210 offset:19456
	ds_read_b128 v[162:165], v210 offset:20480
	ds_read_b128 v[166:169], v210 offset:21504
	ds_read_b128 v[170:173], v210 offset:22528
	ds_read_b128 v[174:177], v210 offset:23552
	global_load_lds_dwordx4 v[216:217], off
	v_lshl_add_u64 v[218:219], s[28:29], 0, v[190:191]
	s_mov_b32 m0, s42
	s_nop 0
	global_load_lds_dwordx4 v[218:219], off
	s_barrier
	s_waitcnt lgkmcnt(0)
	s_setprio 1
	v_mfma_f32_16x16x32_bf16 v[62:65], v[130:133], v[146:149], v[62:65]
	v_mfma_f32_16x16x32_bf16 v[58:61], v[138:141], v[146:149], v[58:61]
	v_mfma_f32_16x16x32_bf16 v[54:57], v[130:133], v[154:157], v[54:57]
	v_mfma_f32_16x16x32_bf16 v[40:43], v[138:141], v[154:157], v[40:43]
	v_mfma_f32_16x16x32_bf16 v[36:39], v[130:133], v[162:165], v[36:39]
	v_mfma_f32_16x16x32_bf16 v[24:27], v[138:141], v[162:165], v[24:27]
	v_mfma_f32_16x16x32_bf16 v[20:23], v[130:133], v[170:173], v[20:23]
	v_mfma_f32_16x16x32_bf16 v[8:11], v[138:141], v[170:173], v[8:11]
	v_mfma_f32_16x16x32_bf16 v[62:65], v[134:137], v[150:153], v[62:65]
	v_mfma_f32_16x16x32_bf16 v[58:61], v[142:145], v[150:153], v[58:61]
	v_mfma_f32_16x16x32_bf16 v[54:57], v[134:137], v[158:161], v[54:57]
	v_mfma_f32_16x16x32_bf16 v[40:43], v[142:145], v[158:161], v[40:43]
	v_mfma_f32_16x16x32_bf16 v[36:39], v[134:137], v[166:169], v[36:39]
	v_mfma_f32_16x16x32_bf16 v[24:27], v[142:145], v[166:169], v[24:27]
	v_mfma_f32_16x16x32_bf16 v[20:23], v[134:137], v[174:177], v[20:23]
	v_mfma_f32_16x16x32_bf16 v[8:11], v[142:145], v[174:177], v[8:11]
	s_setprio 0
	s_barrier
	s_add_u32 s34, s26, 0x40000
	s_addc_u32 s35, s27, 0
	s_add_i32 s31, s50, s40
	s_mov_b32 m0, s31
	s_nop 0
	global_load_lds_dwordx4 v48, s[34:35]
	s_add_i32 m0, s31, 0x2000
	s_nop 0
	global_load_lds_dwordx4 v190, s[34:35]
	s_waitcnt vmcnt(6)
	s_barrier
	s_setprio 1
	v_mfma_f32_16x16x32_bf16 v[50:53], v[178:181], v[146:149], v[50:53]
	v_mfma_f32_16x16x32_bf16 v[44:47], v[186:189], v[146:149], v[44:47]
	v_mfma_f32_16x16x32_bf16 v[32:35], v[178:181], v[154:157], v[32:35]
	v_mfma_f32_16x16x32_bf16 v[28:31], v[186:189], v[154:157], v[28:31]
	v_mfma_f32_16x16x32_bf16 v[16:19], v[178:181], v[162:165], v[16:19]
	v_mfma_f32_16x16x32_bf16 v[12:15], v[186:189], v[162:165], v[12:15]
	v_mfma_f32_16x16x32_bf16 v[4:7], v[178:181], v[170:173], v[4:7]
	v_mfma_f32_16x16x32_bf16 v[0:3], v[186:189], v[170:173], v[0:3]
	v_mfma_f32_16x16x32_bf16 v[50:53], v[182:185], v[150:153], v[50:53]
	v_mfma_f32_16x16x32_bf16 v[44:47], v[204:207], v[150:153], v[44:47]
	v_mfma_f32_16x16x32_bf16 v[32:35], v[182:185], v[158:161], v[32:35]
	v_mfma_f32_16x16x32_bf16 v[28:31], v[204:207], v[158:161], v[28:31]
	v_mfma_f32_16x16x32_bf16 v[16:19], v[182:185], v[166:169], v[16:19]
	v_mfma_f32_16x16x32_bf16 v[12:15], v[204:207], v[166:169], v[12:15]
	v_mfma_f32_16x16x32_bf16 v[4:7], v[182:185], v[174:177], v[4:7]
	v_mfma_f32_16x16x32_bf16 v[0:3], v[204:207], v[174:177], v[0:3]
	s_setprio 0
	s_add_i32 s31, 0, 0x18000
	s_barrier
	ds_read_b128 v[130:133], v201 offset:32768
	ds_read_b128 v[134:137], v201 offset:33792
	ds_read_b128 v[138:141], v201 offset:34816
	ds_read_b128 v[142:145], v201 offset:35840
	s_add_u32 s28, s28, 0x40000
	s_addc_u32 s29, s29, 0
	s_mov_b32 m0, s43
	ds_read_b128 v[146:149], v210 offset:32768
	ds_read_b128 v[150:153], v210 offset:33792
	ds_read_b128 v[154:157], v210 offset:34816
	ds_read_b128 v[158:161], v210 offset:35840
	ds_read_b128 v[162:165], v210 offset:36864
	ds_read_b128 v[166:169], v210 offset:37888
	ds_read_b128 v[170:173], v210 offset:38912
	ds_read_b128 v[174:177], v210 offset:39936
	global_load_lds_dwordx4 v48, s[28:29]
	s_mov_b32 m0, s44
	s_nop 0
	global_load_lds_dwordx4 v190, s[28:29]
	s_waitcnt lgkmcnt(8)
	s_barrier
	s_waitcnt lgkmcnt(0)
	s_setprio 1
	v_mfma_f32_16x16x32_bf16 v[126:129], v[130:133], v[146:149], v[126:129]
	v_mfma_f32_16x16x32_bf16 v[122:125], v[138:141], v[146:149], v[122:125]
	v_mfma_f32_16x16x32_bf16 v[118:121], v[130:133], v[154:157], v[118:121]
	v_mfma_f32_16x16x32_bf16 v[106:109], v[138:141], v[154:157], v[106:109]
	v_mfma_f32_16x16x32_bf16 v[94:97], v[130:133], v[162:165], v[94:97]
	v_mfma_f32_16x16x32_bf16 v[90:93], v[138:141], v[162:165], v[90:93]
	v_mfma_f32_16x16x32_bf16 v[86:89], v[130:133], v[170:173], v[86:89]
	v_mfma_f32_16x16x32_bf16 v[74:77], v[138:141], v[170:173], v[74:77]
	v_mfma_f32_16x16x32_bf16 v[126:129], v[134:137], v[150:153], v[126:129]
	v_mfma_f32_16x16x32_bf16 v[122:125], v[142:145], v[150:153], v[122:125]
	v_mfma_f32_16x16x32_bf16 v[118:121], v[134:137], v[158:161], v[118:121]
	v_mfma_f32_16x16x32_bf16 v[106:109], v[142:145], v[158:161], v[106:109]
	v_mfma_f32_16x16x32_bf16 v[94:97], v[134:137], v[166:169], v[94:97]
	v_mfma_f32_16x16x32_bf16 v[90:93], v[142:145], v[166:169], v[90:93]
	v_mfma_f32_16x16x32_bf16 v[86:89], v[134:137], v[174:177], v[86:89]
	v_mfma_f32_16x16x32_bf16 v[74:77], v[142:145], v[174:177], v[74:77]
	s_setprio 0
	s_barrier
	s_add_i32 s28, 0, 0x1c000
	s_add_i32 s29, s31, s40
	s_add_u32 s52, s26, s66
	s_addc_u32 s53, s27, s67
	s_mov_b32 m0, s29
	ds_read_b128 v[178:181], v201 offset:49152
	ds_read_b128 v[182:185], v201 offset:50176
	ds_read_b128 v[186:189], v201 offset:51200
	ds_read_b128 v[204:207], v201 offset:52224
	global_load_lds_dwordx4 v48, s[52:53]
	s_add_i32 m0, s29, 0x2000
	s_nop 0
	global_load_lds_dwordx4 v190, s[52:53]
	s_barrier
	s_waitcnt lgkmcnt(0)
	s_setprio 1
	v_mfma_f32_16x16x32_bf16 v[114:117], v[178:181], v[146:149], v[114:117]
	v_mfma_f32_16x16x32_bf16 v[110:113], v[186:189], v[146:149], v[110:113]
	v_mfma_f32_16x16x32_bf16 v[102:105], v[178:181], v[154:157], v[102:105]
	v_mfma_f32_16x16x32_bf16 v[98:101], v[186:189], v[154:157], v[98:101]
	v_mfma_f32_16x16x32_bf16 v[82:85], v[178:181], v[162:165], v[82:85]
	v_mfma_f32_16x16x32_bf16 v[78:81], v[186:189], v[162:165], v[78:81]
	v_mfma_f32_16x16x32_bf16 v[70:73], v[178:181], v[170:173], v[70:73]
	v_mfma_f32_16x16x32_bf16 v[66:69], v[186:189], v[170:173], v[66:69]
	v_mfma_f32_16x16x32_bf16 v[114:117], v[182:185], v[150:153], v[114:117]
	v_mfma_f32_16x16x32_bf16 v[110:113], v[204:207], v[150:153], v[110:113]
	v_mfma_f32_16x16x32_bf16 v[102:105], v[182:185], v[158:161], v[102:105]
	v_mfma_f32_16x16x32_bf16 v[98:101], v[204:207], v[158:161], v[98:101]
	v_mfma_f32_16x16x32_bf16 v[82:85], v[182:185], v[166:169], v[82:85]
	v_mfma_f32_16x16x32_bf16 v[78:81], v[204:207], v[166:169], v[78:81]
	v_mfma_f32_16x16x32_bf16 v[70:73], v[182:185], v[174:177], v[70:73]
	v_mfma_f32_16x16x32_bf16 v[66:69], v[204:207], v[174:177], v[66:69]
	s_setprio 0
	s_mov_b32 m0, s47
	v_lshl_add_u64 v[212:213], v[216:217], 0, s[66:67]
	s_barrier
	ds_read_b128 v[146:149], v210 offset:49152
	ds_read_b128 v[150:153], v210 offset:50176
	ds_read_b128 v[154:157], v210 offset:51200
	ds_read_b128 v[158:161], v210 offset:52224
	ds_read_b128 v[162:165], v210 offset:53248
	ds_read_b128 v[166:169], v210 offset:54272
	ds_read_b128 v[170:173], v210 offset:55296
	ds_read_b128 v[174:177], v210 offset:56320
	global_load_lds_dwordx4 v[212:213], off
	v_lshl_add_u64 v[212:213], v[218:219], 0, s[66:67]
	s_mov_b32 m0, s48
	s_nop 0
	global_load_lds_dwordx4 v[212:213], off
	s_barrier
	s_waitcnt lgkmcnt(0)
	s_setprio 1
	v_mfma_f32_16x16x32_bf16 v[62:65], v[130:133], v[146:149], v[62:65]
	v_mfma_f32_16x16x32_bf16 v[58:61], v[138:141], v[146:149], v[58:61]
	v_mfma_f32_16x16x32_bf16 v[54:57], v[130:133], v[154:157], v[54:57]
	v_mfma_f32_16x16x32_bf16 v[40:43], v[138:141], v[154:157], v[40:43]
	v_mfma_f32_16x16x32_bf16 v[36:39], v[130:133], v[162:165], v[36:39]
	v_mfma_f32_16x16x32_bf16 v[24:27], v[138:141], v[162:165], v[24:27]
	v_mfma_f32_16x16x32_bf16 v[20:23], v[130:133], v[170:173], v[20:23]
	v_mfma_f32_16x16x32_bf16 v[8:11], v[138:141], v[170:173], v[8:11]
	v_mfma_f32_16x16x32_bf16 v[62:65], v[134:137], v[150:153], v[62:65]
	v_mfma_f32_16x16x32_bf16 v[58:61], v[142:145], v[150:153], v[58:61]
	v_mfma_f32_16x16x32_bf16 v[54:57], v[134:137], v[158:161], v[54:57]
	v_mfma_f32_16x16x32_bf16 v[40:43], v[142:145], v[158:161], v[40:43]
	v_mfma_f32_16x16x32_bf16 v[36:39], v[134:137], v[166:169], v[36:39]
	v_mfma_f32_16x16x32_bf16 v[24:27], v[142:145], v[166:169], v[24:27]
	v_mfma_f32_16x16x32_bf16 v[20:23], v[134:137], v[174:177], v[20:23]
	v_mfma_f32_16x16x32_bf16 v[8:11], v[142:145], v[174:177], v[8:11]
	s_setprio 0
	s_barrier
	s_add_u32 s26, s26, 0x40080
	s_addc_u32 s27, s27, 0
	s_add_i32 s28, s28, s40
	s_mov_b32 m0, s28
	s_nop 0
	global_load_lds_dwordx4 v48, s[26:27]
	s_add_i32 m0, s28, 0x2000
	s_nop 0
	global_load_lds_dwordx4 v190, s[26:27]
	s_waitcnt vmcnt(6)
	s_barrier
	s_setprio 1
	v_mfma_f32_16x16x32_bf16 v[50:53], v[178:181], v[146:149], v[50:53]
	v_mfma_f32_16x16x32_bf16 v[44:47], v[186:189], v[146:149], v[44:47]
	v_mfma_f32_16x16x32_bf16 v[32:35], v[178:181], v[154:157], v[32:35]
	v_mfma_f32_16x16x32_bf16 v[28:31], v[186:189], v[154:157], v[28:31]
	v_mfma_f32_16x16x32_bf16 v[16:19], v[178:181], v[162:165], v[16:19]
	v_mfma_f32_16x16x32_bf16 v[12:15], v[186:189], v[162:165], v[12:15]
	v_mfma_f32_16x16x32_bf16 v[4:7], v[178:181], v[170:173], v[4:7]
	v_mfma_f32_16x16x32_bf16 v[0:3], v[186:189], v[170:173], v[0:3]
	v_mfma_f32_16x16x32_bf16 v[50:53], v[182:185], v[150:153], v[50:53]
	v_mfma_f32_16x16x32_bf16 v[44:47], v[204:207], v[150:153], v[44:47]
	v_mfma_f32_16x16x32_bf16 v[32:35], v[182:185], v[158:161], v[32:35]
	v_mfma_f32_16x16x32_bf16 v[28:31], v[204:207], v[158:161], v[28:31]
	v_mfma_f32_16x16x32_bf16 v[16:19], v[182:185], v[166:169], v[16:19]
	v_mfma_f32_16x16x32_bf16 v[12:15], v[204:207], v[166:169], v[12:15]
	v_mfma_f32_16x16x32_bf16 v[4:7], v[182:185], v[174:177], v[4:7]
	v_mfma_f32_16x16x32_bf16 v[0:3], v[204:207], v[174:177], v[0:3]
	s_setprio 0
	s_add_i32 s30, s30, 2
	s_add_u32 s24, s24, 0x100
	s_addc_u32 s25, s25, 0
	s_add_u32 s15, s15, 0x100
	s_addc_u32 s17, s17, 0
	s_cmp_gt_u32 s30, 13
	s_barrier
	s_cbranch_scc0 .LBB0_1219
	s_mul_hi_i32 s15, s22, 0x38e38e39
	s_lshr_b32 s17, s15, 31
	s_ashr_i32 s15, s15, 1
	s_add_i32 s24, s15, s17
	s_mul_i32 s15, s24, -9
	s_add_i32 s28, s15, s22
	s_cmp_eq_u32 s28, 0
	s_cselect_b64 s[26:27], -1, 0
	s_ashr_i32 s25, s24, 31
	s_cmp_lg_u32 s28, 0
	s_cbranch_scc0 .LBB0_1222
	s_ashr_i32 s29, s28, 31
	s_lshl_b64 s[28:29], s[28:29], 18
	s_lshl_b64 s[30:31], s[24:25], 21
	s_add_u32 s15, s28, s30
	s_addc_u32 s17, s29, s31
	s_add_u32 s28, s15, 0xfffc0000
	s_addc_u32 s29, s17, -1
	s_mov_b64 s[30:31], s[6:7]
	s_cbranch_execnz .LBB0_1215
	s_branch .LBB0_1214

.LBB0_1356:
	s_add_u32 s28, s26, 0xfffc0080
	s_addc_u32 s29, s27, -1
	s_add_i32 s46, 0, 0x10000
	ds_read_b128 v[146:149], v137
	ds_read_b128 v[150:153], v137 offset:1024
	ds_read_b128 v[154:157], v137 offset:2048
	ds_read_b128 v[158:161], v137 offset:3072
	s_cmp_eq_u32 s45, 12
	s_cselect_b32 s31, s19, s29
	s_cselect_b32 s30, s18, s28
	s_cselect_b32 s29, s21, s17
	s_cselect_b32 s28, s20, s15
	s_add_i32 m0, s23, 0xc000
	ds_read_b128 v[162:165], v145
	ds_read_b128 v[166:169], v145 offset:1024
	ds_read_b128 v[170:173], v145 offset:2048
	ds_read_b128 v[174:177], v145 offset:3072
	ds_read_b128 v[178:181], v145 offset:4096
	ds_read_b128 v[182:185], v145 offset:5120
	ds_read_b128 v[186:189], v145 offset:6144
	ds_read_b128 v[190:193], v145 offset:7168
	global_load_lds_dwordx4 v136, s[26:27]
	s_add_i32 m0, s23, 0xe000
	s_nop 0
	global_load_lds_dwordx4 v138, s[26:27]
	s_waitcnt lgkmcnt(8)
	s_barrier
	s_waitcnt lgkmcnt(0)
	s_setprio 1
	v_mfma_f32_16x16x32_bf16 v[126:129], v[146:149], v[162:165], v[126:129]
	v_mfma_f32_16x16x32_bf16 v[118:121], v[154:157], v[162:165], v[118:121]
	v_mfma_f32_16x16x32_bf16 v[110:113], v[146:149], v[170:173], v[110:113]
	v_mfma_f32_16x16x32_bf16 v[102:105], v[154:157], v[170:173], v[102:105]
	v_mfma_f32_16x16x32_bf16 v[94:97], v[146:149], v[178:181], v[94:97]
	v_mfma_f32_16x16x32_bf16 v[86:89], v[154:157], v[178:181], v[86:89]
	v_mfma_f32_16x16x32_bf16 v[78:81], v[146:149], v[186:189], v[78:81]
	v_mfma_f32_16x16x32_bf16 v[70:73], v[154:157], v[186:189], v[70:73]
	v_mfma_f32_16x16x32_bf16 v[126:129], v[150:153], v[166:169], v[126:129]
	v_mfma_f32_16x16x32_bf16 v[118:121], v[158:161], v[166:169], v[118:121]
	v_mfma_f32_16x16x32_bf16 v[110:113], v[150:153], v[174:177], v[110:113]
	v_mfma_f32_16x16x32_bf16 v[102:105], v[158:161], v[174:177], v[102:105]
	v_mfma_f32_16x16x32_bf16 v[94:97], v[150:153], v[182:185], v[94:97]
	v_mfma_f32_16x16x32_bf16 v[86:89], v[158:161], v[182:185], v[86:89]
	v_mfma_f32_16x16x32_bf16 v[78:81], v[150:153], v[190:193], v[78:81]
	v_mfma_f32_16x16x32_bf16 v[70:73], v[158:161], v[190:193], v[70:73]
	s_setprio 0
	s_barrier
	s_add_i32 s48, 0, 0x14000
	s_add_i32 s46, s46, s37
	ds_read_b128 v[198:201], v137 offset:16384
	ds_read_b128 v[202:205], v137 offset:17408
	ds_read_b128 v[206:209], v137 offset:18432
	ds_read_b128 v[210:213], v137 offset:19456
	s_mov_b32 m0, s46
	global_load_lds_dwordx4 v48, s[28:29]
	s_add_i32 m0, s46, 0x2000
	s_nop 0
	global_load_lds_dwordx4 v130, s[28:29]
	s_barrier
	s_waitcnt lgkmcnt(0)
	s_setprio 1
	v_mfma_f32_16x16x32_bf16 v[122:125], v[198:201], v[162:165], v[122:125]
	v_mfma_f32_16x16x32_bf16 v[114:117], v[206:209], v[162:165], v[114:117]
	v_mfma_f32_16x16x32_bf16 v[106:109], v[198:201], v[170:173], v[106:109]
	v_mfma_f32_16x16x32_bf16 v[98:101], v[206:209], v[170:173], v[98:101]
	v_mfma_f32_16x16x32_bf16 v[90:93], v[198:201], v[178:181], v[90:93]
	v_mfma_f32_16x16x32_bf16 v[82:85], v[206:209], v[178:181], v[82:85]
	v_mfma_f32_16x16x32_bf16 v[74:77], v[198:201], v[186:189], v[74:77]
	v_mfma_f32_16x16x32_bf16 v[66:69], v[206:209], v[186:189], v[66:69]
	v_mfma_f32_16x16x32_bf16 v[122:125], v[202:205], v[166:169], v[122:125]
	v_mfma_f32_16x16x32_bf16 v[114:117], v[210:213], v[166:169], v[114:117]
	v_mfma_f32_16x16x32_bf16 v[106:109], v[202:205], v[174:177], v[106:109]
	v_mfma_f32_16x16x32_bf16 v[98:101], v[210:213], v[174:177], v[98:101]
	v_mfma_f32_16x16x32_bf16 v[90:93], v[202:205], v[182:185], v[90:93]
	v_mfma_f32_16x16x32_bf16 v[82:85], v[210:213], v[182:185], v[82:85]
	v_mfma_f32_16x16x32_bf16 v[74:77], v[202:205], v[190:193], v[74:77]
	v_mfma_f32_16x16x32_bf16 v[66:69], v[210:213], v[190:193], v[66:69]
	s_setprio 0
	s_mov_b32 m0, s23
	v_lshl_add_u64 v[216:217], s[30:31], 0, v[134:135]
	s_barrier
	ds_read_b128 v[162:165], v145 offset:16384
	ds_read_b128 v[166:169], v145 offset:17408
	ds_read_b128 v[170:173], v145 offset:18432
	ds_read_b128 v[174:177], v145 offset:19456
	ds_read_b128 v[178:181], v145 offset:20480
	ds_read_b128 v[182:185], v145 offset:21504
	ds_read_b128 v[186:189], v145 offset:22528
	ds_read_b128 v[190:193], v145 offset:23552
	global_load_lds_dwordx4 v[216:217], off
	v_lshl_add_u64 v[218:219], s[30:31], 0, v[132:133]
	s_mov_b32 m0, s25
	s_nop 0
	global_load_lds_dwordx4 v[218:219], off
	s_barrier
	s_waitcnt lgkmcnt(0)
	s_setprio 1
	v_mfma_f32_16x16x32_bf16 v[62:65], v[146:149], v[162:165], v[62:65]
	v_mfma_f32_16x16x32_bf16 v[54:57], v[154:157], v[162:165], v[54:57]
	v_mfma_f32_16x16x32_bf16 v[44:47], v[146:149], v[170:173], v[44:47]
	v_mfma_f32_16x16x32_bf16 v[36:39], v[154:157], v[170:173], v[36:39]
	v_mfma_f32_16x16x32_bf16 v[28:31], v[146:149], v[178:181], v[28:31]
	v_mfma_f32_16x16x32_bf16 v[20:23], v[154:157], v[178:181], v[20:23]
	v_mfma_f32_16x16x32_bf16 v[12:15], v[146:149], v[186:189], v[12:15]
	v_mfma_f32_16x16x32_bf16 v[4:7], v[154:157], v[186:189], v[4:7]
	v_mfma_f32_16x16x32_bf16 v[62:65], v[150:153], v[166:169], v[62:65]
	v_mfma_f32_16x16x32_bf16 v[54:57], v[158:161], v[166:169], v[54:57]
	v_mfma_f32_16x16x32_bf16 v[44:47], v[150:153], v[174:177], v[44:47]
	v_mfma_f32_16x16x32_bf16 v[36:39], v[158:161], v[174:177], v[36:39]
	v_mfma_f32_16x16x32_bf16 v[28:31], v[150:153], v[182:185], v[28:31]
	v_mfma_f32_16x16x32_bf16 v[20:23], v[158:161], v[182:185], v[20:23]
	v_mfma_f32_16x16x32_bf16 v[12:15], v[150:153], v[190:193], v[12:15]
	v_mfma_f32_16x16x32_bf16 v[4:7], v[158:161], v[190:193], v[4:7]
	s_setprio 0
	s_barrier
	s_add_u32 s46, s28, 0x40000
	s_addc_u32 s47, s29, 0
	s_add_i32 s48, s48, s37
	s_mov_b32 m0, s48
	s_nop 0
	global_load_lds_dwordx4 v48, s[46:47]
	s_add_i32 m0, s48, 0x2000
	s_nop 0
	global_load_lds_dwordx4 v130, s[46:47]
	s_waitcnt vmcnt(6)
	s_barrier
	s_setprio 1
	v_mfma_f32_16x16x32_bf16 v[58:61], v[198:201], v[162:165], v[58:61]
	v_mfma_f32_16x16x32_bf16 v[50:53], v[206:209], v[162:165], v[50:53]
	v_mfma_f32_16x16x32_bf16 v[40:43], v[198:201], v[170:173], v[40:43]
	v_mfma_f32_16x16x32_bf16 v[32:35], v[206:209], v[170:173], v[32:35]
	v_mfma_f32_16x16x32_bf16 v[24:27], v[198:201], v[178:181], v[24:27]
	v_mfma_f32_16x16x32_bf16 v[16:19], v[206:209], v[178:181], v[16:19]
	v_mfma_f32_16x16x32_bf16 v[8:11], v[198:201], v[186:189], v[8:11]
	v_mfma_f32_16x16x32_bf16 v[0:3], v[206:209], v[186:189], v[0:3]
	v_mfma_f32_16x16x32_bf16 v[58:61], v[202:205], v[166:169], v[58:61]
	v_mfma_f32_16x16x32_bf16 v[50:53], v[210:213], v[166:169], v[50:53]
	v_mfma_f32_16x16x32_bf16 v[40:43], v[202:205], v[174:177], v[40:43]
	v_mfma_f32_16x16x32_bf16 v[32:35], v[210:213], v[174:177], v[32:35]
	v_mfma_f32_16x16x32_bf16 v[24:27], v[202:205], v[182:185], v[24:27]
	v_mfma_f32_16x16x32_bf16 v[16:19], v[210:213], v[182:185], v[16:19]
	v_mfma_f32_16x16x32_bf16 v[8:11], v[202:205], v[190:193], v[8:11]
	v_mfma_f32_16x16x32_bf16 v[0:3], v[210:213], v[190:193], v[0:3]
	s_setprio 0
	s_add_i32 s46, 0, 0x18000
	s_barrier
	ds_read_b128 v[146:149], v137 offset:32768
	ds_read_b128 v[150:153], v137 offset:33792
	ds_read_b128 v[154:157], v137 offset:34816
	ds_read_b128 v[158:161], v137 offset:35840
	s_add_u32 s30, s30, 0x40000
	s_addc_u32 s31, s31, 0
	s_mov_b32 m0, s40
	ds_read_b128 v[162:165], v145 offset:32768
	ds_read_b128 v[166:169], v145 offset:33792
	ds_read_b128 v[170:173], v145 offset:34816
	ds_read_b128 v[174:177], v145 offset:35840
	ds_read_b128 v[178:181], v145 offset:36864
	ds_read_b128 v[182:185], v145 offset:37888
	ds_read_b128 v[186:189], v145 offset:38912
	ds_read_b128 v[190:193], v145 offset:39936
	global_load_lds_dwordx4 v134, s[30:31]
	s_mov_b32 m0, s41
	s_nop 0
	global_load_lds_dwordx4 v132, s[30:31]
	s_waitcnt lgkmcnt(8)
	s_barrier
	s_waitcnt lgkmcnt(0)
	s_setprio 1
	v_mfma_f32_16x16x32_bf16 v[126:129], v[146:149], v[162:165], v[126:129]
	v_mfma_f32_16x16x32_bf16 v[118:121], v[154:157], v[162:165], v[118:121]
	v_mfma_f32_16x16x32_bf16 v[110:113], v[146:149], v[170:173], v[110:113]
	v_mfma_f32_16x16x32_bf16 v[102:105], v[154:157], v[170:173], v[102:105]
	v_mfma_f32_16x16x32_bf16 v[94:97], v[146:149], v[178:181], v[94:97]
	v_mfma_f32_16x16x32_bf16 v[86:89], v[154:157], v[178:181], v[86:89]
	v_mfma_f32_16x16x32_bf16 v[78:81], v[146:149], v[186:189], v[78:81]
	v_mfma_f32_16x16x32_bf16 v[70:73], v[154:157], v[186:189], v[70:73]
	v_mfma_f32_16x16x32_bf16 v[126:129], v[150:153], v[166:169], v[126:129]
	v_mfma_f32_16x16x32_bf16 v[118:121], v[158:161], v[166:169], v[118:121]
	v_mfma_f32_16x16x32_bf16 v[110:113], v[150:153], v[174:177], v[110:113]
	v_mfma_f32_16x16x32_bf16 v[102:105], v[158:161], v[174:177], v[102:105]
	v_mfma_f32_16x16x32_bf16 v[94:97], v[150:153], v[182:185], v[94:97]
	v_mfma_f32_16x16x32_bf16 v[86:89], v[158:161], v[182:185], v[86:89]
	v_mfma_f32_16x16x32_bf16 v[78:81], v[150:153], v[190:193], v[78:81]
	v_mfma_f32_16x16x32_bf16 v[70:73], v[158:161], v[190:193], v[70:73]
	s_setprio 0
	s_barrier
	s_add_i32 s30, 0, 0x1c000
	s_add_i32 s31, s46, s37
	s_add_u32 s46, s28, s66
	s_addc_u32 s47, s29, s67
	s_mov_b32 m0, s31
	ds_read_b128 v[198:201], v137 offset:49152
	ds_read_b128 v[202:205], v137 offset:50176
	ds_read_b128 v[206:209], v137 offset:51200
	ds_read_b128 v[210:213], v137 offset:52224
	global_load_lds_dwordx4 v48, s[46:47]
	s_add_i32 m0, s31, 0x2000
	s_nop 0
	global_load_lds_dwordx4 v130, s[46:47]
	s_barrier
	s_waitcnt lgkmcnt(0)
	s_setprio 1
	v_mfma_f32_16x16x32_bf16 v[122:125], v[198:201], v[162:165], v[122:125]
	v_mfma_f32_16x16x32_bf16 v[114:117], v[206:209], v[162:165], v[114:117]
	v_mfma_f32_16x16x32_bf16 v[106:109], v[198:201], v[170:173], v[106:109]
	v_mfma_f32_16x16x32_bf16 v[98:101], v[206:209], v[170:173], v[98:101]
	v_mfma_f32_16x16x32_bf16 v[90:93], v[198:201], v[178:181], v[90:93]
	v_mfma_f32_16x16x32_bf16 v[82:85], v[206:209], v[178:181], v[82:85]
	v_mfma_f32_16x16x32_bf16 v[74:77], v[198:201], v[186:189], v[74:77]
	v_mfma_f32_16x16x32_bf16 v[66:69], v[206:209], v[186:189], v[66:69]
	v_mfma_f32_16x16x32_bf16 v[122:125], v[202:205], v[166:169], v[122:125]
	v_mfma_f32_16x16x32_bf16 v[114:117], v[210:213], v[166:169], v[114:117]
	v_mfma_f32_16x16x32_bf16 v[106:109], v[202:205], v[174:177], v[106:109]
	v_mfma_f32_16x16x32_bf16 v[98:101], v[210:213], v[174:177], v[98:101]
	v_mfma_f32_16x16x32_bf16 v[90:93], v[202:205], v[182:185], v[90:93]
	v_mfma_f32_16x16x32_bf16 v[82:85], v[210:213], v[182:185], v[82:85]
	v_mfma_f32_16x16x32_bf16 v[74:77], v[202:205], v[190:193], v[74:77]
	v_mfma_f32_16x16x32_bf16 v[66:69], v[210:213], v[190:193], v[66:69]
	s_setprio 0
	s_mov_b32 m0, s42
	v_lshl_add_u64 v[140:141], v[216:217], 0, s[66:67]
	s_barrier
	ds_read_b128 v[162:165], v145 offset:49152
	ds_read_b128 v[166:169], v145 offset:50176
	ds_read_b128 v[170:173], v145 offset:51200
	ds_read_b128 v[174:177], v145 offset:52224
	ds_read_b128 v[178:181], v145 offset:53248
	ds_read_b128 v[182:185], v145 offset:54272
	ds_read_b128 v[186:189], v145 offset:55296
	ds_read_b128 v[190:193], v145 offset:56320
	global_load_lds_dwordx4 v[140:141], off
	v_lshl_add_u64 v[140:141], v[218:219], 0, s[66:67]
	s_mov_b32 m0, s43
	s_nop 0
	global_load_lds_dwordx4 v[140:141], off
	s_barrier
	s_waitcnt lgkmcnt(0)
	s_setprio 1
	v_mfma_f32_16x16x32_bf16 v[62:65], v[146:149], v[162:165], v[62:65]
	v_mfma_f32_16x16x32_bf16 v[54:57], v[154:157], v[162:165], v[54:57]
	v_mfma_f32_16x16x32_bf16 v[44:47], v[146:149], v[170:173], v[44:47]
	v_mfma_f32_16x16x32_bf16 v[36:39], v[154:157], v[170:173], v[36:39]
	v_mfma_f32_16x16x32_bf16 v[28:31], v[146:149], v[178:181], v[28:31]
	v_mfma_f32_16x16x32_bf16 v[20:23], v[154:157], v[178:181], v[20:23]
	v_mfma_f32_16x16x32_bf16 v[12:15], v[146:149], v[186:189], v[12:15]
	v_mfma_f32_16x16x32_bf16 v[4:7], v[154:157], v[186:189], v[4:7]
	v_mfma_f32_16x16x32_bf16 v[62:65], v[150:153], v[166:169], v[62:65]
	v_mfma_f32_16x16x32_bf16 v[54:57], v[158:161], v[166:169], v[54:57]
	v_mfma_f32_16x16x32_bf16 v[44:47], v[150:153], v[174:177], v[44:47]
	v_mfma_f32_16x16x32_bf16 v[36:39], v[158:161], v[174:177], v[36:39]
	v_mfma_f32_16x16x32_bf16 v[28:31], v[150:153], v[182:185], v[28:31]
	v_mfma_f32_16x16x32_bf16 v[20:23], v[158:161], v[182:185], v[20:23]
	v_mfma_f32_16x16x32_bf16 v[12:15], v[150:153], v[190:193], v[12:15]
	v_mfma_f32_16x16x32_bf16 v[4:7], v[158:161], v[190:193], v[4:7]
	s_setprio 0
	s_barrier
	s_add_u32 s28, s28, 0x40080
	s_addc_u32 s29, s29, 0
	s_add_i32 s30, s30, s37
	s_mov_b32 m0, s30
	s_nop 0
	global_load_lds_dwordx4 v48, s[28:29]
	s_add_i32 m0, s30, 0x2000
	s_nop 0
	global_load_lds_dwordx4 v130, s[28:29]
	s_waitcnt vmcnt(6)
	s_barrier
	s_setprio 1
	v_mfma_f32_16x16x32_bf16 v[58:61], v[198:201], v[162:165], v[58:61]
	v_mfma_f32_16x16x32_bf16 v[50:53], v[206:209], v[162:165], v[50:53]
	v_mfma_f32_16x16x32_bf16 v[40:43], v[198:201], v[170:173], v[40:43]
	v_mfma_f32_16x16x32_bf16 v[32:35], v[206:209], v[170:173], v[32:35]
	v_mfma_f32_16x16x32_bf16 v[24:27], v[198:201], v[178:181], v[24:27]
	v_mfma_f32_16x16x32_bf16 v[16:19], v[206:209], v[178:181], v[16:19]
	v_mfma_f32_16x16x32_bf16 v[8:11], v[198:201], v[186:189], v[8:11]
	v_mfma_f32_16x16x32_bf16 v[0:3], v[206:209], v[186:189], v[0:3]
	v_mfma_f32_16x16x32_bf16 v[58:61], v[202:205], v[166:169], v[58:61]
	v_mfma_f32_16x16x32_bf16 v[50:53], v[210:213], v[166:169], v[50:53]
	v_mfma_f32_16x16x32_bf16 v[40:43], v[202:205], v[174:177], v[40:43]
	v_mfma_f32_16x16x32_bf16 v[32:35], v[210:213], v[174:177], v[32:35]
	v_mfma_f32_16x16x32_bf16 v[24:27], v[202:205], v[182:185], v[24:27]
	v_mfma_f32_16x16x32_bf16 v[16:19], v[210:213], v[182:185], v[16:19]
	v_mfma_f32_16x16x32_bf16 v[8:11], v[202:205], v[190:193], v[8:11]
	v_mfma_f32_16x16x32_bf16 v[0:3], v[210:213], v[190:193], v[0:3]
	s_setprio 0
	s_add_i32 s45, s45, 2
	s_add_u32 s26, s26, 0x100
	s_addc_u32 s27, s27, 0
	s_add_u32 s15, s15, 0x100
	s_addc_u32 s17, s17, 0
	s_cmp_gt_u32 s45, 13
	s_barrier
	s_cbranch_scc0 .LBB0_1356
	v_mul_f32_e32 v147, 0xbfb8aa3b, v126
	v_exp_f32_e32 v148, v147
	v_mul_f32_e32 v147, 0xbfb8aa3b, v118
	v_exp_f32_e32 v150, v147
	v_mul_f32_e32 v147, 0xbfb8aa3b, v127
	v_exp_f32_e32 v149, v147
	v_lshl_or_b32 v140, s22, 7, v144
	v_lshl_add_u32 v146, s24, 8, v142
	v_ashrrev_i32_e32 v141, 31, v140
	v_pk_add_f32 v[148:149], v[148:149], 1.0 op_sel_hi:[1,0]
	s_movk_i32 s15, 0x1600
	s_mov_b32 s22, s14
	s_mov_b32 s24, s16
	s_mov_b64 s[28:29], s[20:21]
	v_rcp_f32_e32 v147, v149
	s_nop 0
	v_mul_f32_e32 v127, v127, v147
	s_nop 0
	v_rcp_f32_e32 v147, v148
	s_nop 0
	v_mul_f32_e32 v126, v126, v147
	v_pk_mul_f32 v[122:123], v[122:123], v[126:127]
	v_mul_f32_e32 v126, 0xbfb8aa3b, v119
	v_exp_f32_e32 v151, v126
	s_nop 0
	v_pk_add_f32 v[126:127], v[150:151], 1.0 op_sel_hi:[1,0]
	s_nop 0
	s_nop 0
	v_rcp_f32_e32 v147, v127
	s_nop 0
	v_mul_f32_e32 v119, v119, v147
	s_nop 0
	v_rcp_f32_e32 v127, v126
	s_nop 0
	v_mul_f32_e32 v118, v118, v127
	v_pk_mul_f32 v[114:115], v[114:115], v[118:119]
	v_mul_f32_e32 v119, 0xbfb8aa3b, v120
	v_mul_f32_e32 v118, 0xbfb8aa3b, v128
	v_exp_f32_e32 v126, v119
	v_mul_f32_e32 v119, 0xbfb8aa3b, v129
	v_exp_f32_e32 v118, v118
	v_exp_f32_e32 v119, v119
	s_nop 0
	v_pk_add_f32 v[118:119], v[118:119], 1.0 op_sel_hi:[1,0]
	s_nop 0
	s_nop 0
	v_rcp_f32_e32 v127, v119
	s_nop 0
	v_mul_f32_e32 v119, v129, v127
	s_nop 0
	v_rcp_f32_e32 v127, v118
	s_nop 0
	v_mul_f32_e32 v118, v128, v127
	v_pk_mul_f32 v[124:125], v[124:125], v[118:119]
	v_mul_f32_e32 v118, 0xbfb8aa3b, v121
	v_exp_f32_e32 v127, v118
	s_nop 0
	v_pk_add_f32 v[118:119], v[126:127], 1.0 op_sel_hi:[1,0]
	s_nop 0
	s_nop 0
	v_rcp_f32_e32 v126, v119
	s_nop 0
	v_mul_f32_e32 v119, v121, v126
	s_nop 0
	v_rcp_f32_e32 v121, v118
	s_nop 0
	v_mul_f32_e32 v118, v120, v121
	v_pk_mul_f32 v[116:117], v[116:117], v[118:119]
	v_cvt_pk_bf16_f32 v120, v114, v115
	v_mov_b64_e32 v[114:115], s[12:13]
	v_cvt_pk_bf16_f32 v118, v122, v123
	v_cvt_pk_bf16_f32 v121, v116, v117
	v_mad_i64_i32 v[122:123], s[26:27], v146, s15, v[114:115]
	v_lshlrev_b64 v[116:117], 1, v[140:141]
	v_cvt_pk_bf16_f32 v119, v124, v125
	v_lshl_add_u64 v[122:123], v[122:123], 0, v[116:117]
	global_store_dwordx4 v[122:123], v[118:121], off
	s_nop 1
	v_mul_f32_e32 v119, 0xbfb8aa3b, v102
	v_mul_f32_e32 v118, 0xbfb8aa3b, v110
	v_exp_f32_e32 v120, v119
	v_mul_f32_e32 v119, 0xbfb8aa3b, v111
	v_exp_f32_e32 v118, v118
	v_exp_f32_e32 v119, v119
	s_nop 0
	v_pk_add_f32 v[118:119], v[118:119], 1.0 op_sel_hi:[1,0]
	s_nop 0
	s_nop 0
	v_rcp_f32_e32 v121, v119
	s_nop 0
	v_mul_f32_e32 v111, v111, v121
	s_nop 0
	v_rcp_f32_e32 v119, v118
	s_nop 0
	v_mul_f32_e32 v110, v110, v119
	v_pk_mul_f32 v[106:107], v[106:107], v[110:111]
	v_mul_f32_e32 v110, 0xbfb8aa3b, v103
	v_exp_f32_e32 v121, v110
	s_nop 0
	v_pk_add_f32 v[110:111], v[120:121], 1.0 op_sel_hi:[1,0]
	s_nop 0
	s_nop 0
	v_rcp_f32_e32 v118, v111
	s_nop 0
	v_mul_f32_e32 v103, v103, v118
	s_nop 0
	v_rcp_f32_e32 v111, v110
	s_nop 0
	v_mul_f32_e32 v102, v102, v111
	v_pk_mul_f32 v[102:103], v[98:99], v[102:103]
	v_mul_f32_e32 v99, 0xbfb8aa3b, v104
	v_mul_f32_e32 v98, 0xbfb8aa3b, v112
	v_exp_f32_e32 v110, v99
	v_mul_f32_e32 v99, 0xbfb8aa3b, v113
	v_exp_f32_e32 v98, v98
	v_exp_f32_e32 v99, v99
	s_nop 0
	v_pk_add_f32 v[98:99], v[98:99], 1.0 op_sel_hi:[1,0]
	s_nop 0
	s_nop 0
	v_rcp_f32_e32 v111, v99
	s_nop 0
	v_mul_f32_e32 v99, v113, v111
	s_nop 0
	v_rcp_f32_e32 v111, v98
	s_nop 0
	v_mul_f32_e32 v98, v112, v111
	v_pk_mul_f32 v[108:109], v[108:109], v[98:99]
	v_mul_f32_e32 v98, 0xbfb8aa3b, v105
	v_exp_f32_e32 v111, v98
	s_nop 0
	v_pk_add_f32 v[98:99], v[110:111], 1.0 op_sel_hi:[1,0]
	s_nop 0
	s_nop 0
	v_rcp_f32_e32 v110, v99
	s_nop 0
	v_mul_f32_e32 v99, v105, v110
	s_nop 0
	v_rcp_f32_e32 v105, v98
	s_nop 0
	v_mul_f32_e32 v98, v104, v105
	v_or_b32_e32 v110, 16, v146
	v_pk_mul_f32 v[104:105], v[100:101], v[98:99]
	v_cvt_pk_bf16_f32 v100, v102, v103
	v_mad_i64_i32 v[102:103], s[26:27], v110, s15, v[114:115]
	v_cvt_pk_bf16_f32 v98, v106, v107
	v_cvt_pk_bf16_f32 v99, v108, v109
	v_cvt_pk_bf16_f32 v101, v104, v105
	v_lshl_add_u64 v[102:103], v[102:103], 0, v[116:117]
	global_store_dwordx4 v[102:103], v[98:101], off
	s_nop 1
	v_mul_f32_e32 v99, 0xbfb8aa3b, v86
	v_mul_f32_e32 v98, 0xbfb8aa3b, v94
	v_exp_f32_e32 v100, v99
	v_mul_f32_e32 v99, 0xbfb8aa3b, v95
	v_exp_f32_e32 v98, v98
	v_exp_f32_e32 v99, v99
	s_nop 0
	v_pk_add_f32 v[98:99], v[98:99], 1.0 op_sel_hi:[1,0]
	s_nop 0
	s_nop 0
	v_rcp_f32_e32 v101, v99
	s_nop 0
	v_mul_f32_e32 v95, v95, v101
	s_nop 0
	v_rcp_f32_e32 v99, v98
	s_nop 0
	v_mul_f32_e32 v94, v94, v99
	v_pk_mul_f32 v[90:91], v[90:91], v[94:95]
	v_mul_f32_e32 v94, 0xbfb8aa3b, v87
	v_exp_f32_e32 v101, v94
	s_nop 0
	v_pk_add_f32 v[94:95], v[100:101], 1.0 op_sel_hi:[1,0]
	s_nop 0
	s_nop 0
	v_rcp_f32_e32 v98, v95
	s_nop 0
	v_mul_f32_e32 v87, v87, v98
	s_nop 0
	v_rcp_f32_e32 v95, v94
	s_nop 0
	v_mul_f32_e32 v86, v86, v95
	v_pk_mul_f32 v[86:87], v[82:83], v[86:87]
	v_mul_f32_e32 v83, 0xbfb8aa3b, v88
	v_mul_f32_e32 v82, 0xbfb8aa3b, v96
	v_exp_f32_e32 v94, v83
	v_mul_f32_e32 v83, 0xbfb8aa3b, v97
	v_exp_f32_e32 v82, v82
	v_exp_f32_e32 v83, v83
	s_nop 0
	v_pk_add_f32 v[82:83], v[82:83], 1.0 op_sel_hi:[1,0]
	s_nop 0
	s_nop 0
	v_rcp_f32_e32 v95, v83
	s_nop 0
	v_mul_f32_e32 v83, v97, v95
	s_nop 0
	v_rcp_f32_e32 v95, v82
	s_nop 0
	v_mul_f32_e32 v82, v96, v95
	v_pk_mul_f32 v[92:93], v[92:93], v[82:83]
	v_mul_f32_e32 v82, 0xbfb8aa3b, v89
	v_exp_f32_e32 v95, v82
	s_nop 0
	v_pk_add_f32 v[82:83], v[94:95], 1.0 op_sel_hi:[1,0]
	s_nop 0
	s_nop 0
	v_rcp_f32_e32 v94, v83
	s_nop 0
	v_mul_f32_e32 v83, v89, v94
	s_nop 0
	v_rcp_f32_e32 v89, v82
	s_nop 0
	v_mul_f32_e32 v82, v88, v89
	v_or_b32_e32 v94, 32, v146
	v_pk_mul_f32 v[88:89], v[84:85], v[82:83]
	v_cvt_pk_bf16_f32 v84, v86, v87
	v_mad_i64_i32 v[86:87], s[26:27], v94, s15, v[114:115]
	v_cvt_pk_bf16_f32 v82, v90, v91
	v_cvt_pk_bf16_f32 v83, v92, v93
	v_cvt_pk_bf16_f32 v85, v88, v89
	v_lshl_add_u64 v[86:87], v[86:87], 0, v[116:117]
	global_store_dwordx4 v[86:87], v[82:85], off
	s_nop 1
	v_mul_f32_e32 v83, 0xbfb8aa3b, v70
	v_mul_f32_e32 v82, 0xbfb8aa3b, v78
	v_exp_f32_e32 v84, v83
	v_mul_f32_e32 v83, 0xbfb8aa3b, v79
	v_exp_f32_e32 v82, v82
	v_exp_f32_e32 v83, v83
	s_nop 0
	v_pk_add_f32 v[82:83], v[82:83], 1.0 op_sel_hi:[1,0]
	s_nop 0
	s_nop 0
	v_rcp_f32_e32 v85, v83
	s_nop 0
	v_mul_f32_e32 v79, v79, v85
	s_nop 0
	v_rcp_f32_e32 v83, v82
	s_nop 0
	v_mul_f32_e32 v78, v78, v83
	v_pk_mul_f32 v[74:75], v[74:75], v[78:79]
	v_mul_f32_e32 v78, 0xbfb8aa3b, v71
	v_exp_f32_e32 v85, v78
	s_nop 0
	v_pk_add_f32 v[78:79], v[84:85], 1.0 op_sel_hi:[1,0]
	s_nop 0
	s_nop 0
	v_rcp_f32_e32 v82, v79
	s_nop 0
	v_mul_f32_e32 v71, v71, v82
	s_nop 0
	v_rcp_f32_e32 v79, v78
	s_nop 0
	v_mul_f32_e32 v70, v70, v79
	v_pk_mul_f32 v[70:71], v[66:67], v[70:71]
	v_mul_f32_e32 v67, 0xbfb8aa3b, v72
	v_mul_f32_e32 v66, 0xbfb8aa3b, v80
	v_exp_f32_e32 v78, v67
	v_mul_f32_e32 v67, 0xbfb8aa3b, v81
	v_exp_f32_e32 v66, v66
	v_exp_f32_e32 v67, v67
	s_nop 0
	v_pk_add_f32 v[66:67], v[66:67], 1.0 op_sel_hi:[1,0]
	s_nop 0
	s_nop 0
	v_rcp_f32_e32 v79, v67
	s_nop 0
	v_mul_f32_e32 v67, v81, v79
	s_nop 0
	v_rcp_f32_e32 v79, v66
	s_nop 0
	v_mul_f32_e32 v66, v80, v79
	v_pk_mul_f32 v[76:77], v[76:77], v[66:67]
	v_mul_f32_e32 v66, 0xbfb8aa3b, v73
	v_exp_f32_e32 v79, v66
	s_nop 0
	v_pk_add_f32 v[66:67], v[78:79], 1.0 op_sel_hi:[1,0]
	s_nop 0
	s_nop 0
	v_rcp_f32_e32 v78, v67
	s_nop 0
	v_mul_f32_e32 v67, v73, v78
	s_nop 0
	v_rcp_f32_e32 v73, v66
	s_nop 0
	v_mul_f32_e32 v66, v72, v73
	v_or_b32_e32 v78, 48, v146
	v_pk_mul_f32 v[72:73], v[68:69], v[66:67]
	v_cvt_pk_bf16_f32 v68, v70, v71
	v_mad_i64_i32 v[70:71], s[26:27], v78, s15, v[114:115]
	v_cvt_pk_bf16_f32 v66, v74, v75
	v_cvt_pk_bf16_f32 v67, v76, v77
	v_cvt_pk_bf16_f32 v69, v72, v73
	v_lshl_add_u64 v[70:71], v[70:71], 0, v[116:117]
	global_store_dwordx4 v[70:71], v[66:69], off
	v_add_u32_e32 v70, 0x80, v146
	s_nop 0
	v_mul_f32_e32 v67, 0xbfb8aa3b, v54
	v_mul_f32_e32 v66, 0xbfb8aa3b, v62
	v_exp_f32_e32 v68, v67
	v_mul_f32_e32 v67, 0xbfb8aa3b, v63
	v_exp_f32_e32 v66, v66
	v_exp_f32_e32 v67, v67
	s_nop 0
	v_pk_add_f32 v[66:67], v[66:67], 1.0 op_sel_hi:[1,0]
	s_nop 0
	s_nop 0
	v_rcp_f32_e32 v69, v67
	s_nop 0
	v_mul_f32_e32 v63, v63, v69
	s_nop 0
	v_rcp_f32_e32 v67, v66
	s_nop 0
	v_mul_f32_e32 v62, v62, v67
	v_pk_mul_f32 v[58:59], v[58:59], v[62:63]
	v_mul_f32_e32 v62, 0xbfb8aa3b, v55
	v_exp_f32_e32 v69, v62
	s_nop 0
	v_pk_add_f32 v[62:63], v[68:69], 1.0 op_sel_hi:[1,0]
	s_nop 0
	s_nop 0
	v_rcp_f32_e32 v66, v63
	s_nop 0
	v_mul_f32_e32 v55, v55, v66
	s_nop 0
	v_rcp_f32_e32 v63, v62
	s_nop 0
	v_mul_f32_e32 v54, v54, v63
	v_pk_mul_f32 v[54:55], v[50:51], v[54:55]
	v_mul_f32_e32 v51, 0xbfb8aa3b, v56
	v_mul_f32_e32 v50, 0xbfb8aa3b, v64
	v_exp_f32_e32 v62, v51
	v_mul_f32_e32 v51, 0xbfb8aa3b, v65
	v_exp_f32_e32 v50, v50
	v_exp_f32_e32 v51, v51
	s_nop 0
	v_pk_add_f32 v[50:51], v[50:51], 1.0 op_sel_hi:[1,0]
	s_nop 0
	s_nop 0
	v_rcp_f32_e32 v63, v51
	s_nop 0
	v_mul_f32_e32 v51, v65, v63
	s_nop 0
	v_rcp_f32_e32 v63, v50
	s_nop 0
	v_mul_f32_e32 v50, v64, v63
	v_pk_mul_f32 v[60:61], v[60:61], v[50:51]
	v_mul_f32_e32 v50, 0xbfb8aa3b, v57
	v_exp_f32_e32 v63, v50
	s_nop 0
	v_pk_add_f32 v[50:51], v[62:63], 1.0 op_sel_hi:[1,0]
	s_nop 0
	s_nop 0
	v_rcp_f32_e32 v62, v51
	s_nop 0
	v_mul_f32_e32 v51, v57, v62
	s_nop 0
	v_rcp_f32_e32 v57, v50
	s_nop 0
	v_mul_f32_e32 v50, v56, v57
	v_pk_mul_f32 v[56:57], v[52:53], v[50:51]
	v_cvt_pk_bf16_f32 v52, v54, v55
	v_mad_i64_i32 v[54:55], s[26:27], v70, s15, v[114:115]
	v_cvt_pk_bf16_f32 v50, v58, v59
	v_cvt_pk_bf16_f32 v51, v60, v61
	v_cvt_pk_bf16_f32 v53, v56, v57
	v_lshl_add_u64 v[54:55], v[54:55], 0, v[116:117]
	global_store_dwordx4 v[54:55], v[50:53], off
	s_nop 1
	v_mul_f32_e32 v51, 0xbfb8aa3b, v36
	v_mul_f32_e32 v50, 0xbfb8aa3b, v44
	v_exp_f32_e32 v52, v51
	v_mul_f32_e32 v51, 0xbfb8aa3b, v45
	v_exp_f32_e32 v50, v50
	v_exp_f32_e32 v51, v51
	s_nop 0
	v_pk_add_f32 v[50:51], v[50:51], 1.0 op_sel_hi:[1,0]
	s_nop 0
	s_nop 0
	v_rcp_f32_e32 v53, v51
	s_nop 0
	v_mul_f32_e32 v45, v45, v53
	s_nop 0
	v_rcp_f32_e32 v51, v50
	s_nop 0
	v_mul_f32_e32 v44, v44, v51
	v_pk_mul_f32 v[40:41], v[40:41], v[44:45]
	v_mul_f32_e32 v44, 0xbfb8aa3b, v37
	v_exp_f32_e32 v53, v44
	s_nop 0
	v_pk_add_f32 v[44:45], v[52:53], 1.0 op_sel_hi:[1,0]
	s_nop 0
	s_nop 0
	v_rcp_f32_e32 v50, v45
	s_nop 0
	v_mul_f32_e32 v37, v37, v50
	s_nop 0
	v_rcp_f32_e32 v45, v44
	s_nop 0
	v_mul_f32_e32 v36, v36, v45
	v_pk_mul_f32 v[36:37], v[32:33], v[36:37]
	v_mul_f32_e32 v33, 0xbfb8aa3b, v38
	v_mul_f32_e32 v32, 0xbfb8aa3b, v46
	v_exp_f32_e32 v44, v33
	v_mul_f32_e32 v33, 0xbfb8aa3b, v47
	v_exp_f32_e32 v32, v32
	v_exp_f32_e32 v33, v33
	s_nop 0
	v_pk_add_f32 v[32:33], v[32:33], 1.0 op_sel_hi:[1,0]
	s_nop 0
	s_nop 0
	v_rcp_f32_e32 v45, v33
	s_nop 0
	v_mul_f32_e32 v33, v47, v45
	s_nop 0
	v_rcp_f32_e32 v45, v32
	s_nop 0
	v_mul_f32_e32 v32, v46, v45
	v_pk_mul_f32 v[42:43], v[42:43], v[32:33]
	v_mul_f32_e32 v32, 0xbfb8aa3b, v39
	v_exp_f32_e32 v45, v32
	s_nop 0
	v_pk_add_f32 v[32:33], v[44:45], 1.0 op_sel_hi:[1,0]
	s_nop 0
	s_nop 0
	v_rcp_f32_e32 v44, v33
	s_nop 0
	v_mul_f32_e32 v33, v39, v44
	s_nop 0
	v_rcp_f32_e32 v39, v32
	s_nop 0
	v_mul_f32_e32 v32, v38, v39
	v_add_u32_e32 v44, 0x90, v146
	v_pk_mul_f32 v[38:39], v[34:35], v[32:33]
	v_cvt_pk_bf16_f32 v34, v36, v37
	v_mad_i64_i32 v[36:37], s[26:27], v44, s15, v[114:115]
	v_cvt_pk_bf16_f32 v32, v40, v41
	v_cvt_pk_bf16_f32 v33, v42, v43
	v_cvt_pk_bf16_f32 v35, v38, v39
	v_lshl_add_u64 v[36:37], v[36:37], 0, v[116:117]
	global_store_dwordx4 v[36:37], v[32:35], off
	s_nop 1
	v_mul_f32_e32 v33, 0xbfb8aa3b, v20
	v_mul_f32_e32 v32, 0xbfb8aa3b, v28
	v_exp_f32_e32 v34, v33
	v_mul_f32_e32 v33, 0xbfb8aa3b, v29
	v_exp_f32_e32 v32, v32
	v_exp_f32_e32 v33, v33
	s_nop 0
	v_pk_add_f32 v[32:33], v[32:33], 1.0 op_sel_hi:[1,0]
	s_nop 0
	s_nop 0
	v_rcp_f32_e32 v35, v33
	s_nop 0
	v_mul_f32_e32 v29, v29, v35
	s_nop 0
	v_rcp_f32_e32 v33, v32
	s_nop 0
	v_mul_f32_e32 v28, v28, v33
	v_pk_mul_f32 v[24:25], v[24:25], v[28:29]
	v_mul_f32_e32 v28, 0xbfb8aa3b, v21
	v_exp_f32_e32 v35, v28
	s_nop 0
	v_pk_add_f32 v[28:29], v[34:35], 1.0 op_sel_hi:[1,0]
	s_nop 0
	s_nop 0
	v_rcp_f32_e32 v32, v29
	s_nop 0
	v_mul_f32_e32 v21, v21, v32
	s_nop 0
	v_rcp_f32_e32 v29, v28
	s_nop 0
	v_mul_f32_e32 v20, v20, v29
	v_pk_mul_f32 v[20:21], v[16:17], v[20:21]
	v_mul_f32_e32 v17, 0xbfb8aa3b, v22
	v_mul_f32_e32 v16, 0xbfb8aa3b, v30
	v_exp_f32_e32 v28, v17
	v_mul_f32_e32 v17, 0xbfb8aa3b, v31
	v_exp_f32_e32 v16, v16
	v_exp_f32_e32 v17, v17
	s_nop 0
	v_pk_add_f32 v[16:17], v[16:17], 1.0 op_sel_hi:[1,0]
	s_nop 0
	s_nop 0
	v_rcp_f32_e32 v29, v17
	s_nop 0
	v_mul_f32_e32 v17, v31, v29
	s_nop 0
	v_rcp_f32_e32 v29, v16
	s_nop 0
	v_mul_f32_e32 v16, v30, v29
	v_pk_mul_f32 v[26:27], v[26:27], v[16:17]
	v_mul_f32_e32 v16, 0xbfb8aa3b, v23
	v_exp_f32_e32 v29, v16
	s_nop 0
	v_pk_add_f32 v[16:17], v[28:29], 1.0 op_sel_hi:[1,0]
	s_nop 0
	s_nop 0
	v_rcp_f32_e32 v28, v17
	s_nop 0
	v_mul_f32_e32 v17, v23, v28
	s_nop 0
	v_rcp_f32_e32 v23, v16
	s_nop 0
	v_mul_f32_e32 v16, v22, v23
	v_add_u32_e32 v28, 0xa0, v146
	v_pk_mul_f32 v[22:23], v[18:19], v[16:17]
	v_cvt_pk_bf16_f32 v18, v20, v21
	v_mad_i64_i32 v[20:21], s[26:27], v28, s15, v[114:115]
	v_cvt_pk_bf16_f32 v16, v24, v25
	v_cvt_pk_bf16_f32 v17, v26, v27
	v_cvt_pk_bf16_f32 v19, v22, v23
	v_lshl_add_u64 v[20:21], v[20:21], 0, v[116:117]
	global_store_dwordx4 v[20:21], v[16:19], off
	s_nop 1
	v_mul_f32_e32 v17, 0xbfb8aa3b, v4
	v_mul_f32_e32 v16, 0xbfb8aa3b, v12
	v_exp_f32_e32 v18, v17
	v_mul_f32_e32 v17, 0xbfb8aa3b, v13
	v_exp_f32_e32 v16, v16
	v_exp_f32_e32 v17, v17
	s_nop 0
	v_pk_add_f32 v[16:17], v[16:17], 1.0 op_sel_hi:[1,0]
	s_nop 0
	s_nop 0
	v_rcp_f32_e32 v19, v17
	s_nop 0
	v_mul_f32_e32 v13, v13, v19
	s_nop 0
	v_rcp_f32_e32 v17, v16
	s_nop 0
	v_mul_f32_e32 v12, v12, v17
	v_pk_mul_f32 v[8:9], v[8:9], v[12:13]
	v_mul_f32_e32 v12, 0xbfb8aa3b, v5
	v_exp_f32_e32 v19, v12
	s_nop 0
	v_pk_add_f32 v[12:13], v[18:19], 1.0 op_sel_hi:[1,0]
	s_nop 0
	s_nop 0
	v_rcp_f32_e32 v16, v13
	s_nop 0
	v_mul_f32_e32 v5, v5, v16
	s_nop 0
	v_rcp_f32_e32 v13, v12
	s_nop 0
	v_mul_f32_e32 v4, v4, v13
	v_pk_mul_f32 v[4:5], v[0:1], v[4:5]
	v_mul_f32_e32 v1, 0xbfb8aa3b, v6
	v_mul_f32_e32 v0, 0xbfb8aa3b, v14
	v_exp_f32_e32 v12, v1
	v_mul_f32_e32 v1, 0xbfb8aa3b, v15
	v_exp_f32_e32 v0, v0
	v_exp_f32_e32 v1, v1
	s_nop 0
	v_pk_add_f32 v[0:1], v[0:1], 1.0 op_sel_hi:[1,0]
	s_nop 0
	s_nop 0
	v_rcp_f32_e32 v13, v1
	s_nop 0
	v_mul_f32_e32 v1, v15, v13
	s_nop 0
	v_rcp_f32_e32 v13, v0
	s_nop 0
	v_mul_f32_e32 v0, v14, v13
	v_pk_mul_f32 v[10:11], v[10:11], v[0:1]
	v_mul_f32_e32 v0, 0xbfb8aa3b, v7
	v_exp_f32_e32 v13, v0
	s_nop 0
	v_pk_add_f32 v[0:1], v[12:13], 1.0 op_sel_hi:[1,0]
	s_nop 0
	s_nop 0
	v_rcp_f32_e32 v12, v1
	s_nop 0
	v_mul_f32_e32 v1, v7, v12
	s_nop 0
	v_rcp_f32_e32 v7, v0
	s_nop 0
	v_mul_f32_e32 v0, v6, v7
	v_add_u32_e32 v12, 0xb0, v146
	v_pk_mul_f32 v[6:7], v[2:3], v[0:1]
	v_cvt_pk_bf16_f32 v2, v4, v5
	v_mad_i64_i32 v[4:5], s[26:27], v12, s15, v[114:115]
	v_cvt_pk_bf16_f32 v0, v8, v9
	v_cvt_pk_bf16_f32 v1, v10, v11
	v_cvt_pk_bf16_f32 v3, v6, v7
	v_lshl_add_u64 v[4:5], v[4:5], 0, v[116:117]
	s_and_b64 vcc, exec, s[0:1]
	s_mov_b64 s[26:27], s[18:19]
	global_store_dwordx4 v[4:5], v[0:3], off
	s_cbranch_vccz .LBB0_1353
	s_waitcnt vmcnt(0)
	s_cmpk_gt_u32 s5, 0xff
	s_cbranch_scc1 .LBB0_1360
	s_barrier

.LBB0_1421:
	s_add_u32 s18, s16, 0x100
	s_addc_u32 s19, s17, 0
	s_add_i32 s47, 0, 0x10000
	ds_read_b128 v[130:133], v202
	ds_read_b128 v[134:137], v202 offset:1024
	ds_read_b128 v[138:141], v202 offset:2048
	ds_read_b128 v[142:145], v202 offset:3072
	s_cmp_eq_u32 s46, 40
	s_cselect_b32 s23, s11, s19
	s_cselect_b32 s22, s10, s18
	s_cselect_b32 s21, s13, s45
	s_cselect_b32 s20, s12, s44
	v_lshl_add_u64 v[188:189], s[16:17], 0, v[152:153]
	s_add_i32 m0, s31, 0xc000
	ds_read_b128 v[156:159], v206
	ds_read_b128 v[160:163], v206 offset:1024
	ds_read_b128 v[164:167], v206 offset:2048
	ds_read_b128 v[168:171], v206 offset:3072
	ds_read_b128 v[172:175], v206 offset:4096
	ds_read_b128 v[176:179], v206 offset:5120
	ds_read_b128 v[180:183], v206 offset:6144
	ds_read_b128 v[184:187], v206 offset:7168
	global_load_lds_dwordx4 v[188:189], off
	v_lshl_add_u64 v[188:189], s[16:17], 0, v[154:155]
	s_add_i32 m0, s31, 0xe000
	s_nop 0
	global_load_lds_dwordx4 v[188:189], off
	s_waitcnt lgkmcnt(8)
	s_barrier
	s_waitcnt lgkmcnt(0)
	s_setprio 1
	v_mfma_f32_16x16x32_bf16 v[126:129], v[130:133], v[156:159], v[126:129]
	v_mfma_f32_16x16x32_bf16 v[122:125], v[138:141], v[156:159], v[122:125]
	v_mfma_f32_16x16x32_bf16 v[114:117], v[130:133], v[164:167], v[114:117]
	v_mfma_f32_16x16x32_bf16 v[106:109], v[138:141], v[164:167], v[106:109]
	v_mfma_f32_16x16x32_bf16 v[98:101], v[130:133], v[172:175], v[98:101]
	v_mfma_f32_16x16x32_bf16 v[90:93], v[138:141], v[172:175], v[90:93]
	v_mfma_f32_16x16x32_bf16 v[82:85], v[130:133], v[180:183], v[82:85]
	v_mfma_f32_16x16x32_bf16 v[74:77], v[138:141], v[180:183], v[74:77]
	v_mfma_f32_16x16x32_bf16 v[126:129], v[134:137], v[160:163], v[126:129]
	v_mfma_f32_16x16x32_bf16 v[122:125], v[142:145], v[160:163], v[122:125]
	v_mfma_f32_16x16x32_bf16 v[114:117], v[134:137], v[168:171], v[114:117]
	v_mfma_f32_16x16x32_bf16 v[106:109], v[142:145], v[168:171], v[106:109]
	v_mfma_f32_16x16x32_bf16 v[98:101], v[134:137], v[176:179], v[98:101]
	v_mfma_f32_16x16x32_bf16 v[90:93], v[142:145], v[176:179], v[90:93]
	v_mfma_f32_16x16x32_bf16 v[82:85], v[134:137], v[184:187], v[82:85]
	v_mfma_f32_16x16x32_bf16 v[74:77], v[142:145], v[184:187], v[74:77]
	s_setprio 0
	s_barrier
	s_add_i32 s48, 0, 0x14000
	s_add_i32 s16, s47, s25
	ds_read_b128 v[188:191], v202 offset:16384
	ds_read_b128 v[198:201], v202 offset:17408
	ds_read_b128 v[208:211], v202 offset:18432
	ds_read_b128 v[212:215], v202 offset:19456
	s_mov_b32 m0, s16
	global_load_lds_dwordx4 v48, s[20:21]
	s_add_i32 m0, s16, 0x2000
	s_nop 0
	global_load_lds_dwordx4 v146, s[20:21]
	s_barrier
	s_waitcnt lgkmcnt(0)
	s_setprio 1
	v_mfma_f32_16x16x32_bf16 v[118:121], v[188:191], v[156:159], v[118:121]
	v_mfma_f32_16x16x32_bf16 v[110:113], v[208:211], v[156:159], v[110:113]
	v_mfma_f32_16x16x32_bf16 v[102:105], v[188:191], v[164:167], v[102:105]
	v_mfma_f32_16x16x32_bf16 v[94:97], v[208:211], v[164:167], v[94:97]
	v_mfma_f32_16x16x32_bf16 v[86:89], v[188:191], v[172:175], v[86:89]
	v_mfma_f32_16x16x32_bf16 v[78:81], v[208:211], v[172:175], v[78:81]
	v_mfma_f32_16x16x32_bf16 v[70:73], v[188:191], v[180:183], v[70:73]
	v_mfma_f32_16x16x32_bf16 v[66:69], v[208:211], v[180:183], v[66:69]
	v_mfma_f32_16x16x32_bf16 v[118:121], v[198:201], v[160:163], v[118:121]
	v_mfma_f32_16x16x32_bf16 v[110:113], v[212:215], v[160:163], v[110:113]
	v_mfma_f32_16x16x32_bf16 v[102:105], v[198:201], v[168:171], v[102:105]
	v_mfma_f32_16x16x32_bf16 v[94:97], v[212:215], v[168:171], v[94:97]
	v_mfma_f32_16x16x32_bf16 v[86:89], v[198:201], v[176:179], v[86:89]
	v_mfma_f32_16x16x32_bf16 v[78:81], v[212:215], v[176:179], v[78:81]
	v_mfma_f32_16x16x32_bf16 v[70:73], v[198:201], v[184:187], v[70:73]
	v_mfma_f32_16x16x32_bf16 v[66:69], v[212:215], v[184:187], v[66:69]
	s_setprio 0
	s_mov_b32 m0, s31
	v_lshl_add_u64 v[216:217], s[22:23], 0, v[48:49]
	s_barrier
	ds_read_b128 v[156:159], v206 offset:16384
	ds_read_b128 v[160:163], v206 offset:17408
	ds_read_b128 v[164:167], v206 offset:18432
	ds_read_b128 v[168:171], v206 offset:19456
	ds_read_b128 v[172:175], v206 offset:20480
	ds_read_b128 v[176:179], v206 offset:21504
	ds_read_b128 v[180:183], v206 offset:22528
	ds_read_b128 v[184:187], v206 offset:23552
	global_load_lds_dwordx4 v[216:217], off
	v_lshl_add_u64 v[218:219], s[22:23], 0, v[146:147]
	s_mov_b32 m0, s34
	s_nop 0
	global_load_lds_dwordx4 v[218:219], off
	s_barrier
	s_waitcnt lgkmcnt(0)
	s_setprio 1
	v_mfma_f32_16x16x32_bf16 v[62:65], v[130:133], v[156:159], v[62:65]
	v_mfma_f32_16x16x32_bf16 v[58:61], v[138:141], v[156:159], v[58:61]
	v_mfma_f32_16x16x32_bf16 v[50:53], v[130:133], v[164:167], v[50:53]
	v_mfma_f32_16x16x32_bf16 v[40:43], v[138:141], v[164:167], v[40:43]
	v_mfma_f32_16x16x32_bf16 v[32:35], v[130:133], v[172:175], v[32:35]
	v_mfma_f32_16x16x32_bf16 v[24:27], v[138:141], v[172:175], v[24:27]
	v_mfma_f32_16x16x32_bf16 v[16:19], v[130:133], v[180:183], v[16:19]
	v_mfma_f32_16x16x32_bf16 v[8:11], v[138:141], v[180:183], v[8:11]
	v_mfma_f32_16x16x32_bf16 v[62:65], v[134:137], v[160:163], v[62:65]
	v_mfma_f32_16x16x32_bf16 v[58:61], v[142:145], v[160:163], v[58:61]
	v_mfma_f32_16x16x32_bf16 v[50:53], v[134:137], v[168:171], v[50:53]
	v_mfma_f32_16x16x32_bf16 v[40:43], v[142:145], v[168:171], v[40:43]
	v_mfma_f32_16x16x32_bf16 v[32:35], v[134:137], v[176:179], v[32:35]
	v_mfma_f32_16x16x32_bf16 v[24:27], v[142:145], v[176:179], v[24:27]
	v_mfma_f32_16x16x32_bf16 v[16:19], v[134:137], v[184:187], v[16:19]
	v_mfma_f32_16x16x32_bf16 v[8:11], v[142:145], v[184:187], v[8:11]
	s_setprio 0
	s_barrier
	s_add_u32 s16, s20, 0xb0000
	s_addc_u32 s17, s21, 0
	s_add_i32 s47, s48, s25
	s_mov_b32 m0, s47
	s_nop 0
	global_load_lds_dwordx4 v48, s[16:17]
	s_add_i32 m0, s47, 0x2000
	s_nop 0
	global_load_lds_dwordx4 v146, s[16:17]
	s_waitcnt vmcnt(6)
	s_barrier
	s_setprio 1
	v_mfma_f32_16x16x32_bf16 v[54:57], v[188:191], v[156:159], v[54:57]
	v_mfma_f32_16x16x32_bf16 v[44:47], v[208:211], v[156:159], v[44:47]
	v_mfma_f32_16x16x32_bf16 v[36:39], v[188:191], v[164:167], v[36:39]
	v_mfma_f32_16x16x32_bf16 v[28:31], v[208:211], v[164:167], v[28:31]
	v_mfma_f32_16x16x32_bf16 v[20:23], v[188:191], v[172:175], v[20:23]
	v_mfma_f32_16x16x32_bf16 v[12:15], v[208:211], v[172:175], v[12:15]
	v_mfma_f32_16x16x32_bf16 v[4:7], v[188:191], v[180:183], v[4:7]
	v_mfma_f32_16x16x32_bf16 v[0:3], v[208:211], v[180:183], v[0:3]
	v_mfma_f32_16x16x32_bf16 v[54:57], v[198:201], v[160:163], v[54:57]
	v_mfma_f32_16x16x32_bf16 v[44:47], v[212:215], v[160:163], v[44:47]
	v_mfma_f32_16x16x32_bf16 v[36:39], v[198:201], v[168:171], v[36:39]
	v_mfma_f32_16x16x32_bf16 v[28:31], v[212:215], v[168:171], v[28:31]
	v_mfma_f32_16x16x32_bf16 v[20:23], v[198:201], v[176:179], v[20:23]
	v_mfma_f32_16x16x32_bf16 v[12:15], v[212:215], v[176:179], v[12:15]
	v_mfma_f32_16x16x32_bf16 v[4:7], v[198:201], v[184:187], v[4:7]
	v_mfma_f32_16x16x32_bf16 v[0:3], v[212:215], v[184:187], v[0:3]
	s_setprio 0
	s_add_i32 s47, 0, 0x18000
	s_barrier
	ds_read_b128 v[130:133], v202 offset:32768
	ds_read_b128 v[134:137], v202 offset:33792
	ds_read_b128 v[138:141], v202 offset:34816
	ds_read_b128 v[142:145], v202 offset:35840
	s_add_u32 s16, s22, 0xb0000
	s_addc_u32 s17, s23, 0
	s_mov_b32 m0, s35
	ds_read_b128 v[156:159], v206 offset:32768
	ds_read_b128 v[160:163], v206 offset:33792
	ds_read_b128 v[164:167], v206 offset:34816
	ds_read_b128 v[168:171], v206 offset:35840
	ds_read_b128 v[172:175], v206 offset:36864
	ds_read_b128 v[176:179], v206 offset:37888
	ds_read_b128 v[180:183], v206 offset:38912
	ds_read_b128 v[184:187], v206 offset:39936
	global_load_lds_dwordx4 v48, s[16:17]
	s_mov_b32 m0, s36
	s_nop 0
	global_load_lds_dwordx4 v146, s[16:17]
	s_waitcnt lgkmcnt(8)
	s_barrier
	s_waitcnt lgkmcnt(0)
	s_setprio 1
	v_mfma_f32_16x16x32_bf16 v[126:129], v[130:133], v[156:159], v[126:129]
	v_mfma_f32_16x16x32_bf16 v[122:125], v[138:141], v[156:159], v[122:125]
	v_mfma_f32_16x16x32_bf16 v[114:117], v[130:133], v[164:167], v[114:117]
	v_mfma_f32_16x16x32_bf16 v[106:109], v[138:141], v[164:167], v[106:109]
	v_mfma_f32_16x16x32_bf16 v[98:101], v[130:133], v[172:175], v[98:101]
	v_mfma_f32_16x16x32_bf16 v[90:93], v[138:141], v[172:175], v[90:93]
	v_mfma_f32_16x16x32_bf16 v[82:85], v[130:133], v[180:183], v[82:85]
	v_mfma_f32_16x16x32_bf16 v[74:77], v[138:141], v[180:183], v[74:77]
	v_mfma_f32_16x16x32_bf16 v[126:129], v[134:137], v[160:163], v[126:129]
	v_mfma_f32_16x16x32_bf16 v[122:125], v[142:145], v[160:163], v[122:125]
	v_mfma_f32_16x16x32_bf16 v[114:117], v[134:137], v[168:171], v[114:117]
	v_mfma_f32_16x16x32_bf16 v[106:109], v[142:145], v[168:171], v[106:109]
	v_mfma_f32_16x16x32_bf16 v[98:101], v[134:137], v[176:179], v[98:101]
	v_mfma_f32_16x16x32_bf16 v[90:93], v[142:145], v[176:179], v[90:93]
	v_mfma_f32_16x16x32_bf16 v[82:85], v[134:137], v[184:187], v[82:85]
	v_mfma_f32_16x16x32_bf16 v[74:77], v[142:145], v[184:187], v[74:77]
	s_setprio 0
	s_barrier
	s_add_i32 s22, 0, 0x1c000
	s_add_i32 s16, s47, s25
	s_add_u32 s52, s20, s66
	s_addc_u32 s53, s21, s67
	s_mov_b32 m0, s16
	ds_read_b128 v[188:191], v202 offset:49152
	ds_read_b128 v[198:201], v202 offset:50176
	ds_read_b128 v[208:211], v202 offset:51200
	ds_read_b128 v[212:215], v202 offset:52224
	global_load_lds_dwordx4 v48, s[52:53]
	s_add_i32 m0, s16, 0x2000
	s_nop 0
	global_load_lds_dwordx4 v146, s[52:53]
	s_barrier
	s_waitcnt lgkmcnt(0)
	s_setprio 1
	v_mfma_f32_16x16x32_bf16 v[118:121], v[188:191], v[156:159], v[118:121]
	v_mfma_f32_16x16x32_bf16 v[110:113], v[208:211], v[156:159], v[110:113]
	v_mfma_f32_16x16x32_bf16 v[102:105], v[188:191], v[164:167], v[102:105]
	v_mfma_f32_16x16x32_bf16 v[94:97], v[208:211], v[164:167], v[94:97]
	v_mfma_f32_16x16x32_bf16 v[86:89], v[188:191], v[172:175], v[86:89]
	v_mfma_f32_16x16x32_bf16 v[78:81], v[208:211], v[172:175], v[78:81]
	v_mfma_f32_16x16x32_bf16 v[70:73], v[188:191], v[180:183], v[70:73]
	v_mfma_f32_16x16x32_bf16 v[66:69], v[208:211], v[180:183], v[66:69]
	v_mfma_f32_16x16x32_bf16 v[118:121], v[198:201], v[160:163], v[118:121]
	v_mfma_f32_16x16x32_bf16 v[110:113], v[212:215], v[160:163], v[110:113]
	v_mfma_f32_16x16x32_bf16 v[102:105], v[198:201], v[168:171], v[102:105]
	v_mfma_f32_16x16x32_bf16 v[94:97], v[212:215], v[168:171], v[94:97]
	v_mfma_f32_16x16x32_bf16 v[86:89], v[198:201], v[176:179], v[86:89]
	v_mfma_f32_16x16x32_bf16 v[78:81], v[212:215], v[176:179], v[78:81]
	v_mfma_f32_16x16x32_bf16 v[70:73], v[198:201], v[184:187], v[70:73]
	v_mfma_f32_16x16x32_bf16 v[66:69], v[212:215], v[184:187], v[66:69]
	s_setprio 0
	s_mov_b32 m0, s39
	v_lshl_add_u64 v[192:193], v[216:217], 0, s[66:67]
	s_barrier
	ds_read_b128 v[156:159], v206 offset:49152
	ds_read_b128 v[160:163], v206 offset:50176
	ds_read_b128 v[164:167], v206 offset:51200
	ds_read_b128 v[168:171], v206 offset:52224
	ds_read_b128 v[172:175], v206 offset:53248
	ds_read_b128 v[176:179], v206 offset:54272
	ds_read_b128 v[180:183], v206 offset:55296
	ds_read_b128 v[184:187], v206 offset:56320
	global_load_lds_dwordx4 v[192:193], off
	v_lshl_add_u64 v[192:193], v[218:219], 0, s[66:67]
	s_mov_b32 m0, s40
	s_nop 0
	global_load_lds_dwordx4 v[192:193], off
	s_barrier
	s_waitcnt lgkmcnt(0)
	s_setprio 1
	v_mfma_f32_16x16x32_bf16 v[62:65], v[130:133], v[156:159], v[62:65]
	v_mfma_f32_16x16x32_bf16 v[58:61], v[138:141], v[156:159], v[58:61]
	v_mfma_f32_16x16x32_bf16 v[50:53], v[130:133], v[164:167], v[50:53]
	v_mfma_f32_16x16x32_bf16 v[40:43], v[138:141], v[164:167], v[40:43]
	v_mfma_f32_16x16x32_bf16 v[32:35], v[130:133], v[172:175], v[32:35]
	v_mfma_f32_16x16x32_bf16 v[24:27], v[138:141], v[172:175], v[24:27]
	v_mfma_f32_16x16x32_bf16 v[16:19], v[130:133], v[180:183], v[16:19]
	v_mfma_f32_16x16x32_bf16 v[8:11], v[138:141], v[180:183], v[8:11]
	v_mfma_f32_16x16x32_bf16 v[62:65], v[134:137], v[160:163], v[62:65]
	v_mfma_f32_16x16x32_bf16 v[58:61], v[142:145], v[160:163], v[58:61]
	v_mfma_f32_16x16x32_bf16 v[50:53], v[134:137], v[168:171], v[50:53]
	v_mfma_f32_16x16x32_bf16 v[40:43], v[142:145], v[168:171], v[40:43]
	v_mfma_f32_16x16x32_bf16 v[32:35], v[134:137], v[176:179], v[32:35]
	v_mfma_f32_16x16x32_bf16 v[24:27], v[142:145], v[176:179], v[24:27]
	v_mfma_f32_16x16x32_bf16 v[16:19], v[134:137], v[184:187], v[16:19]
	v_mfma_f32_16x16x32_bf16 v[8:11], v[142:145], v[184:187], v[8:11]
	s_setprio 0
	s_barrier
	s_add_u32 s16, s20, 0xb0080
	s_addc_u32 s17, s21, 0
	s_add_i32 s20, s22, s25
	s_mov_b32 m0, s20
	s_nop 0
	global_load_lds_dwordx4 v48, s[16:17]
	s_add_i32 m0, s20, 0x2000
	s_nop 0
	global_load_lds_dwordx4 v146, s[16:17]
	s_waitcnt vmcnt(6)
	s_barrier
	s_setprio 1
	v_mfma_f32_16x16x32_bf16 v[54:57], v[188:191], v[156:159], v[54:57]
	v_mfma_f32_16x16x32_bf16 v[44:47], v[208:211], v[156:159], v[44:47]
	v_mfma_f32_16x16x32_bf16 v[36:39], v[188:191], v[164:167], v[36:39]
	v_mfma_f32_16x16x32_bf16 v[28:31], v[208:211], v[164:167], v[28:31]
	v_mfma_f32_16x16x32_bf16 v[20:23], v[188:191], v[172:175], v[20:23]
	v_mfma_f32_16x16x32_bf16 v[12:15], v[208:211], v[172:175], v[12:15]
	v_mfma_f32_16x16x32_bf16 v[4:7], v[188:191], v[180:183], v[4:7]
	v_mfma_f32_16x16x32_bf16 v[0:3], v[208:211], v[180:183], v[0:3]
	v_mfma_f32_16x16x32_bf16 v[54:57], v[198:201], v[160:163], v[54:57]
	v_mfma_f32_16x16x32_bf16 v[44:47], v[212:215], v[160:163], v[44:47]
	v_mfma_f32_16x16x32_bf16 v[36:39], v[198:201], v[168:171], v[36:39]
	v_mfma_f32_16x16x32_bf16 v[28:31], v[212:215], v[168:171], v[28:31]
	v_mfma_f32_16x16x32_bf16 v[20:23], v[198:201], v[176:179], v[20:23]
	v_mfma_f32_16x16x32_bf16 v[12:15], v[212:215], v[176:179], v[12:15]
	v_mfma_f32_16x16x32_bf16 v[4:7], v[198:201], v[184:187], v[4:7]
	v_mfma_f32_16x16x32_bf16 v[0:3], v[212:215], v[184:187], v[0:3]
	s_setprio 0
	s_add_i32 s46, s46, 2
	s_add_u32 s44, s44, 0x100
	s_addc_u32 s45, s45, 0
	s_cmp_gt_u32 s46, 41
	s_mov_b64 s[16:17], s[18:19]
	s_barrier
	s_cbranch_scc0 .LBB0_1421
	s_mul_hi_i32 s16, s14, 0x38e38e39
	s_lshr_b32 s17, s16, 31
	s_ashr_i32 s16, s16, 1
	s_add_i32 s16, s16, s17
	s_mul_i32 s17, s16, -9
	v_lshl_or_b32 v156, s15, 8, v205
	s_ashr_i32 s15, s14, 31
	s_add_i32 s18, s17, s14
	s_lshl_b64 s[14:15], s[14:15], 19
	s_ashr_i32 s17, s16, 31
	v_lshl_add_u64 v[158:159], v[150:151], 0, s[14:15]
	v_sub_co_u32_e64 v130, s[14:15], s18, 1
	s_lshl_b64 s[18:19], s[16:17], 23
	s_and_b64 s[14:15], s[14:15], exec
	v_ashrrev_i32_e32 v131, 31, v130
	s_cselect_b32 s14, 32, s16
	v_lshlrev_b64 v[130:131], 20, v[130:131]
	s_mul_hi_i32 s15, s14, 0x6000
	s_mulk_i32 s14, 0x6000
	v_ashrrev_i32_e32 v157, 31, v156
	v_lshl_add_u64 v[130:131], s[6:7], 0, v[130:131]
	s_add_u32 s14, s37, s14
	v_lshl_add_u64 v[130:131], v[130:131], 0, s[18:19]
	s_addc_u32 s15, s38, s15
	v_lshlrev_b64 v[208:209], 2, v[156:157]
	v_lshl_add_u64 v[162:163], v[130:131], 0, v[148:149]
	v_lshl_add_u64 v[130:131], s[14:15], 0, v[208:209]
	v_lshl_add_u64 v[156:157], v[156:157], 1, v[158:159]
	global_load_dwordx4 v[142:145], v[130:131], off
	global_load_dwordx4 v[138:141], v[130:131], off offset:64
	global_load_dwordx4 v[134:137], v[130:131], off offset:512
	s_nop 0
	global_load_dwordx4 v[130:133], v[130:131], off offset:576
	s_nop 0
	s_mov_b32 s14, 0x40000
	s_nop 0
	v_lshl_add_u64 v[162:163], v[162:163], 0, v[208:209]
	s_nop 0
	s_mov_b32 s15, s42
	s_nop 0
	s_mov_b32 s14, 0x48000
	s_nop 0
	s_mov_b32 s14, 0x50000
	s_nop 0
	s_mov_b32 s14, 0x58000
	s_nop 0
	s_mov_b32 s14, 0x20000
	s_nop 0
	s_nop 0
	s_mov_b64 s[18:19], s[12:13]
	s_mov_b64 s[16:17], s[10:11]
	v_and_b32_e32 v202, 16, v224
	v_lshrrev_b32_e32 v203, 1, v202
	v_add_u32_e32 v202, v202, v203
	v_mov_b32_e32 v203, 0
	v_mov_b32_e32 v223, 0
	v_lshl_add_u64 v[246:247], v[156:157], 0, v[202:203]
	v_mov_b32_e32 v222, 0x0
	v_lshl_add_u64 v[190:191], v[246:247], 0, v[222:223]
	global_load_dwordx4 v[198:201], v[190:191], off
	global_load_dwordx4 v[218:221], v[190:191], off offset:256
	v_mov_b32_e32 v222, 0x8000
	v_lshl_add_u64 v[190:191], v[246:247], 0, v[222:223]
	global_load_dwordx4 v[242:245], v[190:191], off
	global_load_dwordx4 v[164:167], v[190:191], off offset:256
	v_mov_b32_e32 v222, 0x10000
	v_lshl_add_u64 v[190:191], v[246:247], 0, v[222:223]
	global_load_dwordx4 v[168:171], v[190:191], off
	global_load_dwordx4 v[172:175], v[190:191], off offset:256
	v_mov_b32_e32 v222, 0x18000
	v_lshl_add_u64 v[190:191], v[246:247], 0, v[222:223]
	global_load_dwordx4 v[176:179], v[190:191], off
	global_load_dwordx4 v[180:183], v[190:191], off offset:256
	v_mov_b32_e32 v222, 0x40000
	v_lshl_add_u64 v[190:191], v[246:247], 0, v[222:223]
	global_load_dwordx4 v[184:187], v[190:191], off
	s_waitcnt vmcnt(8)
	v_permlane16_swap_b32 v198, v200
	v_permlane16_swap_b32 v199, v201
	s_nop 1
	v_lshlrev_b32_e32 v210, 16, v198
	v_and_b32_e32 v211, 0xffff0000, v198
	v_lshlrev_b32_e32 v212, 16, v199
	v_and_b32_e32 v213, 0xffff0000, v199
	v_pk_fma_f32 v[126:127], v[126:127], v[142:143], v[210:211]
	v_pk_fma_f32 v[128:129], v[128:129], v[144:145], v[212:213]
	v_lshlrev_b32_e32 v214, 16, v200
	v_and_b32_e32 v215, 0xffff0000, v200
	v_lshlrev_b32_e32 v216, 16, v201
	v_and_b32_e32 v217, 0xffff0000, v201
	v_pk_fma_f32 v[122:123], v[122:123], v[138:139], v[214:215]
	v_pk_fma_f32 v[124:125], v[124:125], v[140:141], v[216:217]
	v_mov_b32_e32 v222, 0x0
	v_lshl_add_u64 v[192:193], v[162:163], 0, v[222:223]
	global_store_dwordx4 v[192:193], v[126:129], off
	global_store_dwordx4 v[192:193], v[122:125], off offset:64
	global_load_dwordx4 v[198:201], v[190:191], off offset:256
	s_waitcnt vmcnt(10)
	v_permlane16_swap_b32 v218, v220
	v_permlane16_swap_b32 v219, v221
	s_nop 1
	v_lshlrev_b32_e32 v210, 16, v218
	v_and_b32_e32 v211, 0xffff0000, v218
	v_lshlrev_b32_e32 v212, 16, v219
	v_and_b32_e32 v213, 0xffff0000, v219
	v_pk_fma_f32 v[118:119], v[118:119], v[134:135], v[210:211]
	v_pk_fma_f32 v[120:121], v[120:121], v[136:137], v[212:213]
	v_lshlrev_b32_e32 v214, 16, v220
	v_and_b32_e32 v215, 0xffff0000, v220
	v_lshlrev_b32_e32 v216, 16, v221
	v_and_b32_e32 v217, 0xffff0000, v221
	v_pk_fma_f32 v[110:111], v[110:111], v[130:131], v[214:215]
	v_pk_fma_f32 v[112:113], v[112:113], v[132:133], v[216:217]
	v_mov_b32_e32 v222, 0x0
	v_lshl_add_u64 v[192:193], v[162:163], 0, v[222:223]
	global_store_dwordx4 v[192:193], v[118:121], off offset:512
	global_store_dwordx4 v[192:193], v[110:113], off offset:576
	v_mov_b32_e32 v222, 0x48000
	v_lshl_add_u64 v[190:191], v[246:247], 0, v[222:223]
	global_load_dwordx4 v[218:221], v[190:191], off
	s_waitcnt vmcnt(12)
	v_permlane16_swap_b32 v242, v244
	v_permlane16_swap_b32 v243, v245
	s_nop 1
	v_lshlrev_b32_e32 v210, 16, v242
	v_and_b32_e32 v211, 0xffff0000, v242
	v_lshlrev_b32_e32 v212, 16, v243
	v_and_b32_e32 v213, 0xffff0000, v243
	v_pk_fma_f32 v[114:115], v[114:115], v[142:143], v[210:211]
	v_pk_fma_f32 v[116:117], v[116:117], v[144:145], v[212:213]
	v_lshlrev_b32_e32 v214, 16, v244
	v_and_b32_e32 v215, 0xffff0000, v244
	v_lshlrev_b32_e32 v216, 16, v245
	v_and_b32_e32 v217, 0xffff0000, v245
	v_pk_fma_f32 v[106:107], v[106:107], v[138:139], v[214:215]
	v_pk_fma_f32 v[108:109], v[108:109], v[140:141], v[216:217]
	v_mov_b32_e32 v222, 0x10000
	v_lshl_add_u64 v[192:193], v[162:163], 0, v[222:223]
	global_store_dwordx4 v[192:193], v[114:117], off
	global_store_dwordx4 v[192:193], v[106:109], off offset:64
	global_load_dwordx4 v[242:245], v[190:191], off offset:256
	s_waitcnt vmcnt(14)
	v_permlane16_swap_b32 v164, v166
	v_permlane16_swap_b32 v165, v167
	s_nop 1
	v_lshlrev_b32_e32 v210, 16, v164
	v_and_b32_e32 v211, 0xffff0000, v164
	v_lshlrev_b32_e32 v212, 16, v165
	v_and_b32_e32 v213, 0xffff0000, v165
	v_pk_fma_f32 v[102:103], v[102:103], v[134:135], v[210:211]
	v_pk_fma_f32 v[104:105], v[104:105], v[136:137], v[212:213]
	v_lshlrev_b32_e32 v214, 16, v166
	v_and_b32_e32 v215, 0xffff0000, v166
	v_lshlrev_b32_e32 v216, 16, v167
	v_and_b32_e32 v217, 0xffff0000, v167
	v_pk_fma_f32 v[94:95], v[94:95], v[130:131], v[214:215]
	v_pk_fma_f32 v[96:97], v[96:97], v[132:133], v[216:217]
	v_mov_b32_e32 v222, 0x10000
	v_lshl_add_u64 v[192:193], v[162:163], 0, v[222:223]
	global_store_dwordx4 v[192:193], v[102:105], off offset:512
	global_store_dwordx4 v[192:193], v[94:97], off offset:576
	v_mov_b32_e32 v222, 0x50000
	v_lshl_add_u64 v[190:191], v[246:247], 0, v[222:223]
	global_load_dwordx4 v[164:167], v[190:191], off
	s_waitcnt vmcnt(16)
	v_permlane16_swap_b32 v168, v170
	v_permlane16_swap_b32 v169, v171
	s_nop 1
	v_lshlrev_b32_e32 v210, 16, v168
	v_and_b32_e32 v211, 0xffff0000, v168
	v_lshlrev_b32_e32 v212, 16, v169
	v_and_b32_e32 v213, 0xffff0000, v169
	v_pk_fma_f32 v[98:99], v[98:99], v[142:143], v[210:211]
	v_pk_fma_f32 v[100:101], v[100:101], v[144:145], v[212:213]
	v_lshlrev_b32_e32 v214, 16, v170
	v_and_b32_e32 v215, 0xffff0000, v170
	v_lshlrev_b32_e32 v216, 16, v171
	v_and_b32_e32 v217, 0xffff0000, v171
	v_pk_fma_f32 v[90:91], v[90:91], v[138:139], v[214:215]
	v_pk_fma_f32 v[92:93], v[92:93], v[140:141], v[216:217]
	v_mov_b32_e32 v222, 0x20000
	v_lshl_add_u64 v[192:193], v[162:163], 0, v[222:223]
	global_store_dwordx4 v[192:193], v[98:101], off
	global_store_dwordx4 v[192:193], v[90:93], off offset:64
	global_load_dwordx4 v[168:171], v[190:191], off offset:256
	s_waitcnt vmcnt(18)
	v_permlane16_swap_b32 v172, v174
	v_permlane16_swap_b32 v173, v175
	s_nop 1
	v_lshlrev_b32_e32 v210, 16, v172
	v_and_b32_e32 v211, 0xffff0000, v172
	v_lshlrev_b32_e32 v212, 16, v173
	v_and_b32_e32 v213, 0xffff0000, v173
	v_pk_fma_f32 v[86:87], v[86:87], v[134:135], v[210:211]
	v_pk_fma_f32 v[88:89], v[88:89], v[136:137], v[212:213]
	v_lshlrev_b32_e32 v214, 16, v174
	v_and_b32_e32 v215, 0xffff0000, v174
	v_lshlrev_b32_e32 v216, 16, v175
	v_and_b32_e32 v217, 0xffff0000, v175
	v_pk_fma_f32 v[78:79], v[78:79], v[130:131], v[214:215]
	v_pk_fma_f32 v[80:81], v[80:81], v[132:133], v[216:217]
	v_mov_b32_e32 v222, 0x20000
	v_lshl_add_u64 v[192:193], v[162:163], 0, v[222:223]
	global_store_dwordx4 v[192:193], v[86:89], off offset:512
	global_store_dwordx4 v[192:193], v[78:81], off offset:576
	v_mov_b32_e32 v222, 0x58000
	v_lshl_add_u64 v[190:191], v[246:247], 0, v[222:223]
	global_load_dwordx4 v[172:175], v[190:191], off
	s_waitcnt vmcnt(20)
	v_permlane16_swap_b32 v176, v178
	v_permlane16_swap_b32 v177, v179
	s_nop 1
	v_lshlrev_b32_e32 v210, 16, v176
	v_and_b32_e32 v211, 0xffff0000, v176
	v_lshlrev_b32_e32 v212, 16, v177
	v_and_b32_e32 v213, 0xffff0000, v177
	v_pk_fma_f32 v[82:83], v[82:83], v[142:143], v[210:211]
	v_pk_fma_f32 v[84:85], v[84:85], v[144:145], v[212:213]
	v_lshlrev_b32_e32 v214, 16, v178
	v_and_b32_e32 v215, 0xffff0000, v178
	v_lshlrev_b32_e32 v216, 16, v179
	v_and_b32_e32 v217, 0xffff0000, v179
	v_pk_fma_f32 v[74:75], v[74:75], v[138:139], v[214:215]
	v_pk_fma_f32 v[76:77], v[76:77], v[140:141], v[216:217]
	v_mov_b32_e32 v222, 0x30000
	v_lshl_add_u64 v[192:193], v[162:163], 0, v[222:223]
	global_store_dwordx4 v[192:193], v[82:85], off
	global_store_dwordx4 v[192:193], v[74:77], off offset:64
	global_load_dwordx4 v[176:179], v[190:191], off offset:256
	s_waitcnt vmcnt(22)
	v_permlane16_swap_b32 v180, v182
	v_permlane16_swap_b32 v181, v183
	s_nop 1
	v_lshlrev_b32_e32 v210, 16, v180
	v_and_b32_e32 v211, 0xffff0000, v180
	v_lshlrev_b32_e32 v212, 16, v181
	v_and_b32_e32 v213, 0xffff0000, v181
	v_pk_fma_f32 v[70:71], v[70:71], v[134:135], v[210:211]
	v_pk_fma_f32 v[72:73], v[72:73], v[136:137], v[212:213]
	v_lshlrev_b32_e32 v214, 16, v182
	v_and_b32_e32 v215, 0xffff0000, v182
	v_lshlrev_b32_e32 v216, 16, v183
	v_and_b32_e32 v217, 0xffff0000, v183
	v_pk_fma_f32 v[66:67], v[66:67], v[130:131], v[214:215]
	v_pk_fma_f32 v[68:69], v[68:69], v[132:133], v[216:217]
	v_mov_b32_e32 v222, 0x30000
	v_lshl_add_u64 v[192:193], v[162:163], 0, v[222:223]
	global_store_dwordx4 v[192:193], v[70:73], off offset:512
	global_store_dwordx4 v[192:193], v[66:69], off offset:576
	s_waitcnt vmcnt(23)
	v_permlane16_swap_b32 v184, v186
	v_permlane16_swap_b32 v185, v187
	s_nop 1
	v_lshlrev_b32_e32 v210, 16, v184
	v_and_b32_e32 v211, 0xffff0000, v184
	v_lshlrev_b32_e32 v212, 16, v185
	v_and_b32_e32 v213, 0xffff0000, v185
	v_pk_fma_f32 v[62:63], v[62:63], v[142:143], v[210:211]
	v_pk_fma_f32 v[64:65], v[64:65], v[144:145], v[212:213]
	v_lshlrev_b32_e32 v214, 16, v186
	v_and_b32_e32 v215, 0xffff0000, v186
	v_lshlrev_b32_e32 v216, 16, v187
	v_and_b32_e32 v217, 0xffff0000, v187
	v_pk_fma_f32 v[58:59], v[58:59], v[138:139], v[214:215]
	v_pk_fma_f32 v[60:61], v[60:61], v[140:141], v[216:217]
	v_mov_b32_e32 v222, 0x80000
	v_lshl_add_u64 v[192:193], v[162:163], 0, v[222:223]
	global_store_dwordx4 v[192:193], v[62:65], off
	global_store_dwordx4 v[192:193], v[58:61], off offset:64
	s_waitcnt vmcnt(22)
	v_permlane16_swap_b32 v198, v200
	v_permlane16_swap_b32 v199, v201
	s_nop 1
	v_lshlrev_b32_e32 v210, 16, v198
	v_and_b32_e32 v211, 0xffff0000, v198
	v_lshlrev_b32_e32 v212, 16, v199
	v_and_b32_e32 v213, 0xffff0000, v199
	v_pk_fma_f32 v[54:55], v[54:55], v[134:135], v[210:211]
	v_pk_fma_f32 v[56:57], v[56:57], v[136:137], v[212:213]
	v_lshlrev_b32_e32 v214, 16, v200
	v_and_b32_e32 v215, 0xffff0000, v200
	v_lshlrev_b32_e32 v216, 16, v201
	v_and_b32_e32 v217, 0xffff0000, v201
	v_pk_fma_f32 v[44:45], v[44:45], v[130:131], v[214:215]
	v_pk_fma_f32 v[46:47], v[46:47], v[132:133], v[216:217]
	v_mov_b32_e32 v222, 0x80000
	v_lshl_add_u64 v[192:193], v[162:163], 0, v[222:223]
	global_store_dwordx4 v[192:193], v[54:57], off offset:512
	global_store_dwordx4 v[192:193], v[44:47], off offset:576
	s_waitcnt vmcnt(21)
	v_permlane16_swap_b32 v218, v220
	v_permlane16_swap_b32 v219, v221
	s_nop 1
	v_lshlrev_b32_e32 v210, 16, v218
	v_and_b32_e32 v211, 0xffff0000, v218
	v_lshlrev_b32_e32 v212, 16, v219
	v_and_b32_e32 v213, 0xffff0000, v219
	v_pk_fma_f32 v[50:51], v[50:51], v[142:143], v[210:211]
	v_pk_fma_f32 v[52:53], v[52:53], v[144:145], v[212:213]
	v_lshlrev_b32_e32 v214, 16, v220
	v_and_b32_e32 v215, 0xffff0000, v220
	v_lshlrev_b32_e32 v216, 16, v221
	v_and_b32_e32 v217, 0xffff0000, v221
	v_pk_fma_f32 v[40:41], v[40:41], v[138:139], v[214:215]
	v_pk_fma_f32 v[42:43], v[42:43], v[140:141], v[216:217]
	v_mov_b32_e32 v222, 0x90000
	v_lshl_add_u64 v[192:193], v[162:163], 0, v[222:223]
	global_store_dwordx4 v[192:193], v[50:53], off
	global_store_dwordx4 v[192:193], v[40:43], off offset:64
	s_waitcnt vmcnt(20)
	v_permlane16_swap_b32 v242, v244
	v_permlane16_swap_b32 v243, v245
	s_nop 1
	v_lshlrev_b32_e32 v210, 16, v242
	v_and_b32_e32 v211, 0xffff0000, v242
	v_lshlrev_b32_e32 v212, 16, v243
	v_and_b32_e32 v213, 0xffff0000, v243
	v_pk_fma_f32 v[36:37], v[36:37], v[134:135], v[210:211]
	v_pk_fma_f32 v[38:39], v[38:39], v[136:137], v[212:213]
	v_lshlrev_b32_e32 v214, 16, v244
	v_and_b32_e32 v215, 0xffff0000, v244
	v_lshlrev_b32_e32 v216, 16, v245
	v_and_b32_e32 v217, 0xffff0000, v245
	v_pk_fma_f32 v[28:29], v[28:29], v[130:131], v[214:215]
	v_pk_fma_f32 v[30:31], v[30:31], v[132:133], v[216:217]
	v_mov_b32_e32 v222, 0x90000
	v_lshl_add_u64 v[192:193], v[162:163], 0, v[222:223]
	global_store_dwordx4 v[192:193], v[36:39], off offset:512
	global_store_dwordx4 v[192:193], v[28:31], off offset:576
	s_waitcnt vmcnt(19)
	v_permlane16_swap_b32 v164, v166
	v_permlane16_swap_b32 v165, v167
	s_nop 1
	v_lshlrev_b32_e32 v210, 16, v164
	v_and_b32_e32 v211, 0xffff0000, v164
	v_lshlrev_b32_e32 v212, 16, v165
	v_and_b32_e32 v213, 0xffff0000, v165
	v_pk_fma_f32 v[32:33], v[32:33], v[142:143], v[210:211]
	v_pk_fma_f32 v[34:35], v[34:35], v[144:145], v[212:213]
	v_lshlrev_b32_e32 v214, 16, v166
	v_and_b32_e32 v215, 0xffff0000, v166
	v_lshlrev_b32_e32 v216, 16, v167
	v_and_b32_e32 v217, 0xffff0000, v167
	v_pk_fma_f32 v[24:25], v[24:25], v[138:139], v[214:215]
	v_pk_fma_f32 v[26:27], v[26:27], v[140:141], v[216:217]
	v_mov_b32_e32 v222, 0xa0000
	v_lshl_add_u64 v[192:193], v[162:163], 0, v[222:223]
	global_store_dwordx4 v[192:193], v[32:35], off
	global_store_dwordx4 v[192:193], v[24:27], off offset:64
	s_waitcnt vmcnt(18)
	v_permlane16_swap_b32 v168, v170
	v_permlane16_swap_b32 v169, v171
	s_nop 1
	v_lshlrev_b32_e32 v210, 16, v168
	v_and_b32_e32 v211, 0xffff0000, v168
	v_lshlrev_b32_e32 v212, 16, v169
	v_and_b32_e32 v213, 0xffff0000, v169
	v_pk_fma_f32 v[20:21], v[20:21], v[134:135], v[210:211]
	v_pk_fma_f32 v[22:23], v[22:23], v[136:137], v[212:213]
	v_lshlrev_b32_e32 v214, 16, v170
	v_and_b32_e32 v215, 0xffff0000, v170
	v_lshlrev_b32_e32 v216, 16, v171
	v_and_b32_e32 v217, 0xffff0000, v171
	v_pk_fma_f32 v[12:13], v[12:13], v[130:131], v[214:215]
	v_pk_fma_f32 v[14:15], v[14:15], v[132:133], v[216:217]
	v_mov_b32_e32 v222, 0xa0000
	v_lshl_add_u64 v[192:193], v[162:163], 0, v[222:223]
	global_store_dwordx4 v[192:193], v[20:23], off offset:512
	global_store_dwordx4 v[192:193], v[12:15], off offset:576
	s_waitcnt vmcnt(17)
	v_permlane16_swap_b32 v172, v174
	v_permlane16_swap_b32 v173, v175
	s_nop 1
	v_lshlrev_b32_e32 v210, 16, v172
	v_and_b32_e32 v211, 0xffff0000, v172
	v_lshlrev_b32_e32 v212, 16, v173
	v_and_b32_e32 v213, 0xffff0000, v173
	v_pk_fma_f32 v[16:17], v[16:17], v[142:143], v[210:211]
	v_pk_fma_f32 v[18:19], v[18:19], v[144:145], v[212:213]
	v_lshlrev_b32_e32 v214, 16, v174
	v_and_b32_e32 v215, 0xffff0000, v174
	v_lshlrev_b32_e32 v216, 16, v175
	v_and_b32_e32 v217, 0xffff0000, v175
	v_pk_fma_f32 v[8:9], v[8:9], v[138:139], v[214:215]
	v_pk_fma_f32 v[10:11], v[10:11], v[140:141], v[216:217]
	v_mov_b32_e32 v222, 0xb0000
	v_lshl_add_u64 v[192:193], v[162:163], 0, v[222:223]
	global_store_dwordx4 v[192:193], v[16:19], off
	global_store_dwordx4 v[192:193], v[8:11], off offset:64
	s_waitcnt vmcnt(16)
	v_permlane16_swap_b32 v176, v178
	v_permlane16_swap_b32 v177, v179
	s_nop 1
	v_lshlrev_b32_e32 v210, 16, v176
	v_and_b32_e32 v211, 0xffff0000, v176
	v_lshlrev_b32_e32 v212, 16, v177
	v_and_b32_e32 v213, 0xffff0000, v177
	v_pk_fma_f32 v[4:5], v[4:5], v[134:135], v[210:211]
	v_pk_fma_f32 v[6:7], v[6:7], v[136:137], v[212:213]
	v_lshlrev_b32_e32 v214, 16, v178
	v_and_b32_e32 v215, 0xffff0000, v178
	v_lshlrev_b32_e32 v216, 16, v179
	v_and_b32_e32 v217, 0xffff0000, v179
	v_pk_fma_f32 v[0:1], v[0:1], v[130:131], v[214:215]
	v_pk_fma_f32 v[2:3], v[2:3], v[132:133], v[216:217]
	v_mov_b32_e32 v222, 0xb0000
	v_lshl_add_u64 v[192:193], v[162:163], 0, v[222:223]
	global_store_dwordx4 v[192:193], v[4:7], off offset:512
	global_store_dwordx4 v[192:193], v[0:3], off offset:576
	s_mov_b32 s14, 0x30000
	s_mov_b32 s14, 0x80000
	s_mov_b32 s14, 0x90000
	s_mov_b32 s14, 0xa0000
	s_mov_b32 s14, 0xb0000
	s_and_b64 vcc, exec, s[0:1]
	s_mov_b32 s14, s43
	s_cbranch_vccz .LBB0_1418
	s_waitcnt vmcnt(0)
	s_cmpk_gt_u32 s24, 0xff
	s_cbranch_scc1 .LBB0_1425
	s_barrier

.LBB0_1435:
	s_add_u32 s20, s18, 0x100
	s_addc_u32 s21, s19, 0
	s_add_i32 s47, 0, 0x10000
	ds_read_b128 v[130:133], v214
	ds_read_b128 v[134:137], v214 offset:1024
	ds_read_b128 v[138:141], v214 offset:2048
	ds_read_b128 v[142:145], v214 offset:3072
	s_cmp_eq_u32 s46, 40
	s_cselect_b32 s25, s13, s21
	s_cselect_b32 s24, s12, s20
	s_cselect_b32 s23, s15, s45
	s_cselect_b32 s22, s14, s44
	v_lshl_add_u64 v[186:187], s[18:19], 0, v[150:151]
	s_add_i32 m0, s31, 0xc000
	ds_read_b128 v[154:157], v244
	ds_read_b128 v[158:161], v244 offset:1024
	ds_read_b128 v[162:165], v244 offset:2048
	ds_read_b128 v[166:169], v244 offset:3072
	ds_read_b128 v[170:173], v244 offset:4096
	ds_read_b128 v[174:177], v244 offset:5120
	ds_read_b128 v[178:181], v244 offset:6144
	ds_read_b128 v[182:185], v244 offset:7168
	global_load_lds_dwordx4 v[186:187], off
	v_lshl_add_u64 v[186:187], s[18:19], 0, v[152:153]
	s_add_i32 m0, s31, 0xe000
	s_nop 0
	global_load_lds_dwordx4 v[186:187], off
	s_waitcnt lgkmcnt(8)
	s_barrier
	s_waitcnt lgkmcnt(0)
	s_setprio 1
	v_mfma_f32_16x16x32_bf16 v[126:129], v[130:133], v[154:157], v[126:129]
	v_mfma_f32_16x16x32_bf16 v[122:125], v[138:141], v[154:157], v[122:125]
	v_mfma_f32_16x16x32_bf16 v[114:117], v[130:133], v[162:165], v[114:117]
	v_mfma_f32_16x16x32_bf16 v[106:109], v[138:141], v[162:165], v[106:109]
	v_mfma_f32_16x16x32_bf16 v[98:101], v[130:133], v[170:173], v[98:101]
	v_mfma_f32_16x16x32_bf16 v[90:93], v[138:141], v[170:173], v[90:93]
	v_mfma_f32_16x16x32_bf16 v[82:85], v[130:133], v[178:181], v[82:85]
	v_mfma_f32_16x16x32_bf16 v[74:77], v[138:141], v[178:181], v[74:77]
	v_mfma_f32_16x16x32_bf16 v[126:129], v[134:137], v[158:161], v[126:129]
	v_mfma_f32_16x16x32_bf16 v[122:125], v[142:145], v[158:161], v[122:125]
	v_mfma_f32_16x16x32_bf16 v[114:117], v[134:137], v[166:169], v[114:117]
	v_mfma_f32_16x16x32_bf16 v[106:109], v[142:145], v[166:169], v[106:109]
	v_mfma_f32_16x16x32_bf16 v[98:101], v[134:137], v[174:177], v[98:101]
	v_mfma_f32_16x16x32_bf16 v[90:93], v[142:145], v[174:177], v[90:93]
	v_mfma_f32_16x16x32_bf16 v[82:85], v[134:137], v[182:185], v[82:85]
	v_mfma_f32_16x16x32_bf16 v[74:77], v[142:145], v[182:185], v[74:77]
	s_setprio 0
	s_barrier
	s_add_i32 s48, 0, 0x14000
	s_add_i32 s18, s47, s30
	s_mov_b32 m0, s18
	ds_read_b128 v[186:189], v214 offset:16384
	ds_read_b128 v[190:193], v214 offset:17408
	ds_read_b128 v[198:201], v214 offset:18432
	ds_read_b128 v[202:205], v214 offset:19456
	global_load_lds_dwordx4 v48, s[22:23]
	v_lshl_add_u64 v[208:209], s[22:23], 0, v[146:147]
	s_add_i32 m0, s18, 0x2000
	s_nop 0
	global_load_lds_dwordx4 v[208:209], off
	s_barrier
	s_waitcnt lgkmcnt(0)
	s_setprio 1
	v_mfma_f32_16x16x32_bf16 v[118:121], v[186:189], v[154:157], v[118:121]
	v_mfma_f32_16x16x32_bf16 v[110:113], v[198:201], v[154:157], v[110:113]
	v_mfma_f32_16x16x32_bf16 v[102:105], v[186:189], v[162:165], v[102:105]
	v_mfma_f32_16x16x32_bf16 v[94:97], v[198:201], v[162:165], v[94:97]
	v_mfma_f32_16x16x32_bf16 v[86:89], v[186:189], v[170:173], v[86:89]
	v_mfma_f32_16x16x32_bf16 v[78:81], v[198:201], v[170:173], v[78:81]
	v_mfma_f32_16x16x32_bf16 v[70:73], v[186:189], v[178:181], v[70:73]
	v_mfma_f32_16x16x32_bf16 v[66:69], v[198:201], v[178:181], v[66:69]
	v_mfma_f32_16x16x32_bf16 v[118:121], v[190:193], v[158:161], v[118:121]
	v_mfma_f32_16x16x32_bf16 v[110:113], v[202:205], v[158:161], v[110:113]
	v_mfma_f32_16x16x32_bf16 v[102:105], v[190:193], v[166:169], v[102:105]
	v_mfma_f32_16x16x32_bf16 v[94:97], v[202:205], v[166:169], v[94:97]
	v_mfma_f32_16x16x32_bf16 v[86:89], v[190:193], v[174:177], v[86:89]
	v_mfma_f32_16x16x32_bf16 v[78:81], v[202:205], v[174:177], v[78:81]
	v_mfma_f32_16x16x32_bf16 v[70:73], v[190:193], v[182:185], v[70:73]
	v_mfma_f32_16x16x32_bf16 v[66:69], v[202:205], v[182:185], v[66:69]
	s_setprio 0
	s_mov_b32 m0, s31
	v_lshl_add_u64 v[210:211], s[24:25], 0, v[48:49]
	s_barrier
	ds_read_b128 v[154:157], v244 offset:16384
	ds_read_b128 v[158:161], v244 offset:17408
	ds_read_b128 v[162:165], v244 offset:18432
	ds_read_b128 v[166:169], v244 offset:19456
	ds_read_b128 v[170:173], v244 offset:20480
	ds_read_b128 v[174:177], v244 offset:21504
	ds_read_b128 v[178:181], v244 offset:22528
	ds_read_b128 v[182:185], v244 offset:23552
	global_load_lds_dwordx4 v[210:211], off
	v_lshl_add_u64 v[212:213], s[24:25], 0, v[146:147]
	s_mov_b32 m0, s34
	s_nop 0
	global_load_lds_dwordx4 v[212:213], off
	s_barrier
	s_waitcnt lgkmcnt(0)
	s_setprio 1
	v_mfma_f32_16x16x32_bf16 v[62:65], v[130:133], v[154:157], v[62:65]
	v_mfma_f32_16x16x32_bf16 v[58:61], v[138:141], v[154:157], v[58:61]
	v_mfma_f32_16x16x32_bf16 v[50:53], v[130:133], v[162:165], v[50:53]
	v_mfma_f32_16x16x32_bf16 v[40:43], v[138:141], v[162:165], v[40:43]
	v_mfma_f32_16x16x32_bf16 v[32:35], v[130:133], v[170:173], v[32:35]
	v_mfma_f32_16x16x32_bf16 v[24:27], v[138:141], v[170:173], v[24:27]
	v_mfma_f32_16x16x32_bf16 v[16:19], v[130:133], v[178:181], v[16:19]
	v_mfma_f32_16x16x32_bf16 v[8:11], v[138:141], v[178:181], v[8:11]
	v_mfma_f32_16x16x32_bf16 v[62:65], v[134:137], v[158:161], v[62:65]
	v_mfma_f32_16x16x32_bf16 v[58:61], v[142:145], v[158:161], v[58:61]
	v_mfma_f32_16x16x32_bf16 v[50:53], v[134:137], v[166:169], v[50:53]
	v_mfma_f32_16x16x32_bf16 v[40:43], v[142:145], v[166:169], v[40:43]
	v_mfma_f32_16x16x32_bf16 v[32:35], v[134:137], v[174:177], v[32:35]
	v_mfma_f32_16x16x32_bf16 v[24:27], v[142:145], v[174:177], v[24:27]
	v_mfma_f32_16x16x32_bf16 v[16:19], v[134:137], v[182:185], v[16:19]
	v_mfma_f32_16x16x32_bf16 v[8:11], v[142:145], v[182:185], v[8:11]
	s_setprio 0
	s_barrier
	s_add_u32 s18, s22, 0xb0000
	s_addc_u32 s19, s23, 0
	s_add_i32 s47, s48, s30
	s_mov_b32 m0, s47
	s_nop 0
	global_load_lds_dwordx4 v48, s[18:19]
	s_add_i32 m0, s47, 0x2000
	s_nop 0
	global_load_lds_dwordx4 v146, s[18:19]
	s_waitcnt vmcnt(6)
	s_barrier
	s_setprio 1
	v_mfma_f32_16x16x32_bf16 v[54:57], v[186:189], v[154:157], v[54:57]
	v_mfma_f32_16x16x32_bf16 v[44:47], v[198:201], v[154:157], v[44:47]
	v_mfma_f32_16x16x32_bf16 v[36:39], v[186:189], v[162:165], v[36:39]
	v_mfma_f32_16x16x32_bf16 v[28:31], v[198:201], v[162:165], v[28:31]
	v_mfma_f32_16x16x32_bf16 v[20:23], v[186:189], v[170:173], v[20:23]
	v_mfma_f32_16x16x32_bf16 v[12:15], v[198:201], v[170:173], v[12:15]
	v_mfma_f32_16x16x32_bf16 v[4:7], v[186:189], v[178:181], v[4:7]
	v_mfma_f32_16x16x32_bf16 v[0:3], v[198:201], v[178:181], v[0:3]
	v_mfma_f32_16x16x32_bf16 v[54:57], v[190:193], v[158:161], v[54:57]
	v_mfma_f32_16x16x32_bf16 v[44:47], v[202:205], v[158:161], v[44:47]
	v_mfma_f32_16x16x32_bf16 v[36:39], v[190:193], v[166:169], v[36:39]
	v_mfma_f32_16x16x32_bf16 v[28:31], v[202:205], v[166:169], v[28:31]
	v_mfma_f32_16x16x32_bf16 v[20:23], v[190:193], v[174:177], v[20:23]
	v_mfma_f32_16x16x32_bf16 v[12:15], v[202:205], v[174:177], v[12:15]
	v_mfma_f32_16x16x32_bf16 v[4:7], v[190:193], v[182:185], v[4:7]
	v_mfma_f32_16x16x32_bf16 v[0:3], v[202:205], v[182:185], v[0:3]
	s_setprio 0
	s_add_i32 s47, 0, 0x18000
	s_barrier
	ds_read_b128 v[130:133], v214 offset:32768
	ds_read_b128 v[134:137], v214 offset:33792
	ds_read_b128 v[138:141], v214 offset:34816
	ds_read_b128 v[142:145], v214 offset:35840
	s_add_u32 s18, s24, 0xb0000
	s_addc_u32 s19, s25, 0
	s_mov_b32 m0, s35
	ds_read_b128 v[154:157], v244 offset:32768
	ds_read_b128 v[158:161], v244 offset:33792
	ds_read_b128 v[162:165], v244 offset:34816
	ds_read_b128 v[166:169], v244 offset:35840
	ds_read_b128 v[170:173], v244 offset:36864
	ds_read_b128 v[174:177], v244 offset:37888
	ds_read_b128 v[178:181], v244 offset:38912
	ds_read_b128 v[182:185], v244 offset:39936
	global_load_lds_dwordx4 v48, s[18:19]
	s_mov_b32 m0, s36
	s_nop 0
	global_load_lds_dwordx4 v146, s[18:19]
	s_waitcnt lgkmcnt(8)
	s_barrier
	s_waitcnt lgkmcnt(0)
	s_setprio 1
	v_mfma_f32_16x16x32_bf16 v[126:129], v[130:133], v[154:157], v[126:129]
	v_mfma_f32_16x16x32_bf16 v[122:125], v[138:141], v[154:157], v[122:125]
	v_mfma_f32_16x16x32_bf16 v[114:117], v[130:133], v[162:165], v[114:117]
	v_mfma_f32_16x16x32_bf16 v[106:109], v[138:141], v[162:165], v[106:109]
	v_mfma_f32_16x16x32_bf16 v[98:101], v[130:133], v[170:173], v[98:101]
	v_mfma_f32_16x16x32_bf16 v[90:93], v[138:141], v[170:173], v[90:93]
	v_mfma_f32_16x16x32_bf16 v[82:85], v[130:133], v[178:181], v[82:85]
	v_mfma_f32_16x16x32_bf16 v[74:77], v[138:141], v[178:181], v[74:77]
	v_mfma_f32_16x16x32_bf16 v[126:129], v[134:137], v[158:161], v[126:129]
	v_mfma_f32_16x16x32_bf16 v[122:125], v[142:145], v[158:161], v[122:125]
	v_mfma_f32_16x16x32_bf16 v[114:117], v[134:137], v[166:169], v[114:117]
	v_mfma_f32_16x16x32_bf16 v[106:109], v[142:145], v[166:169], v[106:109]
	v_mfma_f32_16x16x32_bf16 v[98:101], v[134:137], v[174:177], v[98:101]
	v_mfma_f32_16x16x32_bf16 v[90:93], v[142:145], v[174:177], v[90:93]
	v_mfma_f32_16x16x32_bf16 v[82:85], v[134:137], v[182:185], v[82:85]
	v_mfma_f32_16x16x32_bf16 v[74:77], v[142:145], v[182:185], v[74:77]
	s_setprio 0
	s_barrier
	s_add_i32 s24, 0, 0x1c000
	s_add_i32 s18, s47, s30
	s_add_u32 s52, s22, s66
	s_addc_u32 s53, s23, s67
	s_mov_b32 m0, s18
	ds_read_b128 v[186:189], v214 offset:49152
	ds_read_b128 v[190:193], v214 offset:50176
	ds_read_b128 v[198:201], v214 offset:51200
	ds_read_b128 v[202:205], v214 offset:52224
	global_load_lds_dwordx4 v48, s[52:53]
	s_add_i32 m0, s18, 0x2000
	s_nop 0
	global_load_lds_dwordx4 v146, s[52:53]
	s_barrier
	s_waitcnt lgkmcnt(0)
	s_setprio 1
	v_mfma_f32_16x16x32_bf16 v[118:121], v[186:189], v[154:157], v[118:121]
	v_mfma_f32_16x16x32_bf16 v[110:113], v[198:201], v[154:157], v[110:113]
	v_mfma_f32_16x16x32_bf16 v[102:105], v[186:189], v[162:165], v[102:105]
	v_mfma_f32_16x16x32_bf16 v[94:97], v[198:201], v[162:165], v[94:97]
	v_mfma_f32_16x16x32_bf16 v[86:89], v[186:189], v[170:173], v[86:89]
	v_mfma_f32_16x16x32_bf16 v[78:81], v[198:201], v[170:173], v[78:81]
	v_mfma_f32_16x16x32_bf16 v[70:73], v[186:189], v[178:181], v[70:73]
	v_mfma_f32_16x16x32_bf16 v[66:69], v[198:201], v[178:181], v[66:69]
	v_mfma_f32_16x16x32_bf16 v[118:121], v[190:193], v[158:161], v[118:121]
	v_mfma_f32_16x16x32_bf16 v[110:113], v[202:205], v[158:161], v[110:113]
	v_mfma_f32_16x16x32_bf16 v[102:105], v[190:193], v[166:169], v[102:105]
	v_mfma_f32_16x16x32_bf16 v[94:97], v[202:205], v[166:169], v[94:97]
	v_mfma_f32_16x16x32_bf16 v[86:89], v[190:193], v[174:177], v[86:89]
	v_mfma_f32_16x16x32_bf16 v[78:81], v[202:205], v[174:177], v[78:81]
	v_mfma_f32_16x16x32_bf16 v[70:73], v[190:193], v[182:185], v[70:73]
	v_mfma_f32_16x16x32_bf16 v[66:69], v[202:205], v[182:185], v[66:69]
	s_setprio 0
	s_mov_b32 m0, s39
	v_lshl_add_u64 v[206:207], v[210:211], 0, s[66:67]
	s_barrier
	ds_read_b128 v[154:157], v244 offset:49152
	ds_read_b128 v[158:161], v244 offset:50176
	ds_read_b128 v[162:165], v244 offset:51200
	ds_read_b128 v[166:169], v244 offset:52224
	ds_read_b128 v[170:173], v244 offset:53248
	ds_read_b128 v[174:177], v244 offset:54272
	ds_read_b128 v[178:181], v244 offset:55296
	ds_read_b128 v[182:185], v244 offset:56320
	global_load_lds_dwordx4 v[206:207], off
	v_lshl_add_u64 v[206:207], v[212:213], 0, s[66:67]
	s_mov_b32 m0, s40
	s_nop 0
	global_load_lds_dwordx4 v[206:207], off
	s_barrier
	s_waitcnt lgkmcnt(0)
	s_setprio 1
	v_mfma_f32_16x16x32_bf16 v[62:65], v[130:133], v[154:157], v[62:65]
	v_mfma_f32_16x16x32_bf16 v[58:61], v[138:141], v[154:157], v[58:61]
	v_mfma_f32_16x16x32_bf16 v[50:53], v[130:133], v[162:165], v[50:53]
	v_mfma_f32_16x16x32_bf16 v[40:43], v[138:141], v[162:165], v[40:43]
	v_mfma_f32_16x16x32_bf16 v[32:35], v[130:133], v[170:173], v[32:35]
	v_mfma_f32_16x16x32_bf16 v[24:27], v[138:141], v[170:173], v[24:27]
	v_mfma_f32_16x16x32_bf16 v[16:19], v[130:133], v[178:181], v[16:19]
	v_mfma_f32_16x16x32_bf16 v[8:11], v[138:141], v[178:181], v[8:11]
	v_mfma_f32_16x16x32_bf16 v[62:65], v[134:137], v[158:161], v[62:65]
	v_mfma_f32_16x16x32_bf16 v[58:61], v[142:145], v[158:161], v[58:61]
	v_mfma_f32_16x16x32_bf16 v[50:53], v[134:137], v[166:169], v[50:53]
	v_mfma_f32_16x16x32_bf16 v[40:43], v[142:145], v[166:169], v[40:43]
	v_mfma_f32_16x16x32_bf16 v[32:35], v[134:137], v[174:177], v[32:35]
	v_mfma_f32_16x16x32_bf16 v[24:27], v[142:145], v[174:177], v[24:27]
	v_mfma_f32_16x16x32_bf16 v[16:19], v[134:137], v[182:185], v[16:19]
	v_mfma_f32_16x16x32_bf16 v[8:11], v[142:145], v[182:185], v[8:11]
	s_setprio 0
	s_barrier
	s_add_u32 s18, s22, 0xb0080
	s_addc_u32 s19, s23, 0
	s_add_i32 s22, s24, s30
	s_mov_b32 m0, s22
	s_nop 0
	global_load_lds_dwordx4 v48, s[18:19]
	s_add_i32 m0, s22, 0x2000
	s_nop 0
	global_load_lds_dwordx4 v146, s[18:19]
	s_waitcnt vmcnt(6)
	s_barrier
	s_setprio 1
	v_mfma_f32_16x16x32_bf16 v[54:57], v[186:189], v[154:157], v[54:57]
	v_mfma_f32_16x16x32_bf16 v[44:47], v[198:201], v[154:157], v[44:47]
	v_mfma_f32_16x16x32_bf16 v[36:39], v[186:189], v[162:165], v[36:39]
	v_mfma_f32_16x16x32_bf16 v[28:31], v[198:201], v[162:165], v[28:31]
	v_mfma_f32_16x16x32_bf16 v[20:23], v[186:189], v[170:173], v[20:23]
	v_mfma_f32_16x16x32_bf16 v[12:15], v[198:201], v[170:173], v[12:15]
	v_mfma_f32_16x16x32_bf16 v[4:7], v[186:189], v[178:181], v[4:7]
	v_mfma_f32_16x16x32_bf16 v[0:3], v[198:201], v[178:181], v[0:3]
	v_mfma_f32_16x16x32_bf16 v[54:57], v[190:193], v[158:161], v[54:57]
	v_mfma_f32_16x16x32_bf16 v[44:47], v[202:205], v[158:161], v[44:47]
	v_mfma_f32_16x16x32_bf16 v[36:39], v[190:193], v[166:169], v[36:39]
	v_mfma_f32_16x16x32_bf16 v[28:31], v[202:205], v[166:169], v[28:31]
	v_mfma_f32_16x16x32_bf16 v[20:23], v[190:193], v[174:177], v[20:23]
	v_mfma_f32_16x16x32_bf16 v[12:15], v[202:205], v[174:177], v[12:15]
	v_mfma_f32_16x16x32_bf16 v[4:7], v[190:193], v[182:185], v[4:7]
	v_mfma_f32_16x16x32_bf16 v[0:3], v[202:205], v[182:185], v[0:3]
	s_setprio 0
	s_add_i32 s46, s46, 2
	s_add_u32 s44, s44, 0x100
	s_addc_u32 s45, s45, 0
	s_cmp_gt_u32 s46, 41
	s_mov_b64 s[18:19], s[20:21]
	s_barrier
	s_cbranch_scc0 .LBB0_1435
	s_mul_hi_i32 s18, s16, 0x38e38e39
	s_lshr_b32 s19, s18, 31
	s_ashr_i32 s18, s18, 1
	s_add_i32 s18, s18, s19
	s_mul_i32 s19, s18, -9
	v_lshl_or_b32 v154, s17, 8, v243
	s_sub_i32 s17, 0, s16
	s_cmp_lg_u32 s19, s17
	s_cselect_b32 s17, s18, 32
	s_mul_hi_i32 s19, s17, 0x6000
	s_mulk_i32 s17, 0x6000
	s_add_u32 s18, s37, s17
	s_addc_u32 s19, s38, s19
	s_ashr_i32 s17, s16, 31
	s_lshl_b64 s[16:17], s[16:17], 18
	v_ashrrev_i32_e32 v155, 31, v154
	v_lshl_add_u64 v[156:157], s[16:17], 0, v[148:149]
	v_lshl_add_u64 v[130:131], v[154:155], 2, s[18:19]
	v_lshl_add_u64 v[154:155], v[156:157], 0, v[154:155]
	v_lshlrev_b64 v[184:185], 1, v[154:155]
	v_lshl_add_u64 v[154:155], s[10:11], 0, v[184:185]
	global_load_dwordx4 v[142:145], v[130:131], off
	global_load_dwordx4 v[138:141], v[130:131], off offset:64
	global_load_dwordx4 v[134:137], v[130:131], off offset:512
	s_nop 0
	global_load_dwordx4 v[130:133], v[130:131], off offset:576
	s_nop 0
	s_mov_b32 s16, 0x40000
	s_nop 0
	s_mov_b32 s17, 0x48000
	s_nop 0
	s_mov_b32 s18, 0x50000
	s_nop 0
	s_mov_b32 s19, 0x58000
	s_nop 0
	v_lshl_add_u64 v[184:185], s[6:7], 0, v[184:185]
	s_nop 0
	s_mov_b64 s[20:21], s[14:15]
	s_nop 0
	v_and_b32_e32 v210, 16, v224
	v_lshrrev_b32_e32 v211, 1, v210
	v_add_u32_e32 v210, v210, v211
	v_mov_b32_e32 v211, 0
	v_mov_b32_e32 v213, 0
	v_lshl_add_u64 v[214:215], v[154:155], 0, v[210:211]
	v_lshl_add_u64 v[216:217], v[184:185], 0, v[210:211]
	v_mov_b32_e32 v212, 0x0
	v_lshl_add_u64 v[218:219], v[214:215], 0, v[212:213]
	global_load_dwordx4 v[164:167], v[218:219], off
	global_load_dwordx4 v[168:171], v[218:219], off offset:256
	v_mov_b32_e32 v212, 0x8000
	v_lshl_add_u64 v[218:219], v[214:215], 0, v[212:213]
	global_load_dwordx4 v[172:175], v[218:219], off
	global_load_dwordx4 v[176:179], v[218:219], off offset:256
	v_mov_b32_e32 v212, 0x10000
	v_lshl_add_u64 v[218:219], v[214:215], 0, v[212:213]
	global_load_dwordx4 v[180:183], v[218:219], off
	global_load_dwordx4 v[198:201], v[218:219], off offset:256
	v_mov_b32_e32 v212, 0x18000
	v_lshl_add_u64 v[218:219], v[214:215], 0, v[212:213]
	global_load_dwordx4 v[202:205], v[218:219], off
	global_load_dwordx4 v[206:209], v[218:219], off offset:256
	s_waitcnt vmcnt(7)
	v_permlane16_swap_b32 v164, v166
	v_permlane16_swap_b32 v165, v167
	s_nop 1
	v_lshlrev_b32_e32 v186, 16, v164
	v_and_b32_e32 v187, 0xffff0000, v164
	v_lshlrev_b32_e32 v188, 16, v165
	v_and_b32_e32 v189, 0xffff0000, v165
	v_pk_fma_f32 v[126:127], v[126:127], v[142:143], v[186:187]
	v_pk_fma_f32 v[128:129], v[128:129], v[144:145], v[188:189]
	v_lshlrev_b32_e32 v190, 16, v166
	v_and_b32_e32 v191, 0xffff0000, v166
	v_lshlrev_b32_e32 v192, 16, v167
	v_and_b32_e32 v193, 0xffff0000, v167
	v_pk_fma_f32 v[122:123], v[122:123], v[138:139], v[190:191]
	v_pk_fma_f32 v[124:125], v[124:125], v[140:141], v[192:193]
	v_cvt_pk_bf16_f32 v126, v126, v127
	v_cvt_pk_bf16_f32 v127, v128, v129
	v_cvt_pk_bf16_f32 v128, v122, v123
	v_cvt_pk_bf16_f32 v129, v124, v125
	s_nop 1
	v_permlane16_swap_b32 v126, v128
	v_permlane16_swap_b32 v127, v129
	v_mov_b32_e32 v212, 0x0
	v_lshl_add_u64 v[220:221], v[216:217], 0, v[212:213]
	global_store_dwordx4 v[220:221], v[126:129], off
	v_mov_b32_e32 v212, 0x40000
	v_lshl_add_u64 v[218:219], v[214:215], 0, v[212:213]
	global_load_dwordx4 v[164:167], v[218:219], off
	s_waitcnt vmcnt(8)
	v_permlane16_swap_b32 v168, v170
	v_permlane16_swap_b32 v169, v171
	s_nop 1
	v_lshlrev_b32_e32 v186, 16, v168
	v_and_b32_e32 v187, 0xffff0000, v168
	v_lshlrev_b32_e32 v188, 16, v169
	v_and_b32_e32 v189, 0xffff0000, v169
	v_pk_fma_f32 v[118:119], v[118:119], v[134:135], v[186:187]
	v_pk_fma_f32 v[120:121], v[120:121], v[136:137], v[188:189]
	v_lshlrev_b32_e32 v190, 16, v170
	v_and_b32_e32 v191, 0xffff0000, v170
	v_lshlrev_b32_e32 v192, 16, v171
	v_and_b32_e32 v193, 0xffff0000, v171
	v_pk_fma_f32 v[110:111], v[110:111], v[130:131], v[190:191]
	v_pk_fma_f32 v[112:113], v[112:113], v[132:133], v[192:193]
	v_cvt_pk_bf16_f32 v118, v118, v119
	v_cvt_pk_bf16_f32 v119, v120, v121
	v_cvt_pk_bf16_f32 v120, v110, v111
	v_cvt_pk_bf16_f32 v121, v112, v113
	s_nop 1
	v_permlane16_swap_b32 v118, v120
	v_permlane16_swap_b32 v119, v121
	v_mov_b32_e32 v212, 0x0
	v_lshl_add_u64 v[220:221], v[216:217], 0, v[212:213]
	global_store_dwordx4 v[220:221], v[118:121], off offset:256
	global_load_dwordx4 v[168:171], v[218:219], off offset:256
	s_waitcnt vmcnt(9)
	v_permlane16_swap_b32 v172, v174
	v_permlane16_swap_b32 v173, v175
	s_nop 1
	v_lshlrev_b32_e32 v186, 16, v172
	v_and_b32_e32 v187, 0xffff0000, v172
	v_lshlrev_b32_e32 v188, 16, v173
	v_and_b32_e32 v189, 0xffff0000, v173
	v_pk_fma_f32 v[114:115], v[114:115], v[142:143], v[186:187]
	v_pk_fma_f32 v[116:117], v[116:117], v[144:145], v[188:189]
	v_lshlrev_b32_e32 v190, 16, v174
	v_and_b32_e32 v191, 0xffff0000, v174
	v_lshlrev_b32_e32 v192, 16, v175
	v_and_b32_e32 v193, 0xffff0000, v175
	v_pk_fma_f32 v[106:107], v[106:107], v[138:139], v[190:191]
	v_pk_fma_f32 v[108:109], v[108:109], v[140:141], v[192:193]
	v_cvt_pk_bf16_f32 v114, v114, v115
	v_cvt_pk_bf16_f32 v115, v116, v117
	v_cvt_pk_bf16_f32 v116, v106, v107
	v_cvt_pk_bf16_f32 v117, v108, v109
	s_nop 1
	v_permlane16_swap_b32 v114, v116
	v_permlane16_swap_b32 v115, v117
	v_mov_b32_e32 v212, 0x8000
	v_lshl_add_u64 v[220:221], v[216:217], 0, v[212:213]
	global_store_dwordx4 v[220:221], v[114:117], off
	v_mov_b32_e32 v212, 0x48000
	v_lshl_add_u64 v[218:219], v[214:215], 0, v[212:213]
	global_load_dwordx4 v[172:175], v[218:219], off
	s_waitcnt vmcnt(10)
	v_permlane16_swap_b32 v176, v178
	v_permlane16_swap_b32 v177, v179
	s_nop 1
	v_lshlrev_b32_e32 v186, 16, v176
	v_and_b32_e32 v187, 0xffff0000, v176
	v_lshlrev_b32_e32 v188, 16, v177
	v_and_b32_e32 v189, 0xffff0000, v177
	v_pk_fma_f32 v[102:103], v[102:103], v[134:135], v[186:187]
	v_pk_fma_f32 v[104:105], v[104:105], v[136:137], v[188:189]
	v_lshlrev_b32_e32 v190, 16, v178
	v_and_b32_e32 v191, 0xffff0000, v178
	v_lshlrev_b32_e32 v192, 16, v179
	v_and_b32_e32 v193, 0xffff0000, v179
	v_pk_fma_f32 v[94:95], v[94:95], v[130:131], v[190:191]
	v_pk_fma_f32 v[96:97], v[96:97], v[132:133], v[192:193]
	v_cvt_pk_bf16_f32 v102, v102, v103
	v_cvt_pk_bf16_f32 v103, v104, v105
	v_cvt_pk_bf16_f32 v104, v94, v95
	v_cvt_pk_bf16_f32 v105, v96, v97
	s_nop 1
	v_permlane16_swap_b32 v102, v104
	v_permlane16_swap_b32 v103, v105
	v_mov_b32_e32 v212, 0x8000
	v_lshl_add_u64 v[220:221], v[216:217], 0, v[212:213]
	global_store_dwordx4 v[220:221], v[102:105], off offset:256
	global_load_dwordx4 v[176:179], v[218:219], off offset:256
	s_waitcnt vmcnt(11)
	v_permlane16_swap_b32 v180, v182
	v_permlane16_swap_b32 v181, v183
	s_nop 1
	v_lshlrev_b32_e32 v186, 16, v180
	v_and_b32_e32 v187, 0xffff0000, v180
	v_lshlrev_b32_e32 v188, 16, v181
	v_and_b32_e32 v189, 0xffff0000, v181
	v_pk_fma_f32 v[98:99], v[98:99], v[142:143], v[186:187]
	v_pk_fma_f32 v[100:101], v[100:101], v[144:145], v[188:189]
	v_lshlrev_b32_e32 v190, 16, v182
	v_and_b32_e32 v191, 0xffff0000, v182
	v_lshlrev_b32_e32 v192, 16, v183
	v_and_b32_e32 v193, 0xffff0000, v183
	v_pk_fma_f32 v[90:91], v[90:91], v[138:139], v[190:191]
	v_pk_fma_f32 v[92:93], v[92:93], v[140:141], v[192:193]
	v_cvt_pk_bf16_f32 v98, v98, v99
	v_cvt_pk_bf16_f32 v99, v100, v101
	v_cvt_pk_bf16_f32 v100, v90, v91
	v_cvt_pk_bf16_f32 v101, v92, v93
	s_nop 1
	v_permlane16_swap_b32 v98, v100
	v_permlane16_swap_b32 v99, v101
	v_mov_b32_e32 v212, 0x10000
	v_lshl_add_u64 v[220:221], v[216:217], 0, v[212:213]
	global_store_dwordx4 v[220:221], v[98:101], off
	v_mov_b32_e32 v212, 0x50000
	v_lshl_add_u64 v[218:219], v[214:215], 0, v[212:213]
	global_load_dwordx4 v[180:183], v[218:219], off
	s_waitcnt vmcnt(12)
	v_permlane16_swap_b32 v198, v200
	v_permlane16_swap_b32 v199, v201
	s_nop 1
	v_lshlrev_b32_e32 v186, 16, v198
	v_and_b32_e32 v187, 0xffff0000, v198
	v_lshlrev_b32_e32 v188, 16, v199
	v_and_b32_e32 v189, 0xffff0000, v199
	v_pk_fma_f32 v[86:87], v[86:87], v[134:135], v[186:187]
	v_pk_fma_f32 v[88:89], v[88:89], v[136:137], v[188:189]
	v_lshlrev_b32_e32 v190, 16, v200
	v_and_b32_e32 v191, 0xffff0000, v200
	v_lshlrev_b32_e32 v192, 16, v201
	v_and_b32_e32 v193, 0xffff0000, v201
	v_pk_fma_f32 v[78:79], v[78:79], v[130:131], v[190:191]
	v_pk_fma_f32 v[80:81], v[80:81], v[132:133], v[192:193]
	v_cvt_pk_bf16_f32 v86, v86, v87
	v_cvt_pk_bf16_f32 v87, v88, v89
	v_cvt_pk_bf16_f32 v88, v78, v79
	v_cvt_pk_bf16_f32 v89, v80, v81
	s_nop 1
	v_permlane16_swap_b32 v86, v88
	v_permlane16_swap_b32 v87, v89
	v_mov_b32_e32 v212, 0x10000
	v_lshl_add_u64 v[220:221], v[216:217], 0, v[212:213]
	global_store_dwordx4 v[220:221], v[86:89], off offset:256
	global_load_dwordx4 v[198:201], v[218:219], off offset:256
	s_waitcnt vmcnt(13)
	v_permlane16_swap_b32 v202, v204
	v_permlane16_swap_b32 v203, v205
	s_nop 1
	v_lshlrev_b32_e32 v186, 16, v202
	v_and_b32_e32 v187, 0xffff0000, v202
	v_lshlrev_b32_e32 v188, 16, v203
	v_and_b32_e32 v189, 0xffff0000, v203
	v_pk_fma_f32 v[82:83], v[82:83], v[142:143], v[186:187]
	v_pk_fma_f32 v[84:85], v[84:85], v[144:145], v[188:189]
	v_lshlrev_b32_e32 v190, 16, v204
	v_and_b32_e32 v191, 0xffff0000, v204
	v_lshlrev_b32_e32 v192, 16, v205
	v_and_b32_e32 v193, 0xffff0000, v205
	v_pk_fma_f32 v[74:75], v[74:75], v[138:139], v[190:191]
	v_pk_fma_f32 v[76:77], v[76:77], v[140:141], v[192:193]
	v_cvt_pk_bf16_f32 v82, v82, v83
	v_cvt_pk_bf16_f32 v83, v84, v85
	v_cvt_pk_bf16_f32 v84, v74, v75
	v_cvt_pk_bf16_f32 v85, v76, v77
	s_nop 1
	v_permlane16_swap_b32 v82, v84
	v_permlane16_swap_b32 v83, v85
	v_mov_b32_e32 v212, 0x18000
	v_lshl_add_u64 v[220:221], v[216:217], 0, v[212:213]
	global_store_dwordx4 v[220:221], v[82:85], off
	v_mov_b32_e32 v212, 0x58000
	v_lshl_add_u64 v[218:219], v[214:215], 0, v[212:213]
	global_load_dwordx4 v[202:205], v[218:219], off
	s_waitcnt vmcnt(14)
	v_permlane16_swap_b32 v206, v208
	v_permlane16_swap_b32 v207, v209
	s_nop 1
	v_lshlrev_b32_e32 v186, 16, v206
	v_and_b32_e32 v187, 0xffff0000, v206
	v_lshlrev_b32_e32 v188, 16, v207
	v_and_b32_e32 v189, 0xffff0000, v207
	v_pk_fma_f32 v[70:71], v[70:71], v[134:135], v[186:187]
	v_pk_fma_f32 v[72:73], v[72:73], v[136:137], v[188:189]
	v_lshlrev_b32_e32 v190, 16, v208
	v_and_b32_e32 v191, 0xffff0000, v208
	v_lshlrev_b32_e32 v192, 16, v209
	v_and_b32_e32 v193, 0xffff0000, v209
	v_pk_fma_f32 v[66:67], v[66:67], v[130:131], v[190:191]
	v_pk_fma_f32 v[68:69], v[68:69], v[132:133], v[192:193]
	v_cvt_pk_bf16_f32 v70, v70, v71
	v_cvt_pk_bf16_f32 v71, v72, v73
	v_cvt_pk_bf16_f32 v72, v66, v67
	v_cvt_pk_bf16_f32 v73, v68, v69
	s_nop 1
	v_permlane16_swap_b32 v70, v72
	v_permlane16_swap_b32 v71, v73
	v_mov_b32_e32 v212, 0x18000
	v_lshl_add_u64 v[220:221], v[216:217], 0, v[212:213]
	global_store_dwordx4 v[220:221], v[70:73], off offset:256
	global_load_dwordx4 v[206:209], v[218:219], off offset:256
	s_waitcnt vmcnt(14)
	v_permlane16_swap_b32 v164, v166
	v_permlane16_swap_b32 v165, v167
	s_nop 1
	v_lshlrev_b32_e32 v186, 16, v164
	v_and_b32_e32 v187, 0xffff0000, v164
	v_lshlrev_b32_e32 v188, 16, v165
	v_and_b32_e32 v189, 0xffff0000, v165
	v_pk_fma_f32 v[62:63], v[62:63], v[142:143], v[186:187]
	v_pk_fma_f32 v[64:65], v[64:65], v[144:145], v[188:189]
	v_lshlrev_b32_e32 v190, 16, v166
	v_and_b32_e32 v191, 0xffff0000, v166
	v_lshlrev_b32_e32 v192, 16, v167
	v_and_b32_e32 v193, 0xffff0000, v167
	v_pk_fma_f32 v[58:59], v[58:59], v[138:139], v[190:191]
	v_pk_fma_f32 v[60:61], v[60:61], v[140:141], v[192:193]
	v_cvt_pk_bf16_f32 v62, v62, v63
	v_cvt_pk_bf16_f32 v63, v64, v65
	v_cvt_pk_bf16_f32 v64, v58, v59
	v_cvt_pk_bf16_f32 v65, v60, v61
	s_nop 1
	v_permlane16_swap_b32 v62, v64
	v_permlane16_swap_b32 v63, v65
	v_mov_b32_e32 v212, 0x40000
	v_lshl_add_u64 v[220:221], v[216:217], 0, v[212:213]
	global_store_dwordx4 v[220:221], v[62:65], off
	s_waitcnt vmcnt(13)
	v_permlane16_swap_b32 v168, v170
	v_permlane16_swap_b32 v169, v171
	s_nop 1
	v_lshlrev_b32_e32 v186, 16, v168
	v_and_b32_e32 v187, 0xffff0000, v168
	v_lshlrev_b32_e32 v188, 16, v169
	v_and_b32_e32 v189, 0xffff0000, v169
	v_pk_fma_f32 v[54:55], v[54:55], v[134:135], v[186:187]
	v_pk_fma_f32 v[56:57], v[56:57], v[136:137], v[188:189]
	v_lshlrev_b32_e32 v190, 16, v170
	v_and_b32_e32 v191, 0xffff0000, v170
	v_lshlrev_b32_e32 v192, 16, v171
	v_and_b32_e32 v193, 0xffff0000, v171
	v_pk_fma_f32 v[44:45], v[44:45], v[130:131], v[190:191]
	v_pk_fma_f32 v[46:47], v[46:47], v[132:133], v[192:193]
	v_cvt_pk_bf16_f32 v54, v54, v55
	v_cvt_pk_bf16_f32 v55, v56, v57
	v_cvt_pk_bf16_f32 v56, v44, v45
	v_cvt_pk_bf16_f32 v57, v46, v47
	s_nop 1
	v_permlane16_swap_b32 v54, v56
	v_permlane16_swap_b32 v55, v57
	v_mov_b32_e32 v212, 0x40000
	v_lshl_add_u64 v[220:221], v[216:217], 0, v[212:213]
	global_store_dwordx4 v[220:221], v[54:57], off offset:256
	s_waitcnt vmcnt(12)
	v_permlane16_swap_b32 v172, v174
	v_permlane16_swap_b32 v173, v175
	s_nop 1
	v_lshlrev_b32_e32 v186, 16, v172
	v_and_b32_e32 v187, 0xffff0000, v172
	v_lshlrev_b32_e32 v188, 16, v173
	v_and_b32_e32 v189, 0xffff0000, v173
	v_pk_fma_f32 v[50:51], v[50:51], v[142:143], v[186:187]
	v_pk_fma_f32 v[52:53], v[52:53], v[144:145], v[188:189]
	v_lshlrev_b32_e32 v190, 16, v174
	v_and_b32_e32 v191, 0xffff0000, v174
	v_lshlrev_b32_e32 v192, 16, v175
	v_and_b32_e32 v193, 0xffff0000, v175
	v_pk_fma_f32 v[40:41], v[40:41], v[138:139], v[190:191]
	v_pk_fma_f32 v[42:43], v[42:43], v[140:141], v[192:193]
	v_cvt_pk_bf16_f32 v50, v50, v51
	v_cvt_pk_bf16_f32 v51, v52, v53
	v_cvt_pk_bf16_f32 v52, v40, v41
	v_cvt_pk_bf16_f32 v53, v42, v43
	s_nop 1
	v_permlane16_swap_b32 v50, v52
	v_permlane16_swap_b32 v51, v53
	v_mov_b32_e32 v212, 0x48000
	v_lshl_add_u64 v[220:221], v[216:217], 0, v[212:213]
	global_store_dwordx4 v[220:221], v[50:53], off
	s_waitcnt vmcnt(11)
	v_permlane16_swap_b32 v176, v178
	v_permlane16_swap_b32 v177, v179
	s_nop 1
	v_lshlrev_b32_e32 v186, 16, v176
	v_and_b32_e32 v187, 0xffff0000, v176
	v_lshlrev_b32_e32 v188, 16, v177
	v_and_b32_e32 v189, 0xffff0000, v177
	v_pk_fma_f32 v[36:37], v[36:37], v[134:135], v[186:187]
	v_pk_fma_f32 v[38:39], v[38:39], v[136:137], v[188:189]
	v_lshlrev_b32_e32 v190, 16, v178
	v_and_b32_e32 v191, 0xffff0000, v178
	v_lshlrev_b32_e32 v192, 16, v179
	v_and_b32_e32 v193, 0xffff0000, v179
	v_pk_fma_f32 v[28:29], v[28:29], v[130:131], v[190:191]
	v_pk_fma_f32 v[30:31], v[30:31], v[132:133], v[192:193]
	v_cvt_pk_bf16_f32 v36, v36, v37
	v_cvt_pk_bf16_f32 v37, v38, v39
	v_cvt_pk_bf16_f32 v38, v28, v29
	v_cvt_pk_bf16_f32 v39, v30, v31
	s_nop 1
	v_permlane16_swap_b32 v36, v38
	v_permlane16_swap_b32 v37, v39
	v_mov_b32_e32 v212, 0x48000
	v_lshl_add_u64 v[220:221], v[216:217], 0, v[212:213]
	global_store_dwordx4 v[220:221], v[36:39], off offset:256
	s_waitcnt vmcnt(10)
	v_permlane16_swap_b32 v180, v182
	v_permlane16_swap_b32 v181, v183
	s_nop 1
	v_lshlrev_b32_e32 v186, 16, v180
	v_and_b32_e32 v187, 0xffff0000, v180
	v_lshlrev_b32_e32 v188, 16, v181
	v_and_b32_e32 v189, 0xffff0000, v181
	v_pk_fma_f32 v[32:33], v[32:33], v[142:143], v[186:187]
	v_pk_fma_f32 v[34:35], v[34:35], v[144:145], v[188:189]
	v_lshlrev_b32_e32 v190, 16, v182
	v_and_b32_e32 v191, 0xffff0000, v182
	v_lshlrev_b32_e32 v192, 16, v183
	v_and_b32_e32 v193, 0xffff0000, v183
	v_pk_fma_f32 v[24:25], v[24:25], v[138:139], v[190:191]
	v_pk_fma_f32 v[26:27], v[26:27], v[140:141], v[192:193]
	v_cvt_pk_bf16_f32 v32, v32, v33
	v_cvt_pk_bf16_f32 v33, v34, v35
	v_cvt_pk_bf16_f32 v34, v24, v25
	v_cvt_pk_bf16_f32 v35, v26, v27
	s_nop 1
	v_permlane16_swap_b32 v32, v34
	v_permlane16_swap_b32 v33, v35
	v_mov_b32_e32 v212, 0x50000
	v_lshl_add_u64 v[220:221], v[216:217], 0, v[212:213]
	global_store_dwordx4 v[220:221], v[32:35], off
	s_waitcnt vmcnt(9)
	v_permlane16_swap_b32 v198, v200
	v_permlane16_swap_b32 v199, v201
	s_nop 1
	v_lshlrev_b32_e32 v186, 16, v198
	v_and_b32_e32 v187, 0xffff0000, v198
	v_lshlrev_b32_e32 v188, 16, v199
	v_and_b32_e32 v189, 0xffff0000, v199
	v_pk_fma_f32 v[20:21], v[20:21], v[134:135], v[186:187]
	v_pk_fma_f32 v[22:23], v[22:23], v[136:137], v[188:189]
	v_lshlrev_b32_e32 v190, 16, v200
	v_and_b32_e32 v191, 0xffff0000, v200
	v_lshlrev_b32_e32 v192, 16, v201
	v_and_b32_e32 v193, 0xffff0000, v201
	v_pk_fma_f32 v[12:13], v[12:13], v[130:131], v[190:191]
	v_pk_fma_f32 v[14:15], v[14:15], v[132:133], v[192:193]
	v_cvt_pk_bf16_f32 v20, v20, v21
	v_cvt_pk_bf16_f32 v21, v22, v23
	v_cvt_pk_bf16_f32 v22, v12, v13
	v_cvt_pk_bf16_f32 v23, v14, v15
	s_nop 1
	v_permlane16_swap_b32 v20, v22
	v_permlane16_swap_b32 v21, v23
	v_mov_b32_e32 v212, 0x50000
	v_lshl_add_u64 v[220:221], v[216:217], 0, v[212:213]
	global_store_dwordx4 v[220:221], v[20:23], off offset:256
	s_waitcnt vmcnt(8)
	v_permlane16_swap_b32 v202, v204
	v_permlane16_swap_b32 v203, v205
	s_nop 1
	v_lshlrev_b32_e32 v186, 16, v202
	v_and_b32_e32 v187, 0xffff0000, v202
	v_lshlrev_b32_e32 v188, 16, v203
	v_and_b32_e32 v189, 0xffff0000, v203
	v_pk_fma_f32 v[16:17], v[16:17], v[142:143], v[186:187]
	v_pk_fma_f32 v[18:19], v[18:19], v[144:145], v[188:189]
	v_lshlrev_b32_e32 v190, 16, v204
	v_and_b32_e32 v191, 0xffff0000, v204
	v_lshlrev_b32_e32 v192, 16, v205
	v_and_b32_e32 v193, 0xffff0000, v205
	v_pk_fma_f32 v[8:9], v[8:9], v[138:139], v[190:191]
	v_pk_fma_f32 v[10:11], v[10:11], v[140:141], v[192:193]
	v_cvt_pk_bf16_f32 v16, v16, v17
	v_cvt_pk_bf16_f32 v17, v18, v19
	v_cvt_pk_bf16_f32 v18, v8, v9
	v_cvt_pk_bf16_f32 v19, v10, v11
	s_nop 1
	v_permlane16_swap_b32 v16, v18
	v_permlane16_swap_b32 v17, v19
	v_mov_b32_e32 v212, 0x58000
	v_lshl_add_u64 v[220:221], v[216:217], 0, v[212:213]
	global_store_dwordx4 v[220:221], v[16:19], off
	s_waitcnt vmcnt(7)
	v_permlane16_swap_b32 v206, v208
	v_permlane16_swap_b32 v207, v209
	s_nop 1
	v_lshlrev_b32_e32 v186, 16, v206
	v_and_b32_e32 v187, 0xffff0000, v206
	v_lshlrev_b32_e32 v188, 16, v207
	v_and_b32_e32 v189, 0xffff0000, v207
	v_pk_fma_f32 v[4:5], v[4:5], v[134:135], v[186:187]
	v_pk_fma_f32 v[6:7], v[6:7], v[136:137], v[188:189]
	v_lshlrev_b32_e32 v190, 16, v208
	v_and_b32_e32 v191, 0xffff0000, v208
	v_lshlrev_b32_e32 v192, 16, v209
	v_and_b32_e32 v193, 0xffff0000, v209
	v_pk_fma_f32 v[0:1], v[0:1], v[130:131], v[190:191]
	v_pk_fma_f32 v[2:3], v[2:3], v[132:133], v[192:193]
	v_cvt_pk_bf16_f32 v4, v4, v5
	v_cvt_pk_bf16_f32 v5, v6, v7
	v_cvt_pk_bf16_f32 v6, v0, v1
	v_cvt_pk_bf16_f32 v7, v2, v3
	s_nop 1
	v_permlane16_swap_b32 v4, v6
	v_permlane16_swap_b32 v5, v7
	v_mov_b32_e32 v212, 0x58000
	v_lshl_add_u64 v[220:221], v[216:217], 0, v[212:213]
	global_store_dwordx4 v[220:221], v[4:7], off offset:256
	s_mov_b32 s16, s43
	s_mov_b32 s17, s42
	s_and_b64 vcc, exec, s[0:1]
	s_mov_b64 s[18:19], s[12:13]
	s_cbranch_vccz .LBB0_1432
	s_waitcnt vmcnt(0)
	s_cmpk_gt_u32 s29, 0xff
	s_cbranch_scc1 .LBB0_1439
	s_barrier
